# speedup vs baseline: 1.0075x; 1.0075x over previous
;     DI size_t aoff(const Unit& u, size_t tstep) const { return (size_t)u.pm * tstep; }
;     DI size_t boff(const Unit& u, size_t tstep) const { return (size_t)u.pn * tstep; }
;     DI bool next(int i, Unit& u) const { const long L = (long)i * G + c; if (L >= np) return false; u.pm = pmv; u.pn = (int)(L % nN); u.ks = (int)(L / nN); return true; }
;     DI size_t aoff(const Unit& u, size_t) const { return (size_t)u.ks * kbytes; }
;     DI size_t boff(const Unit& u, size_t tstep) const { return (size_t)u.pn * tstep + (size_t)u.ks * kbytes; }
;     DI bool next(int i, Unit& u) const { Unit t; if (!S.next(i / 3, t)) return false; u.pm = t.pm; u.pn = t.pn; u.ks = i % 3; return true; }
;     DI size_t aoff(const Unit& u, size_t tstep) const { return (u.ks < 2 ? offU : offOA) + (size_t)u.pm * tstep; }
; #define PG8_LDA(dst, b, h) do { _Pragma("unroll") for (int m = 0; m < 4; ++m) _Pragma("unroll") for (int k = 0; k < 2; ++k) dst[m][k] = *(const LAS bf16x8*)(lds + PG8_SA(b, h) + aoff + m * 2048 + k * 1024); } while (0)
; template <class Epi, class Sched>
; DI void gemm_phase(LAS unsigned char* lds, const Gemm g, const Sched& S, const Epi& E) {
;     ...
;         const bool has_next = S.next(ui + 1, nxt);
;         const char* nA = has_next ? (const char*)g.A + S.aoff(nxt, tstep) : cA; const char* nB = has_next ? (const char*)g.Bt + S.boff(nxt, tstep) : cB;
;         for (int t = 0; t < nt; t += 2) {
;             if constexpr (Epi::HAS_MID) { if (t == E.mid_t(nt)) { int fr3 = fr, fq3 = fq; asm volatile("" : "+v"(fr3), "+v"(fq3)); E.mid(acc, cur, wr, wc, fr3, fq3); } }
;             const bool last = (t == nt - 2);
;             const char* a1 = cA + (size_t)(t + 1) * kstep;
;             const char* a2 = last ? nA : cA + (size_t)(t + 2) * kstep; const char* b2 = last ? nB : cB + (size_t)(t + 2) * kstep;
;             const char* a3 = a2 + kstep; const char* b3 = b2 + kstep;
;             PG8_LDB(B0, 0, 0); PG8_SCHED; PG8_LDA(At, 0, 0); PG8_STAGE(PG8_SA(1, 1), a1 + hstep, voffA);
;             PG8_WAIT_L(8); PG8_BAR; PG8_WAIT_L(0); PG8_MMA(0, 0, At, B0); PG8_BAR; PG8_SCHED;
;             PG8_LDB(B1, 0, 1); PG8_STAGE(PG8_SB(0, 0), b2, voffB);
;             PG8_BAR; PG8_WAIT_L(0); PG8_MMA(0, 1, At, B1); PG8_BAR;
;             PG8_LDA(At, 0, 1); PG8_STAGE(PG8_SA(0, 0), a2, voffA);
;             PG8_BAR; PG8_WAIT_L(0); PG8_MMA(1, 0, At, B0); PG8_BAR; PG8_SCHED;
.LBB0_218:
	s_ashr_i32 s17, s16, 31
	s_lshl_b64 s[0:1], s[16:17], 20
	v_cmp_lt_i64_e32 vcc, s[18:19], v[140:141]
	s_add_u32 s18, s47, s0
	s_addc_u32 s19, s48, s1
	s_and_b64 s[0:1], vcc, exec
	s_cselect_b32 s17, s19, s41
	s_cselect_b32 s65, s18, s40
	s_ashr_i32 s15, s14, 31
	s_lshl_b64 s[0:1], s[14:15], 20
	s_add_u32 s36, s49, s0
	s_addc_u32 s37, s50, s1
	s_and_b64 s[0:1], vcc, exec
	s_cselect_b32 s15, s37, s43
	s_cselect_b32 s66, s36, s42
	s_add_u32 s40, s40, 0x80080
	s_addc_u32 s41, s41, 0
	s_add_u32 s67, s42, 0x100
	v_mov_b32_e32 v0, 0
	s_addc_u32 s68, s43, 0
	s_mov_b32 s69, -2
	ds_read_b128 v[150:153], v147
	ds_read_b128 v[154:157], v147 offset:1024
	ds_read_b128 v[162:165], v147 offset:2048
	ds_read_b128 v[166:169], v147 offset:3072
	s_add_i32 m0, s39, 0xc000
	ds_read_b128 v[170:173], v148
	ds_read_b128 v[174:177], v148 offset:1024
	ds_read_b128 v[178:181], v148 offset:2048
	ds_read_b128 v[188:191], v148 offset:3072
	ds_read_b128 v[194:197], v148 offset:4096
	ds_read_b128 v[198:201], v148 offset:5120
	ds_read_b128 v[202:205], v148 offset:6144
	global_load_lds_dwordx4 v136, s[40:41]
	s_add_i32 m0, s39, 0xe000
	ds_read_b128 v[206:209], v148 offset:7168
	global_load_lds_dwordx4 v138, s[40:41]
	s_add_u32 s0, s40, 0xfff80080
	s_addc_u32 s1, s41, -1
	s_cmp_eq_u32 s69, 28
	s_cselect_b32 s45, s17, s1
	s_cselect_b32 s44, s65, s0
	s_cselect_b32 s43, s15, s68
	s_cselect_b32 s42, s66, s67
	s_waitcnt lgkmcnt(8)
	s_barrier
	s_waitcnt lgkmcnt(0)
	s_setprio 1
	v_mfma_f32_16x16x32_bf16 v[124:127], v[150:153], v[170:173], 0
	v_mfma_f32_16x16x32_bf16 v[120:123], v[162:165], v[170:173], 0
	v_mfma_f32_16x16x32_bf16 v[108:111], v[150:153], v[178:181], 0
	v_mfma_f32_16x16x32_bf16 v[104:107], v[162:165], v[178:181], 0
	v_mfma_f32_16x16x32_bf16 v[92:95], v[150:153], v[194:197], 0
	v_mfma_f32_16x16x32_bf16 v[88:91], v[162:165], v[194:197], 0
	v_mfma_f32_16x16x32_bf16 v[76:79], v[150:153], v[202:205], 0
	v_mfma_f32_16x16x32_bf16 v[72:75], v[162:165], v[202:205], 0
	v_mfma_f32_16x16x32_bf16 v[124:127], v[154:157], v[174:177], v[124:127]
	v_mfma_f32_16x16x32_bf16 v[120:123], v[166:169], v[174:177], v[120:123]
	v_mfma_f32_16x16x32_bf16 v[108:111], v[154:157], v[188:191], v[108:111]
	v_mfma_f32_16x16x32_bf16 v[104:107], v[166:169], v[188:191], v[104:107]
	v_mfma_f32_16x16x32_bf16 v[92:95], v[154:157], v[198:201], v[92:95]
	v_mfma_f32_16x16x32_bf16 v[88:91], v[166:169], v[198:201], v[88:91]
	v_mfma_f32_16x16x32_bf16 v[76:79], v[154:157], v[206:209], v[76:79]
	v_mfma_f32_16x16x32_bf16 v[72:75], v[166:169], v[206:209], v[72:75]
	s_setprio 0
	s_barrier
	s_add_i32 s0, s34, s52
	s_mov_b32 m0, s0
	ds_read_b128 v[210:213], v149
	ds_read_b128 v[214:217], v149 offset:1024
	ds_read_b128 v[218:221], v149 offset:2048
	global_load_lds_dwordx4 v130, s[42:43]
	s_add_i32 m0, s0, 0x2000
	ds_read_b128 v[222:225], v149 offset:3072
	global_load_lds_dwordx4 v134, s[42:43]
	s_barrier
	s_waitcnt lgkmcnt(0)
	s_setprio 1
	v_mfma_f32_16x16x32_bf16 v[116:119], v[210:213], v[170:173], 0
	v_mfma_f32_16x16x32_bf16 v[112:115], v[218:221], v[170:173], 0
	v_mfma_f32_16x16x32_bf16 v[100:103], v[210:213], v[178:181], 0
	v_mfma_f32_16x16x32_bf16 v[96:99], v[218:221], v[178:181], 0
	v_mfma_f32_16x16x32_bf16 v[84:87], v[210:213], v[194:197], 0
	v_mfma_f32_16x16x32_bf16 v[80:83], v[218:221], v[194:197], 0
	v_mfma_f32_16x16x32_bf16 v[68:71], v[210:213], v[202:205], 0
	v_mfma_f32_16x16x32_bf16 v[64:67], v[218:221], v[202:205], 0
	v_mfma_f32_16x16x32_bf16 v[116:119], v[214:217], v[174:177], v[116:119]
	v_mfma_f32_16x16x32_bf16 v[112:115], v[222:225], v[174:177], v[112:115]
	v_mfma_f32_16x16x32_bf16 v[100:103], v[214:217], v[188:191], v[100:103]
	v_mfma_f32_16x16x32_bf16 v[96:99], v[222:225], v[188:191], v[96:99]
	v_mfma_f32_16x16x32_bf16 v[84:87], v[214:217], v[198:201], v[84:87]
	v_mfma_f32_16x16x32_bf16 v[80:83], v[222:225], v[198:201], v[80:83]
	v_mfma_f32_16x16x32_bf16 v[68:71], v[214:217], v[206:209], v[68:71]
	v_mfma_f32_16x16x32_bf16 v[64:67], v[222:225], v[206:209], v[64:67]
	s_setprio 0
	s_mov_b32 m0, s39
	s_barrier
	ds_read_b128 v[170:173], v148 offset:16384
	ds_read_b128 v[174:177], v148 offset:17408
	ds_read_b128 v[178:181], v148 offset:18432
	ds_read_b128 v[188:191], v148 offset:19456
	ds_read_b128 v[194:197], v148 offset:20480
	ds_read_b128 v[198:201], v148 offset:21504
	ds_read_b128 v[202:205], v148 offset:22528
	global_load_lds_dwordx4 v128, s[44:45]
	s_mov_b32 m0, s53
	ds_read_b128 v[206:209], v148 offset:23552
	global_load_lds_dwordx4 v132, s[44:45]
	s_barrier
	s_waitcnt lgkmcnt(0)
	s_setprio 1
	v_mfma_f32_16x16x32_bf16 v[60:63], v[150:153], v[170:173], 0
	v_mfma_f32_16x16x32_bf16 v[56:59], v[162:165], v[170:173], 0
	v_mfma_f32_16x16x32_bf16 v[44:47], v[150:153], v[178:181], 0
	v_mfma_f32_16x16x32_bf16 v[40:43], v[162:165], v[178:181], 0
	v_mfma_f32_16x16x32_bf16 v[28:31], v[150:153], v[194:197], 0
	v_mfma_f32_16x16x32_bf16 v[24:27], v[162:165], v[194:197], 0
	v_mfma_f32_16x16x32_bf16 v[12:15], v[150:153], v[202:205], 0
	v_mfma_f32_16x16x32_bf16 v[8:11], v[162:165], v[202:205], 0
	v_mfma_f32_16x16x32_bf16 v[60:63], v[154:157], v[174:177], v[60:63]
	v_mfma_f32_16x16x32_bf16 v[56:59], v[166:169], v[174:177], v[56:59]
	v_mfma_f32_16x16x32_bf16 v[44:47], v[154:157], v[188:191], v[44:47]
	v_mfma_f32_16x16x32_bf16 v[40:43], v[166:169], v[188:191], v[40:43]
	v_mfma_f32_16x16x32_bf16 v[28:31], v[154:157], v[198:201], v[28:31]
	v_mfma_f32_16x16x32_bf16 v[24:27], v[166:169], v[198:201], v[24:27]
	v_mfma_f32_16x16x32_bf16 v[12:15], v[154:157], v[206:209], v[12:15]
	v_mfma_f32_16x16x32_bf16 v[8:11], v[166:169], v[206:209], v[8:11]
	s_setprio 0
	s_barrier
; #define PG8_STAGE(bufoff, gbase, voff) do { _Pragma("unroll") for (int _i = 0; _i < 2; ++_i) \
;         __builtin_amdgcn_global_load_lds((const unsigned*)((const char*)(gbase) + (voff)[_i]), (LAS unsigned*)(lds + (bufoff) + ldsw + _i * 8192), 16, 0, 0); } while (0)
; #define PG8_LDA(dst, b, h) do { _Pragma("unroll") for (int m = 0; m < 4; ++m) _Pragma("unroll") for (int k = 0; k < 2; ++k) dst[m][k] = *(const LAS bf16x8*)(lds + PG8_SA(b, h) + aoff + m * 2048 + k * 1024); } while (0)
; #define PG8_LDB(dst, b, h) do { _Pragma("unroll") for (int n = 0; n < 2; ++n) _Pragma("unroll") for (int k = 0; k < 2; ++k) dst[n][k] = *(const LAS bf16x8*)(lds + PG8_SB(b, h) + boff + n * 2048 + k * 1024); } while (0)
; #define PG8_MMA(ai, bj, At, Bt) do { __builtin_amdgcn_s_setprio(1); _Pragma("unroll") for (int m = 0; m < 4; ++m) _Pragma("unroll") for (int n = 0; n < 2; ++n) _Pragma("unroll") for (int k = 0; k < 2; ++k) \
;         acc[ai][bj][m][n] = __builtin_amdgcn_mfma_f32_16x16x32_bf16(Bt[n][k], At[m][k], acc[ai][bj][m][n], 0, 0, 0); __builtin_amdgcn_s_setprio(0); } while (0)
; #define PG8_WAIT_V(n) asm volatile("s_waitcnt vmcnt(" #n ")" ::: "memory")
; #define PG8_WAIT_L(n) asm volatile("s_waitcnt lgkmcnt(" #n ")" ::: "memory")
; #define PG8_BAR __builtin_amdgcn_s_barrier()
; #define PG8_SCHED __builtin_amdgcn_sched_barrier(0)
; template <class Epi, class Sched>
; DI void gemm_phase(LAS unsigned char* lds, const Gemm g, const Sched& S, const Epi& E) {
;     ...
;             PG8_STAGE(PG8_SB(0, 1), b2 + hstep, voffB);
;             PG8_WAIT_V(6); PG8_BAR; PG8_MMA(1, 1, At, B1); PG8_BAR;
;             PG8_LDB(B0, 1, 0); PG8_SCHED; PG8_LDA(At, 1, 0); PG8_STAGE(PG8_SA(0, 1), a2 + hstep, voffA);
;             PG8_WAIT_L(8); PG8_BAR; PG8_WAIT_L(0); PG8_MMA(0, 0, At, B0); PG8_BAR; PG8_SCHED;
;             PG8_LDB(B1, 1, 1); PG8_STAGE(PG8_SB(1, 0), b3, voffB);
;             PG8_BAR; PG8_WAIT_L(0); PG8_MMA(0, 1, At, B1); PG8_BAR;
;             PG8_LDA(At, 1, 1); PG8_STAGE(PG8_SA(1, 0), a3, voffA);
	s_add_i32 s4, s35, s52
	s_mov_b32 m0, s4
	s_add_u32 s0, s42, 0x80000
	s_addc_u32 s1, s43, 0
	global_load_lds_dwordx4 v130, s[0:1]
	s_add_i32 m0, s4, 0x2000
	s_nop 0
	global_load_lds_dwordx4 v134, s[0:1]
	s_waitcnt vmcnt(6)
	s_barrier
	s_setprio 1
	v_mfma_f32_16x16x32_bf16 v[52:55], v[210:213], v[170:173], 0
	v_mfma_f32_16x16x32_bf16 v[48:51], v[218:221], v[170:173], 0
	v_mfma_f32_16x16x32_bf16 v[36:39], v[210:213], v[178:181], 0
	v_mfma_f32_16x16x32_bf16 v[32:35], v[218:221], v[178:181], 0
	v_mfma_f32_16x16x32_bf16 v[20:23], v[210:213], v[194:197], 0
	v_mfma_f32_16x16x32_bf16 v[16:19], v[218:221], v[194:197], 0
	v_mfma_f32_16x16x32_bf16 v[4:7], v[210:213], v[202:205], 0
	v_mfma_f32_16x16x32_bf16 v[0:3], v[218:221], v[202:205], 0
	v_mfma_f32_16x16x32_bf16 v[52:55], v[214:217], v[174:177], v[52:55]
	v_mfma_f32_16x16x32_bf16 v[48:51], v[222:225], v[174:177], v[48:51]
	v_mfma_f32_16x16x32_bf16 v[36:39], v[214:217], v[188:191], v[36:39]
	v_mfma_f32_16x16x32_bf16 v[32:35], v[222:225], v[188:191], v[32:35]
	v_mfma_f32_16x16x32_bf16 v[20:23], v[214:217], v[198:201], v[20:23]
	v_mfma_f32_16x16x32_bf16 v[16:19], v[222:225], v[198:201], v[16:19]
	v_mfma_f32_16x16x32_bf16 v[4:7], v[214:217], v[206:209], v[4:7]
	v_mfma_f32_16x16x32_bf16 v[0:3], v[222:225], v[206:209], v[0:3]
	s_setprio 0
	s_add_i32 s4, 0, 0x18000
	v_add_u32_e32 v158, s4, v146
	s_barrier
	ds_read_b128 v[150:153], v158
	ds_read_b128 v[154:157], v158 offset:1024
	ds_read_b128 v[162:165], v158 offset:2048
	ds_read_b128 v[166:169], v158 offset:3072
	s_add_u32 s0, s44, 0x80000
	s_addc_u32 s1, s45, 0
	s_mov_b32 m0, s54
	ds_read_b128 v[170:173], v148 offset:32768
	ds_read_b128 v[174:177], v148 offset:33792
	ds_read_b128 v[178:181], v148 offset:34816
	ds_read_b128 v[188:191], v148 offset:35840
	ds_read_b128 v[194:197], v148 offset:36864
	ds_read_b128 v[198:201], v148 offset:37888
	ds_read_b128 v[202:205], v148 offset:38912
	global_load_lds_dwordx4 v128, s[0:1]
	s_mov_b32 m0, s55
	ds_read_b128 v[206:209], v148 offset:39936
	global_load_lds_dwordx4 v132, s[0:1]
	s_waitcnt lgkmcnt(8)
	s_barrier
	s_waitcnt lgkmcnt(0)
	s_setprio 1
	v_mfma_f32_16x16x32_bf16 v[124:127], v[150:153], v[170:173], v[124:127]
	v_mfma_f32_16x16x32_bf16 v[120:123], v[162:165], v[170:173], v[120:123]
	v_mfma_f32_16x16x32_bf16 v[108:111], v[150:153], v[178:181], v[108:111]
	v_mfma_f32_16x16x32_bf16 v[104:107], v[162:165], v[178:181], v[104:107]
	v_mfma_f32_16x16x32_bf16 v[92:95], v[150:153], v[194:197], v[92:95]
	v_mfma_f32_16x16x32_bf16 v[88:91], v[162:165], v[194:197], v[88:91]
	v_mfma_f32_16x16x32_bf16 v[76:79], v[150:153], v[202:205], v[76:79]
	v_mfma_f32_16x16x32_bf16 v[72:75], v[162:165], v[202:205], v[72:75]
	v_mfma_f32_16x16x32_bf16 v[124:127], v[154:157], v[174:177], v[124:127]
	v_mfma_f32_16x16x32_bf16 v[120:123], v[166:169], v[174:177], v[120:123]
	v_mfma_f32_16x16x32_bf16 v[108:111], v[154:157], v[188:191], v[108:111]
	v_mfma_f32_16x16x32_bf16 v[104:107], v[166:169], v[188:191], v[104:107]
	v_mfma_f32_16x16x32_bf16 v[92:95], v[154:157], v[198:201], v[92:95]
	v_mfma_f32_16x16x32_bf16 v[88:91], v[166:169], v[198:201], v[88:91]
	v_mfma_f32_16x16x32_bf16 v[76:79], v[154:157], v[206:209], v[76:79]
	v_mfma_f32_16x16x32_bf16 v[72:75], v[166:169], v[206:209], v[72:75]
	s_setprio 0
	s_barrier
	s_add_i32 s5, 0, 0x1c000
	s_add_i32 s0, s4, s52
	v_add_u32_e32 v159, s5, v146
	s_add_i32 m0, s0, 0xffffff80
	ds_read_b128 v[210:213], v159
	ds_read_b128 v[214:217], v159 offset:1024
	ds_read_b128 v[218:221], v159 offset:2048
	global_load_lds_dwordx4 v130, s[42:43] offset:128
	s_add_i32 m0, s0, 0x1f80
	ds_read_b128 v[222:225], v159 offset:3072
	global_load_lds_dwordx4 v134, s[42:43] offset:128
	s_barrier
	s_waitcnt lgkmcnt(0)
	s_setprio 1
	v_mfma_f32_16x16x32_bf16 v[116:119], v[210:213], v[170:173], v[116:119]
	v_mfma_f32_16x16x32_bf16 v[112:115], v[218:221], v[170:173], v[112:115]
	v_mfma_f32_16x16x32_bf16 v[100:103], v[210:213], v[178:181], v[100:103]
	v_mfma_f32_16x16x32_bf16 v[96:99], v[218:221], v[178:181], v[96:99]
	v_mfma_f32_16x16x32_bf16 v[84:87], v[210:213], v[194:197], v[84:87]
	v_mfma_f32_16x16x32_bf16 v[80:83], v[218:221], v[194:197], v[80:83]
	v_mfma_f32_16x16x32_bf16 v[68:71], v[210:213], v[202:205], v[68:71]
	v_mfma_f32_16x16x32_bf16 v[64:67], v[218:221], v[202:205], v[64:67]
	v_mfma_f32_16x16x32_bf16 v[116:119], v[214:217], v[174:177], v[116:119]
	v_mfma_f32_16x16x32_bf16 v[112:115], v[222:225], v[174:177], v[112:115]
	v_mfma_f32_16x16x32_bf16 v[100:103], v[214:217], v[188:191], v[100:103]
	v_mfma_f32_16x16x32_bf16 v[96:99], v[222:225], v[188:191], v[96:99]
	v_mfma_f32_16x16x32_bf16 v[84:87], v[214:217], v[198:201], v[84:87]
	v_mfma_f32_16x16x32_bf16 v[80:83], v[222:225], v[198:201], v[80:83]
	v_mfma_f32_16x16x32_bf16 v[68:71], v[214:217], v[206:209], v[68:71]
	v_mfma_f32_16x16x32_bf16 v[64:67], v[222:225], v[206:209], v[64:67]
	s_setprio 0
	s_add_i32 m0, s59, 0xffffff80
	s_barrier
	ds_read_b128 v[170:173], v148 offset:49152
	ds_read_b128 v[174:177], v148 offset:50176
	ds_read_b128 v[178:181], v148 offset:51200
	ds_read_b128 v[188:191], v148 offset:52224
	ds_read_b128 v[194:197], v148 offset:53248
	ds_read_b128 v[198:201], v148 offset:54272
	ds_read_b128 v[202:205], v148 offset:55296
	global_load_lds_dwordx4 v128, s[44:45] offset:128
	s_add_i32 m0, s60, 0xffffff80
	ds_read_b128 v[206:209], v148 offset:56320
	global_load_lds_dwordx4 v132, s[44:45] offset:128
	s_barrier
; #define PG8_STAGE(bufoff, gbase, voff) do { _Pragma("unroll") for (int _i = 0; _i < 2; ++_i) \
;         __builtin_amdgcn_global_load_lds((const unsigned*)((const char*)(gbase) + (voff)[_i]), (LAS unsigned*)(lds + (bufoff) + ldsw + _i * 8192), 16, 0, 0); } while (0)
; #define PG8_LDA(dst, b, h) do { _Pragma("unroll") for (int m = 0; m < 4; ++m) _Pragma("unroll") for (int k = 0; k < 2; ++k) dst[m][k] = *(const LAS bf16x8*)(lds + PG8_SA(b, h) + aoff + m * 2048 + k * 1024); } while (0)
; template <class Epi, class Sched>
; DI void gemm_phase(LAS unsigned char* lds, const Gemm g, const Sched& S, const Epi& E) {
;     ...
;         for (int t = 0; t < nt; t += 2) {
;             if constexpr (Epi::HAS_MID) { if (t == E.mid_t(nt)) { int fr3 = fr, fq3 = fq; asm volatile("" : "+v"(fr3), "+v"(fq3)); E.mid(acc, cur, wr, wc, fr3, fq3); } }
;             const bool last = (t == nt - 2);
;             const char* a1 = cA + (size_t)(t + 1) * kstep;
;             const char* a2 = last ? nA : cA + (size_t)(t + 2) * kstep; const char* b2 = last ? nB : cB + (size_t)(t + 2) * kstep;
;             const char* a3 = a2 + kstep; const char* b3 = b2 + kstep;
;             PG8_LDB(B0, 0, 0); PG8_SCHED; PG8_LDA(At, 0, 0); PG8_STAGE(PG8_SA(1, 1), a1 + hstep, voffA);
;             PG8_WAIT_L(8); PG8_BAR; PG8_WAIT_L(0); PG8_MMA(0, 0, At, B0); PG8_BAR; PG8_SCHED;
;             PG8_LDB(B1, 0, 1); PG8_STAGE(PG8_SB(0, 0), b2, voffB);
;             PG8_BAR; PG8_WAIT_L(0); PG8_MMA(0, 1, At, B1); PG8_BAR;
;             PG8_LDA(At, 0, 1); PG8_STAGE(PG8_SA(0, 0), a2, voffA);
;             PG8_BAR; PG8_WAIT_L(0); PG8_MMA(1, 0, At, B0); PG8_BAR; PG8_SCHED;
;             PG8_STAGE(PG8_SB(0, 1), b2 + hstep, voffB);
;             PG8_WAIT_V(6); PG8_BAR; PG8_MMA(1, 1, At, B1); PG8_BAR;
;             PG8_LDB(B0, 1, 0); PG8_SCHED; PG8_LDA(At, 1, 0); PG8_STAGE(PG8_SA(0, 1), a2 + hstep, voffA);
;             PG8_WAIT_L(8); PG8_BAR; PG8_WAIT_L(0); PG8_MMA(0, 0, At, B0); PG8_BAR; PG8_SCHED;
;             PG8_LDB(B1, 1, 1); PG8_STAGE(PG8_SB(1, 0), b3, voffB);
;             PG8_BAR; PG8_WAIT_L(0); PG8_MMA(0, 1, At, B1); PG8_BAR;
;             PG8_LDA(At, 1, 1); PG8_STAGE(PG8_SA(1, 0), a3, voffA);
;             PG8_BAR; PG8_WAIT_L(0); PG8_MMA(1, 0, At, B0); PG8_BAR; PG8_SCHED;
;             PG8_STAGE(PG8_SB(1, 1), b3 + hstep, voffB);
;             PG8_WAIT_V(6); PG8_BAR; PG8_MMA(1, 1, At, B1); PG8_BAR;
	s_waitcnt lgkmcnt(0)
	s_setprio 1
	v_mfma_f32_16x16x32_bf16 v[60:63], v[150:153], v[170:173], v[60:63]
	v_mfma_f32_16x16x32_bf16 v[56:59], v[162:165], v[170:173], v[56:59]
	v_mfma_f32_16x16x32_bf16 v[44:47], v[150:153], v[178:181], v[44:47]
	v_mfma_f32_16x16x32_bf16 v[40:43], v[162:165], v[178:181], v[40:43]
	v_mfma_f32_16x16x32_bf16 v[28:31], v[150:153], v[194:197], v[28:31]
	v_mfma_f32_16x16x32_bf16 v[24:27], v[162:165], v[194:197], v[24:27]
	v_mfma_f32_16x16x32_bf16 v[12:15], v[150:153], v[202:205], v[12:15]
	v_mfma_f32_16x16x32_bf16 v[8:11], v[162:165], v[202:205], v[8:11]
	v_mfma_f32_16x16x32_bf16 v[60:63], v[154:157], v[174:177], v[60:63]
	v_mfma_f32_16x16x32_bf16 v[56:59], v[166:169], v[174:177], v[56:59]
	v_mfma_f32_16x16x32_bf16 v[44:47], v[154:157], v[188:191], v[44:47]
	v_mfma_f32_16x16x32_bf16 v[40:43], v[166:169], v[188:191], v[40:43]
	v_mfma_f32_16x16x32_bf16 v[28:31], v[154:157], v[198:201], v[28:31]
	v_mfma_f32_16x16x32_bf16 v[24:27], v[166:169], v[198:201], v[24:27]
	v_mfma_f32_16x16x32_bf16 v[12:15], v[154:157], v[206:209], v[12:15]
	v_mfma_f32_16x16x32_bf16 v[8:11], v[166:169], v[206:209], v[8:11]
	s_setprio 0
	s_barrier
	s_add_i32 s4, s5, s52
	s_mov_b32 m0, s4
	s_add_u32 s0, s42, 0x80080
	s_addc_u32 s1, s43, 0
	global_load_lds_dwordx4 v130, s[0:1]
	s_add_i32 m0, s4, 0x2000
	s_nop 0
	global_load_lds_dwordx4 v134, s[0:1]
	s_waitcnt vmcnt(6)
	s_barrier
	s_setprio 1
	v_mfma_f32_16x16x32_bf16 v[52:55], v[210:213], v[170:173], v[52:55]
	v_mfma_f32_16x16x32_bf16 v[48:51], v[218:221], v[170:173], v[48:51]
	v_mfma_f32_16x16x32_bf16 v[36:39], v[210:213], v[178:181], v[36:39]
	v_mfma_f32_16x16x32_bf16 v[32:35], v[218:221], v[178:181], v[32:35]
	v_mfma_f32_16x16x32_bf16 v[20:23], v[210:213], v[194:197], v[20:23]
	v_mfma_f32_16x16x32_bf16 v[16:19], v[218:221], v[194:197], v[16:19]
	v_mfma_f32_16x16x32_bf16 v[4:7], v[210:213], v[202:205], v[4:7]
	v_mfma_f32_16x16x32_bf16 v[0:3], v[218:221], v[202:205], v[0:3]
	v_mfma_f32_16x16x32_bf16 v[52:55], v[214:217], v[174:177], v[52:55]
	v_mfma_f32_16x16x32_bf16 v[48:51], v[222:225], v[174:177], v[48:51]
	v_mfma_f32_16x16x32_bf16 v[36:39], v[214:217], v[188:191], v[36:39]
	v_mfma_f32_16x16x32_bf16 v[32:35], v[222:225], v[188:191], v[32:35]
	v_mfma_f32_16x16x32_bf16 v[20:23], v[214:217], v[198:201], v[20:23]
	v_mfma_f32_16x16x32_bf16 v[16:19], v[222:225], v[198:201], v[16:19]
	v_mfma_f32_16x16x32_bf16 v[4:7], v[214:217], v[206:209], v[4:7]
	v_mfma_f32_16x16x32_bf16 v[0:3], v[222:225], v[206:209], v[0:3]
	s_setprio 0
	s_add_i32 s69, s69, 2
	s_add_u32 s40, s40, 0x100
	s_addc_u32 s41, s41, 0
	s_add_u32 s67, s67, 0x100
	s_addc_u32 s68, s68, 0
	s_cmp_gt_u32 s69, 29
	s_barrier
	s_cbranch_scc0 .LBB0_219
	s_branch .Lpeel_done_219
.LBB0_219:
	ds_read_b128 v[150:153], v147
	ds_read_b128 v[154:157], v147 offset:1024
	ds_read_b128 v[162:165], v147 offset:2048
	ds_read_b128 v[166:169], v147 offset:3072
	s_add_i32 m0, s39, 0xc000
	ds_read_b128 v[170:173], v148
	ds_read_b128 v[174:177], v148 offset:1024
	ds_read_b128 v[178:181], v148 offset:2048
	ds_read_b128 v[188:191], v148 offset:3072
	ds_read_b128 v[194:197], v148 offset:4096
	ds_read_b128 v[198:201], v148 offset:5120
	ds_read_b128 v[202:205], v148 offset:6144
	global_load_lds_dwordx4 v136, s[40:41]
	s_add_i32 m0, s39, 0xe000
	ds_read_b128 v[206:209], v148 offset:7168
	global_load_lds_dwordx4 v138, s[40:41]
	s_add_u32 s0, s40, 0xfff80080
	s_addc_u32 s1, s41, -1
	s_cmp_eq_u32 s69, 28
	s_cselect_b32 s45, s17, s1
	s_cselect_b32 s44, s65, s0
	s_cselect_b32 s43, s15, s68
	s_cselect_b32 s42, s66, s67
	s_waitcnt lgkmcnt(8)
	s_barrier
	s_waitcnt lgkmcnt(0)
	s_setprio 1
	v_mfma_f32_16x16x32_bf16 v[124:127], v[150:153], v[170:173], v[124:127]
	v_mfma_f32_16x16x32_bf16 v[120:123], v[162:165], v[170:173], v[120:123]
	v_mfma_f32_16x16x32_bf16 v[108:111], v[150:153], v[178:181], v[108:111]
	v_mfma_f32_16x16x32_bf16 v[104:107], v[162:165], v[178:181], v[104:107]
	v_mfma_f32_16x16x32_bf16 v[92:95], v[150:153], v[194:197], v[92:95]
	v_mfma_f32_16x16x32_bf16 v[88:91], v[162:165], v[194:197], v[88:91]
	v_mfma_f32_16x16x32_bf16 v[76:79], v[150:153], v[202:205], v[76:79]
	v_mfma_f32_16x16x32_bf16 v[72:75], v[162:165], v[202:205], v[72:75]
	v_mfma_f32_16x16x32_bf16 v[124:127], v[154:157], v[174:177], v[124:127]
	v_mfma_f32_16x16x32_bf16 v[120:123], v[166:169], v[174:177], v[120:123]
	v_mfma_f32_16x16x32_bf16 v[108:111], v[154:157], v[188:191], v[108:111]
	v_mfma_f32_16x16x32_bf16 v[104:107], v[166:169], v[188:191], v[104:107]
	v_mfma_f32_16x16x32_bf16 v[92:95], v[154:157], v[198:201], v[92:95]
	v_mfma_f32_16x16x32_bf16 v[88:91], v[166:169], v[198:201], v[88:91]
	v_mfma_f32_16x16x32_bf16 v[76:79], v[154:157], v[206:209], v[76:79]
	v_mfma_f32_16x16x32_bf16 v[72:75], v[166:169], v[206:209], v[72:75]
	s_setprio 0
	s_barrier
	s_add_i32 s0, s34, s52
	s_mov_b32 m0, s0
	ds_read_b128 v[210:213], v149
	ds_read_b128 v[214:217], v149 offset:1024
	ds_read_b128 v[218:221], v149 offset:2048
	global_load_lds_dwordx4 v130, s[42:43]
	s_add_i32 m0, s0, 0x2000
	ds_read_b128 v[222:225], v149 offset:3072
	global_load_lds_dwordx4 v134, s[42:43]
	s_barrier
; #define PG8_STAGE(bufoff, gbase, voff) do { _Pragma("unroll") for (int _i = 0; _i < 2; ++_i) \
;         __builtin_amdgcn_global_load_lds((const unsigned*)((const char*)(gbase) + (voff)[_i]), (LAS unsigned*)(lds + (bufoff) + ldsw + _i * 8192), 16, 0, 0); } while (0)
; #define PG8_LDA(dst, b, h) do { _Pragma("unroll") for (int m = 0; m < 4; ++m) _Pragma("unroll") for (int k = 0; k < 2; ++k) dst[m][k] = *(const LAS bf16x8*)(lds + PG8_SA(b, h) + aoff + m * 2048 + k * 1024); } while (0)
; #define PG8_LDB(dst, b, h) do { _Pragma("unroll") for (int n = 0; n < 2; ++n) _Pragma("unroll") for (int k = 0; k < 2; ++k) dst[n][k] = *(const LAS bf16x8*)(lds + PG8_SB(b, h) + boff + n * 2048 + k * 1024); } while (0)
; #define PG8_WAIT_V(n) asm volatile("s_waitcnt vmcnt(" #n ")" ::: "memory")
; #define PG8_WAIT_L(n) asm volatile("s_waitcnt lgkmcnt(" #n ")" ::: "memory")
; #define PG8_BAR __builtin_amdgcn_s_barrier()
; #define PG8_SCHED __builtin_amdgcn_sched_barrier(0)
; template <class Epi, class Sched>
; DI void gemm_phase(LAS unsigned char* lds, const Gemm g, const Sched& S, const Epi& E) {
;     ...
;             PG8_LDB(B0, 0, 0); PG8_SCHED; PG8_LDA(At, 0, 0); PG8_STAGE(PG8_SA(1, 1), a1 + hstep, voffA);
;             PG8_WAIT_L(8); PG8_BAR; PG8_WAIT_L(0); PG8_MMA(0, 0, At, B0); PG8_BAR; PG8_SCHED;
;             PG8_LDB(B1, 0, 1); PG8_STAGE(PG8_SB(0, 0), b2, voffB);
;             PG8_BAR; PG8_WAIT_L(0); PG8_MMA(0, 1, At, B1); PG8_BAR;
;             PG8_LDA(At, 0, 1); PG8_STAGE(PG8_SA(0, 0), a2, voffA);
;             PG8_BAR; PG8_WAIT_L(0); PG8_MMA(1, 0, At, B0); PG8_BAR; PG8_SCHED;
;             PG8_STAGE(PG8_SB(0, 1), b2 + hstep, voffB);
;             PG8_WAIT_V(6); PG8_BAR; PG8_MMA(1, 1, At, B1); PG8_BAR;
;             PG8_LDB(B0, 1, 0); PG8_SCHED; PG8_LDA(At, 1, 0); PG8_STAGE(PG8_SA(0, 1), a2 + hstep, voffA);
;             PG8_WAIT_L(8); PG8_BAR; PG8_WAIT_L(0); PG8_MMA(0, 0, At, B0); PG8_BAR; PG8_SCHED;
;             PG8_LDB(B1, 1, 1); PG8_STAGE(PG8_SB(1, 0), b3, voffB);
;             PG8_BAR; PG8_WAIT_L(0); PG8_MMA(0, 1, At, B1); PG8_BAR;
;             PG8_LDA(At, 1, 1); PG8_STAGE(PG8_SA(1, 0), a3, voffA);
;             PG8_BAR; PG8_WAIT_L(0); PG8_MMA(1, 0, At, B0); PG8_BAR; PG8_SCHED;
;             PG8_STAGE(PG8_SB(1, 1), b3 + hstep, voffB);
;             PG8_WAIT_V(6); PG8_BAR; PG8_MMA(1, 1, At, B1); PG8_BAR;
	s_waitcnt lgkmcnt(0)
	s_setprio 1
	v_mfma_f32_16x16x32_bf16 v[116:119], v[210:213], v[170:173], v[116:119]
	v_mfma_f32_16x16x32_bf16 v[112:115], v[218:221], v[170:173], v[112:115]
	v_mfma_f32_16x16x32_bf16 v[100:103], v[210:213], v[178:181], v[100:103]
	v_mfma_f32_16x16x32_bf16 v[96:99], v[218:221], v[178:181], v[96:99]
	v_mfma_f32_16x16x32_bf16 v[84:87], v[210:213], v[194:197], v[84:87]
	v_mfma_f32_16x16x32_bf16 v[80:83], v[218:221], v[194:197], v[80:83]
	v_mfma_f32_16x16x32_bf16 v[68:71], v[210:213], v[202:205], v[68:71]
	v_mfma_f32_16x16x32_bf16 v[64:67], v[218:221], v[202:205], v[64:67]
	v_mfma_f32_16x16x32_bf16 v[116:119], v[214:217], v[174:177], v[116:119]
	v_mfma_f32_16x16x32_bf16 v[112:115], v[222:225], v[174:177], v[112:115]
	v_mfma_f32_16x16x32_bf16 v[100:103], v[214:217], v[188:191], v[100:103]
	v_mfma_f32_16x16x32_bf16 v[96:99], v[222:225], v[188:191], v[96:99]
	v_mfma_f32_16x16x32_bf16 v[84:87], v[214:217], v[198:201], v[84:87]
	v_mfma_f32_16x16x32_bf16 v[80:83], v[222:225], v[198:201], v[80:83]
	v_mfma_f32_16x16x32_bf16 v[68:71], v[214:217], v[206:209], v[68:71]
	v_mfma_f32_16x16x32_bf16 v[64:67], v[222:225], v[206:209], v[64:67]
	s_setprio 0
	s_mov_b32 m0, s39
	s_barrier
	ds_read_b128 v[170:173], v148 offset:16384
	ds_read_b128 v[174:177], v148 offset:17408
	ds_read_b128 v[178:181], v148 offset:18432
	ds_read_b128 v[188:191], v148 offset:19456
	ds_read_b128 v[194:197], v148 offset:20480
	ds_read_b128 v[198:201], v148 offset:21504
	ds_read_b128 v[202:205], v148 offset:22528
	global_load_lds_dwordx4 v128, s[44:45]
	s_mov_b32 m0, s53
	ds_read_b128 v[206:209], v148 offset:23552
	global_load_lds_dwordx4 v132, s[44:45]
	s_barrier
	s_waitcnt lgkmcnt(0)
	s_setprio 1
	v_mfma_f32_16x16x32_bf16 v[60:63], v[150:153], v[170:173], v[60:63]
	v_mfma_f32_16x16x32_bf16 v[56:59], v[162:165], v[170:173], v[56:59]
	v_mfma_f32_16x16x32_bf16 v[44:47], v[150:153], v[178:181], v[44:47]
	v_mfma_f32_16x16x32_bf16 v[40:43], v[162:165], v[178:181], v[40:43]
	v_mfma_f32_16x16x32_bf16 v[28:31], v[150:153], v[194:197], v[28:31]
	v_mfma_f32_16x16x32_bf16 v[24:27], v[162:165], v[194:197], v[24:27]
	v_mfma_f32_16x16x32_bf16 v[12:15], v[150:153], v[202:205], v[12:15]
	v_mfma_f32_16x16x32_bf16 v[8:11], v[162:165], v[202:205], v[8:11]
	v_mfma_f32_16x16x32_bf16 v[60:63], v[154:157], v[174:177], v[60:63]
	v_mfma_f32_16x16x32_bf16 v[56:59], v[166:169], v[174:177], v[56:59]
	v_mfma_f32_16x16x32_bf16 v[44:47], v[154:157], v[188:191], v[44:47]
	v_mfma_f32_16x16x32_bf16 v[40:43], v[166:169], v[188:191], v[40:43]
	v_mfma_f32_16x16x32_bf16 v[28:31], v[154:157], v[198:201], v[28:31]
	v_mfma_f32_16x16x32_bf16 v[24:27], v[166:169], v[198:201], v[24:27]
	v_mfma_f32_16x16x32_bf16 v[12:15], v[154:157], v[206:209], v[12:15]
	v_mfma_f32_16x16x32_bf16 v[8:11], v[166:169], v[206:209], v[8:11]
	s_setprio 0
	s_barrier
	s_add_i32 s4, s35, s52
	s_mov_b32 m0, s4
	s_add_u32 s0, s42, 0x80000
	s_addc_u32 s1, s43, 0
	global_load_lds_dwordx4 v130, s[0:1]
	s_add_i32 m0, s4, 0x2000
	s_nop 0
	global_load_lds_dwordx4 v134, s[0:1]
	s_waitcnt vmcnt(6)
	s_barrier
	s_setprio 1
	v_mfma_f32_16x16x32_bf16 v[52:55], v[210:213], v[170:173], v[52:55]
	v_mfma_f32_16x16x32_bf16 v[48:51], v[218:221], v[170:173], v[48:51]
	v_mfma_f32_16x16x32_bf16 v[36:39], v[210:213], v[178:181], v[36:39]
	v_mfma_f32_16x16x32_bf16 v[32:35], v[218:221], v[178:181], v[32:35]
	v_mfma_f32_16x16x32_bf16 v[20:23], v[210:213], v[194:197], v[20:23]
	v_mfma_f32_16x16x32_bf16 v[16:19], v[218:221], v[194:197], v[16:19]
	v_mfma_f32_16x16x32_bf16 v[4:7], v[210:213], v[202:205], v[4:7]
	v_mfma_f32_16x16x32_bf16 v[0:3], v[218:221], v[202:205], v[0:3]
	v_mfma_f32_16x16x32_bf16 v[52:55], v[214:217], v[174:177], v[52:55]
	v_mfma_f32_16x16x32_bf16 v[48:51], v[222:225], v[174:177], v[48:51]
	v_mfma_f32_16x16x32_bf16 v[36:39], v[214:217], v[188:191], v[36:39]
	v_mfma_f32_16x16x32_bf16 v[32:35], v[222:225], v[188:191], v[32:35]
	v_mfma_f32_16x16x32_bf16 v[20:23], v[214:217], v[198:201], v[20:23]
	v_mfma_f32_16x16x32_bf16 v[16:19], v[222:225], v[198:201], v[16:19]
	v_mfma_f32_16x16x32_bf16 v[4:7], v[214:217], v[206:209], v[4:7]
	v_mfma_f32_16x16x32_bf16 v[0:3], v[222:225], v[206:209], v[0:3]
	s_setprio 0
	s_add_i32 s4, 0, 0x18000
	s_barrier
	ds_read_b128 v[150:153], v158
	ds_read_b128 v[154:157], v158 offset:1024
	ds_read_b128 v[162:165], v158 offset:2048
	ds_read_b128 v[166:169], v158 offset:3072
	s_add_u32 s0, s44, 0x80000
	s_addc_u32 s1, s45, 0
	s_mov_b32 m0, s54
	ds_read_b128 v[170:173], v148 offset:32768
	ds_read_b128 v[174:177], v148 offset:33792
	ds_read_b128 v[178:181], v148 offset:34816
	ds_read_b128 v[188:191], v148 offset:35840
	ds_read_b128 v[194:197], v148 offset:36864
	ds_read_b128 v[198:201], v148 offset:37888
	ds_read_b128 v[202:205], v148 offset:38912
	global_load_lds_dwordx4 v128, s[0:1]
	s_mov_b32 m0, s55
	ds_read_b128 v[206:209], v148 offset:39936
	global_load_lds_dwordx4 v132, s[0:1]
	s_waitcnt lgkmcnt(8)
	s_barrier
; #define PG8_STAGE(bufoff, gbase, voff) do { _Pragma("unroll") for (int _i = 0; _i < 2; ++_i) \
;         __builtin_amdgcn_global_load_lds((const unsigned*)((const char*)(gbase) + (voff)[_i]), (LAS unsigned*)(lds + (bufoff) + ldsw + _i * 8192), 16, 0, 0); } while (0)
; #define PG8_LDA(dst, b, h) do { _Pragma("unroll") for (int m = 0; m < 4; ++m) _Pragma("unroll") for (int k = 0; k < 2; ++k) dst[m][k] = *(const LAS bf16x8*)(lds + PG8_SA(b, h) + aoff + m * 2048 + k * 1024); } while (0)
; #define PG8_LDB(dst, b, h) do { _Pragma("unroll") for (int n = 0; n < 2; ++n) _Pragma("unroll") for (int k = 0; k < 2; ++k) dst[n][k] = *(const LAS bf16x8*)(lds + PG8_SB(b, h) + boff + n * 2048 + k * 1024); } while (0)
; #define PG8_WAIT_V(n) asm volatile("s_waitcnt vmcnt(" #n ")" ::: "memory")
; #define PG8_WAIT_L(n) asm volatile("s_waitcnt lgkmcnt(" #n ")" ::: "memory")
; #define PG8_BAR __builtin_amdgcn_s_barrier()
; #define PG8_SCHED __builtin_amdgcn_sched_barrier(0)
; template <class Epi, class Sched>
; DI void gemm_phase(LAS unsigned char* lds, const Gemm g, const Sched& S, const Epi& E) {
;     ...
;             PG8_LDB(B0, 0, 0); PG8_SCHED; PG8_LDA(At, 0, 0); PG8_STAGE(PG8_SA(1, 1), a1 + hstep, voffA);
;             PG8_WAIT_L(8); PG8_BAR; PG8_WAIT_L(0); PG8_MMA(0, 0, At, B0); PG8_BAR; PG8_SCHED;
;             PG8_LDB(B1, 0, 1); PG8_STAGE(PG8_SB(0, 0), b2, voffB);
;             PG8_BAR; PG8_WAIT_L(0); PG8_MMA(0, 1, At, B1); PG8_BAR;
;             PG8_LDA(At, 0, 1); PG8_STAGE(PG8_SA(0, 0), a2, voffA);
;             PG8_BAR; PG8_WAIT_L(0); PG8_MMA(1, 0, At, B0); PG8_BAR; PG8_SCHED;
;             PG8_STAGE(PG8_SB(0, 1), b2 + hstep, voffB);
;             PG8_WAIT_V(6); PG8_BAR; PG8_MMA(1, 1, At, B1); PG8_BAR;
;             PG8_LDB(B0, 1, 0); PG8_SCHED; PG8_LDA(At, 1, 0); PG8_STAGE(PG8_SA(0, 1), a2 + hstep, voffA);
;             PG8_WAIT_L(8); PG8_BAR; PG8_WAIT_L(0); PG8_MMA(0, 0, At, B0); PG8_BAR; PG8_SCHED;
;             PG8_LDB(B1, 1, 1); PG8_STAGE(PG8_SB(1, 0), b3, voffB);
;             PG8_BAR; PG8_WAIT_L(0); PG8_MMA(0, 1, At, B1); PG8_BAR;
;             PG8_LDA(At, 1, 1); PG8_STAGE(PG8_SA(1, 0), a3, voffA);
;             PG8_BAR; PG8_WAIT_L(0); PG8_MMA(1, 0, At, B0); PG8_BAR; PG8_SCHED;
;             PG8_STAGE(PG8_SB(1, 1), b3 + hstep, voffB);
;             PG8_WAIT_V(6); PG8_BAR; PG8_MMA(1, 1, At, B1); PG8_BAR;
	s_waitcnt lgkmcnt(0)
	s_setprio 1
	v_mfma_f32_16x16x32_bf16 v[124:127], v[150:153], v[170:173], v[124:127]
	v_mfma_f32_16x16x32_bf16 v[120:123], v[162:165], v[170:173], v[120:123]
	v_mfma_f32_16x16x32_bf16 v[108:111], v[150:153], v[178:181], v[108:111]
	v_mfma_f32_16x16x32_bf16 v[104:107], v[162:165], v[178:181], v[104:107]
	v_mfma_f32_16x16x32_bf16 v[92:95], v[150:153], v[194:197], v[92:95]
	v_mfma_f32_16x16x32_bf16 v[88:91], v[162:165], v[194:197], v[88:91]
	v_mfma_f32_16x16x32_bf16 v[76:79], v[150:153], v[202:205], v[76:79]
	v_mfma_f32_16x16x32_bf16 v[72:75], v[162:165], v[202:205], v[72:75]
	v_mfma_f32_16x16x32_bf16 v[124:127], v[154:157], v[174:177], v[124:127]
	v_mfma_f32_16x16x32_bf16 v[120:123], v[166:169], v[174:177], v[120:123]
	v_mfma_f32_16x16x32_bf16 v[108:111], v[154:157], v[188:191], v[108:111]
	v_mfma_f32_16x16x32_bf16 v[104:107], v[166:169], v[188:191], v[104:107]
	v_mfma_f32_16x16x32_bf16 v[92:95], v[154:157], v[198:201], v[92:95]
	v_mfma_f32_16x16x32_bf16 v[88:91], v[166:169], v[198:201], v[88:91]
	v_mfma_f32_16x16x32_bf16 v[76:79], v[154:157], v[206:209], v[76:79]
	v_mfma_f32_16x16x32_bf16 v[72:75], v[166:169], v[206:209], v[72:75]
	s_setprio 0
	s_barrier
	s_add_i32 s5, 0, 0x1c000
	s_add_i32 s0, s4, s52
	s_add_i32 m0, s0, 0xffffff80
	ds_read_b128 v[210:213], v159
	ds_read_b128 v[214:217], v159 offset:1024
	ds_read_b128 v[218:221], v159 offset:2048
	global_load_lds_dwordx4 v130, s[42:43] offset:128
	s_add_i32 m0, s0, 0x1f80
	ds_read_b128 v[222:225], v159 offset:3072
	global_load_lds_dwordx4 v134, s[42:43] offset:128
	s_barrier
	s_waitcnt lgkmcnt(0)
	s_setprio 1
	v_mfma_f32_16x16x32_bf16 v[116:119], v[210:213], v[170:173], v[116:119]
	v_mfma_f32_16x16x32_bf16 v[112:115], v[218:221], v[170:173], v[112:115]
	v_mfma_f32_16x16x32_bf16 v[100:103], v[210:213], v[178:181], v[100:103]
	v_mfma_f32_16x16x32_bf16 v[96:99], v[218:221], v[178:181], v[96:99]
	v_mfma_f32_16x16x32_bf16 v[84:87], v[210:213], v[194:197], v[84:87]
	v_mfma_f32_16x16x32_bf16 v[80:83], v[218:221], v[194:197], v[80:83]
	v_mfma_f32_16x16x32_bf16 v[68:71], v[210:213], v[202:205], v[68:71]
	v_mfma_f32_16x16x32_bf16 v[64:67], v[218:221], v[202:205], v[64:67]
	v_mfma_f32_16x16x32_bf16 v[116:119], v[214:217], v[174:177], v[116:119]
	v_mfma_f32_16x16x32_bf16 v[112:115], v[222:225], v[174:177], v[112:115]
	v_mfma_f32_16x16x32_bf16 v[100:103], v[214:217], v[188:191], v[100:103]
	v_mfma_f32_16x16x32_bf16 v[96:99], v[222:225], v[188:191], v[96:99]
	v_mfma_f32_16x16x32_bf16 v[84:87], v[214:217], v[198:201], v[84:87]
	v_mfma_f32_16x16x32_bf16 v[80:83], v[222:225], v[198:201], v[80:83]
	v_mfma_f32_16x16x32_bf16 v[68:71], v[214:217], v[206:209], v[68:71]
	v_mfma_f32_16x16x32_bf16 v[64:67], v[222:225], v[206:209], v[64:67]
	s_setprio 0
	s_add_i32 m0, s59, 0xffffff80
	s_barrier
	ds_read_b128 v[170:173], v148 offset:49152
	ds_read_b128 v[174:177], v148 offset:50176
	ds_read_b128 v[178:181], v148 offset:51200
	ds_read_b128 v[188:191], v148 offset:52224
	ds_read_b128 v[194:197], v148 offset:53248
	ds_read_b128 v[198:201], v148 offset:54272
	ds_read_b128 v[202:205], v148 offset:55296
	global_load_lds_dwordx4 v128, s[44:45] offset:128
	s_add_i32 m0, s60, 0xffffff80
	ds_read_b128 v[206:209], v148 offset:56320
	global_load_lds_dwordx4 v132, s[44:45] offset:128
	s_barrier
	s_waitcnt lgkmcnt(0)
	s_setprio 1
	v_mfma_f32_16x16x32_bf16 v[60:63], v[150:153], v[170:173], v[60:63]
	v_mfma_f32_16x16x32_bf16 v[56:59], v[162:165], v[170:173], v[56:59]
	v_mfma_f32_16x16x32_bf16 v[44:47], v[150:153], v[178:181], v[44:47]
	v_mfma_f32_16x16x32_bf16 v[40:43], v[162:165], v[178:181], v[40:43]
	v_mfma_f32_16x16x32_bf16 v[28:31], v[150:153], v[194:197], v[28:31]
	v_mfma_f32_16x16x32_bf16 v[24:27], v[162:165], v[194:197], v[24:27]
	v_mfma_f32_16x16x32_bf16 v[12:15], v[150:153], v[202:205], v[12:15]
	v_mfma_f32_16x16x32_bf16 v[8:11], v[162:165], v[202:205], v[8:11]
	v_mfma_f32_16x16x32_bf16 v[60:63], v[154:157], v[174:177], v[60:63]
	v_mfma_f32_16x16x32_bf16 v[56:59], v[166:169], v[174:177], v[56:59]
	v_mfma_f32_16x16x32_bf16 v[44:47], v[154:157], v[188:191], v[44:47]
	v_mfma_f32_16x16x32_bf16 v[40:43], v[166:169], v[188:191], v[40:43]
	v_mfma_f32_16x16x32_bf16 v[28:31], v[154:157], v[198:201], v[28:31]
	v_mfma_f32_16x16x32_bf16 v[24:27], v[166:169], v[198:201], v[24:27]
	v_mfma_f32_16x16x32_bf16 v[12:15], v[154:157], v[206:209], v[12:15]
	v_mfma_f32_16x16x32_bf16 v[8:11], v[166:169], v[206:209], v[8:11]
	s_setprio 0
	s_barrier
	s_add_i32 s4, s5, s52
	s_mov_b32 m0, s4
	s_add_u32 s0, s42, 0x80080
	s_addc_u32 s1, s43, 0
	global_load_lds_dwordx4 v130, s[0:1]
	s_add_i32 m0, s4, 0x2000
	s_nop 0
	global_load_lds_dwordx4 v134, s[0:1]
	s_waitcnt vmcnt(6)
	s_barrier
	s_setprio 1
	v_mfma_f32_16x16x32_bf16 v[52:55], v[210:213], v[170:173], v[52:55]
	v_mfma_f32_16x16x32_bf16 v[48:51], v[218:221], v[170:173], v[48:51]
	v_mfma_f32_16x16x32_bf16 v[36:39], v[210:213], v[178:181], v[36:39]
	v_mfma_f32_16x16x32_bf16 v[32:35], v[218:221], v[178:181], v[32:35]
	v_mfma_f32_16x16x32_bf16 v[20:23], v[210:213], v[194:197], v[20:23]
	v_mfma_f32_16x16x32_bf16 v[16:19], v[218:221], v[194:197], v[16:19]
	v_mfma_f32_16x16x32_bf16 v[4:7], v[210:213], v[202:205], v[4:7]
	v_mfma_f32_16x16x32_bf16 v[0:3], v[218:221], v[202:205], v[0:3]
	v_mfma_f32_16x16x32_bf16 v[52:55], v[214:217], v[174:177], v[52:55]
	v_mfma_f32_16x16x32_bf16 v[48:51], v[222:225], v[174:177], v[48:51]
	v_mfma_f32_16x16x32_bf16 v[36:39], v[214:217], v[188:191], v[36:39]
	v_mfma_f32_16x16x32_bf16 v[32:35], v[222:225], v[188:191], v[32:35]
	v_mfma_f32_16x16x32_bf16 v[20:23], v[214:217], v[198:201], v[20:23]
	v_mfma_f32_16x16x32_bf16 v[16:19], v[222:225], v[198:201], v[16:19]
	v_mfma_f32_16x16x32_bf16 v[4:7], v[214:217], v[206:209], v[4:7]
	v_mfma_f32_16x16x32_bf16 v[0:3], v[222:225], v[206:209], v[0:3]
	s_setprio 0
	s_add_i32 s69, s69, 2
	s_add_u32 s40, s40, 0x100
	s_addc_u32 s41, s41, 0
	s_add_u32 s67, s67, 0x100
	s_addc_u32 s68, s68, 0
	s_cmp_gt_u32 s69, 29
	s_barrier
	s_cbranch_scc0 .LBB0_219

; template <class Epi, class Sched>
; DI void gemm_phase(LAS unsigned char* lds, const Gemm g, const Sched& S, const Epi& E) {
;     ...
;         const bool has_next = S.next(ui + 1, nxt);
;         const char* nA = has_next ? (const char*)g.A + S.aoff(nxt, tstep) : cA; const char* nB = has_next ? (const char*)g.Bt + S.boff(nxt, tstep) : cB;
;         for (int t = 0; t < nt; t += 2) {
;             if constexpr (Epi::HAS_MID) { if (t == E.mid_t(nt)) { int fr3 = fr, fq3 = fq; asm volatile("" : "+v"(fr3), "+v"(fq3)); E.mid(acc, cur, wr, wc, fr3, fq3); } }
;             const bool last = (t == nt - 2);
;             const char* a1 = cA + (size_t)(t + 1) * kstep;
;             const char* a2 = last ? nA : cA + (size_t)(t + 2) * kstep; const char* b2 = last ? nB : cB + (size_t)(t + 2) * kstep;
;             const char* a3 = a2 + kstep; const char* b3 = b2 + kstep;
;             PG8_LDB(B0, 0, 0); PG8_SCHED; PG8_LDA(At, 0, 0); PG8_STAGE(PG8_SA(1, 1), a1 + hstep, voffA);
;             PG8_WAIT_L(8); PG8_BAR; PG8_WAIT_L(0); PG8_MMA(0, 0, At, B0); PG8_BAR; PG8_SCHED;
;             PG8_LDB(B1, 0, 1); PG8_STAGE(PG8_SB(0, 0), b2, voffB);
;             PG8_BAR; PG8_WAIT_L(0); PG8_MMA(0, 1, At, B1); PG8_BAR;
;             PG8_LDA(At, 0, 1); PG8_STAGE(PG8_SA(0, 0), a2, voffA);
;             PG8_BAR; PG8_WAIT_L(0); PG8_MMA(1, 0, At, B0); PG8_BAR; PG8_SCHED;
;             PG8_STAGE(PG8_SB(0, 1), b2 + hstep, voffB);
;             PG8_WAIT_V(6); PG8_BAR; PG8_MMA(1, 1, At, B1); PG8_BAR;
;             PG8_LDB(B0, 1, 0); PG8_SCHED; PG8_LDA(At, 1, 0); PG8_STAGE(PG8_SA(0, 1), a2 + hstep, voffA);
;             PG8_WAIT_L(8); PG8_BAR; PG8_WAIT_L(0); PG8_MMA(0, 0, At, B0); PG8_BAR; PG8_SCHED;
;             PG8_LDB(B1, 1, 1); PG8_STAGE(PG8_SB(1, 0), b3, voffB);
;             PG8_BAR; PG8_WAIT_L(0); PG8_MMA(0, 1, At, B1); PG8_BAR;
;             PG8_LDA(At, 1, 1); PG8_STAGE(PG8_SA(1, 0), a3, voffA);
;             PG8_BAR; PG8_WAIT_L(0); PG8_MMA(1, 0, At, B0); PG8_BAR; PG8_SCHED;
;             PG8_STAGE(PG8_SB(1, 1), b3 + hstep, voffB);
;             PG8_WAIT_V(6); PG8_BAR; PG8_MMA(1, 1, At, B1); PG8_BAR;
;         }
;         { int fr2 = fr, fq2 = fq; asm volatile("" : "+v"(fr2), "+v"(fq2)); E(acc, cur, wr, wc, fr2, fq2); }
;         if (!has_next) break;
; #pragma unroll
;         for (int a = 0; a < 2; ++a)
; #pragma unroll
;             for (int b = 0; b < 2; ++b)
; #pragma unroll
.LBB0_325:
	s_add_u32 s28, s40, s28
	s_addc_u32 s29, s41, s29
	s_and_b64 s[0:1], s[8:9], exec
	s_cselect_b32 s15, s29, s39
	s_cselect_b32 s17, s28, s38
	s_add_u32 s8, s38, 0x160080
	s_addc_u32 s9, s39, 0
	s_add_u32 s66, s36, 0x100
	v_mov_b32_e32 v0, 0
	s_addc_u32 s67, s37, 0
	s_mov_b32 s68, -2
	ds_read_b128 v[150:153], v141
	ds_read_b128 v[154:157], v141 offset:1024
	ds_read_b128 v[162:165], v141 offset:2048
	ds_read_b128 v[166:169], v141 offset:3072
	s_mov_b32 m0, s58
	ds_read_b128 v[170:173], v142
	ds_read_b128 v[174:177], v142 offset:1024
	ds_read_b128 v[178:181], v142 offset:2048
	ds_read_b128 v[188:191], v142 offset:3072
	ds_read_b128 v[194:197], v142 offset:4096
	ds_read_b128 v[198:201], v142 offset:5120
	ds_read_b128 v[202:205], v142 offset:6144
	global_load_lds_dwordx4 v132, s[8:9]
	s_mov_b32 m0, s59
	ds_read_b128 v[206:209], v142 offset:7168
	global_load_lds_dwordx4 v134, s[8:9]
	s_add_u32 s0, s8, 0xffea0080
	s_addc_u32 s1, s9, -1
	s_cmp_eq_u32 s68, 4
	s_cselect_b32 s39, s15, s1
	s_cselect_b32 s38, s17, s0
	s_cselect_b32 s37, s19, s67
	s_cselect_b32 s36, s18, s66
	s_waitcnt lgkmcnt(8)
	s_barrier
	s_waitcnt lgkmcnt(0)
	s_setprio 1
	v_mfma_f32_16x16x32_bf16 v[124:127], v[150:153], v[170:173], 0
	v_mfma_f32_16x16x32_bf16 v[120:123], v[162:165], v[170:173], 0
	v_mfma_f32_16x16x32_bf16 v[116:119], v[150:153], v[178:181], 0
	v_mfma_f32_16x16x32_bf16 v[112:115], v[162:165], v[178:181], 0
	v_mfma_f32_16x16x32_bf16 v[104:107], v[150:153], v[194:197], 0
	v_mfma_f32_16x16x32_bf16 v[96:99], v[162:165], v[194:197], 0
	v_mfma_f32_16x16x32_bf16 v[88:91], v[150:153], v[202:205], 0
	v_mfma_f32_16x16x32_bf16 v[80:83], v[162:165], v[202:205], 0
	v_mfma_f32_16x16x32_bf16 v[124:127], v[154:157], v[174:177], v[124:127]
	v_mfma_f32_16x16x32_bf16 v[120:123], v[166:169], v[174:177], v[120:123]
	v_mfma_f32_16x16x32_bf16 v[116:119], v[154:157], v[188:191], v[116:119]
	v_mfma_f32_16x16x32_bf16 v[112:115], v[166:169], v[188:191], v[112:115]
	v_mfma_f32_16x16x32_bf16 v[104:107], v[154:157], v[198:201], v[104:107]
	v_mfma_f32_16x16x32_bf16 v[96:99], v[166:169], v[198:201], v[96:99]
	v_mfma_f32_16x16x32_bf16 v[88:91], v[154:157], v[206:209], v[88:91]
	v_mfma_f32_16x16x32_bf16 v[80:83], v[166:169], v[206:209], v[80:83]
	s_setprio 0
	s_barrier
	s_mov_b32 m0, s60
	ds_read_b128 v[210:213], v143
	ds_read_b128 v[214:217], v143 offset:1024
	ds_read_b128 v[218:221], v143 offset:2048
	global_load_lds_dwordx4 v130, s[36:37]
	s_mov_b32 m0, s61
	ds_read_b128 v[222:225], v143 offset:3072
	global_load_lds_dwordx4 v128, s[36:37]
	s_barrier
	s_waitcnt lgkmcnt(0)
	s_setprio 1
	v_mfma_f32_16x16x32_bf16 v[108:111], v[210:213], v[170:173], 0
	v_mfma_f32_16x16x32_bf16 v[100:103], v[218:221], v[170:173], 0
	v_mfma_f32_16x16x32_bf16 v[92:95], v[210:213], v[178:181], 0
	v_mfma_f32_16x16x32_bf16 v[84:87], v[218:221], v[178:181], 0
	v_mfma_f32_16x16x32_bf16 v[76:79], v[210:213], v[194:197], 0
	v_mfma_f32_16x16x32_bf16 v[72:75], v[218:221], v[194:197], 0
	v_mfma_f32_16x16x32_bf16 v[68:71], v[210:213], v[202:205], 0
	v_mfma_f32_16x16x32_bf16 v[64:67], v[218:221], v[202:205], 0
	v_mfma_f32_16x16x32_bf16 v[108:111], v[214:217], v[174:177], v[108:111]
	v_mfma_f32_16x16x32_bf16 v[100:103], v[222:225], v[174:177], v[100:103]
	v_mfma_f32_16x16x32_bf16 v[92:95], v[214:217], v[188:191], v[92:95]
	v_mfma_f32_16x16x32_bf16 v[84:87], v[222:225], v[188:191], v[84:87]
	v_mfma_f32_16x16x32_bf16 v[76:79], v[214:217], v[198:201], v[76:79]
	v_mfma_f32_16x16x32_bf16 v[72:75], v[222:225], v[198:201], v[72:75]
	v_mfma_f32_16x16x32_bf16 v[68:71], v[214:217], v[206:209], v[68:71]
	v_mfma_f32_16x16x32_bf16 v[64:67], v[222:225], v[206:209], v[64:67]
	s_setprio 0
	s_mov_b32 m0, s42
	s_barrier
	ds_read_b128 v[170:173], v142 offset:16384
	ds_read_b128 v[174:177], v142 offset:17408
	ds_read_b128 v[178:181], v142 offset:18432
	ds_read_b128 v[188:191], v142 offset:19456
	ds_read_b128 v[194:197], v142 offset:20480
	ds_read_b128 v[198:201], v142 offset:21504
	ds_read_b128 v[202:205], v142 offset:22528
	global_load_lds_dwordx4 v130, s[38:39]
	s_mov_b32 m0, s43
	ds_read_b128 v[206:209], v142 offset:23552
	global_load_lds_dwordx4 v128, s[38:39]
	s_barrier
	s_waitcnt lgkmcnt(0)
	s_setprio 1
	v_mfma_f32_16x16x32_bf16 v[60:63], v[150:153], v[170:173], 0
	v_mfma_f32_16x16x32_bf16 v[56:59], v[162:165], v[170:173], 0
	v_mfma_f32_16x16x32_bf16 v[52:55], v[150:153], v[178:181], 0
	v_mfma_f32_16x16x32_bf16 v[48:51], v[162:165], v[178:181], 0
	v_mfma_f32_16x16x32_bf16 v[40:43], v[150:153], v[194:197], 0
	v_mfma_f32_16x16x32_bf16 v[32:35], v[162:165], v[194:197], 0
	v_mfma_f32_16x16x32_bf16 v[24:27], v[150:153], v[202:205], 0
	v_mfma_f32_16x16x32_bf16 v[16:19], v[162:165], v[202:205], 0
	v_mfma_f32_16x16x32_bf16 v[60:63], v[154:157], v[174:177], v[60:63]
	v_mfma_f32_16x16x32_bf16 v[56:59], v[166:169], v[174:177], v[56:59]
	v_mfma_f32_16x16x32_bf16 v[52:55], v[154:157], v[188:191], v[52:55]
	v_mfma_f32_16x16x32_bf16 v[48:51], v[166:169], v[188:191], v[48:51]
	v_mfma_f32_16x16x32_bf16 v[40:43], v[154:157], v[198:201], v[40:43]
	v_mfma_f32_16x16x32_bf16 v[32:35], v[166:169], v[198:201], v[32:35]
	v_mfma_f32_16x16x32_bf16 v[24:27], v[154:157], v[206:209], v[24:27]
	v_mfma_f32_16x16x32_bf16 v[16:19], v[166:169], v[206:209], v[16:19]
	s_setprio 0
	s_barrier
	s_add_u32 s0, s36, 0x160000
	s_addc_u32 s1, s37, 0
	s_mov_b32 m0, s62
	s_nop 0
	global_load_lds_dwordx4 v130, s[0:1]
	s_mov_b32 m0, s63
	s_nop 0
	global_load_lds_dwordx4 v128, s[0:1]
	s_waitcnt vmcnt(6)
	s_barrier
; #define PG8_STAGE(bufoff, gbase, voff) do { _Pragma("unroll") for (int _i = 0; _i < 2; ++_i) \
;         __builtin_amdgcn_global_load_lds((const unsigned*)((const char*)(gbase) + (voff)[_i]), (LAS unsigned*)(lds + (bufoff) + ldsw + _i * 8192), 16, 0, 0); } while (0)
; #define PG8_LDA(dst, b, h) do { _Pragma("unroll") for (int m = 0; m < 4; ++m) _Pragma("unroll") for (int k = 0; k < 2; ++k) dst[m][k] = *(const LAS bf16x8*)(lds + PG8_SA(b, h) + aoff + m * 2048 + k * 1024); } while (0)
; #define PG8_LDB(dst, b, h) do { _Pragma("unroll") for (int n = 0; n < 2; ++n) _Pragma("unroll") for (int k = 0; k < 2; ++k) dst[n][k] = *(const LAS bf16x8*)(lds + PG8_SB(b, h) + boff + n * 2048 + k * 1024); } while (0)
; #define PG8_WAIT_V(n) asm volatile("s_waitcnt vmcnt(" #n ")" ::: "memory")
; #define PG8_WAIT_L(n) asm volatile("s_waitcnt lgkmcnt(" #n ")" ::: "memory")
; #define PG8_BAR __builtin_amdgcn_s_barrier()
; #define PG8_SCHED __builtin_amdgcn_sched_barrier(0)
; template <class Epi, class Sched>
; DI void gemm_phase(LAS unsigned char* lds, const Gemm g, const Sched& S, const Epi& E) {
;     ...
;             PG8_LDB(B0, 0, 0); PG8_SCHED; PG8_LDA(At, 0, 0); PG8_STAGE(PG8_SA(1, 1), a1 + hstep, voffA);
;             PG8_WAIT_L(8); PG8_BAR; PG8_WAIT_L(0); PG8_MMA(0, 0, At, B0); PG8_BAR; PG8_SCHED;
;             PG8_LDB(B1, 0, 1); PG8_STAGE(PG8_SB(0, 0), b2, voffB);
;             PG8_BAR; PG8_WAIT_L(0); PG8_MMA(0, 1, At, B1); PG8_BAR;
;             PG8_LDA(At, 0, 1); PG8_STAGE(PG8_SA(0, 0), a2, voffA);
;             PG8_BAR; PG8_WAIT_L(0); PG8_MMA(1, 0, At, B0); PG8_BAR; PG8_SCHED;
;             PG8_STAGE(PG8_SB(0, 1), b2 + hstep, voffB);
;             PG8_WAIT_V(6); PG8_BAR; PG8_MMA(1, 1, At, B1); PG8_BAR;
;             PG8_LDB(B0, 1, 0); PG8_SCHED; PG8_LDA(At, 1, 0); PG8_STAGE(PG8_SA(0, 1), a2 + hstep, voffA);
;             PG8_WAIT_L(8); PG8_BAR; PG8_WAIT_L(0); PG8_MMA(0, 0, At, B0); PG8_BAR; PG8_SCHED;
;             PG8_LDB(B1, 1, 1); PG8_STAGE(PG8_SB(1, 0), b3, voffB);
;             PG8_BAR; PG8_WAIT_L(0); PG8_MMA(0, 1, At, B1); PG8_BAR;
;             PG8_LDA(At, 1, 1); PG8_STAGE(PG8_SA(1, 0), a3, voffA);
;             PG8_BAR; PG8_WAIT_L(0); PG8_MMA(1, 0, At, B0); PG8_BAR; PG8_SCHED;
;             PG8_STAGE(PG8_SB(1, 1), b3 + hstep, voffB);
;             PG8_WAIT_V(6); PG8_BAR; PG8_MMA(1, 1, At, B1); PG8_BAR;
	s_setprio 1
	v_mfma_f32_16x16x32_bf16 v[44:47], v[210:213], v[170:173], 0
	v_mfma_f32_16x16x32_bf16 v[36:39], v[218:221], v[170:173], 0
	v_mfma_f32_16x16x32_bf16 v[28:31], v[210:213], v[178:181], 0
	v_mfma_f32_16x16x32_bf16 v[20:23], v[218:221], v[178:181], 0
	v_mfma_f32_16x16x32_bf16 v[12:15], v[210:213], v[194:197], 0
	v_mfma_f32_16x16x32_bf16 v[8:11], v[218:221], v[194:197], 0
	v_mfma_f32_16x16x32_bf16 v[4:7], v[210:213], v[202:205], 0
	v_mfma_f32_16x16x32_bf16 v[0:3], v[218:221], v[202:205], 0
	v_mfma_f32_16x16x32_bf16 v[44:47], v[214:217], v[174:177], v[44:47]
	v_mfma_f32_16x16x32_bf16 v[36:39], v[222:225], v[174:177], v[36:39]
	v_mfma_f32_16x16x32_bf16 v[28:31], v[214:217], v[188:191], v[28:31]
	v_mfma_f32_16x16x32_bf16 v[20:23], v[222:225], v[188:191], v[20:23]
	v_mfma_f32_16x16x32_bf16 v[12:15], v[214:217], v[198:201], v[12:15]
	v_mfma_f32_16x16x32_bf16 v[8:11], v[222:225], v[198:201], v[8:11]
	v_mfma_f32_16x16x32_bf16 v[4:7], v[214:217], v[206:209], v[4:7]
	v_mfma_f32_16x16x32_bf16 v[0:3], v[222:225], v[206:209], v[0:3]
	s_setprio 0
	s_barrier
	ds_read_b128 v[150:153], v144
	ds_read_b128 v[154:157], v144 offset:1024
	ds_read_b128 v[162:165], v144 offset:2048
	ds_read_b128 v[166:169], v144 offset:3072
	s_add_u32 s0, s38, 0x160000
	s_addc_u32 s1, s39, 0
	s_mov_b32 m0, s44
	ds_read_b128 v[170:173], v142 offset:32768
	ds_read_b128 v[174:177], v142 offset:33792
	ds_read_b128 v[178:181], v142 offset:34816
	ds_read_b128 v[188:191], v142 offset:35840
	ds_read_b128 v[194:197], v142 offset:36864
	ds_read_b128 v[198:201], v142 offset:37888
	ds_read_b128 v[202:205], v142 offset:38912
	global_load_lds_dwordx4 v130, s[0:1]
	s_mov_b32 m0, s45
	ds_read_b128 v[206:209], v142 offset:39936
	global_load_lds_dwordx4 v128, s[0:1]
	s_waitcnt lgkmcnt(8)
	s_barrier
	s_waitcnt lgkmcnt(0)
	s_setprio 1
	v_mfma_f32_16x16x32_bf16 v[124:127], v[150:153], v[170:173], v[124:127]
	v_mfma_f32_16x16x32_bf16 v[120:123], v[162:165], v[170:173], v[120:123]
	v_mfma_f32_16x16x32_bf16 v[116:119], v[150:153], v[178:181], v[116:119]
	v_mfma_f32_16x16x32_bf16 v[112:115], v[162:165], v[178:181], v[112:115]
	v_mfma_f32_16x16x32_bf16 v[104:107], v[150:153], v[194:197], v[104:107]
	v_mfma_f32_16x16x32_bf16 v[96:99], v[162:165], v[194:197], v[96:99]
	v_mfma_f32_16x16x32_bf16 v[88:91], v[150:153], v[202:205], v[88:91]
	v_mfma_f32_16x16x32_bf16 v[80:83], v[162:165], v[202:205], v[80:83]
	v_mfma_f32_16x16x32_bf16 v[124:127], v[154:157], v[174:177], v[124:127]
	v_mfma_f32_16x16x32_bf16 v[120:123], v[166:169], v[174:177], v[120:123]
	v_mfma_f32_16x16x32_bf16 v[116:119], v[154:157], v[188:191], v[116:119]
	v_mfma_f32_16x16x32_bf16 v[112:115], v[166:169], v[188:191], v[112:115]
	v_mfma_f32_16x16x32_bf16 v[104:107], v[154:157], v[198:201], v[104:107]
	v_mfma_f32_16x16x32_bf16 v[96:99], v[166:169], v[198:201], v[96:99]
	v_mfma_f32_16x16x32_bf16 v[88:91], v[154:157], v[206:209], v[88:91]
	v_mfma_f32_16x16x32_bf16 v[80:83], v[166:169], v[206:209], v[80:83]
	s_setprio 0
	s_barrier
	s_add_i32 s4, 0, 0x1c000
	s_add_i32 s0, s64, s35
	v_add_u32_e32 v145, s4, v140
	s_add_i32 m0, s0, 0xffffff80
	ds_read_b128 v[210:213], v145
	ds_read_b128 v[214:217], v145 offset:1024
	ds_read_b128 v[218:221], v145 offset:2048
	global_load_lds_dwordx4 v130, s[36:37] offset:128
	s_add_i32 m0, s0, 0x1f80
	ds_read_b128 v[222:225], v145 offset:3072
	global_load_lds_dwordx4 v128, s[36:37] offset:128
	s_barrier
	s_waitcnt lgkmcnt(0)
	s_setprio 1
	v_mfma_f32_16x16x32_bf16 v[108:111], v[210:213], v[170:173], v[108:111]
	v_mfma_f32_16x16x32_bf16 v[100:103], v[218:221], v[170:173], v[100:103]
	v_mfma_f32_16x16x32_bf16 v[92:95], v[210:213], v[178:181], v[92:95]
	v_mfma_f32_16x16x32_bf16 v[84:87], v[218:221], v[178:181], v[84:87]
	v_mfma_f32_16x16x32_bf16 v[76:79], v[210:213], v[194:197], v[76:79]
	v_mfma_f32_16x16x32_bf16 v[72:75], v[218:221], v[194:197], v[72:75]
	v_mfma_f32_16x16x32_bf16 v[68:71], v[210:213], v[202:205], v[68:71]
	v_mfma_f32_16x16x32_bf16 v[64:67], v[218:221], v[202:205], v[64:67]
	v_mfma_f32_16x16x32_bf16 v[108:111], v[214:217], v[174:177], v[108:111]
	v_mfma_f32_16x16x32_bf16 v[100:103], v[222:225], v[174:177], v[100:103]
	v_mfma_f32_16x16x32_bf16 v[92:95], v[214:217], v[188:191], v[92:95]
	v_mfma_f32_16x16x32_bf16 v[84:87], v[222:225], v[188:191], v[84:87]
	v_mfma_f32_16x16x32_bf16 v[76:79], v[214:217], v[198:201], v[76:79]
	v_mfma_f32_16x16x32_bf16 v[72:75], v[222:225], v[198:201], v[72:75]
	v_mfma_f32_16x16x32_bf16 v[68:71], v[214:217], v[206:209], v[68:71]
	v_mfma_f32_16x16x32_bf16 v[64:67], v[222:225], v[206:209], v[64:67]
	s_setprio 0
	s_add_i32 m0, s56, 0xffffff80
	s_barrier
	ds_read_b128 v[170:173], v142 offset:49152
	ds_read_b128 v[174:177], v142 offset:50176
	ds_read_b128 v[178:181], v142 offset:51200
	ds_read_b128 v[188:191], v142 offset:52224
	ds_read_b128 v[194:197], v142 offset:53248
	ds_read_b128 v[198:201], v142 offset:54272
	ds_read_b128 v[202:205], v142 offset:55296
	global_load_lds_dwordx4 v130, s[38:39] offset:128
	s_add_i32 m0, s57, 0xffffff80
	ds_read_b128 v[206:209], v142 offset:56320
	global_load_lds_dwordx4 v128, s[38:39] offset:128
	s_barrier
; #define PG8_STAGE(bufoff, gbase, voff) do { _Pragma("unroll") for (int _i = 0; _i < 2; ++_i) \
;         __builtin_amdgcn_global_load_lds((const unsigned*)((const char*)(gbase) + (voff)[_i]), (LAS unsigned*)(lds + (bufoff) + ldsw + _i * 8192), 16, 0, 0); } while (0)
; #define PG8_LDA(dst, b, h) do { _Pragma("unroll") for (int m = 0; m < 4; ++m) _Pragma("unroll") for (int k = 0; k < 2; ++k) dst[m][k] = *(const LAS bf16x8*)(lds + PG8_SA(b, h) + aoff + m * 2048 + k * 1024); } while (0)
; template <class Epi, class Sched>
; DI void gemm_phase(LAS unsigned char* lds, const Gemm g, const Sched& S, const Epi& E) {
;     ...
;         for (int t = 0; t < nt; t += 2) {
;             if constexpr (Epi::HAS_MID) { if (t == E.mid_t(nt)) { int fr3 = fr, fq3 = fq; asm volatile("" : "+v"(fr3), "+v"(fq3)); E.mid(acc, cur, wr, wc, fr3, fq3); } }
;             const bool last = (t == nt - 2);
;             const char* a1 = cA + (size_t)(t + 1) * kstep;
;             const char* a2 = last ? nA : cA + (size_t)(t + 2) * kstep; const char* b2 = last ? nB : cB + (size_t)(t + 2) * kstep;
;             const char* a3 = a2 + kstep; const char* b3 = b2 + kstep;
;             PG8_LDB(B0, 0, 0); PG8_SCHED; PG8_LDA(At, 0, 0); PG8_STAGE(PG8_SA(1, 1), a1 + hstep, voffA);
;             PG8_WAIT_L(8); PG8_BAR; PG8_WAIT_L(0); PG8_MMA(0, 0, At, B0); PG8_BAR; PG8_SCHED;
;             PG8_LDB(B1, 0, 1); PG8_STAGE(PG8_SB(0, 0), b2, voffB);
;             PG8_BAR; PG8_WAIT_L(0); PG8_MMA(0, 1, At, B1); PG8_BAR;
;             PG8_LDA(At, 0, 1); PG8_STAGE(PG8_SA(0, 0), a2, voffA);
;             PG8_BAR; PG8_WAIT_L(0); PG8_MMA(1, 0, At, B0); PG8_BAR; PG8_SCHED;
;             PG8_STAGE(PG8_SB(0, 1), b2 + hstep, voffB);
;             PG8_WAIT_V(6); PG8_BAR; PG8_MMA(1, 1, At, B1); PG8_BAR;
;             PG8_LDB(B0, 1, 0); PG8_SCHED; PG8_LDA(At, 1, 0); PG8_STAGE(PG8_SA(0, 1), a2 + hstep, voffA);
;             PG8_WAIT_L(8); PG8_BAR; PG8_WAIT_L(0); PG8_MMA(0, 0, At, B0); PG8_BAR; PG8_SCHED;
;             PG8_LDB(B1, 1, 1); PG8_STAGE(PG8_SB(1, 0), b3, voffB);
;             PG8_BAR; PG8_WAIT_L(0); PG8_MMA(0, 1, At, B1); PG8_BAR;
;             PG8_LDA(At, 1, 1); PG8_STAGE(PG8_SA(1, 0), a3, voffA);
;             PG8_BAR; PG8_WAIT_L(0); PG8_MMA(1, 0, At, B0); PG8_BAR; PG8_SCHED;
;             PG8_STAGE(PG8_SB(1, 1), b3 + hstep, voffB);
;             PG8_WAIT_V(6); PG8_BAR; PG8_MMA(1, 1, At, B1); PG8_BAR;
	s_waitcnt lgkmcnt(0)
	s_setprio 1
	v_mfma_f32_16x16x32_bf16 v[60:63], v[150:153], v[170:173], v[60:63]
	v_mfma_f32_16x16x32_bf16 v[56:59], v[162:165], v[170:173], v[56:59]
	v_mfma_f32_16x16x32_bf16 v[52:55], v[150:153], v[178:181], v[52:55]
	v_mfma_f32_16x16x32_bf16 v[48:51], v[162:165], v[178:181], v[48:51]
	v_mfma_f32_16x16x32_bf16 v[40:43], v[150:153], v[194:197], v[40:43]
	v_mfma_f32_16x16x32_bf16 v[32:35], v[162:165], v[194:197], v[32:35]
	v_mfma_f32_16x16x32_bf16 v[24:27], v[150:153], v[202:205], v[24:27]
	v_mfma_f32_16x16x32_bf16 v[16:19], v[162:165], v[202:205], v[16:19]
	v_mfma_f32_16x16x32_bf16 v[60:63], v[154:157], v[174:177], v[60:63]
	v_mfma_f32_16x16x32_bf16 v[56:59], v[166:169], v[174:177], v[56:59]
	v_mfma_f32_16x16x32_bf16 v[52:55], v[154:157], v[188:191], v[52:55]
	v_mfma_f32_16x16x32_bf16 v[48:51], v[166:169], v[188:191], v[48:51]
	v_mfma_f32_16x16x32_bf16 v[40:43], v[154:157], v[198:201], v[40:43]
	v_mfma_f32_16x16x32_bf16 v[32:35], v[166:169], v[198:201], v[32:35]
	v_mfma_f32_16x16x32_bf16 v[24:27], v[154:157], v[206:209], v[24:27]
	v_mfma_f32_16x16x32_bf16 v[16:19], v[166:169], v[206:209], v[16:19]
	s_setprio 0
	s_barrier
	s_add_i32 s4, s4, s35
	s_mov_b32 m0, s4
	s_add_u32 s0, s36, 0x160080
	s_addc_u32 s1, s37, 0
	global_load_lds_dwordx4 v130, s[0:1]
	s_add_i32 m0, s4, 0x2000
	s_nop 0
	global_load_lds_dwordx4 v128, s[0:1]
	s_waitcnt vmcnt(6)
	s_barrier
	s_setprio 1
	v_mfma_f32_16x16x32_bf16 v[44:47], v[210:213], v[170:173], v[44:47]
	v_mfma_f32_16x16x32_bf16 v[36:39], v[218:221], v[170:173], v[36:39]
	v_mfma_f32_16x16x32_bf16 v[28:31], v[210:213], v[178:181], v[28:31]
	v_mfma_f32_16x16x32_bf16 v[20:23], v[218:221], v[178:181], v[20:23]
	v_mfma_f32_16x16x32_bf16 v[12:15], v[210:213], v[194:197], v[12:15]
	v_mfma_f32_16x16x32_bf16 v[8:11], v[218:221], v[194:197], v[8:11]
	v_mfma_f32_16x16x32_bf16 v[4:7], v[210:213], v[202:205], v[4:7]
	v_mfma_f32_16x16x32_bf16 v[0:3], v[218:221], v[202:205], v[0:3]
	v_mfma_f32_16x16x32_bf16 v[44:47], v[214:217], v[174:177], v[44:47]
	v_mfma_f32_16x16x32_bf16 v[36:39], v[222:225], v[174:177], v[36:39]
	v_mfma_f32_16x16x32_bf16 v[28:31], v[214:217], v[188:191], v[28:31]
	v_mfma_f32_16x16x32_bf16 v[20:23], v[222:225], v[188:191], v[20:23]
	v_mfma_f32_16x16x32_bf16 v[12:15], v[214:217], v[198:201], v[12:15]
	v_mfma_f32_16x16x32_bf16 v[8:11], v[222:225], v[198:201], v[8:11]
	v_mfma_f32_16x16x32_bf16 v[4:7], v[214:217], v[206:209], v[4:7]
	v_mfma_f32_16x16x32_bf16 v[0:3], v[222:225], v[206:209], v[0:3]
	s_setprio 0
	s_add_i32 s68, s68, 2
	s_add_u32 s8, s8, 0x100
	s_addc_u32 s9, s9, 0
	s_add_u32 s66, s66, 0x100
	s_addc_u32 s67, s67, 0
	s_cmp_gt_u32 s68, 5
	s_barrier
	s_cbranch_scc0 .LBB0_326
	s_branch .Lpeel_done_326
.LBB0_326:
	ds_read_b128 v[150:153], v141
	ds_read_b128 v[154:157], v141 offset:1024
	ds_read_b128 v[162:165], v141 offset:2048
	ds_read_b128 v[166:169], v141 offset:3072
	s_mov_b32 m0, s58
	ds_read_b128 v[170:173], v142
	ds_read_b128 v[174:177], v142 offset:1024
	ds_read_b128 v[178:181], v142 offset:2048
	ds_read_b128 v[188:191], v142 offset:3072
	ds_read_b128 v[194:197], v142 offset:4096
	ds_read_b128 v[198:201], v142 offset:5120
	ds_read_b128 v[202:205], v142 offset:6144
	global_load_lds_dwordx4 v132, s[8:9]
	s_mov_b32 m0, s59
	ds_read_b128 v[206:209], v142 offset:7168
	global_load_lds_dwordx4 v134, s[8:9]
	s_add_u32 s0, s8, 0xffea0080
	s_addc_u32 s1, s9, -1
	s_cmp_eq_u32 s68, 4
	s_cselect_b32 s39, s15, s1
	s_cselect_b32 s38, s17, s0
	s_cselect_b32 s37, s19, s67
	s_cselect_b32 s36, s18, s66
	s_waitcnt lgkmcnt(8)
	s_barrier
	s_waitcnt lgkmcnt(0)
	s_setprio 1
	v_mfma_f32_16x16x32_bf16 v[124:127], v[150:153], v[170:173], v[124:127]
	v_mfma_f32_16x16x32_bf16 v[120:123], v[162:165], v[170:173], v[120:123]
	v_mfma_f32_16x16x32_bf16 v[116:119], v[150:153], v[178:181], v[116:119]
	v_mfma_f32_16x16x32_bf16 v[112:115], v[162:165], v[178:181], v[112:115]
	v_mfma_f32_16x16x32_bf16 v[104:107], v[150:153], v[194:197], v[104:107]
	v_mfma_f32_16x16x32_bf16 v[96:99], v[162:165], v[194:197], v[96:99]
	v_mfma_f32_16x16x32_bf16 v[88:91], v[150:153], v[202:205], v[88:91]
	v_mfma_f32_16x16x32_bf16 v[80:83], v[162:165], v[202:205], v[80:83]
	v_mfma_f32_16x16x32_bf16 v[124:127], v[154:157], v[174:177], v[124:127]
	v_mfma_f32_16x16x32_bf16 v[120:123], v[166:169], v[174:177], v[120:123]
	v_mfma_f32_16x16x32_bf16 v[116:119], v[154:157], v[188:191], v[116:119]
	v_mfma_f32_16x16x32_bf16 v[112:115], v[166:169], v[188:191], v[112:115]
	v_mfma_f32_16x16x32_bf16 v[104:107], v[154:157], v[198:201], v[104:107]
	v_mfma_f32_16x16x32_bf16 v[96:99], v[166:169], v[198:201], v[96:99]
	v_mfma_f32_16x16x32_bf16 v[88:91], v[154:157], v[206:209], v[88:91]
	v_mfma_f32_16x16x32_bf16 v[80:83], v[166:169], v[206:209], v[80:83]
	s_setprio 0
	s_barrier
	s_mov_b32 m0, s60
	ds_read_b128 v[210:213], v143
	ds_read_b128 v[214:217], v143 offset:1024
	ds_read_b128 v[218:221], v143 offset:2048
	global_load_lds_dwordx4 v130, s[36:37]
	s_mov_b32 m0, s61
	ds_read_b128 v[222:225], v143 offset:3072
	global_load_lds_dwordx4 v128, s[36:37]
	s_barrier
; #define PG8_STAGE(bufoff, gbase, voff) do { _Pragma("unroll") for (int _i = 0; _i < 2; ++_i) \
;         __builtin_amdgcn_global_load_lds((const unsigned*)((const char*)(gbase) + (voff)[_i]), (LAS unsigned*)(lds + (bufoff) + ldsw + _i * 8192), 16, 0, 0); } while (0)
; #define PG8_LDA(dst, b, h) do { _Pragma("unroll") for (int m = 0; m < 4; ++m) _Pragma("unroll") for (int k = 0; k < 2; ++k) dst[m][k] = *(const LAS bf16x8*)(lds + PG8_SA(b, h) + aoff + m * 2048 + k * 1024); } while (0)
; #define PG8_LDB(dst, b, h) do { _Pragma("unroll") for (int n = 0; n < 2; ++n) _Pragma("unroll") for (int k = 0; k < 2; ++k) dst[n][k] = *(const LAS bf16x8*)(lds + PG8_SB(b, h) + boff + n * 2048 + k * 1024); } while (0)
; #define PG8_WAIT_V(n) asm volatile("s_waitcnt vmcnt(" #n ")" ::: "memory")
; #define PG8_WAIT_L(n) asm volatile("s_waitcnt lgkmcnt(" #n ")" ::: "memory")
; #define PG8_BAR __builtin_amdgcn_s_barrier()
; #define PG8_SCHED __builtin_amdgcn_sched_barrier(0)
; template <class Epi, class Sched>
; DI void gemm_phase(LAS unsigned char* lds, const Gemm g, const Sched& S, const Epi& E) {
;     ...
;             PG8_LDB(B0, 0, 0); PG8_SCHED; PG8_LDA(At, 0, 0); PG8_STAGE(PG8_SA(1, 1), a1 + hstep, voffA);
;             PG8_WAIT_L(8); PG8_BAR; PG8_WAIT_L(0); PG8_MMA(0, 0, At, B0); PG8_BAR; PG8_SCHED;
;             PG8_LDB(B1, 0, 1); PG8_STAGE(PG8_SB(0, 0), b2, voffB);
;             PG8_BAR; PG8_WAIT_L(0); PG8_MMA(0, 1, At, B1); PG8_BAR;
;             PG8_LDA(At, 0, 1); PG8_STAGE(PG8_SA(0, 0), a2, voffA);
;             PG8_BAR; PG8_WAIT_L(0); PG8_MMA(1, 0, At, B0); PG8_BAR; PG8_SCHED;
;             PG8_STAGE(PG8_SB(0, 1), b2 + hstep, voffB);
;             PG8_WAIT_V(6); PG8_BAR; PG8_MMA(1, 1, At, B1); PG8_BAR;
;             PG8_LDB(B0, 1, 0); PG8_SCHED; PG8_LDA(At, 1, 0); PG8_STAGE(PG8_SA(0, 1), a2 + hstep, voffA);
;             PG8_WAIT_L(8); PG8_BAR; PG8_WAIT_L(0); PG8_MMA(0, 0, At, B0); PG8_BAR; PG8_SCHED;
;             PG8_LDB(B1, 1, 1); PG8_STAGE(PG8_SB(1, 0), b3, voffB);
;             PG8_BAR; PG8_WAIT_L(0); PG8_MMA(0, 1, At, B1); PG8_BAR;
;             PG8_LDA(At, 1, 1); PG8_STAGE(PG8_SA(1, 0), a3, voffA);
;             PG8_BAR; PG8_WAIT_L(0); PG8_MMA(1, 0, At, B0); PG8_BAR; PG8_SCHED;
;             PG8_STAGE(PG8_SB(1, 1), b3 + hstep, voffB);
;             PG8_WAIT_V(6); PG8_BAR; PG8_MMA(1, 1, At, B1); PG8_BAR;
	s_waitcnt lgkmcnt(0)
	s_setprio 1
	v_mfma_f32_16x16x32_bf16 v[108:111], v[210:213], v[170:173], v[108:111]
	v_mfma_f32_16x16x32_bf16 v[100:103], v[218:221], v[170:173], v[100:103]
	v_mfma_f32_16x16x32_bf16 v[92:95], v[210:213], v[178:181], v[92:95]
	v_mfma_f32_16x16x32_bf16 v[84:87], v[218:221], v[178:181], v[84:87]
	v_mfma_f32_16x16x32_bf16 v[76:79], v[210:213], v[194:197], v[76:79]
	v_mfma_f32_16x16x32_bf16 v[72:75], v[218:221], v[194:197], v[72:75]
	v_mfma_f32_16x16x32_bf16 v[68:71], v[210:213], v[202:205], v[68:71]
	v_mfma_f32_16x16x32_bf16 v[64:67], v[218:221], v[202:205], v[64:67]
	v_mfma_f32_16x16x32_bf16 v[108:111], v[214:217], v[174:177], v[108:111]
	v_mfma_f32_16x16x32_bf16 v[100:103], v[222:225], v[174:177], v[100:103]
	v_mfma_f32_16x16x32_bf16 v[92:95], v[214:217], v[188:191], v[92:95]
	v_mfma_f32_16x16x32_bf16 v[84:87], v[222:225], v[188:191], v[84:87]
	v_mfma_f32_16x16x32_bf16 v[76:79], v[214:217], v[198:201], v[76:79]
	v_mfma_f32_16x16x32_bf16 v[72:75], v[222:225], v[198:201], v[72:75]
	v_mfma_f32_16x16x32_bf16 v[68:71], v[214:217], v[206:209], v[68:71]
	v_mfma_f32_16x16x32_bf16 v[64:67], v[222:225], v[206:209], v[64:67]
	s_setprio 0
	s_mov_b32 m0, s42
	s_barrier
	ds_read_b128 v[170:173], v142 offset:16384
	ds_read_b128 v[174:177], v142 offset:17408
	ds_read_b128 v[178:181], v142 offset:18432
	ds_read_b128 v[188:191], v142 offset:19456
	ds_read_b128 v[194:197], v142 offset:20480
	ds_read_b128 v[198:201], v142 offset:21504
	ds_read_b128 v[202:205], v142 offset:22528
	global_load_lds_dwordx4 v130, s[38:39]
	s_mov_b32 m0, s43
	ds_read_b128 v[206:209], v142 offset:23552
	global_load_lds_dwordx4 v128, s[38:39]
	s_barrier
	s_waitcnt lgkmcnt(0)
	s_setprio 1
	v_mfma_f32_16x16x32_bf16 v[60:63], v[150:153], v[170:173], v[60:63]
	v_mfma_f32_16x16x32_bf16 v[56:59], v[162:165], v[170:173], v[56:59]
	v_mfma_f32_16x16x32_bf16 v[52:55], v[150:153], v[178:181], v[52:55]
	v_mfma_f32_16x16x32_bf16 v[48:51], v[162:165], v[178:181], v[48:51]
	v_mfma_f32_16x16x32_bf16 v[40:43], v[150:153], v[194:197], v[40:43]
	v_mfma_f32_16x16x32_bf16 v[32:35], v[162:165], v[194:197], v[32:35]
	v_mfma_f32_16x16x32_bf16 v[24:27], v[150:153], v[202:205], v[24:27]
	v_mfma_f32_16x16x32_bf16 v[16:19], v[162:165], v[202:205], v[16:19]
	v_mfma_f32_16x16x32_bf16 v[60:63], v[154:157], v[174:177], v[60:63]
	v_mfma_f32_16x16x32_bf16 v[56:59], v[166:169], v[174:177], v[56:59]
	v_mfma_f32_16x16x32_bf16 v[52:55], v[154:157], v[188:191], v[52:55]
	v_mfma_f32_16x16x32_bf16 v[48:51], v[166:169], v[188:191], v[48:51]
	v_mfma_f32_16x16x32_bf16 v[40:43], v[154:157], v[198:201], v[40:43]
	v_mfma_f32_16x16x32_bf16 v[32:35], v[166:169], v[198:201], v[32:35]
	v_mfma_f32_16x16x32_bf16 v[24:27], v[154:157], v[206:209], v[24:27]
	v_mfma_f32_16x16x32_bf16 v[16:19], v[166:169], v[206:209], v[16:19]
	s_setprio 0
	s_barrier
	s_add_u32 s0, s36, 0x160000
	s_addc_u32 s1, s37, 0
	s_mov_b32 m0, s62
	s_nop 0
	global_load_lds_dwordx4 v130, s[0:1]
	s_mov_b32 m0, s63
	s_nop 0
	global_load_lds_dwordx4 v128, s[0:1]
	s_waitcnt vmcnt(6)
	s_barrier
	s_setprio 1
	v_mfma_f32_16x16x32_bf16 v[44:47], v[210:213], v[170:173], v[44:47]
	v_mfma_f32_16x16x32_bf16 v[36:39], v[218:221], v[170:173], v[36:39]
	v_mfma_f32_16x16x32_bf16 v[28:31], v[210:213], v[178:181], v[28:31]
	v_mfma_f32_16x16x32_bf16 v[20:23], v[218:221], v[178:181], v[20:23]
	v_mfma_f32_16x16x32_bf16 v[12:15], v[210:213], v[194:197], v[12:15]
	v_mfma_f32_16x16x32_bf16 v[8:11], v[218:221], v[194:197], v[8:11]
	v_mfma_f32_16x16x32_bf16 v[4:7], v[210:213], v[202:205], v[4:7]
	v_mfma_f32_16x16x32_bf16 v[0:3], v[218:221], v[202:205], v[0:3]
	v_mfma_f32_16x16x32_bf16 v[44:47], v[214:217], v[174:177], v[44:47]
	v_mfma_f32_16x16x32_bf16 v[36:39], v[222:225], v[174:177], v[36:39]
	v_mfma_f32_16x16x32_bf16 v[28:31], v[214:217], v[188:191], v[28:31]
	v_mfma_f32_16x16x32_bf16 v[20:23], v[222:225], v[188:191], v[20:23]
	v_mfma_f32_16x16x32_bf16 v[12:15], v[214:217], v[198:201], v[12:15]
	v_mfma_f32_16x16x32_bf16 v[8:11], v[222:225], v[198:201], v[8:11]
	v_mfma_f32_16x16x32_bf16 v[4:7], v[214:217], v[206:209], v[4:7]
	v_mfma_f32_16x16x32_bf16 v[0:3], v[222:225], v[206:209], v[0:3]
	s_setprio 0
	s_barrier
	ds_read_b128 v[150:153], v144
	ds_read_b128 v[154:157], v144 offset:1024
	ds_read_b128 v[162:165], v144 offset:2048
	ds_read_b128 v[166:169], v144 offset:3072
	s_add_u32 s0, s38, 0x160000
	s_addc_u32 s1, s39, 0
	s_mov_b32 m0, s44
	ds_read_b128 v[170:173], v142 offset:32768
	ds_read_b128 v[174:177], v142 offset:33792
	ds_read_b128 v[178:181], v142 offset:34816
	ds_read_b128 v[188:191], v142 offset:35840
	ds_read_b128 v[194:197], v142 offset:36864
	ds_read_b128 v[198:201], v142 offset:37888
	ds_read_b128 v[202:205], v142 offset:38912
	global_load_lds_dwordx4 v130, s[0:1]
	s_mov_b32 m0, s45
	ds_read_b128 v[206:209], v142 offset:39936
	global_load_lds_dwordx4 v128, s[0:1]
	s_waitcnt lgkmcnt(8)
	s_barrier
; #define PG8_STAGE(bufoff, gbase, voff) do { _Pragma("unroll") for (int _i = 0; _i < 2; ++_i) \
;         __builtin_amdgcn_global_load_lds((const unsigned*)((const char*)(gbase) + (voff)[_i]), (LAS unsigned*)(lds + (bufoff) + ldsw + _i * 8192), 16, 0, 0); } while (0)
; #define PG8_LDA(dst, b, h) do { _Pragma("unroll") for (int m = 0; m < 4; ++m) _Pragma("unroll") for (int k = 0; k < 2; ++k) dst[m][k] = *(const LAS bf16x8*)(lds + PG8_SA(b, h) + aoff + m * 2048 + k * 1024); } while (0)
; #define PG8_LDB(dst, b, h) do { _Pragma("unroll") for (int n = 0; n < 2; ++n) _Pragma("unroll") for (int k = 0; k < 2; ++k) dst[n][k] = *(const LAS bf16x8*)(lds + PG8_SB(b, h) + boff + n * 2048 + k * 1024); } while (0)
; #define PG8_WAIT_V(n) asm volatile("s_waitcnt vmcnt(" #n ")" ::: "memory")
; #define PG8_WAIT_L(n) asm volatile("s_waitcnt lgkmcnt(" #n ")" ::: "memory")
; #define PG8_BAR __builtin_amdgcn_s_barrier()
; #define PG8_SCHED __builtin_amdgcn_sched_barrier(0)
; template <class Epi, class Sched>
; DI void gemm_phase(LAS unsigned char* lds, const Gemm g, const Sched& S, const Epi& E) {
;     ...
;             PG8_LDB(B0, 0, 0); PG8_SCHED; PG8_LDA(At, 0, 0); PG8_STAGE(PG8_SA(1, 1), a1 + hstep, voffA);
;             PG8_WAIT_L(8); PG8_BAR; PG8_WAIT_L(0); PG8_MMA(0, 0, At, B0); PG8_BAR; PG8_SCHED;
;             PG8_LDB(B1, 0, 1); PG8_STAGE(PG8_SB(0, 0), b2, voffB);
;             PG8_BAR; PG8_WAIT_L(0); PG8_MMA(0, 1, At, B1); PG8_BAR;
;             PG8_LDA(At, 0, 1); PG8_STAGE(PG8_SA(0, 0), a2, voffA);
;             PG8_BAR; PG8_WAIT_L(0); PG8_MMA(1, 0, At, B0); PG8_BAR; PG8_SCHED;
;             PG8_STAGE(PG8_SB(0, 1), b2 + hstep, voffB);
;             PG8_WAIT_V(6); PG8_BAR; PG8_MMA(1, 1, At, B1); PG8_BAR;
;             PG8_LDB(B0, 1, 0); PG8_SCHED; PG8_LDA(At, 1, 0); PG8_STAGE(PG8_SA(0, 1), a2 + hstep, voffA);
;             PG8_WAIT_L(8); PG8_BAR; PG8_WAIT_L(0); PG8_MMA(0, 0, At, B0); PG8_BAR; PG8_SCHED;
;             PG8_LDB(B1, 1, 1); PG8_STAGE(PG8_SB(1, 0), b3, voffB);
;             PG8_BAR; PG8_WAIT_L(0); PG8_MMA(0, 1, At, B1); PG8_BAR;
;             PG8_LDA(At, 1, 1); PG8_STAGE(PG8_SA(1, 0), a3, voffA);
;             PG8_BAR; PG8_WAIT_L(0); PG8_MMA(1, 0, At, B0); PG8_BAR; PG8_SCHED;
;             PG8_STAGE(PG8_SB(1, 1), b3 + hstep, voffB);
;             PG8_WAIT_V(6); PG8_BAR; PG8_MMA(1, 1, At, B1); PG8_BAR;
	s_waitcnt lgkmcnt(0)
	s_setprio 1
	v_mfma_f32_16x16x32_bf16 v[124:127], v[150:153], v[170:173], v[124:127]
	v_mfma_f32_16x16x32_bf16 v[120:123], v[162:165], v[170:173], v[120:123]
	v_mfma_f32_16x16x32_bf16 v[116:119], v[150:153], v[178:181], v[116:119]
	v_mfma_f32_16x16x32_bf16 v[112:115], v[162:165], v[178:181], v[112:115]
	v_mfma_f32_16x16x32_bf16 v[104:107], v[150:153], v[194:197], v[104:107]
	v_mfma_f32_16x16x32_bf16 v[96:99], v[162:165], v[194:197], v[96:99]
	v_mfma_f32_16x16x32_bf16 v[88:91], v[150:153], v[202:205], v[88:91]
	v_mfma_f32_16x16x32_bf16 v[80:83], v[162:165], v[202:205], v[80:83]
	v_mfma_f32_16x16x32_bf16 v[124:127], v[154:157], v[174:177], v[124:127]
	v_mfma_f32_16x16x32_bf16 v[120:123], v[166:169], v[174:177], v[120:123]
	v_mfma_f32_16x16x32_bf16 v[116:119], v[154:157], v[188:191], v[116:119]
	v_mfma_f32_16x16x32_bf16 v[112:115], v[166:169], v[188:191], v[112:115]
	v_mfma_f32_16x16x32_bf16 v[104:107], v[154:157], v[198:201], v[104:107]
	v_mfma_f32_16x16x32_bf16 v[96:99], v[166:169], v[198:201], v[96:99]
	v_mfma_f32_16x16x32_bf16 v[88:91], v[154:157], v[206:209], v[88:91]
	v_mfma_f32_16x16x32_bf16 v[80:83], v[166:169], v[206:209], v[80:83]
	s_setprio 0
	s_barrier
	s_add_i32 s4, 0, 0x1c000
	s_add_i32 s0, s64, s35
	v_add_u32_e32 v145, s4, v140
	s_add_i32 m0, s0, 0xffffff80
	ds_read_b128 v[210:213], v145
	ds_read_b128 v[214:217], v145 offset:1024
	ds_read_b128 v[218:221], v145 offset:2048
	global_load_lds_dwordx4 v130, s[36:37] offset:128
	s_add_i32 m0, s0, 0x1f80
	ds_read_b128 v[222:225], v145 offset:3072
	global_load_lds_dwordx4 v128, s[36:37] offset:128
	s_barrier
	s_waitcnt lgkmcnt(0)
	s_setprio 1
	v_mfma_f32_16x16x32_bf16 v[108:111], v[210:213], v[170:173], v[108:111]
	v_mfma_f32_16x16x32_bf16 v[100:103], v[218:221], v[170:173], v[100:103]
	v_mfma_f32_16x16x32_bf16 v[92:95], v[210:213], v[178:181], v[92:95]
	v_mfma_f32_16x16x32_bf16 v[84:87], v[218:221], v[178:181], v[84:87]
	v_mfma_f32_16x16x32_bf16 v[76:79], v[210:213], v[194:197], v[76:79]
	v_mfma_f32_16x16x32_bf16 v[72:75], v[218:221], v[194:197], v[72:75]
	v_mfma_f32_16x16x32_bf16 v[68:71], v[210:213], v[202:205], v[68:71]
	v_mfma_f32_16x16x32_bf16 v[64:67], v[218:221], v[202:205], v[64:67]
	v_mfma_f32_16x16x32_bf16 v[108:111], v[214:217], v[174:177], v[108:111]
	v_mfma_f32_16x16x32_bf16 v[100:103], v[222:225], v[174:177], v[100:103]
	v_mfma_f32_16x16x32_bf16 v[92:95], v[214:217], v[188:191], v[92:95]
	v_mfma_f32_16x16x32_bf16 v[84:87], v[222:225], v[188:191], v[84:87]
	v_mfma_f32_16x16x32_bf16 v[76:79], v[214:217], v[198:201], v[76:79]
	v_mfma_f32_16x16x32_bf16 v[72:75], v[222:225], v[198:201], v[72:75]
	v_mfma_f32_16x16x32_bf16 v[68:71], v[214:217], v[206:209], v[68:71]
	v_mfma_f32_16x16x32_bf16 v[64:67], v[222:225], v[206:209], v[64:67]
	s_setprio 0
	s_add_i32 m0, s56, 0xffffff80
	s_barrier
	ds_read_b128 v[170:173], v142 offset:49152
	ds_read_b128 v[174:177], v142 offset:50176
	ds_read_b128 v[178:181], v142 offset:51200
	ds_read_b128 v[188:191], v142 offset:52224
	ds_read_b128 v[194:197], v142 offset:53248
	ds_read_b128 v[198:201], v142 offset:54272
	ds_read_b128 v[202:205], v142 offset:55296
	global_load_lds_dwordx4 v130, s[38:39] offset:128
	s_add_i32 m0, s57, 0xffffff80
	ds_read_b128 v[206:209], v142 offset:56320
	global_load_lds_dwordx4 v128, s[38:39] offset:128
	s_barrier
	s_waitcnt lgkmcnt(0)
	s_setprio 1
	v_mfma_f32_16x16x32_bf16 v[60:63], v[150:153], v[170:173], v[60:63]
	v_mfma_f32_16x16x32_bf16 v[56:59], v[162:165], v[170:173], v[56:59]
	v_mfma_f32_16x16x32_bf16 v[52:55], v[150:153], v[178:181], v[52:55]
	v_mfma_f32_16x16x32_bf16 v[48:51], v[162:165], v[178:181], v[48:51]
	v_mfma_f32_16x16x32_bf16 v[40:43], v[150:153], v[194:197], v[40:43]
	v_mfma_f32_16x16x32_bf16 v[32:35], v[162:165], v[194:197], v[32:35]
	v_mfma_f32_16x16x32_bf16 v[24:27], v[150:153], v[202:205], v[24:27]
	v_mfma_f32_16x16x32_bf16 v[16:19], v[162:165], v[202:205], v[16:19]
	v_mfma_f32_16x16x32_bf16 v[60:63], v[154:157], v[174:177], v[60:63]
	v_mfma_f32_16x16x32_bf16 v[56:59], v[166:169], v[174:177], v[56:59]
	v_mfma_f32_16x16x32_bf16 v[52:55], v[154:157], v[188:191], v[52:55]
	v_mfma_f32_16x16x32_bf16 v[48:51], v[166:169], v[188:191], v[48:51]
	v_mfma_f32_16x16x32_bf16 v[40:43], v[154:157], v[198:201], v[40:43]
	v_mfma_f32_16x16x32_bf16 v[32:35], v[166:169], v[198:201], v[32:35]
	v_mfma_f32_16x16x32_bf16 v[24:27], v[154:157], v[206:209], v[24:27]
	v_mfma_f32_16x16x32_bf16 v[16:19], v[166:169], v[206:209], v[16:19]
	s_setprio 0
	s_barrier
	s_add_i32 s4, s4, s35
	s_mov_b32 m0, s4
	s_add_u32 s0, s36, 0x160080
	s_addc_u32 s1, s37, 0
	global_load_lds_dwordx4 v130, s[0:1]
	s_add_i32 m0, s4, 0x2000
	s_nop 0
	global_load_lds_dwordx4 v128, s[0:1]
	s_waitcnt vmcnt(6)
	s_barrier
	s_setprio 1
	v_mfma_f32_16x16x32_bf16 v[44:47], v[210:213], v[170:173], v[44:47]
	v_mfma_f32_16x16x32_bf16 v[36:39], v[218:221], v[170:173], v[36:39]
	v_mfma_f32_16x16x32_bf16 v[28:31], v[210:213], v[178:181], v[28:31]
	v_mfma_f32_16x16x32_bf16 v[20:23], v[218:221], v[178:181], v[20:23]
	v_mfma_f32_16x16x32_bf16 v[12:15], v[210:213], v[194:197], v[12:15]
	v_mfma_f32_16x16x32_bf16 v[8:11], v[218:221], v[194:197], v[8:11]
	v_mfma_f32_16x16x32_bf16 v[4:7], v[210:213], v[202:205], v[4:7]
	v_mfma_f32_16x16x32_bf16 v[0:3], v[218:221], v[202:205], v[0:3]
	v_mfma_f32_16x16x32_bf16 v[44:47], v[214:217], v[174:177], v[44:47]
	v_mfma_f32_16x16x32_bf16 v[36:39], v[222:225], v[174:177], v[36:39]
	v_mfma_f32_16x16x32_bf16 v[28:31], v[214:217], v[188:191], v[28:31]
	v_mfma_f32_16x16x32_bf16 v[20:23], v[222:225], v[188:191], v[20:23]
	v_mfma_f32_16x16x32_bf16 v[12:15], v[214:217], v[198:201], v[12:15]
	v_mfma_f32_16x16x32_bf16 v[8:11], v[222:225], v[198:201], v[8:11]
	v_mfma_f32_16x16x32_bf16 v[4:7], v[214:217], v[206:209], v[4:7]
	v_mfma_f32_16x16x32_bf16 v[0:3], v[222:225], v[206:209], v[0:3]
	s_setprio 0
	s_add_i32 s68, s68, 2
	s_add_u32 s8, s8, 0x100
	s_addc_u32 s9, s9, 0
	s_add_u32 s66, s66, 0x100
	s_addc_u32 s67, s67, 0
	s_cmp_gt_u32 s68, 5
	s_barrier
	s_cbranch_scc0 .LBB0_326

;     DI size_t aoff(const Unit& u, size_t) const { return (size_t)u.ks * kbytes; }
;     DI size_t aoff(const Unit& u, size_t tstep) const { return (size_t)u.pm * tstep; }
;     DI size_t boff(const Unit& u, size_t tstep) const { return (size_t)u.pn * tstep; }
; template <class Epi, class Sched>
; DI void gemm_phase(LAS unsigned char* lds, const Gemm g, const Sched& S, const Epi& E) {
;     ...
;         const bool has_next = S.next(ui + 1, nxt);
;         const char* nA = has_next ? (const char*)g.A + S.aoff(nxt, tstep) : cA; const char* nB = has_next ? (const char*)g.Bt + S.boff(nxt, tstep) : cB;
;         for (int t = 0; t < nt; t += 2) {
;             if constexpr (Epi::HAS_MID) { if (t == E.mid_t(nt)) { int fr3 = fr, fq3 = fq; asm volatile("" : "+v"(fr3), "+v"(fq3)); E.mid(acc, cur, wr, wc, fr3, fq3); } }
;             const bool last = (t == nt - 2);
;             const char* a1 = cA + (size_t)(t + 1) * kstep;
;             const char* a2 = last ? nA : cA + (size_t)(t + 2) * kstep; const char* b2 = last ? nB : cB + (size_t)(t + 2) * kstep;
;             const char* a3 = a2 + kstep; const char* b3 = b2 + kstep;
;             PG8_LDB(B0, 0, 0); PG8_SCHED; PG8_LDA(At, 0, 0); PG8_STAGE(PG8_SA(1, 1), a1 + hstep, voffA);
;             PG8_WAIT_L(8); PG8_BAR; PG8_WAIT_L(0); PG8_MMA(0, 0, At, B0); PG8_BAR; PG8_SCHED;
;             PG8_LDB(B1, 0, 1); PG8_STAGE(PG8_SB(0, 0), b2, voffB);
;             PG8_BAR; PG8_WAIT_L(0); PG8_MMA(0, 1, At, B1); PG8_BAR;
;             PG8_LDA(At, 0, 1); PG8_STAGE(PG8_SA(0, 0), a2, voffA);
;             PG8_BAR; PG8_WAIT_L(0); PG8_MMA(1, 0, At, B0); PG8_BAR; PG8_SCHED;
;             PG8_STAGE(PG8_SB(0, 1), b2 + hstep, voffB);
;             PG8_WAIT_V(6); PG8_BAR; PG8_MMA(1, 1, At, B1); PG8_BAR;
;             PG8_LDB(B0, 1, 0); PG8_SCHED; PG8_LDA(At, 1, 0); PG8_STAGE(PG8_SA(0, 1), a2 + hstep, voffA);
;             PG8_WAIT_L(8); PG8_BAR; PG8_WAIT_L(0); PG8_MMA(0, 0, At, B0); PG8_BAR; PG8_SCHED;
;             PG8_LDB(B1, 1, 1); PG8_STAGE(PG8_SB(1, 0), b3, voffB);
;             PG8_BAR; PG8_WAIT_L(0); PG8_MMA(0, 1, At, B1); PG8_BAR;
;             PG8_LDA(At, 1, 1); PG8_STAGE(PG8_SA(1, 0), a3, voffA);
;             PG8_BAR; PG8_WAIT_L(0); PG8_MMA(1, 0, At, B0); PG8_BAR; PG8_SCHED;
;             PG8_STAGE(PG8_SB(1, 1), b3 + hstep, voffB);
;             PG8_WAIT_V(6); PG8_BAR; PG8_MMA(1, 1, At, B1); PG8_BAR;
.LBB0_526:
	s_ashr_i32 s51, s50, 31
	s_lshl_b64 s[0:1], s[50:51], 20
	s_add_u32 s52, s70, s0
	v_cmp_lt_i64_e32 vcc, s[12:13], v[142:143]
	s_addc_u32 s53, s71, s1
	s_and_b64 s[0:1], vcc, exec
	s_cselect_b32 s14, s53, s9
	s_cselect_b32 s15, s52, s8
	s_ashr_i32 s49, s48, 31
	s_lshl_b64 s[0:1], s[48:49], 20
	s_add_u32 s54, s72, s0
	s_addc_u32 s55, s73, s1
	s_and_b64 s[0:1], vcc, exec
	s_cselect_b32 s16, s55, s11
	s_cselect_b32 s17, s54, s10
	s_add_u32 s8, s8, 0x80080
	s_addc_u32 s9, s9, 0
	s_add_u32 s28, s10, 0x100
	v_mov_b32_e32 v0, 0
	s_addc_u32 s34, s11, 0
	s_mov_b32 s35, -2
	ds_read_b128 v[146:149], v164
	ds_read_b128 v[150:153], v164 offset:1024
	ds_read_b128 v[154:157], v164 offset:2048
	ds_read_b128 v[170:173], v164 offset:3072
	s_add_i32 m0, s59, 0xc000
	ds_read_b128 v[174:177], v165
	ds_read_b128 v[178:181], v165 offset:1024
	ds_read_b128 v[188:191], v165 offset:2048
	ds_read_b128 v[194:197], v165 offset:3072
	ds_read_b128 v[198:201], v165 offset:4096
	ds_read_b128 v[202:205], v165 offset:5120
	ds_read_b128 v[206:209], v165 offset:6144
	global_load_lds_dwordx4 v138, s[8:9]
	s_add_i32 m0, s59, 0xe000
	ds_read_b128 v[210:213], v165 offset:7168
	global_load_lds_dwordx4 v140, s[8:9]
	s_add_u32 s0, s8, 0xfff80080
	s_addc_u32 s1, s9, -1
	s_cmp_eq_u32 s35, 28
	s_cselect_b32 s13, s14, s1
	s_cselect_b32 s12, s15, s0
	s_cselect_b32 s11, s16, s34
	s_cselect_b32 s10, s17, s28
	s_waitcnt lgkmcnt(8)
	s_barrier
	s_waitcnt lgkmcnt(0)
	s_setprio 1
	v_mfma_f32_16x16x32_bf16 v[124:127], v[146:149], v[174:177], 0
	v_mfma_f32_16x16x32_bf16 v[120:123], v[154:157], v[174:177], 0
	v_mfma_f32_16x16x32_bf16 v[108:111], v[146:149], v[188:191], 0
	v_mfma_f32_16x16x32_bf16 v[104:107], v[154:157], v[188:191], 0
	v_mfma_f32_16x16x32_bf16 v[92:95], v[146:149], v[198:201], 0
	v_mfma_f32_16x16x32_bf16 v[88:91], v[154:157], v[198:201], 0
	v_mfma_f32_16x16x32_bf16 v[76:79], v[146:149], v[206:209], 0
	v_mfma_f32_16x16x32_bf16 v[72:75], v[154:157], v[206:209], 0
	v_mfma_f32_16x16x32_bf16 v[124:127], v[150:153], v[178:181], v[124:127]
	v_mfma_f32_16x16x32_bf16 v[120:123], v[170:173], v[178:181], v[120:123]
	v_mfma_f32_16x16x32_bf16 v[108:111], v[150:153], v[194:197], v[108:111]
	v_mfma_f32_16x16x32_bf16 v[104:107], v[170:173], v[194:197], v[104:107]
	v_mfma_f32_16x16x32_bf16 v[92:95], v[150:153], v[202:205], v[92:95]
	v_mfma_f32_16x16x32_bf16 v[88:91], v[170:173], v[202:205], v[88:91]
	v_mfma_f32_16x16x32_bf16 v[76:79], v[150:153], v[210:213], v[76:79]
	v_mfma_f32_16x16x32_bf16 v[72:75], v[170:173], v[210:213], v[72:75]
	s_setprio 0
	s_barrier
	s_add_i32 s0, s47, s74
	s_mov_b32 m0, s0
	ds_read_b128 v[214:217], v166
	ds_read_b128 v[218:221], v166 offset:1024
	ds_read_b128 v[222:225], v166 offset:2048
	global_load_lds_dwordx4 v130, s[10:11]
	s_add_i32 m0, s0, 0x2000
	ds_read_b128 v[226:229], v166 offset:3072
	global_load_lds_dwordx4 v134, s[10:11]
	s_barrier
	s_waitcnt lgkmcnt(0)
	s_setprio 1
	v_mfma_f32_16x16x32_bf16 v[116:119], v[214:217], v[174:177], 0
	v_mfma_f32_16x16x32_bf16 v[112:115], v[222:225], v[174:177], 0
	v_mfma_f32_16x16x32_bf16 v[100:103], v[214:217], v[188:191], 0
	v_mfma_f32_16x16x32_bf16 v[96:99], v[222:225], v[188:191], 0
	v_mfma_f32_16x16x32_bf16 v[84:87], v[214:217], v[198:201], 0
	v_mfma_f32_16x16x32_bf16 v[80:83], v[222:225], v[198:201], 0
	v_mfma_f32_16x16x32_bf16 v[68:71], v[214:217], v[206:209], 0
	v_mfma_f32_16x16x32_bf16 v[64:67], v[222:225], v[206:209], 0
	v_mfma_f32_16x16x32_bf16 v[116:119], v[218:221], v[178:181], v[116:119]
	v_mfma_f32_16x16x32_bf16 v[112:115], v[226:229], v[178:181], v[112:115]
	v_mfma_f32_16x16x32_bf16 v[100:103], v[218:221], v[194:197], v[100:103]
	v_mfma_f32_16x16x32_bf16 v[96:99], v[226:229], v[194:197], v[96:99]
	v_mfma_f32_16x16x32_bf16 v[84:87], v[218:221], v[202:205], v[84:87]
	v_mfma_f32_16x16x32_bf16 v[80:83], v[226:229], v[202:205], v[80:83]
	v_mfma_f32_16x16x32_bf16 v[68:71], v[218:221], v[210:213], v[68:71]
	v_mfma_f32_16x16x32_bf16 v[64:67], v[226:229], v[210:213], v[64:67]
	s_setprio 0
	s_mov_b32 m0, s59
	s_barrier
	ds_read_b128 v[174:177], v165 offset:16384
	ds_read_b128 v[178:181], v165 offset:17408
	ds_read_b128 v[188:191], v165 offset:18432
	ds_read_b128 v[194:197], v165 offset:19456
	ds_read_b128 v[198:201], v165 offset:20480
	ds_read_b128 v[202:205], v165 offset:21504
	ds_read_b128 v[206:209], v165 offset:22528
	global_load_lds_dwordx4 v128, s[12:13]
	s_mov_b32 m0, s75
	ds_read_b128 v[210:213], v165 offset:23552
	global_load_lds_dwordx4 v132, s[12:13]
	s_barrier
	s_waitcnt lgkmcnt(0)
	s_setprio 1
	v_mfma_f32_16x16x32_bf16 v[60:63], v[146:149], v[174:177], 0
	v_mfma_f32_16x16x32_bf16 v[56:59], v[154:157], v[174:177], 0
	v_mfma_f32_16x16x32_bf16 v[44:47], v[146:149], v[188:191], 0
	v_mfma_f32_16x16x32_bf16 v[40:43], v[154:157], v[188:191], 0
	v_mfma_f32_16x16x32_bf16 v[28:31], v[146:149], v[198:201], 0
	v_mfma_f32_16x16x32_bf16 v[24:27], v[154:157], v[198:201], 0
	v_mfma_f32_16x16x32_bf16 v[12:15], v[146:149], v[206:209], 0
	v_mfma_f32_16x16x32_bf16 v[8:11], v[154:157], v[206:209], 0
	v_mfma_f32_16x16x32_bf16 v[60:63], v[150:153], v[178:181], v[60:63]
	v_mfma_f32_16x16x32_bf16 v[56:59], v[170:173], v[178:181], v[56:59]
	v_mfma_f32_16x16x32_bf16 v[44:47], v[150:153], v[194:197], v[44:47]
	v_mfma_f32_16x16x32_bf16 v[40:43], v[170:173], v[194:197], v[40:43]
	v_mfma_f32_16x16x32_bf16 v[28:31], v[150:153], v[202:205], v[28:31]
	v_mfma_f32_16x16x32_bf16 v[24:27], v[170:173], v[202:205], v[24:27]
	v_mfma_f32_16x16x32_bf16 v[12:15], v[150:153], v[210:213], v[12:15]
	v_mfma_f32_16x16x32_bf16 v[8:11], v[170:173], v[210:213], v[8:11]
	s_setprio 0
	s_barrier
; #define PG8_STAGE(bufoff, gbase, voff) do { _Pragma("unroll") for (int _i = 0; _i < 2; ++_i) \
;         __builtin_amdgcn_global_load_lds((const unsigned*)((const char*)(gbase) + (voff)[_i]), (LAS unsigned*)(lds + (bufoff) + ldsw + _i * 8192), 16, 0, 0); } while (0)
; #define PG8_LDA(dst, b, h) do { _Pragma("unroll") for (int m = 0; m < 4; ++m) _Pragma("unroll") for (int k = 0; k < 2; ++k) dst[m][k] = *(const LAS bf16x8*)(lds + PG8_SA(b, h) + aoff + m * 2048 + k * 1024); } while (0)
; #define PG8_LDB(dst, b, h) do { _Pragma("unroll") for (int n = 0; n < 2; ++n) _Pragma("unroll") for (int k = 0; k < 2; ++k) dst[n][k] = *(const LAS bf16x8*)(lds + PG8_SB(b, h) + boff + n * 2048 + k * 1024); } while (0)
; #define PG8_WAIT_V(n) asm volatile("s_waitcnt vmcnt(" #n ")" ::: "memory")
; #define PG8_WAIT_L(n) asm volatile("s_waitcnt lgkmcnt(" #n ")" ::: "memory")
; #define PG8_BAR __builtin_amdgcn_s_barrier()
; #define PG8_SCHED __builtin_amdgcn_sched_barrier(0)
; template <class Epi, class Sched>
; DI void gemm_phase(LAS unsigned char* lds, const Gemm g, const Sched& S, const Epi& E) {
;     ...
;             PG8_LDB(B0, 0, 0); PG8_SCHED; PG8_LDA(At, 0, 0); PG8_STAGE(PG8_SA(1, 1), a1 + hstep, voffA);
;             PG8_WAIT_L(8); PG8_BAR; PG8_WAIT_L(0); PG8_MMA(0, 0, At, B0); PG8_BAR; PG8_SCHED;
;             PG8_LDB(B1, 0, 1); PG8_STAGE(PG8_SB(0, 0), b2, voffB);
;             PG8_BAR; PG8_WAIT_L(0); PG8_MMA(0, 1, At, B1); PG8_BAR;
;             PG8_LDA(At, 0, 1); PG8_STAGE(PG8_SA(0, 0), a2, voffA);
;             PG8_BAR; PG8_WAIT_L(0); PG8_MMA(1, 0, At, B0); PG8_BAR; PG8_SCHED;
;             PG8_STAGE(PG8_SB(0, 1), b2 + hstep, voffB);
;             PG8_WAIT_V(6); PG8_BAR; PG8_MMA(1, 1, At, B1); PG8_BAR;
;             PG8_LDB(B0, 1, 0); PG8_SCHED; PG8_LDA(At, 1, 0); PG8_STAGE(PG8_SA(0, 1), a2 + hstep, voffA);
;             PG8_WAIT_L(8); PG8_BAR; PG8_WAIT_L(0); PG8_MMA(0, 0, At, B0); PG8_BAR; PG8_SCHED;
;             PG8_LDB(B1, 1, 1); PG8_STAGE(PG8_SB(1, 0), b3, voffB);
;             PG8_BAR; PG8_WAIT_L(0); PG8_MMA(0, 1, At, B1); PG8_BAR;
;             PG8_LDA(At, 1, 1); PG8_STAGE(PG8_SA(1, 0), a3, voffA);
;             PG8_BAR; PG8_WAIT_L(0); PG8_MMA(1, 0, At, B0); PG8_BAR; PG8_SCHED;
;             PG8_STAGE(PG8_SB(1, 1), b3 + hstep, voffB);
;             PG8_WAIT_V(6); PG8_BAR; PG8_MMA(1, 1, At, B1); PG8_BAR;
	s_add_i32 s4, s87, s74
	s_mov_b32 m0, s4
	s_add_u32 s0, s10, 0x80000
	s_addc_u32 s1, s11, 0
	global_load_lds_dwordx4 v130, s[0:1]
	s_add_i32 m0, s4, 0x2000
	s_nop 0
	global_load_lds_dwordx4 v134, s[0:1]
	s_waitcnt vmcnt(6)
	s_barrier
	s_setprio 1
	v_mfma_f32_16x16x32_bf16 v[52:55], v[214:217], v[174:177], 0
	v_mfma_f32_16x16x32_bf16 v[48:51], v[222:225], v[174:177], 0
	v_mfma_f32_16x16x32_bf16 v[36:39], v[214:217], v[188:191], 0
	v_mfma_f32_16x16x32_bf16 v[32:35], v[222:225], v[188:191], 0
	v_mfma_f32_16x16x32_bf16 v[20:23], v[214:217], v[198:201], 0
	v_mfma_f32_16x16x32_bf16 v[16:19], v[222:225], v[198:201], 0
	v_mfma_f32_16x16x32_bf16 v[4:7], v[214:217], v[206:209], 0
	v_mfma_f32_16x16x32_bf16 v[0:3], v[222:225], v[206:209], 0
	v_mfma_f32_16x16x32_bf16 v[52:55], v[218:221], v[178:181], v[52:55]
	v_mfma_f32_16x16x32_bf16 v[48:51], v[226:229], v[178:181], v[48:51]
	v_mfma_f32_16x16x32_bf16 v[36:39], v[218:221], v[194:197], v[36:39]
	v_mfma_f32_16x16x32_bf16 v[32:35], v[226:229], v[194:197], v[32:35]
	v_mfma_f32_16x16x32_bf16 v[20:23], v[218:221], v[202:205], v[20:23]
	v_mfma_f32_16x16x32_bf16 v[16:19], v[226:229], v[202:205], v[16:19]
	v_mfma_f32_16x16x32_bf16 v[4:7], v[218:221], v[210:213], v[4:7]
	v_mfma_f32_16x16x32_bf16 v[0:3], v[226:229], v[210:213], v[0:3]
	s_setprio 0
	s_add_i32 s4, 0, 0x18000
	v_add_u32_e32 v158, s4, v163
	s_barrier
	ds_read_b128 v[146:149], v158
	ds_read_b128 v[150:153], v158 offset:1024
	ds_read_b128 v[154:157], v158 offset:2048
	ds_read_b128 v[170:173], v158 offset:3072
	s_add_u32 s0, s12, 0x80000
	s_addc_u32 s1, s13, 0
	s_mov_b32 m0, s76
	ds_read_b128 v[174:177], v165 offset:32768
	ds_read_b128 v[178:181], v165 offset:33792
	ds_read_b128 v[188:191], v165 offset:34816
	ds_read_b128 v[194:197], v165 offset:35840
	ds_read_b128 v[198:201], v165 offset:36864
	ds_read_b128 v[202:205], v165 offset:37888
	ds_read_b128 v[206:209], v165 offset:38912
	global_load_lds_dwordx4 v128, s[0:1]
	s_mov_b32 m0, s77
	ds_read_b128 v[210:213], v165 offset:39936
	global_load_lds_dwordx4 v132, s[0:1]
	s_waitcnt lgkmcnt(8)
	s_barrier
	s_waitcnt lgkmcnt(0)
	s_setprio 1
	v_mfma_f32_16x16x32_bf16 v[124:127], v[146:149], v[174:177], v[124:127]
	v_mfma_f32_16x16x32_bf16 v[120:123], v[154:157], v[174:177], v[120:123]
	v_mfma_f32_16x16x32_bf16 v[108:111], v[146:149], v[188:191], v[108:111]
	v_mfma_f32_16x16x32_bf16 v[104:107], v[154:157], v[188:191], v[104:107]
	v_mfma_f32_16x16x32_bf16 v[92:95], v[146:149], v[198:201], v[92:95]
	v_mfma_f32_16x16x32_bf16 v[88:91], v[154:157], v[198:201], v[88:91]
	v_mfma_f32_16x16x32_bf16 v[76:79], v[146:149], v[206:209], v[76:79]
	v_mfma_f32_16x16x32_bf16 v[72:75], v[154:157], v[206:209], v[72:75]
	v_mfma_f32_16x16x32_bf16 v[124:127], v[150:153], v[178:181], v[124:127]
	v_mfma_f32_16x16x32_bf16 v[120:123], v[170:173], v[178:181], v[120:123]
	v_mfma_f32_16x16x32_bf16 v[108:111], v[150:153], v[194:197], v[108:111]
	v_mfma_f32_16x16x32_bf16 v[104:107], v[170:173], v[194:197], v[104:107]
	v_mfma_f32_16x16x32_bf16 v[92:95], v[150:153], v[202:205], v[92:95]
	v_mfma_f32_16x16x32_bf16 v[88:91], v[170:173], v[202:205], v[88:91]
	v_mfma_f32_16x16x32_bf16 v[76:79], v[150:153], v[210:213], v[76:79]
	v_mfma_f32_16x16x32_bf16 v[72:75], v[170:173], v[210:213], v[72:75]
	s_setprio 0
	s_barrier
	s_add_i32 s5, 0, 0x1c000
	s_add_i32 s0, s4, s74
	v_add_u32_e32 v159, s5, v163
	s_add_i32 m0, s0, 0xffffff80
	ds_read_b128 v[214:217], v159
	ds_read_b128 v[218:221], v159 offset:1024
	ds_read_b128 v[222:225], v159 offset:2048
	global_load_lds_dwordx4 v130, s[10:11] offset:128
	s_add_i32 m0, s0, 0x1f80
	ds_read_b128 v[226:229], v159 offset:3072
	global_load_lds_dwordx4 v134, s[10:11] offset:128
	s_barrier
	s_waitcnt lgkmcnt(0)
	s_setprio 1
	v_mfma_f32_16x16x32_bf16 v[116:119], v[214:217], v[174:177], v[116:119]
	v_mfma_f32_16x16x32_bf16 v[112:115], v[222:225], v[174:177], v[112:115]
	v_mfma_f32_16x16x32_bf16 v[100:103], v[214:217], v[188:191], v[100:103]
	v_mfma_f32_16x16x32_bf16 v[96:99], v[222:225], v[188:191], v[96:99]
	v_mfma_f32_16x16x32_bf16 v[84:87], v[214:217], v[198:201], v[84:87]
	v_mfma_f32_16x16x32_bf16 v[80:83], v[222:225], v[198:201], v[80:83]
	v_mfma_f32_16x16x32_bf16 v[68:71], v[214:217], v[206:209], v[68:71]
	v_mfma_f32_16x16x32_bf16 v[64:67], v[222:225], v[206:209], v[64:67]
	v_mfma_f32_16x16x32_bf16 v[116:119], v[218:221], v[178:181], v[116:119]
	v_mfma_f32_16x16x32_bf16 v[112:115], v[226:229], v[178:181], v[112:115]
	v_mfma_f32_16x16x32_bf16 v[100:103], v[218:221], v[194:197], v[100:103]
	v_mfma_f32_16x16x32_bf16 v[96:99], v[226:229], v[194:197], v[96:99]
	v_mfma_f32_16x16x32_bf16 v[84:87], v[218:221], v[202:205], v[84:87]
	v_mfma_f32_16x16x32_bf16 v[80:83], v[226:229], v[202:205], v[80:83]
	v_mfma_f32_16x16x32_bf16 v[68:71], v[218:221], v[210:213], v[68:71]
	v_mfma_f32_16x16x32_bf16 v[64:67], v[226:229], v[210:213], v[64:67]
	s_setprio 0
	s_add_i32 m0, s97, 0xffffff80
	s_barrier
	ds_read_b128 v[174:177], v165 offset:49152
	ds_read_b128 v[178:181], v165 offset:50176
	ds_read_b128 v[188:191], v165 offset:51200
	ds_read_b128 v[194:197], v165 offset:52224
	ds_read_b128 v[198:201], v165 offset:53248
	ds_read_b128 v[202:205], v165 offset:54272
	ds_read_b128 v[206:209], v165 offset:55296
	global_load_lds_dwordx4 v128, s[12:13] offset:128
	s_add_i32 m0, s84, 0xffffff80
	ds_read_b128 v[210:213], v165 offset:56320
	global_load_lds_dwordx4 v132, s[12:13] offset:128
	s_barrier
; #define PG8_STAGE(bufoff, gbase, voff) do { _Pragma("unroll") for (int _i = 0; _i < 2; ++_i) \
;         __builtin_amdgcn_global_load_lds((const unsigned*)((const char*)(gbase) + (voff)[_i]), (LAS unsigned*)(lds + (bufoff) + ldsw + _i * 8192), 16, 0, 0); } while (0)
; #define PG8_LDA(dst, b, h) do { _Pragma("unroll") for (int m = 0; m < 4; ++m) _Pragma("unroll") for (int k = 0; k < 2; ++k) dst[m][k] = *(const LAS bf16x8*)(lds + PG8_SA(b, h) + aoff + m * 2048 + k * 1024); } while (0)
; template <class Epi, class Sched>
; DI void gemm_phase(LAS unsigned char* lds, const Gemm g, const Sched& S, const Epi& E) {
;     ...
;         for (int t = 0; t < nt; t += 2) {
;             if constexpr (Epi::HAS_MID) { if (t == E.mid_t(nt)) { int fr3 = fr, fq3 = fq; asm volatile("" : "+v"(fr3), "+v"(fq3)); E.mid(acc, cur, wr, wc, fr3, fq3); } }
;             const bool last = (t == nt - 2);
;             const char* a1 = cA + (size_t)(t + 1) * kstep;
;             const char* a2 = last ? nA : cA + (size_t)(t + 2) * kstep; const char* b2 = last ? nB : cB + (size_t)(t + 2) * kstep;
;             const char* a3 = a2 + kstep; const char* b3 = b2 + kstep;
;             PG8_LDB(B0, 0, 0); PG8_SCHED; PG8_LDA(At, 0, 0); PG8_STAGE(PG8_SA(1, 1), a1 + hstep, voffA);
;             PG8_WAIT_L(8); PG8_BAR; PG8_WAIT_L(0); PG8_MMA(0, 0, At, B0); PG8_BAR; PG8_SCHED;
;             PG8_LDB(B1, 0, 1); PG8_STAGE(PG8_SB(0, 0), b2, voffB);
;             PG8_BAR; PG8_WAIT_L(0); PG8_MMA(0, 1, At, B1); PG8_BAR;
;             PG8_LDA(At, 0, 1); PG8_STAGE(PG8_SA(0, 0), a2, voffA);
;             PG8_BAR; PG8_WAIT_L(0); PG8_MMA(1, 0, At, B0); PG8_BAR; PG8_SCHED;
;             PG8_STAGE(PG8_SB(0, 1), b2 + hstep, voffB);
;             PG8_WAIT_V(6); PG8_BAR; PG8_MMA(1, 1, At, B1); PG8_BAR;
;             PG8_LDB(B0, 1, 0); PG8_SCHED; PG8_LDA(At, 1, 0); PG8_STAGE(PG8_SA(0, 1), a2 + hstep, voffA);
;             PG8_WAIT_L(8); PG8_BAR; PG8_WAIT_L(0); PG8_MMA(0, 0, At, B0); PG8_BAR; PG8_SCHED;
;             PG8_LDB(B1, 1, 1); PG8_STAGE(PG8_SB(1, 0), b3, voffB);
;             PG8_BAR; PG8_WAIT_L(0); PG8_MMA(0, 1, At, B1); PG8_BAR;
;             PG8_LDA(At, 1, 1); PG8_STAGE(PG8_SA(1, 0), a3, voffA);
;             PG8_BAR; PG8_WAIT_L(0); PG8_MMA(1, 0, At, B0); PG8_BAR; PG8_SCHED;
;             PG8_STAGE(PG8_SB(1, 1), b3 + hstep, voffB);
;             PG8_WAIT_V(6); PG8_BAR; PG8_MMA(1, 1, At, B1); PG8_BAR;
	s_waitcnt lgkmcnt(0)
	s_setprio 1
	v_mfma_f32_16x16x32_bf16 v[60:63], v[146:149], v[174:177], v[60:63]
	v_mfma_f32_16x16x32_bf16 v[56:59], v[154:157], v[174:177], v[56:59]
	v_mfma_f32_16x16x32_bf16 v[44:47], v[146:149], v[188:191], v[44:47]
	v_mfma_f32_16x16x32_bf16 v[40:43], v[154:157], v[188:191], v[40:43]
	v_mfma_f32_16x16x32_bf16 v[28:31], v[146:149], v[198:201], v[28:31]
	v_mfma_f32_16x16x32_bf16 v[24:27], v[154:157], v[198:201], v[24:27]
	v_mfma_f32_16x16x32_bf16 v[12:15], v[146:149], v[206:209], v[12:15]
	v_mfma_f32_16x16x32_bf16 v[8:11], v[154:157], v[206:209], v[8:11]
	v_mfma_f32_16x16x32_bf16 v[60:63], v[150:153], v[178:181], v[60:63]
	v_mfma_f32_16x16x32_bf16 v[56:59], v[170:173], v[178:181], v[56:59]
	v_mfma_f32_16x16x32_bf16 v[44:47], v[150:153], v[194:197], v[44:47]
	v_mfma_f32_16x16x32_bf16 v[40:43], v[170:173], v[194:197], v[40:43]
	v_mfma_f32_16x16x32_bf16 v[28:31], v[150:153], v[202:205], v[28:31]
	v_mfma_f32_16x16x32_bf16 v[24:27], v[170:173], v[202:205], v[24:27]
	v_mfma_f32_16x16x32_bf16 v[12:15], v[150:153], v[210:213], v[12:15]
	v_mfma_f32_16x16x32_bf16 v[8:11], v[170:173], v[210:213], v[8:11]
	s_setprio 0
	s_barrier
	s_add_i32 s4, s5, s74
	s_mov_b32 m0, s4
	s_add_u32 s0, s10, 0x80080
	s_addc_u32 s1, s11, 0
	global_load_lds_dwordx4 v130, s[0:1]
	v_lshl_add_u64 v[146:147], s[0:1], 0, v[134:135]
	s_add_i32 m0, s4, 0x2000
	s_nop 0
	global_load_lds_dwordx4 v134, s[0:1]
	s_waitcnt vmcnt(6)
	s_barrier
	s_setprio 1
	v_mfma_f32_16x16x32_bf16 v[52:55], v[214:217], v[174:177], v[52:55]
	v_mfma_f32_16x16x32_bf16 v[48:51], v[222:225], v[174:177], v[48:51]
	v_mfma_f32_16x16x32_bf16 v[36:39], v[214:217], v[188:191], v[36:39]
	v_mfma_f32_16x16x32_bf16 v[32:35], v[222:225], v[188:191], v[32:35]
	v_mfma_f32_16x16x32_bf16 v[20:23], v[214:217], v[198:201], v[20:23]
	v_mfma_f32_16x16x32_bf16 v[16:19], v[222:225], v[198:201], v[16:19]
	v_mfma_f32_16x16x32_bf16 v[4:7], v[214:217], v[206:209], v[4:7]
	v_mfma_f32_16x16x32_bf16 v[0:3], v[222:225], v[206:209], v[0:3]
	v_mfma_f32_16x16x32_bf16 v[52:55], v[218:221], v[178:181], v[52:55]
	v_mfma_f32_16x16x32_bf16 v[48:51], v[226:229], v[178:181], v[48:51]
	v_mfma_f32_16x16x32_bf16 v[36:39], v[218:221], v[194:197], v[36:39]
	v_mfma_f32_16x16x32_bf16 v[32:35], v[226:229], v[194:197], v[32:35]
	v_mfma_f32_16x16x32_bf16 v[20:23], v[218:221], v[202:205], v[20:23]
	v_mfma_f32_16x16x32_bf16 v[16:19], v[226:229], v[202:205], v[16:19]
	v_mfma_f32_16x16x32_bf16 v[4:7], v[218:221], v[210:213], v[4:7]
	v_mfma_f32_16x16x32_bf16 v[0:3], v[226:229], v[210:213], v[0:3]
	s_setprio 0
	s_add_i32 s35, s35, 2
	s_add_u32 s8, s8, 0x100
	s_addc_u32 s9, s9, 0
	s_add_u32 s28, s28, 0x100
	s_addc_u32 s34, s34, 0
	s_cmp_gt_u32 s35, 29
	s_barrier
	s_cbranch_scc0 .LBB0_527
	s_branch .Lpeel_done_527
.LBB0_527:
	ds_read_b128 v[146:149], v164
	ds_read_b128 v[150:153], v164 offset:1024
	ds_read_b128 v[154:157], v164 offset:2048
	ds_read_b128 v[170:173], v164 offset:3072
	s_add_i32 m0, s59, 0xc000
	ds_read_b128 v[174:177], v165
	ds_read_b128 v[178:181], v165 offset:1024
	ds_read_b128 v[188:191], v165 offset:2048
	ds_read_b128 v[194:197], v165 offset:3072
	ds_read_b128 v[198:201], v165 offset:4096
	ds_read_b128 v[202:205], v165 offset:5120
	ds_read_b128 v[206:209], v165 offset:6144
	global_load_lds_dwordx4 v138, s[8:9]
	s_add_i32 m0, s59, 0xe000
	ds_read_b128 v[210:213], v165 offset:7168
	global_load_lds_dwordx4 v140, s[8:9]
	s_add_u32 s0, s8, 0xfff80080
	s_addc_u32 s1, s9, -1
	s_cmp_eq_u32 s35, 28
	s_cselect_b32 s13, s14, s1
	s_cselect_b32 s12, s15, s0
	s_cselect_b32 s11, s16, s34
	s_cselect_b32 s10, s17, s28
	s_waitcnt lgkmcnt(8)
	s_barrier
	s_waitcnt lgkmcnt(0)
	s_setprio 1
	v_mfma_f32_16x16x32_bf16 v[124:127], v[146:149], v[174:177], v[124:127]
	v_mfma_f32_16x16x32_bf16 v[120:123], v[154:157], v[174:177], v[120:123]
	v_mfma_f32_16x16x32_bf16 v[108:111], v[146:149], v[188:191], v[108:111]
	v_mfma_f32_16x16x32_bf16 v[104:107], v[154:157], v[188:191], v[104:107]
	v_mfma_f32_16x16x32_bf16 v[92:95], v[146:149], v[198:201], v[92:95]
	v_mfma_f32_16x16x32_bf16 v[88:91], v[154:157], v[198:201], v[88:91]
	v_mfma_f32_16x16x32_bf16 v[76:79], v[146:149], v[206:209], v[76:79]
	v_mfma_f32_16x16x32_bf16 v[72:75], v[154:157], v[206:209], v[72:75]
	v_mfma_f32_16x16x32_bf16 v[124:127], v[150:153], v[178:181], v[124:127]
	v_mfma_f32_16x16x32_bf16 v[120:123], v[170:173], v[178:181], v[120:123]
	v_mfma_f32_16x16x32_bf16 v[108:111], v[150:153], v[194:197], v[108:111]
	v_mfma_f32_16x16x32_bf16 v[104:107], v[170:173], v[194:197], v[104:107]
	v_mfma_f32_16x16x32_bf16 v[92:95], v[150:153], v[202:205], v[92:95]
	v_mfma_f32_16x16x32_bf16 v[88:91], v[170:173], v[202:205], v[88:91]
	v_mfma_f32_16x16x32_bf16 v[76:79], v[150:153], v[210:213], v[76:79]
	v_mfma_f32_16x16x32_bf16 v[72:75], v[170:173], v[210:213], v[72:75]
	s_setprio 0
	s_barrier
	s_add_i32 s0, s47, s74
	s_mov_b32 m0, s0
	ds_read_b128 v[214:217], v166
	ds_read_b128 v[218:221], v166 offset:1024
	ds_read_b128 v[222:225], v166 offset:2048
	global_load_lds_dwordx4 v130, s[10:11]
	s_add_i32 m0, s0, 0x2000
	ds_read_b128 v[226:229], v166 offset:3072
	global_load_lds_dwordx4 v134, s[10:11]
	s_barrier
; #define PG8_STAGE(bufoff, gbase, voff) do { _Pragma("unroll") for (int _i = 0; _i < 2; ++_i) \
;         __builtin_amdgcn_global_load_lds((const unsigned*)((const char*)(gbase) + (voff)[_i]), (LAS unsigned*)(lds + (bufoff) + ldsw + _i * 8192), 16, 0, 0); } while (0)
; #define PG8_LDA(dst, b, h) do { _Pragma("unroll") for (int m = 0; m < 4; ++m) _Pragma("unroll") for (int k = 0; k < 2; ++k) dst[m][k] = *(const LAS bf16x8*)(lds + PG8_SA(b, h) + aoff + m * 2048 + k * 1024); } while (0)
; #define PG8_LDB(dst, b, h) do { _Pragma("unroll") for (int n = 0; n < 2; ++n) _Pragma("unroll") for (int k = 0; k < 2; ++k) dst[n][k] = *(const LAS bf16x8*)(lds + PG8_SB(b, h) + boff + n * 2048 + k * 1024); } while (0)
; #define PG8_WAIT_V(n) asm volatile("s_waitcnt vmcnt(" #n ")" ::: "memory")
; #define PG8_WAIT_L(n) asm volatile("s_waitcnt lgkmcnt(" #n ")" ::: "memory")
; #define PG8_BAR __builtin_amdgcn_s_barrier()
; #define PG8_SCHED __builtin_amdgcn_sched_barrier(0)
; template <class Epi, class Sched>
; DI void gemm_phase(LAS unsigned char* lds, const Gemm g, const Sched& S, const Epi& E) {
;     ...
;             PG8_LDB(B0, 0, 0); PG8_SCHED; PG8_LDA(At, 0, 0); PG8_STAGE(PG8_SA(1, 1), a1 + hstep, voffA);
;             PG8_WAIT_L(8); PG8_BAR; PG8_WAIT_L(0); PG8_MMA(0, 0, At, B0); PG8_BAR; PG8_SCHED;
;             PG8_LDB(B1, 0, 1); PG8_STAGE(PG8_SB(0, 0), b2, voffB);
;             PG8_BAR; PG8_WAIT_L(0); PG8_MMA(0, 1, At, B1); PG8_BAR;
;             PG8_LDA(At, 0, 1); PG8_STAGE(PG8_SA(0, 0), a2, voffA);
;             PG8_BAR; PG8_WAIT_L(0); PG8_MMA(1, 0, At, B0); PG8_BAR; PG8_SCHED;
;             PG8_STAGE(PG8_SB(0, 1), b2 + hstep, voffB);
;             PG8_WAIT_V(6); PG8_BAR; PG8_MMA(1, 1, At, B1); PG8_BAR;
;             PG8_LDB(B0, 1, 0); PG8_SCHED; PG8_LDA(At, 1, 0); PG8_STAGE(PG8_SA(0, 1), a2 + hstep, voffA);
;             PG8_WAIT_L(8); PG8_BAR; PG8_WAIT_L(0); PG8_MMA(0, 0, At, B0); PG8_BAR; PG8_SCHED;
;             PG8_LDB(B1, 1, 1); PG8_STAGE(PG8_SB(1, 0), b3, voffB);
;             PG8_BAR; PG8_WAIT_L(0); PG8_MMA(0, 1, At, B1); PG8_BAR;
;             PG8_LDA(At, 1, 1); PG8_STAGE(PG8_SA(1, 0), a3, voffA);
;             PG8_BAR; PG8_WAIT_L(0); PG8_MMA(1, 0, At, B0); PG8_BAR; PG8_SCHED;
;             PG8_STAGE(PG8_SB(1, 1), b3 + hstep, voffB);
;             PG8_WAIT_V(6); PG8_BAR; PG8_MMA(1, 1, At, B1); PG8_BAR;
	s_waitcnt lgkmcnt(0)
	s_setprio 1
	v_mfma_f32_16x16x32_bf16 v[116:119], v[214:217], v[174:177], v[116:119]
	v_mfma_f32_16x16x32_bf16 v[112:115], v[222:225], v[174:177], v[112:115]
	v_mfma_f32_16x16x32_bf16 v[100:103], v[214:217], v[188:191], v[100:103]
	v_mfma_f32_16x16x32_bf16 v[96:99], v[222:225], v[188:191], v[96:99]
	v_mfma_f32_16x16x32_bf16 v[84:87], v[214:217], v[198:201], v[84:87]
	v_mfma_f32_16x16x32_bf16 v[80:83], v[222:225], v[198:201], v[80:83]
	v_mfma_f32_16x16x32_bf16 v[68:71], v[214:217], v[206:209], v[68:71]
	v_mfma_f32_16x16x32_bf16 v[64:67], v[222:225], v[206:209], v[64:67]
	v_mfma_f32_16x16x32_bf16 v[116:119], v[218:221], v[178:181], v[116:119]
	v_mfma_f32_16x16x32_bf16 v[112:115], v[226:229], v[178:181], v[112:115]
	v_mfma_f32_16x16x32_bf16 v[100:103], v[218:221], v[194:197], v[100:103]
	v_mfma_f32_16x16x32_bf16 v[96:99], v[226:229], v[194:197], v[96:99]
	v_mfma_f32_16x16x32_bf16 v[84:87], v[218:221], v[202:205], v[84:87]
	v_mfma_f32_16x16x32_bf16 v[80:83], v[226:229], v[202:205], v[80:83]
	v_mfma_f32_16x16x32_bf16 v[68:71], v[218:221], v[210:213], v[68:71]
	v_mfma_f32_16x16x32_bf16 v[64:67], v[226:229], v[210:213], v[64:67]
	s_setprio 0
	s_mov_b32 m0, s59
	s_barrier
	ds_read_b128 v[174:177], v165 offset:16384
	ds_read_b128 v[178:181], v165 offset:17408
	ds_read_b128 v[188:191], v165 offset:18432
	ds_read_b128 v[194:197], v165 offset:19456
	ds_read_b128 v[198:201], v165 offset:20480
	ds_read_b128 v[202:205], v165 offset:21504
	ds_read_b128 v[206:209], v165 offset:22528
	global_load_lds_dwordx4 v128, s[12:13]
	s_mov_b32 m0, s75
	ds_read_b128 v[210:213], v165 offset:23552
	global_load_lds_dwordx4 v132, s[12:13]
	s_barrier
	s_waitcnt lgkmcnt(0)
	s_setprio 1
	v_mfma_f32_16x16x32_bf16 v[60:63], v[146:149], v[174:177], v[60:63]
	v_mfma_f32_16x16x32_bf16 v[56:59], v[154:157], v[174:177], v[56:59]
	v_mfma_f32_16x16x32_bf16 v[44:47], v[146:149], v[188:191], v[44:47]
	v_mfma_f32_16x16x32_bf16 v[40:43], v[154:157], v[188:191], v[40:43]
	v_mfma_f32_16x16x32_bf16 v[28:31], v[146:149], v[198:201], v[28:31]
	v_mfma_f32_16x16x32_bf16 v[24:27], v[154:157], v[198:201], v[24:27]
	v_mfma_f32_16x16x32_bf16 v[12:15], v[146:149], v[206:209], v[12:15]
	v_mfma_f32_16x16x32_bf16 v[8:11], v[154:157], v[206:209], v[8:11]
	v_mfma_f32_16x16x32_bf16 v[60:63], v[150:153], v[178:181], v[60:63]
	v_mfma_f32_16x16x32_bf16 v[56:59], v[170:173], v[178:181], v[56:59]
	v_mfma_f32_16x16x32_bf16 v[44:47], v[150:153], v[194:197], v[44:47]
	v_mfma_f32_16x16x32_bf16 v[40:43], v[170:173], v[194:197], v[40:43]
	v_mfma_f32_16x16x32_bf16 v[28:31], v[150:153], v[202:205], v[28:31]
	v_mfma_f32_16x16x32_bf16 v[24:27], v[170:173], v[202:205], v[24:27]
	v_mfma_f32_16x16x32_bf16 v[12:15], v[150:153], v[210:213], v[12:15]
	v_mfma_f32_16x16x32_bf16 v[8:11], v[170:173], v[210:213], v[8:11]
	s_setprio 0
	s_barrier
	s_add_i32 s4, s87, s74
	s_mov_b32 m0, s4
	s_add_u32 s0, s10, 0x80000
	s_addc_u32 s1, s11, 0
	global_load_lds_dwordx4 v130, s[0:1]
	s_add_i32 m0, s4, 0x2000
	s_nop 0
	global_load_lds_dwordx4 v134, s[0:1]
	s_waitcnt vmcnt(6)
	s_barrier
	s_setprio 1
	v_mfma_f32_16x16x32_bf16 v[52:55], v[214:217], v[174:177], v[52:55]
	v_mfma_f32_16x16x32_bf16 v[48:51], v[222:225], v[174:177], v[48:51]
	v_mfma_f32_16x16x32_bf16 v[36:39], v[214:217], v[188:191], v[36:39]
	v_mfma_f32_16x16x32_bf16 v[32:35], v[222:225], v[188:191], v[32:35]
	v_mfma_f32_16x16x32_bf16 v[20:23], v[214:217], v[198:201], v[20:23]
	v_mfma_f32_16x16x32_bf16 v[16:19], v[222:225], v[198:201], v[16:19]
	v_mfma_f32_16x16x32_bf16 v[4:7], v[214:217], v[206:209], v[4:7]
	v_mfma_f32_16x16x32_bf16 v[0:3], v[222:225], v[206:209], v[0:3]
	v_mfma_f32_16x16x32_bf16 v[52:55], v[218:221], v[178:181], v[52:55]
	v_mfma_f32_16x16x32_bf16 v[48:51], v[226:229], v[178:181], v[48:51]
	v_mfma_f32_16x16x32_bf16 v[36:39], v[218:221], v[194:197], v[36:39]
	v_mfma_f32_16x16x32_bf16 v[32:35], v[226:229], v[194:197], v[32:35]
	v_mfma_f32_16x16x32_bf16 v[20:23], v[218:221], v[202:205], v[20:23]
	v_mfma_f32_16x16x32_bf16 v[16:19], v[226:229], v[202:205], v[16:19]
	v_mfma_f32_16x16x32_bf16 v[4:7], v[218:221], v[210:213], v[4:7]
	v_mfma_f32_16x16x32_bf16 v[0:3], v[226:229], v[210:213], v[0:3]
	s_setprio 0
	s_add_i32 s4, 0, 0x18000
	s_barrier
	ds_read_b128 v[146:149], v158
	ds_read_b128 v[150:153], v158 offset:1024
	ds_read_b128 v[154:157], v158 offset:2048
	ds_read_b128 v[170:173], v158 offset:3072
	s_add_u32 s0, s12, 0x80000
	s_addc_u32 s1, s13, 0
	s_mov_b32 m0, s76
	ds_read_b128 v[174:177], v165 offset:32768
	ds_read_b128 v[178:181], v165 offset:33792
	ds_read_b128 v[188:191], v165 offset:34816
	ds_read_b128 v[194:197], v165 offset:35840
	ds_read_b128 v[198:201], v165 offset:36864
	ds_read_b128 v[202:205], v165 offset:37888
	ds_read_b128 v[206:209], v165 offset:38912
	global_load_lds_dwordx4 v128, s[0:1]
	s_mov_b32 m0, s77
	ds_read_b128 v[210:213], v165 offset:39936
	global_load_lds_dwordx4 v132, s[0:1]
	s_waitcnt lgkmcnt(8)
	s_barrier
; #define PG8_STAGE(bufoff, gbase, voff) do { _Pragma("unroll") for (int _i = 0; _i < 2; ++_i) \
;         __builtin_amdgcn_global_load_lds((const unsigned*)((const char*)(gbase) + (voff)[_i]), (LAS unsigned*)(lds + (bufoff) + ldsw + _i * 8192), 16, 0, 0); } while (0)
; #define PG8_LDA(dst, b, h) do { _Pragma("unroll") for (int m = 0; m < 4; ++m) _Pragma("unroll") for (int k = 0; k < 2; ++k) dst[m][k] = *(const LAS bf16x8*)(lds + PG8_SA(b, h) + aoff + m * 2048 + k * 1024); } while (0)
; #define PG8_LDB(dst, b, h) do { _Pragma("unroll") for (int n = 0; n < 2; ++n) _Pragma("unroll") for (int k = 0; k < 2; ++k) dst[n][k] = *(const LAS bf16x8*)(lds + PG8_SB(b, h) + boff + n * 2048 + k * 1024); } while (0)
; #define PG8_WAIT_V(n) asm volatile("s_waitcnt vmcnt(" #n ")" ::: "memory")
; #define PG8_WAIT_L(n) asm volatile("s_waitcnt lgkmcnt(" #n ")" ::: "memory")
; #define PG8_BAR __builtin_amdgcn_s_barrier()
; #define PG8_SCHED __builtin_amdgcn_sched_barrier(0)
; template <class Epi, class Sched>
; DI void gemm_phase(LAS unsigned char* lds, const Gemm g, const Sched& S, const Epi& E) {
;     ...
;             PG8_LDB(B0, 0, 0); PG8_SCHED; PG8_LDA(At, 0, 0); PG8_STAGE(PG8_SA(1, 1), a1 + hstep, voffA);
;             PG8_WAIT_L(8); PG8_BAR; PG8_WAIT_L(0); PG8_MMA(0, 0, At, B0); PG8_BAR; PG8_SCHED;
;             PG8_LDB(B1, 0, 1); PG8_STAGE(PG8_SB(0, 0), b2, voffB);
;             PG8_BAR; PG8_WAIT_L(0); PG8_MMA(0, 1, At, B1); PG8_BAR;
;             PG8_LDA(At, 0, 1); PG8_STAGE(PG8_SA(0, 0), a2, voffA);
;             PG8_BAR; PG8_WAIT_L(0); PG8_MMA(1, 0, At, B0); PG8_BAR; PG8_SCHED;
;             PG8_STAGE(PG8_SB(0, 1), b2 + hstep, voffB);
;             PG8_WAIT_V(6); PG8_BAR; PG8_MMA(1, 1, At, B1); PG8_BAR;
;             PG8_LDB(B0, 1, 0); PG8_SCHED; PG8_LDA(At, 1, 0); PG8_STAGE(PG8_SA(0, 1), a2 + hstep, voffA);
;             PG8_WAIT_L(8); PG8_BAR; PG8_WAIT_L(0); PG8_MMA(0, 0, At, B0); PG8_BAR; PG8_SCHED;
;             PG8_LDB(B1, 1, 1); PG8_STAGE(PG8_SB(1, 0), b3, voffB);
;             PG8_BAR; PG8_WAIT_L(0); PG8_MMA(0, 1, At, B1); PG8_BAR;
;             PG8_LDA(At, 1, 1); PG8_STAGE(PG8_SA(1, 0), a3, voffA);
;             PG8_BAR; PG8_WAIT_L(0); PG8_MMA(1, 0, At, B0); PG8_BAR; PG8_SCHED;
;             PG8_STAGE(PG8_SB(1, 1), b3 + hstep, voffB);
;             PG8_WAIT_V(6); PG8_BAR; PG8_MMA(1, 1, At, B1); PG8_BAR;
	s_waitcnt lgkmcnt(0)
	s_setprio 1
	v_mfma_f32_16x16x32_bf16 v[124:127], v[146:149], v[174:177], v[124:127]
	v_mfma_f32_16x16x32_bf16 v[120:123], v[154:157], v[174:177], v[120:123]
	v_mfma_f32_16x16x32_bf16 v[108:111], v[146:149], v[188:191], v[108:111]
	v_mfma_f32_16x16x32_bf16 v[104:107], v[154:157], v[188:191], v[104:107]
	v_mfma_f32_16x16x32_bf16 v[92:95], v[146:149], v[198:201], v[92:95]
	v_mfma_f32_16x16x32_bf16 v[88:91], v[154:157], v[198:201], v[88:91]
	v_mfma_f32_16x16x32_bf16 v[76:79], v[146:149], v[206:209], v[76:79]
	v_mfma_f32_16x16x32_bf16 v[72:75], v[154:157], v[206:209], v[72:75]
	v_mfma_f32_16x16x32_bf16 v[124:127], v[150:153], v[178:181], v[124:127]
	v_mfma_f32_16x16x32_bf16 v[120:123], v[170:173], v[178:181], v[120:123]
	v_mfma_f32_16x16x32_bf16 v[108:111], v[150:153], v[194:197], v[108:111]
	v_mfma_f32_16x16x32_bf16 v[104:107], v[170:173], v[194:197], v[104:107]
	v_mfma_f32_16x16x32_bf16 v[92:95], v[150:153], v[202:205], v[92:95]
	v_mfma_f32_16x16x32_bf16 v[88:91], v[170:173], v[202:205], v[88:91]
	v_mfma_f32_16x16x32_bf16 v[76:79], v[150:153], v[210:213], v[76:79]
	v_mfma_f32_16x16x32_bf16 v[72:75], v[170:173], v[210:213], v[72:75]
	s_setprio 0
	s_barrier
	s_add_i32 s5, 0, 0x1c000
	s_add_i32 s0, s4, s74
	s_add_i32 m0, s0, 0xffffff80
	ds_read_b128 v[214:217], v159
	ds_read_b128 v[218:221], v159 offset:1024
	ds_read_b128 v[222:225], v159 offset:2048
	global_load_lds_dwordx4 v130, s[10:11] offset:128
	s_add_i32 m0, s0, 0x1f80
	ds_read_b128 v[226:229], v159 offset:3072
	global_load_lds_dwordx4 v134, s[10:11] offset:128
	s_barrier
	s_waitcnt lgkmcnt(0)
	s_setprio 1
	v_mfma_f32_16x16x32_bf16 v[116:119], v[214:217], v[174:177], v[116:119]
	v_mfma_f32_16x16x32_bf16 v[112:115], v[222:225], v[174:177], v[112:115]
	v_mfma_f32_16x16x32_bf16 v[100:103], v[214:217], v[188:191], v[100:103]
	v_mfma_f32_16x16x32_bf16 v[96:99], v[222:225], v[188:191], v[96:99]
	v_mfma_f32_16x16x32_bf16 v[84:87], v[214:217], v[198:201], v[84:87]
	v_mfma_f32_16x16x32_bf16 v[80:83], v[222:225], v[198:201], v[80:83]
	v_mfma_f32_16x16x32_bf16 v[68:71], v[214:217], v[206:209], v[68:71]
	v_mfma_f32_16x16x32_bf16 v[64:67], v[222:225], v[206:209], v[64:67]
	v_mfma_f32_16x16x32_bf16 v[116:119], v[218:221], v[178:181], v[116:119]
	v_mfma_f32_16x16x32_bf16 v[112:115], v[226:229], v[178:181], v[112:115]
	v_mfma_f32_16x16x32_bf16 v[100:103], v[218:221], v[194:197], v[100:103]
	v_mfma_f32_16x16x32_bf16 v[96:99], v[226:229], v[194:197], v[96:99]
	v_mfma_f32_16x16x32_bf16 v[84:87], v[218:221], v[202:205], v[84:87]
	v_mfma_f32_16x16x32_bf16 v[80:83], v[226:229], v[202:205], v[80:83]
	v_mfma_f32_16x16x32_bf16 v[68:71], v[218:221], v[210:213], v[68:71]
	v_mfma_f32_16x16x32_bf16 v[64:67], v[226:229], v[210:213], v[64:67]
	s_setprio 0
	s_add_i32 m0, s97, 0xffffff80
	s_barrier
	ds_read_b128 v[174:177], v165 offset:49152
	ds_read_b128 v[178:181], v165 offset:50176
	ds_read_b128 v[188:191], v165 offset:51200
	ds_read_b128 v[194:197], v165 offset:52224
	ds_read_b128 v[198:201], v165 offset:53248
	ds_read_b128 v[202:205], v165 offset:54272
	ds_read_b128 v[206:209], v165 offset:55296
	global_load_lds_dwordx4 v128, s[12:13] offset:128
	s_add_i32 m0, s84, 0xffffff80
	ds_read_b128 v[210:213], v165 offset:56320
	global_load_lds_dwordx4 v132, s[12:13] offset:128
	s_barrier
	s_waitcnt lgkmcnt(0)
	s_setprio 1
	v_mfma_f32_16x16x32_bf16 v[60:63], v[146:149], v[174:177], v[60:63]
	v_mfma_f32_16x16x32_bf16 v[56:59], v[154:157], v[174:177], v[56:59]
	v_mfma_f32_16x16x32_bf16 v[44:47], v[146:149], v[188:191], v[44:47]
	v_mfma_f32_16x16x32_bf16 v[40:43], v[154:157], v[188:191], v[40:43]
	v_mfma_f32_16x16x32_bf16 v[28:31], v[146:149], v[198:201], v[28:31]
	v_mfma_f32_16x16x32_bf16 v[24:27], v[154:157], v[198:201], v[24:27]
	v_mfma_f32_16x16x32_bf16 v[12:15], v[146:149], v[206:209], v[12:15]
	v_mfma_f32_16x16x32_bf16 v[8:11], v[154:157], v[206:209], v[8:11]
	v_mfma_f32_16x16x32_bf16 v[60:63], v[150:153], v[178:181], v[60:63]
	v_mfma_f32_16x16x32_bf16 v[56:59], v[170:173], v[178:181], v[56:59]
	v_mfma_f32_16x16x32_bf16 v[44:47], v[150:153], v[194:197], v[44:47]
	v_mfma_f32_16x16x32_bf16 v[40:43], v[170:173], v[194:197], v[40:43]
	v_mfma_f32_16x16x32_bf16 v[28:31], v[150:153], v[202:205], v[28:31]
	v_mfma_f32_16x16x32_bf16 v[24:27], v[170:173], v[202:205], v[24:27]
	v_mfma_f32_16x16x32_bf16 v[12:15], v[150:153], v[210:213], v[12:15]
	v_mfma_f32_16x16x32_bf16 v[8:11], v[170:173], v[210:213], v[8:11]
	s_setprio 0
	s_barrier
	s_add_i32 s4, s5, s74
	s_mov_b32 m0, s4
	s_add_u32 s0, s10, 0x80080
	s_addc_u32 s1, s11, 0
	global_load_lds_dwordx4 v130, s[0:1]
	v_lshl_add_u64 v[146:147], s[0:1], 0, v[134:135]
	s_add_i32 m0, s4, 0x2000
	s_nop 0
	global_load_lds_dwordx4 v134, s[0:1]
	s_waitcnt vmcnt(6)
	s_barrier
	s_setprio 1
	v_mfma_f32_16x16x32_bf16 v[52:55], v[214:217], v[174:177], v[52:55]
	v_mfma_f32_16x16x32_bf16 v[48:51], v[222:225], v[174:177], v[48:51]
	v_mfma_f32_16x16x32_bf16 v[36:39], v[214:217], v[188:191], v[36:39]
	v_mfma_f32_16x16x32_bf16 v[32:35], v[222:225], v[188:191], v[32:35]
	v_mfma_f32_16x16x32_bf16 v[20:23], v[214:217], v[198:201], v[20:23]
	v_mfma_f32_16x16x32_bf16 v[16:19], v[222:225], v[198:201], v[16:19]
	v_mfma_f32_16x16x32_bf16 v[4:7], v[214:217], v[206:209], v[4:7]
	v_mfma_f32_16x16x32_bf16 v[0:3], v[222:225], v[206:209], v[0:3]
	v_mfma_f32_16x16x32_bf16 v[52:55], v[218:221], v[178:181], v[52:55]
	v_mfma_f32_16x16x32_bf16 v[48:51], v[226:229], v[178:181], v[48:51]
	v_mfma_f32_16x16x32_bf16 v[36:39], v[218:221], v[194:197], v[36:39]
	v_mfma_f32_16x16x32_bf16 v[32:35], v[226:229], v[194:197], v[32:35]
	v_mfma_f32_16x16x32_bf16 v[20:23], v[218:221], v[202:205], v[20:23]
	v_mfma_f32_16x16x32_bf16 v[16:19], v[226:229], v[202:205], v[16:19]
	v_mfma_f32_16x16x32_bf16 v[4:7], v[218:221], v[210:213], v[4:7]
	v_mfma_f32_16x16x32_bf16 v[0:3], v[226:229], v[210:213], v[0:3]
	s_setprio 0
	s_add_i32 s35, s35, 2
	s_add_u32 s8, s8, 0x100
	s_addc_u32 s9, s9, 0
	s_add_u32 s28, s28, 0x100
	s_addc_u32 s34, s34, 0
	s_cmp_gt_u32 s35, 29
	s_barrier
	s_cbranch_scc0 .LBB0_527

;     DI size_t aoff(const Unit& u, size_t tstep) const { return (size_t)u.pm * tstep; }
;     DI size_t boff(const Unit& u, size_t tstep) const { return (size_t)u.pn * tstep; }
;     DI size_t aoff(const Unit& u, size_t) const { return (size_t)u.ks * kbytes; }
; template <class Epi, class Sched>
; DI void gemm_phase(LAS unsigned char* lds, const Gemm g, const Sched& S, const Epi& E) {
;     ...
;         const bool has_next = S.next(ui + 1, nxt);
;         const char* nA = has_next ? (const char*)g.A + S.aoff(nxt, tstep) : cA; const char* nB = has_next ? (const char*)g.Bt + S.boff(nxt, tstep) : cB;
;         for (int t = 0; t < nt; t += 2) {
;             if constexpr (Epi::HAS_MID) { if (t == E.mid_t(nt)) { int fr3 = fr, fq3 = fq; asm volatile("" : "+v"(fr3), "+v"(fq3)); E.mid(acc, cur, wr, wc, fr3, fq3); } }
;             const bool last = (t == nt - 2);
;             const char* a1 = cA + (size_t)(t + 1) * kstep;
;             const char* a2 = last ? nA : cA + (size_t)(t + 2) * kstep; const char* b2 = last ? nB : cB + (size_t)(t + 2) * kstep;
;             const char* a3 = a2 + kstep; const char* b3 = b2 + kstep;
;             PG8_LDB(B0, 0, 0); PG8_SCHED; PG8_LDA(At, 0, 0); PG8_STAGE(PG8_SA(1, 1), a1 + hstep, voffA);
;             PG8_WAIT_L(8); PG8_BAR; PG8_WAIT_L(0); PG8_MMA(0, 0, At, B0); PG8_BAR; PG8_SCHED;
;             PG8_LDB(B1, 0, 1); PG8_STAGE(PG8_SB(0, 0), b2, voffB);
;             PG8_BAR; PG8_WAIT_L(0); PG8_MMA(0, 1, At, B1); PG8_BAR;
;             PG8_LDA(At, 0, 1); PG8_STAGE(PG8_SA(0, 0), a2, voffA);
;             PG8_BAR; PG8_WAIT_L(0); PG8_MMA(1, 0, At, B0); PG8_BAR; PG8_SCHED;
;             PG8_STAGE(PG8_SB(0, 1), b2 + hstep, voffB);
;             PG8_WAIT_V(6); PG8_BAR; PG8_MMA(1, 1, At, B1); PG8_BAR;
;             PG8_LDB(B0, 1, 0); PG8_SCHED; PG8_LDA(At, 1, 0); PG8_STAGE(PG8_SA(0, 1), a2 + hstep, voffA);
;             PG8_WAIT_L(8); PG8_BAR; PG8_WAIT_L(0); PG8_MMA(0, 0, At, B0); PG8_BAR; PG8_SCHED;
;             PG8_LDB(B1, 1, 1); PG8_STAGE(PG8_SB(1, 0), b3, voffB);
;             PG8_BAR; PG8_WAIT_L(0); PG8_MMA(0, 1, At, B1); PG8_BAR;
;             PG8_LDA(At, 1, 1); PG8_STAGE(PG8_SA(1, 0), a3, voffA);
;             PG8_BAR; PG8_WAIT_L(0); PG8_MMA(1, 0, At, B0); PG8_BAR; PG8_SCHED;
;             PG8_STAGE(PG8_SB(1, 1), b3 + hstep, voffB);
;             PG8_WAIT_V(6); PG8_BAR; PG8_MMA(1, 1, At, B1); PG8_BAR;
.LBB0_937:
	s_add_u32 s8, s38, 0x30080
	s_addc_u32 s9, s39, 0
	s_add_u32 s35, s36, 0x100
	v_mov_b32_e32 v0, 0
	s_addc_u32 s40, s37, 0
	s_mov_b32 s41, -2
	ds_read_b128 v[144:147], v165
	ds_read_b128 v[168:171], v165 offset:1024
	ds_read_b128 v[172:175], v165 offset:2048
	ds_read_b128 v[176:179], v165 offset:3072
	s_add_i32 m0, s51, 0xc000
	ds_read_b128 v[180:183], v166
	ds_read_b128 v[188:191], v166 offset:1024
	ds_read_b128 v[194:197], v166 offset:2048
	ds_read_b128 v[198:201], v166 offset:3072
	ds_read_b128 v[202:205], v166 offset:4096
	ds_read_b128 v[206:209], v166 offset:5120
	ds_read_b128 v[210:213], v166 offset:6144
	global_load_lds_dwordx4 v136, s[8:9]
	s_add_i32 m0, s51, 0xe000
	ds_read_b128 v[214:217], v166 offset:7168
	global_load_lds_dwordx4 v138, s[8:9]
	s_add_u32 s0, s8, 0xfffd0080
	s_addc_u32 s1, s9, -1
	s_cmp_eq_u32 s41, 8
	s_cselect_b32 s39, s31, s1
	s_cselect_b32 s38, s30, s0
	s_cselect_b32 s37, s11, s40
	s_cselect_b32 s36, s10, s35
	s_waitcnt lgkmcnt(8)
	s_barrier
	s_waitcnt lgkmcnt(0)
	s_setprio 1
	v_mfma_f32_16x16x32_bf16 v[124:127], v[144:147], v[180:183], 0
	v_mfma_f32_16x16x32_bf16 v[120:123], v[172:175], v[180:183], 0
	v_mfma_f32_16x16x32_bf16 v[108:111], v[144:147], v[194:197], 0
	v_mfma_f32_16x16x32_bf16 v[104:107], v[172:175], v[194:197], 0
	v_mfma_f32_16x16x32_bf16 v[92:95], v[144:147], v[202:205], 0
	v_mfma_f32_16x16x32_bf16 v[88:91], v[172:175], v[202:205], 0
	v_mfma_f32_16x16x32_bf16 v[76:79], v[144:147], v[210:213], 0
	v_mfma_f32_16x16x32_bf16 v[72:75], v[172:175], v[210:213], 0
	v_mfma_f32_16x16x32_bf16 v[124:127], v[168:171], v[188:191], v[124:127]
	v_mfma_f32_16x16x32_bf16 v[120:123], v[176:179], v[188:191], v[120:123]
	v_mfma_f32_16x16x32_bf16 v[108:111], v[168:171], v[198:201], v[108:111]
	v_mfma_f32_16x16x32_bf16 v[104:107], v[176:179], v[198:201], v[104:107]
	v_mfma_f32_16x16x32_bf16 v[92:95], v[168:171], v[206:209], v[92:95]
	v_mfma_f32_16x16x32_bf16 v[88:91], v[176:179], v[206:209], v[88:91]
	v_mfma_f32_16x16x32_bf16 v[76:79], v[168:171], v[214:217], v[76:79]
	v_mfma_f32_16x16x32_bf16 v[72:75], v[176:179], v[214:217], v[72:75]
	s_setprio 0
	s_barrier
	s_add_i32 s0, s61, s50
	s_mov_b32 m0, s0
	ds_read_b128 v[218:221], v167
	ds_read_b128 v[222:225], v167 offset:1024
	ds_read_b128 v[226:229], v167 offset:2048
	global_load_lds_dwordx4 v130, s[36:37]
	s_add_i32 m0, s0, 0x2000
	ds_read_b128 v[230:233], v167 offset:3072
	global_load_lds_dwordx4 v134, s[36:37]
	s_barrier
	s_waitcnt lgkmcnt(0)
	s_setprio 1
	v_mfma_f32_16x16x32_bf16 v[116:119], v[218:221], v[180:183], 0
	v_mfma_f32_16x16x32_bf16 v[112:115], v[226:229], v[180:183], 0
	v_mfma_f32_16x16x32_bf16 v[100:103], v[218:221], v[194:197], 0
	v_mfma_f32_16x16x32_bf16 v[96:99], v[226:229], v[194:197], 0
	v_mfma_f32_16x16x32_bf16 v[84:87], v[218:221], v[202:205], 0
	v_mfma_f32_16x16x32_bf16 v[80:83], v[226:229], v[202:205], 0
	v_mfma_f32_16x16x32_bf16 v[68:71], v[218:221], v[210:213], 0
	v_mfma_f32_16x16x32_bf16 v[64:67], v[226:229], v[210:213], 0
	v_mfma_f32_16x16x32_bf16 v[116:119], v[222:225], v[188:191], v[116:119]
	v_mfma_f32_16x16x32_bf16 v[112:115], v[230:233], v[188:191], v[112:115]
	v_mfma_f32_16x16x32_bf16 v[100:103], v[222:225], v[198:201], v[100:103]
	v_mfma_f32_16x16x32_bf16 v[96:99], v[230:233], v[198:201], v[96:99]
	v_mfma_f32_16x16x32_bf16 v[84:87], v[222:225], v[206:209], v[84:87]
	v_mfma_f32_16x16x32_bf16 v[80:83], v[230:233], v[206:209], v[80:83]
	v_mfma_f32_16x16x32_bf16 v[68:71], v[222:225], v[214:217], v[68:71]
	v_mfma_f32_16x16x32_bf16 v[64:67], v[230:233], v[214:217], v[64:67]
	s_setprio 0
	s_mov_b32 m0, s51
	s_barrier
	ds_read_b128 v[180:183], v166 offset:16384
	ds_read_b128 v[188:191], v166 offset:17408
	ds_read_b128 v[194:197], v166 offset:18432
	ds_read_b128 v[198:201], v166 offset:19456
	ds_read_b128 v[202:205], v166 offset:20480
	ds_read_b128 v[206:209], v166 offset:21504
	ds_read_b128 v[210:213], v166 offset:22528
	global_load_lds_dwordx4 v128, s[38:39]
	s_mov_b32 m0, s52
	ds_read_b128 v[214:217], v166 offset:23552
	global_load_lds_dwordx4 v132, s[38:39]
	s_barrier
	s_waitcnt lgkmcnt(0)
	s_setprio 1
	v_mfma_f32_16x16x32_bf16 v[60:63], v[144:147], v[180:183], 0
	v_mfma_f32_16x16x32_bf16 v[56:59], v[172:175], v[180:183], 0
	v_mfma_f32_16x16x32_bf16 v[44:47], v[144:147], v[194:197], 0
	v_mfma_f32_16x16x32_bf16 v[40:43], v[172:175], v[194:197], 0
	v_mfma_f32_16x16x32_bf16 v[28:31], v[144:147], v[202:205], 0
	v_mfma_f32_16x16x32_bf16 v[24:27], v[172:175], v[202:205], 0
	v_mfma_f32_16x16x32_bf16 v[12:15], v[144:147], v[210:213], 0
	v_mfma_f32_16x16x32_bf16 v[8:11], v[172:175], v[210:213], 0
	v_mfma_f32_16x16x32_bf16 v[60:63], v[168:171], v[188:191], v[60:63]
	v_mfma_f32_16x16x32_bf16 v[56:59], v[176:179], v[188:191], v[56:59]
	v_mfma_f32_16x16x32_bf16 v[44:47], v[168:171], v[198:201], v[44:47]
	v_mfma_f32_16x16x32_bf16 v[40:43], v[176:179], v[198:201], v[40:43]
	v_mfma_f32_16x16x32_bf16 v[28:31], v[168:171], v[206:209], v[28:31]
	v_mfma_f32_16x16x32_bf16 v[24:27], v[176:179], v[206:209], v[24:27]
	v_mfma_f32_16x16x32_bf16 v[12:15], v[168:171], v[214:217], v[12:15]
	v_mfma_f32_16x16x32_bf16 v[8:11], v[176:179], v[214:217], v[8:11]
	s_setprio 0
	s_barrier
	s_add_i32 s4, s62, s50
	s_mov_b32 m0, s4
	s_add_u32 s0, s36, 0x30000
	s_addc_u32 s1, s37, 0
	global_load_lds_dwordx4 v130, s[0:1]
	s_add_i32 m0, s4, 0x2000
	s_nop 0
	global_load_lds_dwordx4 v134, s[0:1]
	s_waitcnt vmcnt(6)
	s_barrier
; #define PG8_STAGE(bufoff, gbase, voff) do { _Pragma("unroll") for (int _i = 0; _i < 2; ++_i) \
;         __builtin_amdgcn_global_load_lds((const unsigned*)((const char*)(gbase) + (voff)[_i]), (LAS unsigned*)(lds + (bufoff) + ldsw + _i * 8192), 16, 0, 0); } while (0)
; #define PG8_LDA(dst, b, h) do { _Pragma("unroll") for (int m = 0; m < 4; ++m) _Pragma("unroll") for (int k = 0; k < 2; ++k) dst[m][k] = *(const LAS bf16x8*)(lds + PG8_SA(b, h) + aoff + m * 2048 + k * 1024); } while (0)
; #define PG8_LDB(dst, b, h) do { _Pragma("unroll") for (int n = 0; n < 2; ++n) _Pragma("unroll") for (int k = 0; k < 2; ++k) dst[n][k] = *(const LAS bf16x8*)(lds + PG8_SB(b, h) + boff + n * 2048 + k * 1024); } while (0)
; #define PG8_WAIT_V(n) asm volatile("s_waitcnt vmcnt(" #n ")" ::: "memory")
; #define PG8_WAIT_L(n) asm volatile("s_waitcnt lgkmcnt(" #n ")" ::: "memory")
; #define PG8_BAR __builtin_amdgcn_s_barrier()
; #define PG8_SCHED __builtin_amdgcn_sched_barrier(0)
; template <class Epi, class Sched>
; DI void gemm_phase(LAS unsigned char* lds, const Gemm g, const Sched& S, const Epi& E) {
;     ...
;             PG8_LDB(B0, 0, 0); PG8_SCHED; PG8_LDA(At, 0, 0); PG8_STAGE(PG8_SA(1, 1), a1 + hstep, voffA);
;             PG8_WAIT_L(8); PG8_BAR; PG8_WAIT_L(0); PG8_MMA(0, 0, At, B0); PG8_BAR; PG8_SCHED;
;             PG8_LDB(B1, 0, 1); PG8_STAGE(PG8_SB(0, 0), b2, voffB);
;             PG8_BAR; PG8_WAIT_L(0); PG8_MMA(0, 1, At, B1); PG8_BAR;
;             PG8_LDA(At, 0, 1); PG8_STAGE(PG8_SA(0, 0), a2, voffA);
;             PG8_BAR; PG8_WAIT_L(0); PG8_MMA(1, 0, At, B0); PG8_BAR; PG8_SCHED;
;             PG8_STAGE(PG8_SB(0, 1), b2 + hstep, voffB);
;             PG8_WAIT_V(6); PG8_BAR; PG8_MMA(1, 1, At, B1); PG8_BAR;
;             PG8_LDB(B0, 1, 0); PG8_SCHED; PG8_LDA(At, 1, 0); PG8_STAGE(PG8_SA(0, 1), a2 + hstep, voffA);
;             PG8_WAIT_L(8); PG8_BAR; PG8_WAIT_L(0); PG8_MMA(0, 0, At, B0); PG8_BAR; PG8_SCHED;
;             PG8_LDB(B1, 1, 1); PG8_STAGE(PG8_SB(1, 0), b3, voffB);
;             PG8_BAR; PG8_WAIT_L(0); PG8_MMA(0, 1, At, B1); PG8_BAR;
;             PG8_LDA(At, 1, 1); PG8_STAGE(PG8_SA(1, 0), a3, voffA);
;             PG8_BAR; PG8_WAIT_L(0); PG8_MMA(1, 0, At, B0); PG8_BAR; PG8_SCHED;
;             PG8_STAGE(PG8_SB(1, 1), b3 + hstep, voffB);
;             PG8_WAIT_V(6); PG8_BAR; PG8_MMA(1, 1, At, B1); PG8_BAR;
	s_setprio 1
	v_mfma_f32_16x16x32_bf16 v[52:55], v[218:221], v[180:183], 0
	v_mfma_f32_16x16x32_bf16 v[48:51], v[226:229], v[180:183], 0
	v_mfma_f32_16x16x32_bf16 v[36:39], v[218:221], v[194:197], 0
	v_mfma_f32_16x16x32_bf16 v[32:35], v[226:229], v[194:197], 0
	v_mfma_f32_16x16x32_bf16 v[20:23], v[218:221], v[202:205], 0
	v_mfma_f32_16x16x32_bf16 v[16:19], v[226:229], v[202:205], 0
	v_mfma_f32_16x16x32_bf16 v[4:7], v[218:221], v[210:213], 0
	v_mfma_f32_16x16x32_bf16 v[0:3], v[226:229], v[210:213], 0
	v_mfma_f32_16x16x32_bf16 v[52:55], v[222:225], v[188:191], v[52:55]
	v_mfma_f32_16x16x32_bf16 v[48:51], v[230:233], v[188:191], v[48:51]
	v_mfma_f32_16x16x32_bf16 v[36:39], v[222:225], v[198:201], v[36:39]
	v_mfma_f32_16x16x32_bf16 v[32:35], v[230:233], v[198:201], v[32:35]
	v_mfma_f32_16x16x32_bf16 v[20:23], v[222:225], v[206:209], v[20:23]
	v_mfma_f32_16x16x32_bf16 v[16:19], v[230:233], v[206:209], v[16:19]
	v_mfma_f32_16x16x32_bf16 v[4:7], v[222:225], v[214:217], v[4:7]
	v_mfma_f32_16x16x32_bf16 v[0:3], v[230:233], v[214:217], v[0:3]
	s_setprio 0
	s_add_i32 s4, 0, 0x18000
	v_add_u32_e32 v148, s4, v164
	s_barrier
	ds_read_b128 v[144:147], v148
	ds_read_b128 v[168:171], v148 offset:1024
	ds_read_b128 v[172:175], v148 offset:2048
	ds_read_b128 v[176:179], v148 offset:3072
	s_add_u32 s0, s38, 0x30000
	s_addc_u32 s1, s39, 0
	s_mov_b32 m0, s53
	ds_read_b128 v[180:183], v166 offset:32768
	ds_read_b128 v[188:191], v166 offset:33792
	ds_read_b128 v[194:197], v166 offset:34816
	ds_read_b128 v[198:201], v166 offset:35840
	ds_read_b128 v[202:205], v166 offset:36864
	ds_read_b128 v[206:209], v166 offset:37888
	ds_read_b128 v[210:213], v166 offset:38912
	global_load_lds_dwordx4 v128, s[0:1]
	s_mov_b32 m0, s54
	ds_read_b128 v[214:217], v166 offset:39936
	global_load_lds_dwordx4 v132, s[0:1]
	s_waitcnt lgkmcnt(8)
	s_barrier
	s_waitcnt lgkmcnt(0)
	s_setprio 1
	v_mfma_f32_16x16x32_bf16 v[124:127], v[144:147], v[180:183], v[124:127]
	v_mfma_f32_16x16x32_bf16 v[120:123], v[172:175], v[180:183], v[120:123]
	v_mfma_f32_16x16x32_bf16 v[108:111], v[144:147], v[194:197], v[108:111]
	v_mfma_f32_16x16x32_bf16 v[104:107], v[172:175], v[194:197], v[104:107]
	v_mfma_f32_16x16x32_bf16 v[92:95], v[144:147], v[202:205], v[92:95]
	v_mfma_f32_16x16x32_bf16 v[88:91], v[172:175], v[202:205], v[88:91]
	v_mfma_f32_16x16x32_bf16 v[76:79], v[144:147], v[210:213], v[76:79]
	v_mfma_f32_16x16x32_bf16 v[72:75], v[172:175], v[210:213], v[72:75]
	v_mfma_f32_16x16x32_bf16 v[124:127], v[168:171], v[188:191], v[124:127]
	v_mfma_f32_16x16x32_bf16 v[120:123], v[176:179], v[188:191], v[120:123]
	v_mfma_f32_16x16x32_bf16 v[108:111], v[168:171], v[198:201], v[108:111]
	v_mfma_f32_16x16x32_bf16 v[104:107], v[176:179], v[198:201], v[104:107]
	v_mfma_f32_16x16x32_bf16 v[92:95], v[168:171], v[206:209], v[92:95]
	v_mfma_f32_16x16x32_bf16 v[88:91], v[176:179], v[206:209], v[88:91]
	v_mfma_f32_16x16x32_bf16 v[76:79], v[168:171], v[214:217], v[76:79]
	v_mfma_f32_16x16x32_bf16 v[72:75], v[176:179], v[214:217], v[72:75]
	s_setprio 0
	s_barrier
	s_add_i32 s5, 0, 0x1c000
	s_add_i32 s0, s4, s50
	v_add_u32_e32 v149, s5, v164
	s_add_i32 m0, s0, 0xffffff80
	ds_read_b128 v[218:221], v149
	ds_read_b128 v[222:225], v149 offset:1024
	ds_read_b128 v[226:229], v149 offset:2048
	global_load_lds_dwordx4 v130, s[36:37] offset:128
	s_add_i32 m0, s0, 0x1f80
	ds_read_b128 v[230:233], v149 offset:3072
	global_load_lds_dwordx4 v134, s[36:37] offset:128
	s_barrier
	s_waitcnt lgkmcnt(0)
	s_setprio 1
	v_mfma_f32_16x16x32_bf16 v[116:119], v[218:221], v[180:183], v[116:119]
	v_mfma_f32_16x16x32_bf16 v[112:115], v[226:229], v[180:183], v[112:115]
	v_mfma_f32_16x16x32_bf16 v[100:103], v[218:221], v[194:197], v[100:103]
	v_mfma_f32_16x16x32_bf16 v[96:99], v[226:229], v[194:197], v[96:99]
	v_mfma_f32_16x16x32_bf16 v[84:87], v[218:221], v[202:205], v[84:87]
	v_mfma_f32_16x16x32_bf16 v[80:83], v[226:229], v[202:205], v[80:83]
	v_mfma_f32_16x16x32_bf16 v[68:71], v[218:221], v[210:213], v[68:71]
	v_mfma_f32_16x16x32_bf16 v[64:67], v[226:229], v[210:213], v[64:67]
	v_mfma_f32_16x16x32_bf16 v[116:119], v[222:225], v[188:191], v[116:119]
	v_mfma_f32_16x16x32_bf16 v[112:115], v[230:233], v[188:191], v[112:115]
	v_mfma_f32_16x16x32_bf16 v[100:103], v[222:225], v[198:201], v[100:103]
	v_mfma_f32_16x16x32_bf16 v[96:99], v[230:233], v[198:201], v[96:99]
	v_mfma_f32_16x16x32_bf16 v[84:87], v[222:225], v[206:209], v[84:87]
	v_mfma_f32_16x16x32_bf16 v[80:83], v[230:233], v[206:209], v[80:83]
	v_mfma_f32_16x16x32_bf16 v[68:71], v[222:225], v[214:217], v[68:71]
	v_mfma_f32_16x16x32_bf16 v[64:67], v[230:233], v[214:217], v[64:67]
	s_setprio 0
	s_add_i32 m0, s57, 0xffffff80
	s_barrier
	ds_read_b128 v[180:183], v166 offset:49152
	ds_read_b128 v[188:191], v166 offset:50176
	ds_read_b128 v[194:197], v166 offset:51200
	ds_read_b128 v[198:201], v166 offset:52224
	ds_read_b128 v[202:205], v166 offset:53248
	ds_read_b128 v[206:209], v166 offset:54272
	ds_read_b128 v[210:213], v166 offset:55296
	global_load_lds_dwordx4 v128, s[38:39] offset:128
	s_add_i32 m0, s58, 0xffffff80
	ds_read_b128 v[214:217], v166 offset:56320
	global_load_lds_dwordx4 v132, s[38:39] offset:128
	s_barrier
; #define PG8_STAGE(bufoff, gbase, voff) do { _Pragma("unroll") for (int _i = 0; _i < 2; ++_i) \
;         __builtin_amdgcn_global_load_lds((const unsigned*)((const char*)(gbase) + (voff)[_i]), (LAS unsigned*)(lds + (bufoff) + ldsw + _i * 8192), 16, 0, 0); } while (0)
; #define PG8_LDA(dst, b, h) do { _Pragma("unroll") for (int m = 0; m < 4; ++m) _Pragma("unroll") for (int k = 0; k < 2; ++k) dst[m][k] = *(const LAS bf16x8*)(lds + PG8_SA(b, h) + aoff + m * 2048 + k * 1024); } while (0)
; template <class Epi, class Sched>
; DI void gemm_phase(LAS unsigned char* lds, const Gemm g, const Sched& S, const Epi& E) {
;     ...
;         for (int t = 0; t < nt; t += 2) {
;             if constexpr (Epi::HAS_MID) { if (t == E.mid_t(nt)) { int fr3 = fr, fq3 = fq; asm volatile("" : "+v"(fr3), "+v"(fq3)); E.mid(acc, cur, wr, wc, fr3, fq3); } }
;             const bool last = (t == nt - 2);
;             const char* a1 = cA + (size_t)(t + 1) * kstep;
;             const char* a2 = last ? nA : cA + (size_t)(t + 2) * kstep; const char* b2 = last ? nB : cB + (size_t)(t + 2) * kstep;
;             const char* a3 = a2 + kstep; const char* b3 = b2 + kstep;
;             PG8_LDB(B0, 0, 0); PG8_SCHED; PG8_LDA(At, 0, 0); PG8_STAGE(PG8_SA(1, 1), a1 + hstep, voffA);
;             PG8_WAIT_L(8); PG8_BAR; PG8_WAIT_L(0); PG8_MMA(0, 0, At, B0); PG8_BAR; PG8_SCHED;
;             PG8_LDB(B1, 0, 1); PG8_STAGE(PG8_SB(0, 0), b2, voffB);
;             PG8_BAR; PG8_WAIT_L(0); PG8_MMA(0, 1, At, B1); PG8_BAR;
;             PG8_LDA(At, 0, 1); PG8_STAGE(PG8_SA(0, 0), a2, voffA);
;             PG8_BAR; PG8_WAIT_L(0); PG8_MMA(1, 0, At, B0); PG8_BAR; PG8_SCHED;
;             PG8_STAGE(PG8_SB(0, 1), b2 + hstep, voffB);
;             PG8_WAIT_V(6); PG8_BAR; PG8_MMA(1, 1, At, B1); PG8_BAR;
;             PG8_LDB(B0, 1, 0); PG8_SCHED; PG8_LDA(At, 1, 0); PG8_STAGE(PG8_SA(0, 1), a2 + hstep, voffA);
;             PG8_WAIT_L(8); PG8_BAR; PG8_WAIT_L(0); PG8_MMA(0, 0, At, B0); PG8_BAR; PG8_SCHED;
;             PG8_LDB(B1, 1, 1); PG8_STAGE(PG8_SB(1, 0), b3, voffB);
;             PG8_BAR; PG8_WAIT_L(0); PG8_MMA(0, 1, At, B1); PG8_BAR;
;             PG8_LDA(At, 1, 1); PG8_STAGE(PG8_SA(1, 0), a3, voffA);
;             PG8_BAR; PG8_WAIT_L(0); PG8_MMA(1, 0, At, B0); PG8_BAR; PG8_SCHED;
;             PG8_STAGE(PG8_SB(1, 1), b3 + hstep, voffB);
;             PG8_WAIT_V(6); PG8_BAR; PG8_MMA(1, 1, At, B1); PG8_BAR;
	s_waitcnt lgkmcnt(0)
	s_setprio 1
	v_mfma_f32_16x16x32_bf16 v[60:63], v[144:147], v[180:183], v[60:63]
	v_mfma_f32_16x16x32_bf16 v[56:59], v[172:175], v[180:183], v[56:59]
	v_mfma_f32_16x16x32_bf16 v[44:47], v[144:147], v[194:197], v[44:47]
	v_mfma_f32_16x16x32_bf16 v[40:43], v[172:175], v[194:197], v[40:43]
	v_mfma_f32_16x16x32_bf16 v[28:31], v[144:147], v[202:205], v[28:31]
	v_mfma_f32_16x16x32_bf16 v[24:27], v[172:175], v[202:205], v[24:27]
	v_mfma_f32_16x16x32_bf16 v[12:15], v[144:147], v[210:213], v[12:15]
	v_mfma_f32_16x16x32_bf16 v[8:11], v[172:175], v[210:213], v[8:11]
	v_mfma_f32_16x16x32_bf16 v[60:63], v[168:171], v[188:191], v[60:63]
	v_mfma_f32_16x16x32_bf16 v[56:59], v[176:179], v[188:191], v[56:59]
	v_mfma_f32_16x16x32_bf16 v[44:47], v[168:171], v[198:201], v[44:47]
	v_mfma_f32_16x16x32_bf16 v[40:43], v[176:179], v[198:201], v[40:43]
	v_mfma_f32_16x16x32_bf16 v[28:31], v[168:171], v[206:209], v[28:31]
	v_mfma_f32_16x16x32_bf16 v[24:27], v[176:179], v[206:209], v[24:27]
	v_mfma_f32_16x16x32_bf16 v[12:15], v[168:171], v[214:217], v[12:15]
	v_mfma_f32_16x16x32_bf16 v[8:11], v[176:179], v[214:217], v[8:11]
	s_setprio 0
	s_barrier
	s_add_i32 s4, s5, s50
	s_mov_b32 m0, s4
	s_add_u32 s0, s36, 0x30080
	s_addc_u32 s1, s37, 0
	global_load_lds_dwordx4 v130, s[0:1]
	s_add_i32 m0, s4, 0x2000
	s_nop 0
	global_load_lds_dwordx4 v134, s[0:1]
	s_waitcnt vmcnt(6)
	s_barrier
	s_setprio 1
	v_mfma_f32_16x16x32_bf16 v[52:55], v[218:221], v[180:183], v[52:55]
	v_mfma_f32_16x16x32_bf16 v[48:51], v[226:229], v[180:183], v[48:51]
	v_mfma_f32_16x16x32_bf16 v[36:39], v[218:221], v[194:197], v[36:39]
	v_mfma_f32_16x16x32_bf16 v[32:35], v[226:229], v[194:197], v[32:35]
	v_mfma_f32_16x16x32_bf16 v[20:23], v[218:221], v[202:205], v[20:23]
	v_mfma_f32_16x16x32_bf16 v[16:19], v[226:229], v[202:205], v[16:19]
	v_mfma_f32_16x16x32_bf16 v[4:7], v[218:221], v[210:213], v[4:7]
	v_mfma_f32_16x16x32_bf16 v[0:3], v[226:229], v[210:213], v[0:3]
	v_mfma_f32_16x16x32_bf16 v[52:55], v[222:225], v[188:191], v[52:55]
	v_mfma_f32_16x16x32_bf16 v[48:51], v[230:233], v[188:191], v[48:51]
	v_mfma_f32_16x16x32_bf16 v[36:39], v[222:225], v[198:201], v[36:39]
	v_mfma_f32_16x16x32_bf16 v[32:35], v[230:233], v[198:201], v[32:35]
	v_mfma_f32_16x16x32_bf16 v[20:23], v[222:225], v[206:209], v[20:23]
	v_mfma_f32_16x16x32_bf16 v[16:19], v[230:233], v[206:209], v[16:19]
	v_mfma_f32_16x16x32_bf16 v[4:7], v[222:225], v[214:217], v[4:7]
	v_mfma_f32_16x16x32_bf16 v[0:3], v[230:233], v[214:217], v[0:3]
	s_setprio 0
	s_add_i32 s41, s41, 2
	s_add_u32 s8, s8, 0x100
	s_addc_u32 s9, s9, 0
	s_add_u32 s35, s35, 0x100
	s_addc_u32 s40, s40, 0
	s_cmp_gt_u32 s41, 9
	s_barrier
	s_cbranch_scc0 .LBB0_938
	s_branch .Lpeel_done_938
.LBB0_938:
	ds_read_b128 v[144:147], v165
	ds_read_b128 v[168:171], v165 offset:1024
	ds_read_b128 v[172:175], v165 offset:2048
	ds_read_b128 v[176:179], v165 offset:3072
	s_add_i32 m0, s51, 0xc000
	ds_read_b128 v[180:183], v166
	ds_read_b128 v[188:191], v166 offset:1024
	ds_read_b128 v[194:197], v166 offset:2048
	ds_read_b128 v[198:201], v166 offset:3072
	ds_read_b128 v[202:205], v166 offset:4096
	ds_read_b128 v[206:209], v166 offset:5120
	ds_read_b128 v[210:213], v166 offset:6144
	global_load_lds_dwordx4 v136, s[8:9]
	s_add_i32 m0, s51, 0xe000
	ds_read_b128 v[214:217], v166 offset:7168
	global_load_lds_dwordx4 v138, s[8:9]
	s_add_u32 s0, s8, 0xfffd0080
	s_addc_u32 s1, s9, -1
	s_cmp_eq_u32 s41, 8
	s_cselect_b32 s39, s31, s1
	s_cselect_b32 s38, s30, s0
	s_cselect_b32 s37, s11, s40
	s_cselect_b32 s36, s10, s35
	s_waitcnt lgkmcnt(8)
	s_barrier
	s_waitcnt lgkmcnt(0)
	s_setprio 1
	v_mfma_f32_16x16x32_bf16 v[124:127], v[144:147], v[180:183], v[124:127]
	v_mfma_f32_16x16x32_bf16 v[120:123], v[172:175], v[180:183], v[120:123]
	v_mfma_f32_16x16x32_bf16 v[108:111], v[144:147], v[194:197], v[108:111]
	v_mfma_f32_16x16x32_bf16 v[104:107], v[172:175], v[194:197], v[104:107]
	v_mfma_f32_16x16x32_bf16 v[92:95], v[144:147], v[202:205], v[92:95]
	v_mfma_f32_16x16x32_bf16 v[88:91], v[172:175], v[202:205], v[88:91]
	v_mfma_f32_16x16x32_bf16 v[76:79], v[144:147], v[210:213], v[76:79]
	v_mfma_f32_16x16x32_bf16 v[72:75], v[172:175], v[210:213], v[72:75]
	v_mfma_f32_16x16x32_bf16 v[124:127], v[168:171], v[188:191], v[124:127]
	v_mfma_f32_16x16x32_bf16 v[120:123], v[176:179], v[188:191], v[120:123]
	v_mfma_f32_16x16x32_bf16 v[108:111], v[168:171], v[198:201], v[108:111]
	v_mfma_f32_16x16x32_bf16 v[104:107], v[176:179], v[198:201], v[104:107]
	v_mfma_f32_16x16x32_bf16 v[92:95], v[168:171], v[206:209], v[92:95]
	v_mfma_f32_16x16x32_bf16 v[88:91], v[176:179], v[206:209], v[88:91]
	v_mfma_f32_16x16x32_bf16 v[76:79], v[168:171], v[214:217], v[76:79]
	v_mfma_f32_16x16x32_bf16 v[72:75], v[176:179], v[214:217], v[72:75]
	s_setprio 0
	s_barrier
	s_add_i32 s0, s61, s50
	s_mov_b32 m0, s0
	ds_read_b128 v[218:221], v167
	ds_read_b128 v[222:225], v167 offset:1024
	ds_read_b128 v[226:229], v167 offset:2048
	global_load_lds_dwordx4 v130, s[36:37]
	s_add_i32 m0, s0, 0x2000
	ds_read_b128 v[230:233], v167 offset:3072
	global_load_lds_dwordx4 v134, s[36:37]
	s_barrier
; #define PG8_STAGE(bufoff, gbase, voff) do { _Pragma("unroll") for (int _i = 0; _i < 2; ++_i) \
;         __builtin_amdgcn_global_load_lds((const unsigned*)((const char*)(gbase) + (voff)[_i]), (LAS unsigned*)(lds + (bufoff) + ldsw + _i * 8192), 16, 0, 0); } while (0)
; #define PG8_LDA(dst, b, h) do { _Pragma("unroll") for (int m = 0; m < 4; ++m) _Pragma("unroll") for (int k = 0; k < 2; ++k) dst[m][k] = *(const LAS bf16x8*)(lds + PG8_SA(b, h) + aoff + m * 2048 + k * 1024); } while (0)
; #define PG8_LDB(dst, b, h) do { _Pragma("unroll") for (int n = 0; n < 2; ++n) _Pragma("unroll") for (int k = 0; k < 2; ++k) dst[n][k] = *(const LAS bf16x8*)(lds + PG8_SB(b, h) + boff + n * 2048 + k * 1024); } while (0)
; #define PG8_WAIT_V(n) asm volatile("s_waitcnt vmcnt(" #n ")" ::: "memory")
; #define PG8_WAIT_L(n) asm volatile("s_waitcnt lgkmcnt(" #n ")" ::: "memory")
; #define PG8_BAR __builtin_amdgcn_s_barrier()
; #define PG8_SCHED __builtin_amdgcn_sched_barrier(0)
; template <class Epi, class Sched>
; DI void gemm_phase(LAS unsigned char* lds, const Gemm g, const Sched& S, const Epi& E) {
;     ...
;             PG8_LDB(B0, 0, 0); PG8_SCHED; PG8_LDA(At, 0, 0); PG8_STAGE(PG8_SA(1, 1), a1 + hstep, voffA);
;             PG8_WAIT_L(8); PG8_BAR; PG8_WAIT_L(0); PG8_MMA(0, 0, At, B0); PG8_BAR; PG8_SCHED;
;             PG8_LDB(B1, 0, 1); PG8_STAGE(PG8_SB(0, 0), b2, voffB);
;             PG8_BAR; PG8_WAIT_L(0); PG8_MMA(0, 1, At, B1); PG8_BAR;
;             PG8_LDA(At, 0, 1); PG8_STAGE(PG8_SA(0, 0), a2, voffA);
;             PG8_BAR; PG8_WAIT_L(0); PG8_MMA(1, 0, At, B0); PG8_BAR; PG8_SCHED;
;             PG8_STAGE(PG8_SB(0, 1), b2 + hstep, voffB);
;             PG8_WAIT_V(6); PG8_BAR; PG8_MMA(1, 1, At, B1); PG8_BAR;
;             PG8_LDB(B0, 1, 0); PG8_SCHED; PG8_LDA(At, 1, 0); PG8_STAGE(PG8_SA(0, 1), a2 + hstep, voffA);
;             PG8_WAIT_L(8); PG8_BAR; PG8_WAIT_L(0); PG8_MMA(0, 0, At, B0); PG8_BAR; PG8_SCHED;
;             PG8_LDB(B1, 1, 1); PG8_STAGE(PG8_SB(1, 0), b3, voffB);
;             PG8_BAR; PG8_WAIT_L(0); PG8_MMA(0, 1, At, B1); PG8_BAR;
;             PG8_LDA(At, 1, 1); PG8_STAGE(PG8_SA(1, 0), a3, voffA);
;             PG8_BAR; PG8_WAIT_L(0); PG8_MMA(1, 0, At, B0); PG8_BAR; PG8_SCHED;
;             PG8_STAGE(PG8_SB(1, 1), b3 + hstep, voffB);
;             PG8_WAIT_V(6); PG8_BAR; PG8_MMA(1, 1, At, B1); PG8_BAR;
	s_waitcnt lgkmcnt(0)
	s_setprio 1
	v_mfma_f32_16x16x32_bf16 v[116:119], v[218:221], v[180:183], v[116:119]
	v_mfma_f32_16x16x32_bf16 v[112:115], v[226:229], v[180:183], v[112:115]
	v_mfma_f32_16x16x32_bf16 v[100:103], v[218:221], v[194:197], v[100:103]
	v_mfma_f32_16x16x32_bf16 v[96:99], v[226:229], v[194:197], v[96:99]
	v_mfma_f32_16x16x32_bf16 v[84:87], v[218:221], v[202:205], v[84:87]
	v_mfma_f32_16x16x32_bf16 v[80:83], v[226:229], v[202:205], v[80:83]
	v_mfma_f32_16x16x32_bf16 v[68:71], v[218:221], v[210:213], v[68:71]
	v_mfma_f32_16x16x32_bf16 v[64:67], v[226:229], v[210:213], v[64:67]
	v_mfma_f32_16x16x32_bf16 v[116:119], v[222:225], v[188:191], v[116:119]
	v_mfma_f32_16x16x32_bf16 v[112:115], v[230:233], v[188:191], v[112:115]
	v_mfma_f32_16x16x32_bf16 v[100:103], v[222:225], v[198:201], v[100:103]
	v_mfma_f32_16x16x32_bf16 v[96:99], v[230:233], v[198:201], v[96:99]
	v_mfma_f32_16x16x32_bf16 v[84:87], v[222:225], v[206:209], v[84:87]
	v_mfma_f32_16x16x32_bf16 v[80:83], v[230:233], v[206:209], v[80:83]
	v_mfma_f32_16x16x32_bf16 v[68:71], v[222:225], v[214:217], v[68:71]
	v_mfma_f32_16x16x32_bf16 v[64:67], v[230:233], v[214:217], v[64:67]
	s_setprio 0
	s_mov_b32 m0, s51
	s_barrier
	ds_read_b128 v[180:183], v166 offset:16384
	ds_read_b128 v[188:191], v166 offset:17408
	ds_read_b128 v[194:197], v166 offset:18432
	ds_read_b128 v[198:201], v166 offset:19456
	ds_read_b128 v[202:205], v166 offset:20480
	ds_read_b128 v[206:209], v166 offset:21504
	ds_read_b128 v[210:213], v166 offset:22528
	global_load_lds_dwordx4 v128, s[38:39]
	s_mov_b32 m0, s52
	ds_read_b128 v[214:217], v166 offset:23552
	global_load_lds_dwordx4 v132, s[38:39]
	s_barrier
	s_waitcnt lgkmcnt(0)
	s_setprio 1
	v_mfma_f32_16x16x32_bf16 v[60:63], v[144:147], v[180:183], v[60:63]
	v_mfma_f32_16x16x32_bf16 v[56:59], v[172:175], v[180:183], v[56:59]
	v_mfma_f32_16x16x32_bf16 v[44:47], v[144:147], v[194:197], v[44:47]
	v_mfma_f32_16x16x32_bf16 v[40:43], v[172:175], v[194:197], v[40:43]
	v_mfma_f32_16x16x32_bf16 v[28:31], v[144:147], v[202:205], v[28:31]
	v_mfma_f32_16x16x32_bf16 v[24:27], v[172:175], v[202:205], v[24:27]
	v_mfma_f32_16x16x32_bf16 v[12:15], v[144:147], v[210:213], v[12:15]
	v_mfma_f32_16x16x32_bf16 v[8:11], v[172:175], v[210:213], v[8:11]
	v_mfma_f32_16x16x32_bf16 v[60:63], v[168:171], v[188:191], v[60:63]
	v_mfma_f32_16x16x32_bf16 v[56:59], v[176:179], v[188:191], v[56:59]
	v_mfma_f32_16x16x32_bf16 v[44:47], v[168:171], v[198:201], v[44:47]
	v_mfma_f32_16x16x32_bf16 v[40:43], v[176:179], v[198:201], v[40:43]
	v_mfma_f32_16x16x32_bf16 v[28:31], v[168:171], v[206:209], v[28:31]
	v_mfma_f32_16x16x32_bf16 v[24:27], v[176:179], v[206:209], v[24:27]
	v_mfma_f32_16x16x32_bf16 v[12:15], v[168:171], v[214:217], v[12:15]
	v_mfma_f32_16x16x32_bf16 v[8:11], v[176:179], v[214:217], v[8:11]
	s_setprio 0
	s_barrier
	s_add_i32 s4, s62, s50
	s_mov_b32 m0, s4
	s_add_u32 s0, s36, 0x30000
	s_addc_u32 s1, s37, 0
	global_load_lds_dwordx4 v130, s[0:1]
	s_add_i32 m0, s4, 0x2000
	s_nop 0
	global_load_lds_dwordx4 v134, s[0:1]
	s_waitcnt vmcnt(6)
	s_barrier
	s_setprio 1
	v_mfma_f32_16x16x32_bf16 v[52:55], v[218:221], v[180:183], v[52:55]
	v_mfma_f32_16x16x32_bf16 v[48:51], v[226:229], v[180:183], v[48:51]
	v_mfma_f32_16x16x32_bf16 v[36:39], v[218:221], v[194:197], v[36:39]
	v_mfma_f32_16x16x32_bf16 v[32:35], v[226:229], v[194:197], v[32:35]
	v_mfma_f32_16x16x32_bf16 v[20:23], v[218:221], v[202:205], v[20:23]
	v_mfma_f32_16x16x32_bf16 v[16:19], v[226:229], v[202:205], v[16:19]
	v_mfma_f32_16x16x32_bf16 v[4:7], v[218:221], v[210:213], v[4:7]
	v_mfma_f32_16x16x32_bf16 v[0:3], v[226:229], v[210:213], v[0:3]
	v_mfma_f32_16x16x32_bf16 v[52:55], v[222:225], v[188:191], v[52:55]
	v_mfma_f32_16x16x32_bf16 v[48:51], v[230:233], v[188:191], v[48:51]
	v_mfma_f32_16x16x32_bf16 v[36:39], v[222:225], v[198:201], v[36:39]
	v_mfma_f32_16x16x32_bf16 v[32:35], v[230:233], v[198:201], v[32:35]
	v_mfma_f32_16x16x32_bf16 v[20:23], v[222:225], v[206:209], v[20:23]
	v_mfma_f32_16x16x32_bf16 v[16:19], v[230:233], v[206:209], v[16:19]
	v_mfma_f32_16x16x32_bf16 v[4:7], v[222:225], v[214:217], v[4:7]
	v_mfma_f32_16x16x32_bf16 v[0:3], v[230:233], v[214:217], v[0:3]
	s_setprio 0
	s_add_i32 s4, 0, 0x18000
	s_barrier
	ds_read_b128 v[144:147], v148
	ds_read_b128 v[168:171], v148 offset:1024
	ds_read_b128 v[172:175], v148 offset:2048
	ds_read_b128 v[176:179], v148 offset:3072
	s_add_u32 s0, s38, 0x30000
	s_addc_u32 s1, s39, 0
	s_mov_b32 m0, s53
	ds_read_b128 v[180:183], v166 offset:32768
	ds_read_b128 v[188:191], v166 offset:33792
	ds_read_b128 v[194:197], v166 offset:34816
	ds_read_b128 v[198:201], v166 offset:35840
	ds_read_b128 v[202:205], v166 offset:36864
	ds_read_b128 v[206:209], v166 offset:37888
	ds_read_b128 v[210:213], v166 offset:38912
	global_load_lds_dwordx4 v128, s[0:1]
	s_mov_b32 m0, s54
	ds_read_b128 v[214:217], v166 offset:39936
	global_load_lds_dwordx4 v132, s[0:1]
	s_waitcnt lgkmcnt(8)
	s_barrier
; #define PG8_STAGE(bufoff, gbase, voff) do { _Pragma("unroll") for (int _i = 0; _i < 2; ++_i) \
;         __builtin_amdgcn_global_load_lds((const unsigned*)((const char*)(gbase) + (voff)[_i]), (LAS unsigned*)(lds + (bufoff) + ldsw + _i * 8192), 16, 0, 0); } while (0)
; #define PG8_LDA(dst, b, h) do { _Pragma("unroll") for (int m = 0; m < 4; ++m) _Pragma("unroll") for (int k = 0; k < 2; ++k) dst[m][k] = *(const LAS bf16x8*)(lds + PG8_SA(b, h) + aoff + m * 2048 + k * 1024); } while (0)
; #define PG8_LDB(dst, b, h) do { _Pragma("unroll") for (int n = 0; n < 2; ++n) _Pragma("unroll") for (int k = 0; k < 2; ++k) dst[n][k] = *(const LAS bf16x8*)(lds + PG8_SB(b, h) + boff + n * 2048 + k * 1024); } while (0)
; #define PG8_WAIT_V(n) asm volatile("s_waitcnt vmcnt(" #n ")" ::: "memory")
; #define PG8_WAIT_L(n) asm volatile("s_waitcnt lgkmcnt(" #n ")" ::: "memory")
; #define PG8_BAR __builtin_amdgcn_s_barrier()
; #define PG8_SCHED __builtin_amdgcn_sched_barrier(0)
; template <class Epi, class Sched>
; DI void gemm_phase(LAS unsigned char* lds, const Gemm g, const Sched& S, const Epi& E) {
;     ...
;             PG8_LDB(B0, 0, 0); PG8_SCHED; PG8_LDA(At, 0, 0); PG8_STAGE(PG8_SA(1, 1), a1 + hstep, voffA);
;             PG8_WAIT_L(8); PG8_BAR; PG8_WAIT_L(0); PG8_MMA(0, 0, At, B0); PG8_BAR; PG8_SCHED;
;             PG8_LDB(B1, 0, 1); PG8_STAGE(PG8_SB(0, 0), b2, voffB);
;             PG8_BAR; PG8_WAIT_L(0); PG8_MMA(0, 1, At, B1); PG8_BAR;
;             PG8_LDA(At, 0, 1); PG8_STAGE(PG8_SA(0, 0), a2, voffA);
;             PG8_BAR; PG8_WAIT_L(0); PG8_MMA(1, 0, At, B0); PG8_BAR; PG8_SCHED;
;             PG8_STAGE(PG8_SB(0, 1), b2 + hstep, voffB);
;             PG8_WAIT_V(6); PG8_BAR; PG8_MMA(1, 1, At, B1); PG8_BAR;
;             PG8_LDB(B0, 1, 0); PG8_SCHED; PG8_LDA(At, 1, 0); PG8_STAGE(PG8_SA(0, 1), a2 + hstep, voffA);
;             PG8_WAIT_L(8); PG8_BAR; PG8_WAIT_L(0); PG8_MMA(0, 0, At, B0); PG8_BAR; PG8_SCHED;
;             PG8_LDB(B1, 1, 1); PG8_STAGE(PG8_SB(1, 0), b3, voffB);
;             PG8_BAR; PG8_WAIT_L(0); PG8_MMA(0, 1, At, B1); PG8_BAR;
;             PG8_LDA(At, 1, 1); PG8_STAGE(PG8_SA(1, 0), a3, voffA);
;             PG8_BAR; PG8_WAIT_L(0); PG8_MMA(1, 0, At, B0); PG8_BAR; PG8_SCHED;
;             PG8_STAGE(PG8_SB(1, 1), b3 + hstep, voffB);
;             PG8_WAIT_V(6); PG8_BAR; PG8_MMA(1, 1, At, B1); PG8_BAR;
	s_waitcnt lgkmcnt(0)
	s_setprio 1
	v_mfma_f32_16x16x32_bf16 v[124:127], v[144:147], v[180:183], v[124:127]
	v_mfma_f32_16x16x32_bf16 v[120:123], v[172:175], v[180:183], v[120:123]
	v_mfma_f32_16x16x32_bf16 v[108:111], v[144:147], v[194:197], v[108:111]
	v_mfma_f32_16x16x32_bf16 v[104:107], v[172:175], v[194:197], v[104:107]
	v_mfma_f32_16x16x32_bf16 v[92:95], v[144:147], v[202:205], v[92:95]
	v_mfma_f32_16x16x32_bf16 v[88:91], v[172:175], v[202:205], v[88:91]
	v_mfma_f32_16x16x32_bf16 v[76:79], v[144:147], v[210:213], v[76:79]
	v_mfma_f32_16x16x32_bf16 v[72:75], v[172:175], v[210:213], v[72:75]
	v_mfma_f32_16x16x32_bf16 v[124:127], v[168:171], v[188:191], v[124:127]
	v_mfma_f32_16x16x32_bf16 v[120:123], v[176:179], v[188:191], v[120:123]
	v_mfma_f32_16x16x32_bf16 v[108:111], v[168:171], v[198:201], v[108:111]
	v_mfma_f32_16x16x32_bf16 v[104:107], v[176:179], v[198:201], v[104:107]
	v_mfma_f32_16x16x32_bf16 v[92:95], v[168:171], v[206:209], v[92:95]
	v_mfma_f32_16x16x32_bf16 v[88:91], v[176:179], v[206:209], v[88:91]
	v_mfma_f32_16x16x32_bf16 v[76:79], v[168:171], v[214:217], v[76:79]
	v_mfma_f32_16x16x32_bf16 v[72:75], v[176:179], v[214:217], v[72:75]
	s_setprio 0
	s_barrier
	s_add_i32 s5, 0, 0x1c000
	s_add_i32 s0, s4, s50
	s_add_i32 m0, s0, 0xffffff80
	ds_read_b128 v[218:221], v149
	ds_read_b128 v[222:225], v149 offset:1024
	ds_read_b128 v[226:229], v149 offset:2048
	global_load_lds_dwordx4 v130, s[36:37] offset:128
	s_add_i32 m0, s0, 0x1f80
	ds_read_b128 v[230:233], v149 offset:3072
	global_load_lds_dwordx4 v134, s[36:37] offset:128
	s_barrier
	s_waitcnt lgkmcnt(0)
	s_setprio 1
	v_mfma_f32_16x16x32_bf16 v[116:119], v[218:221], v[180:183], v[116:119]
	v_mfma_f32_16x16x32_bf16 v[112:115], v[226:229], v[180:183], v[112:115]
	v_mfma_f32_16x16x32_bf16 v[100:103], v[218:221], v[194:197], v[100:103]
	v_mfma_f32_16x16x32_bf16 v[96:99], v[226:229], v[194:197], v[96:99]
	v_mfma_f32_16x16x32_bf16 v[84:87], v[218:221], v[202:205], v[84:87]
	v_mfma_f32_16x16x32_bf16 v[80:83], v[226:229], v[202:205], v[80:83]
	v_mfma_f32_16x16x32_bf16 v[68:71], v[218:221], v[210:213], v[68:71]
	v_mfma_f32_16x16x32_bf16 v[64:67], v[226:229], v[210:213], v[64:67]
	v_mfma_f32_16x16x32_bf16 v[116:119], v[222:225], v[188:191], v[116:119]
	v_mfma_f32_16x16x32_bf16 v[112:115], v[230:233], v[188:191], v[112:115]
	v_mfma_f32_16x16x32_bf16 v[100:103], v[222:225], v[198:201], v[100:103]
	v_mfma_f32_16x16x32_bf16 v[96:99], v[230:233], v[198:201], v[96:99]
	v_mfma_f32_16x16x32_bf16 v[84:87], v[222:225], v[206:209], v[84:87]
	v_mfma_f32_16x16x32_bf16 v[80:83], v[230:233], v[206:209], v[80:83]
	v_mfma_f32_16x16x32_bf16 v[68:71], v[222:225], v[214:217], v[68:71]
	v_mfma_f32_16x16x32_bf16 v[64:67], v[230:233], v[214:217], v[64:67]
	s_setprio 0
	s_add_i32 m0, s57, 0xffffff80
	s_barrier
	ds_read_b128 v[180:183], v166 offset:49152
	ds_read_b128 v[188:191], v166 offset:50176
	ds_read_b128 v[194:197], v166 offset:51200
	ds_read_b128 v[198:201], v166 offset:52224
	ds_read_b128 v[202:205], v166 offset:53248
	ds_read_b128 v[206:209], v166 offset:54272
	ds_read_b128 v[210:213], v166 offset:55296
	global_load_lds_dwordx4 v128, s[38:39] offset:128
	s_add_i32 m0, s58, 0xffffff80
	ds_read_b128 v[214:217], v166 offset:56320
	global_load_lds_dwordx4 v132, s[38:39] offset:128
	s_barrier
	s_waitcnt lgkmcnt(0)
	s_setprio 1
	v_mfma_f32_16x16x32_bf16 v[60:63], v[144:147], v[180:183], v[60:63]
	v_mfma_f32_16x16x32_bf16 v[56:59], v[172:175], v[180:183], v[56:59]
	v_mfma_f32_16x16x32_bf16 v[44:47], v[144:147], v[194:197], v[44:47]
	v_mfma_f32_16x16x32_bf16 v[40:43], v[172:175], v[194:197], v[40:43]
	v_mfma_f32_16x16x32_bf16 v[28:31], v[144:147], v[202:205], v[28:31]
	v_mfma_f32_16x16x32_bf16 v[24:27], v[172:175], v[202:205], v[24:27]
	v_mfma_f32_16x16x32_bf16 v[12:15], v[144:147], v[210:213], v[12:15]
	v_mfma_f32_16x16x32_bf16 v[8:11], v[172:175], v[210:213], v[8:11]
	v_mfma_f32_16x16x32_bf16 v[60:63], v[168:171], v[188:191], v[60:63]
	v_mfma_f32_16x16x32_bf16 v[56:59], v[176:179], v[188:191], v[56:59]
	v_mfma_f32_16x16x32_bf16 v[44:47], v[168:171], v[198:201], v[44:47]
	v_mfma_f32_16x16x32_bf16 v[40:43], v[176:179], v[198:201], v[40:43]
	v_mfma_f32_16x16x32_bf16 v[28:31], v[168:171], v[206:209], v[28:31]
	v_mfma_f32_16x16x32_bf16 v[24:27], v[176:179], v[206:209], v[24:27]
	v_mfma_f32_16x16x32_bf16 v[12:15], v[168:171], v[214:217], v[12:15]
	v_mfma_f32_16x16x32_bf16 v[8:11], v[176:179], v[214:217], v[8:11]
	s_setprio 0
	s_barrier
	s_add_i32 s4, s5, s50
	s_mov_b32 m0, s4
	s_add_u32 s0, s36, 0x30080
	s_addc_u32 s1, s37, 0
	global_load_lds_dwordx4 v130, s[0:1]
	s_add_i32 m0, s4, 0x2000
	s_nop 0
	global_load_lds_dwordx4 v134, s[0:1]
	s_waitcnt vmcnt(6)
	s_barrier
	s_setprio 1
	v_mfma_f32_16x16x32_bf16 v[52:55], v[218:221], v[180:183], v[52:55]
	v_mfma_f32_16x16x32_bf16 v[48:51], v[226:229], v[180:183], v[48:51]
	v_mfma_f32_16x16x32_bf16 v[36:39], v[218:221], v[194:197], v[36:39]
	v_mfma_f32_16x16x32_bf16 v[32:35], v[226:229], v[194:197], v[32:35]
	v_mfma_f32_16x16x32_bf16 v[20:23], v[218:221], v[202:205], v[20:23]
	v_mfma_f32_16x16x32_bf16 v[16:19], v[226:229], v[202:205], v[16:19]
	v_mfma_f32_16x16x32_bf16 v[4:7], v[218:221], v[210:213], v[4:7]
	v_mfma_f32_16x16x32_bf16 v[0:3], v[226:229], v[210:213], v[0:3]
	v_mfma_f32_16x16x32_bf16 v[52:55], v[222:225], v[188:191], v[52:55]
	v_mfma_f32_16x16x32_bf16 v[48:51], v[230:233], v[188:191], v[48:51]
	v_mfma_f32_16x16x32_bf16 v[36:39], v[222:225], v[198:201], v[36:39]
	v_mfma_f32_16x16x32_bf16 v[32:35], v[230:233], v[198:201], v[32:35]
	v_mfma_f32_16x16x32_bf16 v[20:23], v[222:225], v[206:209], v[20:23]
	v_mfma_f32_16x16x32_bf16 v[16:19], v[230:233], v[206:209], v[16:19]
	v_mfma_f32_16x16x32_bf16 v[4:7], v[222:225], v[214:217], v[4:7]
	v_mfma_f32_16x16x32_bf16 v[0:3], v[230:233], v[214:217], v[0:3]
	s_setprio 0
	s_add_i32 s41, s41, 2
	s_add_u32 s8, s8, 0x100
	s_addc_u32 s9, s9, 0
	s_add_u32 s35, s35, 0x100
	s_addc_u32 s40, s40, 0
	s_cmp_gt_u32 s41, 9
	s_barrier
	s_cbranch_scc0 .LBB0_938

;     DI size_t aoff(const Unit& u, size_t) const { return (size_t)u.ks * kbytes; }
;     DI size_t aoff(const Unit& u, size_t tstep) const { return (size_t)u.pm * tstep; }
;     DI size_t boff(const Unit& u, size_t tstep) const { return (size_t)u.pn * tstep; }
; template <class Epi, class Sched>
; DI void gemm_phase(LAS unsigned char* lds, const Gemm g, const Sched& S, const Epi& E) {
;     ...
;         const bool has_next = S.next(ui + 1, nxt);
;         const char* nA = has_next ? (const char*)g.A + S.aoff(nxt, tstep) : cA; const char* nB = has_next ? (const char*)g.Bt + S.boff(nxt, tstep) : cB;
;         for (int t = 0; t < nt; t += 2) {
;             if constexpr (Epi::HAS_MID) { if (t == E.mid_t(nt)) { int fr3 = fr, fq3 = fq; asm volatile("" : "+v"(fr3), "+v"(fq3)); E.mid(acc, cur, wr, wc, fr3, fq3); } }
;             const bool last = (t == nt - 2);
;             const char* a1 = cA + (size_t)(t + 1) * kstep;
;             const char* a2 = last ? nA : cA + (size_t)(t + 2) * kstep; const char* b2 = last ? nB : cB + (size_t)(t + 2) * kstep;
;             const char* a3 = a2 + kstep; const char* b3 = b2 + kstep;
;             PG8_LDB(B0, 0, 0); PG8_SCHED; PG8_LDA(At, 0, 0); PG8_STAGE(PG8_SA(1, 1), a1 + hstep, voffA);
;             PG8_WAIT_L(8); PG8_BAR; PG8_WAIT_L(0); PG8_MMA(0, 0, At, B0); PG8_BAR; PG8_SCHED;
;             PG8_LDB(B1, 0, 1); PG8_STAGE(PG8_SB(0, 0), b2, voffB);
;             PG8_BAR; PG8_WAIT_L(0); PG8_MMA(0, 1, At, B1); PG8_BAR;
;             PG8_LDA(At, 0, 1); PG8_STAGE(PG8_SA(0, 0), a2, voffA);
;             PG8_BAR; PG8_WAIT_L(0); PG8_MMA(1, 0, At, B0); PG8_BAR; PG8_SCHED;
;             PG8_STAGE(PG8_SB(0, 1), b2 + hstep, voffB);
;             PG8_WAIT_V(6); PG8_BAR; PG8_MMA(1, 1, At, B1); PG8_BAR;
;             PG8_LDB(B0, 1, 0); PG8_SCHED; PG8_LDA(At, 1, 0); PG8_STAGE(PG8_SA(0, 1), a2 + hstep, voffA);
;             PG8_WAIT_L(8); PG8_BAR; PG8_WAIT_L(0); PG8_MMA(0, 0, At, B0); PG8_BAR; PG8_SCHED;
;             PG8_LDB(B1, 1, 1); PG8_STAGE(PG8_SB(1, 0), b3, voffB);
;             PG8_BAR; PG8_WAIT_L(0); PG8_MMA(0, 1, At, B1); PG8_BAR;
;             PG8_LDA(At, 1, 1); PG8_STAGE(PG8_SA(1, 0), a3, voffA);
;             PG8_BAR; PG8_WAIT_L(0); PG8_MMA(1, 0, At, B0); PG8_BAR; PG8_SCHED;
;             PG8_STAGE(PG8_SB(1, 1), b3 + hstep, voffB);
;             PG8_WAIT_V(6); PG8_BAR; PG8_MMA(1, 1, At, B1); PG8_BAR;
.LBB0_983:
	s_ashr_i32 s31, s30, 31
	s_lshl_b64 s[0:1], s[30:31], 18
	v_cmp_lt_i64_e32 vcc, s[36:37], v[142:143]
	s_add_u32 s36, s51, s0
	s_addc_u32 s37, s52, s1
	s_and_b64 s[0:1], vcc, exec
	s_cselect_b32 s9, s37, s43
	s_cselect_b32 s31, s36, s42
	s_ashr_i32 s29, s28, 31
	s_lshl_b64 s[0:1], s[28:29], 18
	s_add_u32 s38, s53, s0
	s_addc_u32 s39, s54, s1
	s_and_b64 s[0:1], vcc, exec
	s_cselect_b32 s29, s39, s45
	s_cselect_b32 s34, s38, s44
	s_add_u32 s42, s42, 0x20080
	s_addc_u32 s43, s43, 0
	s_add_u32 s35, s44, 0x100
	v_mov_b32_e32 v0, 0
	s_addc_u32 s41, s45, 0
	s_mov_b32 s79, -2
	ds_read_b128 v[146:149], v156
	ds_read_b128 v[150:153], v156 offset:1024
	ds_read_b128 v[160:163], v156 offset:2048
	ds_read_b128 v[164:167], v156 offset:3072
	s_add_i32 m0, s55, 0xc000
	ds_read_b128 v[168:171], v158
	ds_read_b128 v[172:175], v158 offset:1024
	ds_read_b128 v[176:179], v158 offset:2048
	ds_read_b128 v[180:183], v158 offset:3072
	ds_read_b128 v[188:191], v158 offset:4096
	ds_read_b128 v[194:197], v158 offset:5120
	ds_read_b128 v[198:201], v158 offset:6144
	global_load_lds_dwordx4 v138, s[42:43]
	s_add_i32 m0, s55, 0xe000
	ds_read_b128 v[202:205], v158 offset:7168
	global_load_lds_dwordx4 v140, s[42:43]
	s_add_u32 s0, s42, 0xfffe0080
	s_addc_u32 s1, s43, -1
	s_cmp_eq_u32 s79, 4
	s_cselect_b32 s47, s9, s1
	s_cselect_b32 s46, s31, s0
	s_cselect_b32 s45, s29, s41
	s_cselect_b32 s44, s34, s35
	s_waitcnt lgkmcnt(8)
	s_barrier
	s_waitcnt lgkmcnt(0)
	s_setprio 1
	v_mfma_f32_16x16x32_bf16 v[124:127], v[146:149], v[168:171], 0
	v_mfma_f32_16x16x32_bf16 v[120:123], v[160:163], v[168:171], 0
	v_mfma_f32_16x16x32_bf16 v[108:111], v[146:149], v[176:179], 0
	v_mfma_f32_16x16x32_bf16 v[104:107], v[160:163], v[176:179], 0
	v_mfma_f32_16x16x32_bf16 v[92:95], v[146:149], v[188:191], 0
	v_mfma_f32_16x16x32_bf16 v[88:91], v[160:163], v[188:191], 0
	v_mfma_f32_16x16x32_bf16 v[76:79], v[146:149], v[198:201], 0
	v_mfma_f32_16x16x32_bf16 v[72:75], v[160:163], v[198:201], 0
	v_mfma_f32_16x16x32_bf16 v[124:127], v[150:153], v[172:175], v[124:127]
	v_mfma_f32_16x16x32_bf16 v[120:123], v[164:167], v[172:175], v[120:123]
	v_mfma_f32_16x16x32_bf16 v[108:111], v[150:153], v[180:183], v[108:111]
	v_mfma_f32_16x16x32_bf16 v[104:107], v[164:167], v[180:183], v[104:107]
	v_mfma_f32_16x16x32_bf16 v[92:95], v[150:153], v[194:197], v[92:95]
	v_mfma_f32_16x16x32_bf16 v[88:91], v[164:167], v[194:197], v[88:91]
	v_mfma_f32_16x16x32_bf16 v[76:79], v[150:153], v[202:205], v[76:79]
	v_mfma_f32_16x16x32_bf16 v[72:75], v[164:167], v[202:205], v[72:75]
	s_setprio 0
	s_barrier
	s_add_i32 s0, s66, s50
	s_mov_b32 m0, s0
	ds_read_b128 v[206:209], v159
	ds_read_b128 v[210:213], v159 offset:1024
	ds_read_b128 v[214:217], v159 offset:2048
	global_load_lds_dwordx4 v130, s[44:45]
	s_add_i32 m0, s0, 0x2000
	ds_read_b128 v[218:221], v159 offset:3072
	global_load_lds_dwordx4 v134, s[44:45]
	s_barrier
	s_waitcnt lgkmcnt(0)
	s_setprio 1
	v_mfma_f32_16x16x32_bf16 v[116:119], v[206:209], v[168:171], 0
	v_mfma_f32_16x16x32_bf16 v[112:115], v[214:217], v[168:171], 0
	v_mfma_f32_16x16x32_bf16 v[100:103], v[206:209], v[176:179], 0
	v_mfma_f32_16x16x32_bf16 v[96:99], v[214:217], v[176:179], 0
	v_mfma_f32_16x16x32_bf16 v[84:87], v[206:209], v[188:191], 0
	v_mfma_f32_16x16x32_bf16 v[80:83], v[214:217], v[188:191], 0
	v_mfma_f32_16x16x32_bf16 v[68:71], v[206:209], v[198:201], 0
	v_mfma_f32_16x16x32_bf16 v[64:67], v[214:217], v[198:201], 0
	v_mfma_f32_16x16x32_bf16 v[116:119], v[210:213], v[172:175], v[116:119]
	v_mfma_f32_16x16x32_bf16 v[112:115], v[218:221], v[172:175], v[112:115]
	v_mfma_f32_16x16x32_bf16 v[100:103], v[210:213], v[180:183], v[100:103]
	v_mfma_f32_16x16x32_bf16 v[96:99], v[218:221], v[180:183], v[96:99]
	v_mfma_f32_16x16x32_bf16 v[84:87], v[210:213], v[194:197], v[84:87]
	v_mfma_f32_16x16x32_bf16 v[80:83], v[218:221], v[194:197], v[80:83]
	v_mfma_f32_16x16x32_bf16 v[68:71], v[210:213], v[202:205], v[68:71]
	v_mfma_f32_16x16x32_bf16 v[64:67], v[218:221], v[202:205], v[64:67]
	s_setprio 0
	s_mov_b32 m0, s55
	s_barrier
	ds_read_b128 v[168:171], v158 offset:16384
	ds_read_b128 v[172:175], v158 offset:17408
	ds_read_b128 v[176:179], v158 offset:18432
	ds_read_b128 v[180:183], v158 offset:19456
	ds_read_b128 v[188:191], v158 offset:20480
	ds_read_b128 v[194:197], v158 offset:21504
	ds_read_b128 v[198:201], v158 offset:22528
	global_load_lds_dwordx4 v128, s[46:47]
	s_mov_b32 m0, s56
	ds_read_b128 v[202:205], v158 offset:23552
	global_load_lds_dwordx4 v132, s[46:47]
	s_barrier
	s_waitcnt lgkmcnt(0)
	s_setprio 1
	v_mfma_f32_16x16x32_bf16 v[60:63], v[146:149], v[168:171], 0
	v_mfma_f32_16x16x32_bf16 v[56:59], v[160:163], v[168:171], 0
	v_mfma_f32_16x16x32_bf16 v[44:47], v[146:149], v[176:179], 0
	v_mfma_f32_16x16x32_bf16 v[40:43], v[160:163], v[176:179], 0
	v_mfma_f32_16x16x32_bf16 v[28:31], v[146:149], v[188:191], 0
	v_mfma_f32_16x16x32_bf16 v[24:27], v[160:163], v[188:191], 0
	v_mfma_f32_16x16x32_bf16 v[12:15], v[146:149], v[198:201], 0
	v_mfma_f32_16x16x32_bf16 v[8:11], v[160:163], v[198:201], 0
	v_mfma_f32_16x16x32_bf16 v[60:63], v[150:153], v[172:175], v[60:63]
	v_mfma_f32_16x16x32_bf16 v[56:59], v[164:167], v[172:175], v[56:59]
	v_mfma_f32_16x16x32_bf16 v[44:47], v[150:153], v[180:183], v[44:47]
	v_mfma_f32_16x16x32_bf16 v[40:43], v[164:167], v[180:183], v[40:43]
	v_mfma_f32_16x16x32_bf16 v[28:31], v[150:153], v[194:197], v[28:31]
	v_mfma_f32_16x16x32_bf16 v[24:27], v[164:167], v[194:197], v[24:27]
	v_mfma_f32_16x16x32_bf16 v[12:15], v[150:153], v[202:205], v[12:15]
	v_mfma_f32_16x16x32_bf16 v[8:11], v[164:167], v[202:205], v[8:11]
	s_setprio 0
	s_barrier
; #define PG8_STAGE(bufoff, gbase, voff) do { _Pragma("unroll") for (int _i = 0; _i < 2; ++_i) \
;         __builtin_amdgcn_global_load_lds((const unsigned*)((const char*)(gbase) + (voff)[_i]), (LAS unsigned*)(lds + (bufoff) + ldsw + _i * 8192), 16, 0, 0); } while (0)
; #define PG8_LDA(dst, b, h) do { _Pragma("unroll") for (int m = 0; m < 4; ++m) _Pragma("unroll") for (int k = 0; k < 2; ++k) dst[m][k] = *(const LAS bf16x8*)(lds + PG8_SA(b, h) + aoff + m * 2048 + k * 1024); } while (0)
; #define PG8_LDB(dst, b, h) do { _Pragma("unroll") for (int n = 0; n < 2; ++n) _Pragma("unroll") for (int k = 0; k < 2; ++k) dst[n][k] = *(const LAS bf16x8*)(lds + PG8_SB(b, h) + boff + n * 2048 + k * 1024); } while (0)
; #define PG8_WAIT_V(n) asm volatile("s_waitcnt vmcnt(" #n ")" ::: "memory")
; #define PG8_WAIT_L(n) asm volatile("s_waitcnt lgkmcnt(" #n ")" ::: "memory")
; #define PG8_BAR __builtin_amdgcn_s_barrier()
; #define PG8_SCHED __builtin_amdgcn_sched_barrier(0)
; template <class Epi, class Sched>
; DI void gemm_phase(LAS unsigned char* lds, const Gemm g, const Sched& S, const Epi& E) {
;     ...
;             PG8_LDB(B0, 0, 0); PG8_SCHED; PG8_LDA(At, 0, 0); PG8_STAGE(PG8_SA(1, 1), a1 + hstep, voffA);
;             PG8_WAIT_L(8); PG8_BAR; PG8_WAIT_L(0); PG8_MMA(0, 0, At, B0); PG8_BAR; PG8_SCHED;
;             PG8_LDB(B1, 0, 1); PG8_STAGE(PG8_SB(0, 0), b2, voffB);
;             PG8_BAR; PG8_WAIT_L(0); PG8_MMA(0, 1, At, B1); PG8_BAR;
;             PG8_LDA(At, 0, 1); PG8_STAGE(PG8_SA(0, 0), a2, voffA);
;             PG8_BAR; PG8_WAIT_L(0); PG8_MMA(1, 0, At, B0); PG8_BAR; PG8_SCHED;
;             PG8_STAGE(PG8_SB(0, 1), b2 + hstep, voffB);
;             PG8_WAIT_V(6); PG8_BAR; PG8_MMA(1, 1, At, B1); PG8_BAR;
;             PG8_LDB(B0, 1, 0); PG8_SCHED; PG8_LDA(At, 1, 0); PG8_STAGE(PG8_SA(0, 1), a2 + hstep, voffA);
;             PG8_WAIT_L(8); PG8_BAR; PG8_WAIT_L(0); PG8_MMA(0, 0, At, B0); PG8_BAR; PG8_SCHED;
;             PG8_LDB(B1, 1, 1); PG8_STAGE(PG8_SB(1, 0), b3, voffB);
;             PG8_BAR; PG8_WAIT_L(0); PG8_MMA(0, 1, At, B1); PG8_BAR;
;             PG8_LDA(At, 1, 1); PG8_STAGE(PG8_SA(1, 0), a3, voffA);
;             PG8_BAR; PG8_WAIT_L(0); PG8_MMA(1, 0, At, B0); PG8_BAR; PG8_SCHED;
;             PG8_STAGE(PG8_SB(1, 1), b3 + hstep, voffB);
;             PG8_WAIT_V(6); PG8_BAR; PG8_MMA(1, 1, At, B1); PG8_BAR;
	s_add_i32 s4, s67, s50
	s_mov_b32 m0, s4
	s_add_u32 s0, s44, 0x20000
	s_addc_u32 s1, s45, 0
	global_load_lds_dwordx4 v130, s[0:1]
	s_add_i32 m0, s4, 0x2000
	s_nop 0
	global_load_lds_dwordx4 v134, s[0:1]
	s_waitcnt vmcnt(6)
	s_barrier
	s_setprio 1
	v_mfma_f32_16x16x32_bf16 v[52:55], v[206:209], v[168:171], 0
	v_mfma_f32_16x16x32_bf16 v[48:51], v[214:217], v[168:171], 0
	v_mfma_f32_16x16x32_bf16 v[36:39], v[206:209], v[176:179], 0
	v_mfma_f32_16x16x32_bf16 v[32:35], v[214:217], v[176:179], 0
	v_mfma_f32_16x16x32_bf16 v[20:23], v[206:209], v[188:191], 0
	v_mfma_f32_16x16x32_bf16 v[16:19], v[214:217], v[188:191], 0
	v_mfma_f32_16x16x32_bf16 v[4:7], v[206:209], v[198:201], 0
	v_mfma_f32_16x16x32_bf16 v[0:3], v[214:217], v[198:201], 0
	v_mfma_f32_16x16x32_bf16 v[52:55], v[210:213], v[172:175], v[52:55]
	v_mfma_f32_16x16x32_bf16 v[48:51], v[218:221], v[172:175], v[48:51]
	v_mfma_f32_16x16x32_bf16 v[36:39], v[210:213], v[180:183], v[36:39]
	v_mfma_f32_16x16x32_bf16 v[32:35], v[218:221], v[180:183], v[32:35]
	v_mfma_f32_16x16x32_bf16 v[20:23], v[210:213], v[194:197], v[20:23]
	v_mfma_f32_16x16x32_bf16 v[16:19], v[218:221], v[194:197], v[16:19]
	v_mfma_f32_16x16x32_bf16 v[4:7], v[210:213], v[202:205], v[4:7]
	v_mfma_f32_16x16x32_bf16 v[0:3], v[218:221], v[202:205], v[0:3]
	s_setprio 0
	s_add_i32 s4, 0, 0x18000
	v_add_u32_e32 v222, s4, v157
	s_barrier
	ds_read_b128 v[146:149], v222
	ds_read_b128 v[150:153], v222 offset:1024
	ds_read_b128 v[160:163], v222 offset:2048
	ds_read_b128 v[164:167], v222 offset:3072
	s_add_u32 s0, s46, 0x20000
	s_addc_u32 s1, s47, 0
	s_mov_b32 m0, s57
	ds_read_b128 v[168:171], v158 offset:32768
	ds_read_b128 v[172:175], v158 offset:33792
	ds_read_b128 v[176:179], v158 offset:34816
	ds_read_b128 v[180:183], v158 offset:35840
	ds_read_b128 v[188:191], v158 offset:36864
	ds_read_b128 v[194:197], v158 offset:37888
	ds_read_b128 v[198:201], v158 offset:38912
	global_load_lds_dwordx4 v128, s[0:1]
	s_mov_b32 m0, s58
	ds_read_b128 v[202:205], v158 offset:39936
	global_load_lds_dwordx4 v132, s[0:1]
	s_waitcnt lgkmcnt(8)
	s_barrier
	s_waitcnt lgkmcnt(0)
	s_setprio 1
	v_mfma_f32_16x16x32_bf16 v[124:127], v[146:149], v[168:171], v[124:127]
	v_mfma_f32_16x16x32_bf16 v[120:123], v[160:163], v[168:171], v[120:123]
	v_mfma_f32_16x16x32_bf16 v[108:111], v[146:149], v[176:179], v[108:111]
	v_mfma_f32_16x16x32_bf16 v[104:107], v[160:163], v[176:179], v[104:107]
	v_mfma_f32_16x16x32_bf16 v[92:95], v[146:149], v[188:191], v[92:95]
	v_mfma_f32_16x16x32_bf16 v[88:91], v[160:163], v[188:191], v[88:91]
	v_mfma_f32_16x16x32_bf16 v[76:79], v[146:149], v[198:201], v[76:79]
	v_mfma_f32_16x16x32_bf16 v[72:75], v[160:163], v[198:201], v[72:75]
	v_mfma_f32_16x16x32_bf16 v[124:127], v[150:153], v[172:175], v[124:127]
	v_mfma_f32_16x16x32_bf16 v[120:123], v[164:167], v[172:175], v[120:123]
	v_mfma_f32_16x16x32_bf16 v[108:111], v[150:153], v[180:183], v[108:111]
	v_mfma_f32_16x16x32_bf16 v[104:107], v[164:167], v[180:183], v[104:107]
	v_mfma_f32_16x16x32_bf16 v[92:95], v[150:153], v[194:197], v[92:95]
	v_mfma_f32_16x16x32_bf16 v[88:91], v[164:167], v[194:197], v[88:91]
	v_mfma_f32_16x16x32_bf16 v[76:79], v[150:153], v[202:205], v[76:79]
	v_mfma_f32_16x16x32_bf16 v[72:75], v[164:167], v[202:205], v[72:75]
	s_setprio 0
	s_barrier
	s_add_i32 s5, 0, 0x1c000
	s_add_i32 s0, s4, s50
	v_add_u32_e32 v223, s5, v157
	s_add_i32 m0, s0, 0xffffff80
	ds_read_b128 v[206:209], v223
	ds_read_b128 v[210:213], v223 offset:1024
	ds_read_b128 v[214:217], v223 offset:2048
	global_load_lds_dwordx4 v130, s[44:45] offset:128
	s_add_i32 m0, s0, 0x1f80
	ds_read_b128 v[218:221], v223 offset:3072
	global_load_lds_dwordx4 v134, s[44:45] offset:128
	s_barrier
	s_waitcnt lgkmcnt(0)
	s_setprio 1
	v_mfma_f32_16x16x32_bf16 v[116:119], v[206:209], v[168:171], v[116:119]
	v_mfma_f32_16x16x32_bf16 v[112:115], v[214:217], v[168:171], v[112:115]
	v_mfma_f32_16x16x32_bf16 v[100:103], v[206:209], v[176:179], v[100:103]
	v_mfma_f32_16x16x32_bf16 v[96:99], v[214:217], v[176:179], v[96:99]
	v_mfma_f32_16x16x32_bf16 v[84:87], v[206:209], v[188:191], v[84:87]
	v_mfma_f32_16x16x32_bf16 v[80:83], v[214:217], v[188:191], v[80:83]
	v_mfma_f32_16x16x32_bf16 v[68:71], v[206:209], v[198:201], v[68:71]
	v_mfma_f32_16x16x32_bf16 v[64:67], v[214:217], v[198:201], v[64:67]
	v_mfma_f32_16x16x32_bf16 v[116:119], v[210:213], v[172:175], v[116:119]
	v_mfma_f32_16x16x32_bf16 v[112:115], v[218:221], v[172:175], v[112:115]
	v_mfma_f32_16x16x32_bf16 v[100:103], v[210:213], v[180:183], v[100:103]
	v_mfma_f32_16x16x32_bf16 v[96:99], v[218:221], v[180:183], v[96:99]
	v_mfma_f32_16x16x32_bf16 v[84:87], v[210:213], v[194:197], v[84:87]
	v_mfma_f32_16x16x32_bf16 v[80:83], v[218:221], v[194:197], v[80:83]
	v_mfma_f32_16x16x32_bf16 v[68:71], v[210:213], v[202:205], v[68:71]
	v_mfma_f32_16x16x32_bf16 v[64:67], v[218:221], v[202:205], v[64:67]
	s_setprio 0
	s_add_i32 m0, s62, 0xffffff80
	s_barrier
	ds_read_b128 v[168:171], v158 offset:49152
	ds_read_b128 v[172:175], v158 offset:50176
	ds_read_b128 v[176:179], v158 offset:51200
	ds_read_b128 v[180:183], v158 offset:52224
	ds_read_b128 v[188:191], v158 offset:53248
	ds_read_b128 v[194:197], v158 offset:54272
	ds_read_b128 v[198:201], v158 offset:55296
	global_load_lds_dwordx4 v128, s[46:47] offset:128
	s_add_i32 m0, s63, 0xffffff80
	ds_read_b128 v[202:205], v158 offset:56320
	global_load_lds_dwordx4 v132, s[46:47] offset:128
	s_barrier
; #define PG8_STAGE(bufoff, gbase, voff) do { _Pragma("unroll") for (int _i = 0; _i < 2; ++_i) \
;         __builtin_amdgcn_global_load_lds((const unsigned*)((const char*)(gbase) + (voff)[_i]), (LAS unsigned*)(lds + (bufoff) + ldsw + _i * 8192), 16, 0, 0); } while (0)
; #define PG8_LDA(dst, b, h) do { _Pragma("unroll") for (int m = 0; m < 4; ++m) _Pragma("unroll") for (int k = 0; k < 2; ++k) dst[m][k] = *(const LAS bf16x8*)(lds + PG8_SA(b, h) + aoff + m * 2048 + k * 1024); } while (0)
; template <class Epi, class Sched>
; DI void gemm_phase(LAS unsigned char* lds, const Gemm g, const Sched& S, const Epi& E) {
;     ...
;         for (int t = 0; t < nt; t += 2) {
;             if constexpr (Epi::HAS_MID) { if (t == E.mid_t(nt)) { int fr3 = fr, fq3 = fq; asm volatile("" : "+v"(fr3), "+v"(fq3)); E.mid(acc, cur, wr, wc, fr3, fq3); } }
;             const bool last = (t == nt - 2);
;             const char* a1 = cA + (size_t)(t + 1) * kstep;
;             const char* a2 = last ? nA : cA + (size_t)(t + 2) * kstep; const char* b2 = last ? nB : cB + (size_t)(t + 2) * kstep;
;             const char* a3 = a2 + kstep; const char* b3 = b2 + kstep;
;             PG8_LDB(B0, 0, 0); PG8_SCHED; PG8_LDA(At, 0, 0); PG8_STAGE(PG8_SA(1, 1), a1 + hstep, voffA);
;             PG8_WAIT_L(8); PG8_BAR; PG8_WAIT_L(0); PG8_MMA(0, 0, At, B0); PG8_BAR; PG8_SCHED;
;             PG8_LDB(B1, 0, 1); PG8_STAGE(PG8_SB(0, 0), b2, voffB);
;             PG8_BAR; PG8_WAIT_L(0); PG8_MMA(0, 1, At, B1); PG8_BAR;
;             PG8_LDA(At, 0, 1); PG8_STAGE(PG8_SA(0, 0), a2, voffA);
;             PG8_BAR; PG8_WAIT_L(0); PG8_MMA(1, 0, At, B0); PG8_BAR; PG8_SCHED;
;             PG8_STAGE(PG8_SB(0, 1), b2 + hstep, voffB);
;             PG8_WAIT_V(6); PG8_BAR; PG8_MMA(1, 1, At, B1); PG8_BAR;
;             PG8_LDB(B0, 1, 0); PG8_SCHED; PG8_LDA(At, 1, 0); PG8_STAGE(PG8_SA(0, 1), a2 + hstep, voffA);
;             PG8_WAIT_L(8); PG8_BAR; PG8_WAIT_L(0); PG8_MMA(0, 0, At, B0); PG8_BAR; PG8_SCHED;
;             PG8_LDB(B1, 1, 1); PG8_STAGE(PG8_SB(1, 0), b3, voffB);
;             PG8_BAR; PG8_WAIT_L(0); PG8_MMA(0, 1, At, B1); PG8_BAR;
;             PG8_LDA(At, 1, 1); PG8_STAGE(PG8_SA(1, 0), a3, voffA);
;             PG8_BAR; PG8_WAIT_L(0); PG8_MMA(1, 0, At, B0); PG8_BAR; PG8_SCHED;
;             PG8_STAGE(PG8_SB(1, 1), b3 + hstep, voffB);
;             PG8_WAIT_V(6); PG8_BAR; PG8_MMA(1, 1, At, B1); PG8_BAR;
	s_waitcnt lgkmcnt(0)
	s_setprio 1
	v_mfma_f32_16x16x32_bf16 v[60:63], v[146:149], v[168:171], v[60:63]
	v_mfma_f32_16x16x32_bf16 v[56:59], v[160:163], v[168:171], v[56:59]
	v_mfma_f32_16x16x32_bf16 v[44:47], v[146:149], v[176:179], v[44:47]
	v_mfma_f32_16x16x32_bf16 v[40:43], v[160:163], v[176:179], v[40:43]
	v_mfma_f32_16x16x32_bf16 v[28:31], v[146:149], v[188:191], v[28:31]
	v_mfma_f32_16x16x32_bf16 v[24:27], v[160:163], v[188:191], v[24:27]
	v_mfma_f32_16x16x32_bf16 v[12:15], v[146:149], v[198:201], v[12:15]
	v_mfma_f32_16x16x32_bf16 v[8:11], v[160:163], v[198:201], v[8:11]
	v_mfma_f32_16x16x32_bf16 v[60:63], v[150:153], v[172:175], v[60:63]
	v_mfma_f32_16x16x32_bf16 v[56:59], v[164:167], v[172:175], v[56:59]
	v_mfma_f32_16x16x32_bf16 v[44:47], v[150:153], v[180:183], v[44:47]
	v_mfma_f32_16x16x32_bf16 v[40:43], v[164:167], v[180:183], v[40:43]
	v_mfma_f32_16x16x32_bf16 v[28:31], v[150:153], v[194:197], v[28:31]
	v_mfma_f32_16x16x32_bf16 v[24:27], v[164:167], v[194:197], v[24:27]
	v_mfma_f32_16x16x32_bf16 v[12:15], v[150:153], v[202:205], v[12:15]
	v_mfma_f32_16x16x32_bf16 v[8:11], v[164:167], v[202:205], v[8:11]
	s_setprio 0
	s_barrier
	s_add_i32 s4, s5, s50
	s_mov_b32 m0, s4
	s_add_u32 s0, s44, 0x20080
	s_addc_u32 s1, s45, 0
	global_load_lds_dwordx4 v130, s[0:1]
	v_lshl_add_u64 v[146:147], s[0:1], 0, v[134:135]
	s_add_i32 m0, s4, 0x2000
	s_nop 0
	global_load_lds_dwordx4 v134, s[0:1]
	s_waitcnt vmcnt(6)
	s_barrier
	s_setprio 1
	v_mfma_f32_16x16x32_bf16 v[52:55], v[206:209], v[168:171], v[52:55]
	v_mfma_f32_16x16x32_bf16 v[48:51], v[214:217], v[168:171], v[48:51]
	v_mfma_f32_16x16x32_bf16 v[36:39], v[206:209], v[176:179], v[36:39]
	v_mfma_f32_16x16x32_bf16 v[32:35], v[214:217], v[176:179], v[32:35]
	v_mfma_f32_16x16x32_bf16 v[20:23], v[206:209], v[188:191], v[20:23]
	v_mfma_f32_16x16x32_bf16 v[16:19], v[214:217], v[188:191], v[16:19]
	v_mfma_f32_16x16x32_bf16 v[4:7], v[206:209], v[198:201], v[4:7]
	v_mfma_f32_16x16x32_bf16 v[0:3], v[214:217], v[198:201], v[0:3]
	v_mfma_f32_16x16x32_bf16 v[52:55], v[210:213], v[172:175], v[52:55]
	v_mfma_f32_16x16x32_bf16 v[48:51], v[218:221], v[172:175], v[48:51]
	v_mfma_f32_16x16x32_bf16 v[36:39], v[210:213], v[180:183], v[36:39]
	v_mfma_f32_16x16x32_bf16 v[32:35], v[218:221], v[180:183], v[32:35]
	v_mfma_f32_16x16x32_bf16 v[20:23], v[210:213], v[194:197], v[20:23]
	v_mfma_f32_16x16x32_bf16 v[16:19], v[218:221], v[194:197], v[16:19]
	v_mfma_f32_16x16x32_bf16 v[4:7], v[210:213], v[202:205], v[4:7]
	v_mfma_f32_16x16x32_bf16 v[0:3], v[218:221], v[202:205], v[0:3]
	s_setprio 0
	s_add_i32 s79, s79, 2
	s_add_u32 s42, s42, 0x100
	s_addc_u32 s43, s43, 0
	s_add_u32 s35, s35, 0x100
	s_addc_u32 s41, s41, 0
	s_cmp_gt_u32 s79, 5
	s_barrier
	s_cbranch_scc0 .LBB0_984
	s_branch .Lpeel_done_984
.LBB0_984:
	ds_read_b128 v[146:149], v156
	ds_read_b128 v[150:153], v156 offset:1024
	ds_read_b128 v[160:163], v156 offset:2048
	ds_read_b128 v[164:167], v156 offset:3072
	s_add_i32 m0, s55, 0xc000
	ds_read_b128 v[168:171], v158
	ds_read_b128 v[172:175], v158 offset:1024
	ds_read_b128 v[176:179], v158 offset:2048
	ds_read_b128 v[180:183], v158 offset:3072
	ds_read_b128 v[188:191], v158 offset:4096
	ds_read_b128 v[194:197], v158 offset:5120
	ds_read_b128 v[198:201], v158 offset:6144
	global_load_lds_dwordx4 v138, s[42:43]
	s_add_i32 m0, s55, 0xe000
	ds_read_b128 v[202:205], v158 offset:7168
	global_load_lds_dwordx4 v140, s[42:43]
	s_add_u32 s0, s42, 0xfffe0080
	s_addc_u32 s1, s43, -1
	s_cmp_eq_u32 s79, 4
	s_cselect_b32 s47, s9, s1
	s_cselect_b32 s46, s31, s0
	s_cselect_b32 s45, s29, s41
	s_cselect_b32 s44, s34, s35
	s_waitcnt lgkmcnt(8)
	s_barrier
	s_waitcnt lgkmcnt(0)
	s_setprio 1
	v_mfma_f32_16x16x32_bf16 v[124:127], v[146:149], v[168:171], v[124:127]
	v_mfma_f32_16x16x32_bf16 v[120:123], v[160:163], v[168:171], v[120:123]
	v_mfma_f32_16x16x32_bf16 v[108:111], v[146:149], v[176:179], v[108:111]
	v_mfma_f32_16x16x32_bf16 v[104:107], v[160:163], v[176:179], v[104:107]
	v_mfma_f32_16x16x32_bf16 v[92:95], v[146:149], v[188:191], v[92:95]
	v_mfma_f32_16x16x32_bf16 v[88:91], v[160:163], v[188:191], v[88:91]
	v_mfma_f32_16x16x32_bf16 v[76:79], v[146:149], v[198:201], v[76:79]
	v_mfma_f32_16x16x32_bf16 v[72:75], v[160:163], v[198:201], v[72:75]
	v_mfma_f32_16x16x32_bf16 v[124:127], v[150:153], v[172:175], v[124:127]
	v_mfma_f32_16x16x32_bf16 v[120:123], v[164:167], v[172:175], v[120:123]
	v_mfma_f32_16x16x32_bf16 v[108:111], v[150:153], v[180:183], v[108:111]
	v_mfma_f32_16x16x32_bf16 v[104:107], v[164:167], v[180:183], v[104:107]
	v_mfma_f32_16x16x32_bf16 v[92:95], v[150:153], v[194:197], v[92:95]
	v_mfma_f32_16x16x32_bf16 v[88:91], v[164:167], v[194:197], v[88:91]
	v_mfma_f32_16x16x32_bf16 v[76:79], v[150:153], v[202:205], v[76:79]
	v_mfma_f32_16x16x32_bf16 v[72:75], v[164:167], v[202:205], v[72:75]
	s_setprio 0
	s_barrier
	s_add_i32 s0, s66, s50
	s_mov_b32 m0, s0
	ds_read_b128 v[206:209], v159
	ds_read_b128 v[210:213], v159 offset:1024
	ds_read_b128 v[214:217], v159 offset:2048
	global_load_lds_dwordx4 v130, s[44:45]
	s_add_i32 m0, s0, 0x2000
	ds_read_b128 v[218:221], v159 offset:3072
	global_load_lds_dwordx4 v134, s[44:45]
	s_barrier
; #define PG8_STAGE(bufoff, gbase, voff) do { _Pragma("unroll") for (int _i = 0; _i < 2; ++_i) \
;         __builtin_amdgcn_global_load_lds((const unsigned*)((const char*)(gbase) + (voff)[_i]), (LAS unsigned*)(lds + (bufoff) + ldsw + _i * 8192), 16, 0, 0); } while (0)
; #define PG8_LDA(dst, b, h) do { _Pragma("unroll") for (int m = 0; m < 4; ++m) _Pragma("unroll") for (int k = 0; k < 2; ++k) dst[m][k] = *(const LAS bf16x8*)(lds + PG8_SA(b, h) + aoff + m * 2048 + k * 1024); } while (0)
; #define PG8_LDB(dst, b, h) do { _Pragma("unroll") for (int n = 0; n < 2; ++n) _Pragma("unroll") for (int k = 0; k < 2; ++k) dst[n][k] = *(const LAS bf16x8*)(lds + PG8_SB(b, h) + boff + n * 2048 + k * 1024); } while (0)
; #define PG8_WAIT_V(n) asm volatile("s_waitcnt vmcnt(" #n ")" ::: "memory")
; #define PG8_WAIT_L(n) asm volatile("s_waitcnt lgkmcnt(" #n ")" ::: "memory")
; #define PG8_BAR __builtin_amdgcn_s_barrier()
; #define PG8_SCHED __builtin_amdgcn_sched_barrier(0)
; template <class Epi, class Sched>
; DI void gemm_phase(LAS unsigned char* lds, const Gemm g, const Sched& S, const Epi& E) {
;     ...
;             PG8_LDB(B0, 0, 0); PG8_SCHED; PG8_LDA(At, 0, 0); PG8_STAGE(PG8_SA(1, 1), a1 + hstep, voffA);
;             PG8_WAIT_L(8); PG8_BAR; PG8_WAIT_L(0); PG8_MMA(0, 0, At, B0); PG8_BAR; PG8_SCHED;
;             PG8_LDB(B1, 0, 1); PG8_STAGE(PG8_SB(0, 0), b2, voffB);
;             PG8_BAR; PG8_WAIT_L(0); PG8_MMA(0, 1, At, B1); PG8_BAR;
;             PG8_LDA(At, 0, 1); PG8_STAGE(PG8_SA(0, 0), a2, voffA);
;             PG8_BAR; PG8_WAIT_L(0); PG8_MMA(1, 0, At, B0); PG8_BAR; PG8_SCHED;
;             PG8_STAGE(PG8_SB(0, 1), b2 + hstep, voffB);
;             PG8_WAIT_V(6); PG8_BAR; PG8_MMA(1, 1, At, B1); PG8_BAR;
;             PG8_LDB(B0, 1, 0); PG8_SCHED; PG8_LDA(At, 1, 0); PG8_STAGE(PG8_SA(0, 1), a2 + hstep, voffA);
;             PG8_WAIT_L(8); PG8_BAR; PG8_WAIT_L(0); PG8_MMA(0, 0, At, B0); PG8_BAR; PG8_SCHED;
;             PG8_LDB(B1, 1, 1); PG8_STAGE(PG8_SB(1, 0), b3, voffB);
;             PG8_BAR; PG8_WAIT_L(0); PG8_MMA(0, 1, At, B1); PG8_BAR;
;             PG8_LDA(At, 1, 1); PG8_STAGE(PG8_SA(1, 0), a3, voffA);
;             PG8_BAR; PG8_WAIT_L(0); PG8_MMA(1, 0, At, B0); PG8_BAR; PG8_SCHED;
;             PG8_STAGE(PG8_SB(1, 1), b3 + hstep, voffB);
;             PG8_WAIT_V(6); PG8_BAR; PG8_MMA(1, 1, At, B1); PG8_BAR;
	s_waitcnt lgkmcnt(0)
	s_setprio 1
	v_mfma_f32_16x16x32_bf16 v[116:119], v[206:209], v[168:171], v[116:119]
	v_mfma_f32_16x16x32_bf16 v[112:115], v[214:217], v[168:171], v[112:115]
	v_mfma_f32_16x16x32_bf16 v[100:103], v[206:209], v[176:179], v[100:103]
	v_mfma_f32_16x16x32_bf16 v[96:99], v[214:217], v[176:179], v[96:99]
	v_mfma_f32_16x16x32_bf16 v[84:87], v[206:209], v[188:191], v[84:87]
	v_mfma_f32_16x16x32_bf16 v[80:83], v[214:217], v[188:191], v[80:83]
	v_mfma_f32_16x16x32_bf16 v[68:71], v[206:209], v[198:201], v[68:71]
	v_mfma_f32_16x16x32_bf16 v[64:67], v[214:217], v[198:201], v[64:67]
	v_mfma_f32_16x16x32_bf16 v[116:119], v[210:213], v[172:175], v[116:119]
	v_mfma_f32_16x16x32_bf16 v[112:115], v[218:221], v[172:175], v[112:115]
	v_mfma_f32_16x16x32_bf16 v[100:103], v[210:213], v[180:183], v[100:103]
	v_mfma_f32_16x16x32_bf16 v[96:99], v[218:221], v[180:183], v[96:99]
	v_mfma_f32_16x16x32_bf16 v[84:87], v[210:213], v[194:197], v[84:87]
	v_mfma_f32_16x16x32_bf16 v[80:83], v[218:221], v[194:197], v[80:83]
	v_mfma_f32_16x16x32_bf16 v[68:71], v[210:213], v[202:205], v[68:71]
	v_mfma_f32_16x16x32_bf16 v[64:67], v[218:221], v[202:205], v[64:67]
	s_setprio 0
	s_mov_b32 m0, s55
	s_barrier
	ds_read_b128 v[168:171], v158 offset:16384
	ds_read_b128 v[172:175], v158 offset:17408
	ds_read_b128 v[176:179], v158 offset:18432
	ds_read_b128 v[180:183], v158 offset:19456
	ds_read_b128 v[188:191], v158 offset:20480
	ds_read_b128 v[194:197], v158 offset:21504
	ds_read_b128 v[198:201], v158 offset:22528
	global_load_lds_dwordx4 v128, s[46:47]
	s_mov_b32 m0, s56
	ds_read_b128 v[202:205], v158 offset:23552
	global_load_lds_dwordx4 v132, s[46:47]
	s_barrier
	s_waitcnt lgkmcnt(0)
	s_setprio 1
	v_mfma_f32_16x16x32_bf16 v[60:63], v[146:149], v[168:171], v[60:63]
	v_mfma_f32_16x16x32_bf16 v[56:59], v[160:163], v[168:171], v[56:59]
	v_mfma_f32_16x16x32_bf16 v[44:47], v[146:149], v[176:179], v[44:47]
	v_mfma_f32_16x16x32_bf16 v[40:43], v[160:163], v[176:179], v[40:43]
	v_mfma_f32_16x16x32_bf16 v[28:31], v[146:149], v[188:191], v[28:31]
	v_mfma_f32_16x16x32_bf16 v[24:27], v[160:163], v[188:191], v[24:27]
	v_mfma_f32_16x16x32_bf16 v[12:15], v[146:149], v[198:201], v[12:15]
	v_mfma_f32_16x16x32_bf16 v[8:11], v[160:163], v[198:201], v[8:11]
	v_mfma_f32_16x16x32_bf16 v[60:63], v[150:153], v[172:175], v[60:63]
	v_mfma_f32_16x16x32_bf16 v[56:59], v[164:167], v[172:175], v[56:59]
	v_mfma_f32_16x16x32_bf16 v[44:47], v[150:153], v[180:183], v[44:47]
	v_mfma_f32_16x16x32_bf16 v[40:43], v[164:167], v[180:183], v[40:43]
	v_mfma_f32_16x16x32_bf16 v[28:31], v[150:153], v[194:197], v[28:31]
	v_mfma_f32_16x16x32_bf16 v[24:27], v[164:167], v[194:197], v[24:27]
	v_mfma_f32_16x16x32_bf16 v[12:15], v[150:153], v[202:205], v[12:15]
	v_mfma_f32_16x16x32_bf16 v[8:11], v[164:167], v[202:205], v[8:11]
	s_setprio 0
	s_barrier
	s_add_i32 s4, s67, s50
	s_mov_b32 m0, s4
	s_add_u32 s0, s44, 0x20000
	s_addc_u32 s1, s45, 0
	global_load_lds_dwordx4 v130, s[0:1]
	s_add_i32 m0, s4, 0x2000
	s_nop 0
	global_load_lds_dwordx4 v134, s[0:1]
	s_waitcnt vmcnt(6)
	s_barrier
	s_setprio 1
	v_mfma_f32_16x16x32_bf16 v[52:55], v[206:209], v[168:171], v[52:55]
	v_mfma_f32_16x16x32_bf16 v[48:51], v[214:217], v[168:171], v[48:51]
	v_mfma_f32_16x16x32_bf16 v[36:39], v[206:209], v[176:179], v[36:39]
	v_mfma_f32_16x16x32_bf16 v[32:35], v[214:217], v[176:179], v[32:35]
	v_mfma_f32_16x16x32_bf16 v[20:23], v[206:209], v[188:191], v[20:23]
	v_mfma_f32_16x16x32_bf16 v[16:19], v[214:217], v[188:191], v[16:19]
	v_mfma_f32_16x16x32_bf16 v[4:7], v[206:209], v[198:201], v[4:7]
	v_mfma_f32_16x16x32_bf16 v[0:3], v[214:217], v[198:201], v[0:3]
	v_mfma_f32_16x16x32_bf16 v[52:55], v[210:213], v[172:175], v[52:55]
	v_mfma_f32_16x16x32_bf16 v[48:51], v[218:221], v[172:175], v[48:51]
	v_mfma_f32_16x16x32_bf16 v[36:39], v[210:213], v[180:183], v[36:39]
	v_mfma_f32_16x16x32_bf16 v[32:35], v[218:221], v[180:183], v[32:35]
	v_mfma_f32_16x16x32_bf16 v[20:23], v[210:213], v[194:197], v[20:23]
	v_mfma_f32_16x16x32_bf16 v[16:19], v[218:221], v[194:197], v[16:19]
	v_mfma_f32_16x16x32_bf16 v[4:7], v[210:213], v[202:205], v[4:7]
	v_mfma_f32_16x16x32_bf16 v[0:3], v[218:221], v[202:205], v[0:3]
	s_setprio 0
	s_add_i32 s4, 0, 0x18000
	s_barrier
	ds_read_b128 v[146:149], v222
	ds_read_b128 v[150:153], v222 offset:1024
	ds_read_b128 v[160:163], v222 offset:2048
	ds_read_b128 v[164:167], v222 offset:3072
	s_add_u32 s0, s46, 0x20000
	s_addc_u32 s1, s47, 0
	s_mov_b32 m0, s57
	ds_read_b128 v[168:171], v158 offset:32768
	ds_read_b128 v[172:175], v158 offset:33792
	ds_read_b128 v[176:179], v158 offset:34816
	ds_read_b128 v[180:183], v158 offset:35840
	ds_read_b128 v[188:191], v158 offset:36864
	ds_read_b128 v[194:197], v158 offset:37888
	ds_read_b128 v[198:201], v158 offset:38912
	global_load_lds_dwordx4 v128, s[0:1]
	s_mov_b32 m0, s58
	ds_read_b128 v[202:205], v158 offset:39936
	global_load_lds_dwordx4 v132, s[0:1]
	s_waitcnt lgkmcnt(8)
	s_barrier
; #define PG8_STAGE(bufoff, gbase, voff) do { _Pragma("unroll") for (int _i = 0; _i < 2; ++_i) \
;         __builtin_amdgcn_global_load_lds((const unsigned*)((const char*)(gbase) + (voff)[_i]), (LAS unsigned*)(lds + (bufoff) + ldsw + _i * 8192), 16, 0, 0); } while (0)
; #define PG8_LDA(dst, b, h) do { _Pragma("unroll") for (int m = 0; m < 4; ++m) _Pragma("unroll") for (int k = 0; k < 2; ++k) dst[m][k] = *(const LAS bf16x8*)(lds + PG8_SA(b, h) + aoff + m * 2048 + k * 1024); } while (0)
; #define PG8_LDB(dst, b, h) do { _Pragma("unroll") for (int n = 0; n < 2; ++n) _Pragma("unroll") for (int k = 0; k < 2; ++k) dst[n][k] = *(const LAS bf16x8*)(lds + PG8_SB(b, h) + boff + n * 2048 + k * 1024); } while (0)
; #define PG8_MMA(ai, bj, At, Bt) do { __builtin_amdgcn_s_setprio(1); _Pragma("unroll") for (int m = 0; m < 4; ++m) _Pragma("unroll") for (int n = 0; n < 2; ++n) _Pragma("unroll") for (int k = 0; k < 2; ++k) \
;         acc[ai][bj][m][n] = __builtin_amdgcn_mfma_f32_16x16x32_bf16(Bt[n][k], At[m][k], acc[ai][bj][m][n], 0, 0, 0); __builtin_amdgcn_s_setprio(0); } while (0)
; #define PG8_WAIT_V(n) asm volatile("s_waitcnt vmcnt(" #n ")" ::: "memory")
; #define PG8_WAIT_L(n) asm volatile("s_waitcnt lgkmcnt(" #n ")" ::: "memory")
; #define PG8_BAR __builtin_amdgcn_s_barrier()
; #define PG8_SCHED __builtin_amdgcn_sched_barrier(0)
; template <class Epi, class Sched>
; DI void gemm_phase(LAS unsigned char* lds, const Gemm g, const Sched& S, const Epi& E) {
;     ...
;             PG8_WAIT_L(8); PG8_BAR; PG8_WAIT_L(0); PG8_MMA(0, 0, At, B0); PG8_BAR; PG8_SCHED;
;             PG8_LDB(B1, 1, 1); PG8_STAGE(PG8_SB(1, 0), b3, voffB);
;             PG8_BAR; PG8_WAIT_L(0); PG8_MMA(0, 1, At, B1); PG8_BAR;
;             PG8_LDA(At, 1, 1); PG8_STAGE(PG8_SA(1, 0), a3, voffA);
;             PG8_BAR; PG8_WAIT_L(0); PG8_MMA(1, 0, At, B0); PG8_BAR; PG8_SCHED;
;             PG8_STAGE(PG8_SB(1, 1), b3 + hstep, voffB);
;             PG8_WAIT_V(6); PG8_BAR; PG8_MMA(1, 1, At, B1); PG8_BAR;
	s_waitcnt lgkmcnt(0)
	s_setprio 1
	v_mfma_f32_16x16x32_bf16 v[124:127], v[146:149], v[168:171], v[124:127]
	v_mfma_f32_16x16x32_bf16 v[120:123], v[160:163], v[168:171], v[120:123]
	v_mfma_f32_16x16x32_bf16 v[108:111], v[146:149], v[176:179], v[108:111]
	v_mfma_f32_16x16x32_bf16 v[104:107], v[160:163], v[176:179], v[104:107]
	v_mfma_f32_16x16x32_bf16 v[92:95], v[146:149], v[188:191], v[92:95]
	v_mfma_f32_16x16x32_bf16 v[88:91], v[160:163], v[188:191], v[88:91]
	v_mfma_f32_16x16x32_bf16 v[76:79], v[146:149], v[198:201], v[76:79]
	v_mfma_f32_16x16x32_bf16 v[72:75], v[160:163], v[198:201], v[72:75]
	v_mfma_f32_16x16x32_bf16 v[124:127], v[150:153], v[172:175], v[124:127]
	v_mfma_f32_16x16x32_bf16 v[120:123], v[164:167], v[172:175], v[120:123]
	v_mfma_f32_16x16x32_bf16 v[108:111], v[150:153], v[180:183], v[108:111]
	v_mfma_f32_16x16x32_bf16 v[104:107], v[164:167], v[180:183], v[104:107]
	v_mfma_f32_16x16x32_bf16 v[92:95], v[150:153], v[194:197], v[92:95]
	v_mfma_f32_16x16x32_bf16 v[88:91], v[164:167], v[194:197], v[88:91]
	v_mfma_f32_16x16x32_bf16 v[76:79], v[150:153], v[202:205], v[76:79]
	v_mfma_f32_16x16x32_bf16 v[72:75], v[164:167], v[202:205], v[72:75]
	s_setprio 0
	s_barrier
	s_add_i32 s5, 0, 0x1c000
	s_add_i32 s0, s4, s50
	s_add_i32 m0, s0, 0xffffff80
	ds_read_b128 v[206:209], v223
	ds_read_b128 v[210:213], v223 offset:1024
	ds_read_b128 v[214:217], v223 offset:2048
	global_load_lds_dwordx4 v130, s[44:45] offset:128
	s_add_i32 m0, s0, 0x1f80
	ds_read_b128 v[218:221], v223 offset:3072
	global_load_lds_dwordx4 v134, s[44:45] offset:128
	s_barrier
	s_waitcnt lgkmcnt(0)
	s_setprio 1
	v_mfma_f32_16x16x32_bf16 v[116:119], v[206:209], v[168:171], v[116:119]
	v_mfma_f32_16x16x32_bf16 v[112:115], v[214:217], v[168:171], v[112:115]
	v_mfma_f32_16x16x32_bf16 v[100:103], v[206:209], v[176:179], v[100:103]
	v_mfma_f32_16x16x32_bf16 v[96:99], v[214:217], v[176:179], v[96:99]
	v_mfma_f32_16x16x32_bf16 v[84:87], v[206:209], v[188:191], v[84:87]
	v_mfma_f32_16x16x32_bf16 v[80:83], v[214:217], v[188:191], v[80:83]
	v_mfma_f32_16x16x32_bf16 v[68:71], v[206:209], v[198:201], v[68:71]
	v_mfma_f32_16x16x32_bf16 v[64:67], v[214:217], v[198:201], v[64:67]
	v_mfma_f32_16x16x32_bf16 v[116:119], v[210:213], v[172:175], v[116:119]
	v_mfma_f32_16x16x32_bf16 v[112:115], v[218:221], v[172:175], v[112:115]
	v_mfma_f32_16x16x32_bf16 v[100:103], v[210:213], v[180:183], v[100:103]
	v_mfma_f32_16x16x32_bf16 v[96:99], v[218:221], v[180:183], v[96:99]
	v_mfma_f32_16x16x32_bf16 v[84:87], v[210:213], v[194:197], v[84:87]
	v_mfma_f32_16x16x32_bf16 v[80:83], v[218:221], v[194:197], v[80:83]
	v_mfma_f32_16x16x32_bf16 v[68:71], v[210:213], v[202:205], v[68:71]
	v_mfma_f32_16x16x32_bf16 v[64:67], v[218:221], v[202:205], v[64:67]
	s_setprio 0
	s_add_i32 m0, s62, 0xffffff80
	s_barrier
	ds_read_b128 v[168:171], v158 offset:49152
	ds_read_b128 v[172:175], v158 offset:50176
	ds_read_b128 v[176:179], v158 offset:51200
	ds_read_b128 v[180:183], v158 offset:52224
	ds_read_b128 v[188:191], v158 offset:53248
	ds_read_b128 v[194:197], v158 offset:54272
	ds_read_b128 v[198:201], v158 offset:55296
	global_load_lds_dwordx4 v128, s[46:47] offset:128
	s_add_i32 m0, s63, 0xffffff80
	ds_read_b128 v[202:205], v158 offset:56320
	global_load_lds_dwordx4 v132, s[46:47] offset:128
	s_barrier
	s_waitcnt lgkmcnt(0)
	s_setprio 1
	v_mfma_f32_16x16x32_bf16 v[60:63], v[146:149], v[168:171], v[60:63]
	v_mfma_f32_16x16x32_bf16 v[56:59], v[160:163], v[168:171], v[56:59]
	v_mfma_f32_16x16x32_bf16 v[44:47], v[146:149], v[176:179], v[44:47]
	v_mfma_f32_16x16x32_bf16 v[40:43], v[160:163], v[176:179], v[40:43]
	v_mfma_f32_16x16x32_bf16 v[28:31], v[146:149], v[188:191], v[28:31]
	v_mfma_f32_16x16x32_bf16 v[24:27], v[160:163], v[188:191], v[24:27]
	v_mfma_f32_16x16x32_bf16 v[12:15], v[146:149], v[198:201], v[12:15]
	v_mfma_f32_16x16x32_bf16 v[8:11], v[160:163], v[198:201], v[8:11]
	v_mfma_f32_16x16x32_bf16 v[60:63], v[150:153], v[172:175], v[60:63]
	v_mfma_f32_16x16x32_bf16 v[56:59], v[164:167], v[172:175], v[56:59]
	v_mfma_f32_16x16x32_bf16 v[44:47], v[150:153], v[180:183], v[44:47]
	v_mfma_f32_16x16x32_bf16 v[40:43], v[164:167], v[180:183], v[40:43]
	v_mfma_f32_16x16x32_bf16 v[28:31], v[150:153], v[194:197], v[28:31]
	v_mfma_f32_16x16x32_bf16 v[24:27], v[164:167], v[194:197], v[24:27]
	v_mfma_f32_16x16x32_bf16 v[12:15], v[150:153], v[202:205], v[12:15]
	v_mfma_f32_16x16x32_bf16 v[8:11], v[164:167], v[202:205], v[8:11]
	s_setprio 0
	s_barrier
	s_add_i32 s4, s5, s50
	s_mov_b32 m0, s4
	s_add_u32 s0, s44, 0x20080
	s_addc_u32 s1, s45, 0
	global_load_lds_dwordx4 v130, s[0:1]
	v_lshl_add_u64 v[146:147], s[0:1], 0, v[134:135]
	s_add_i32 m0, s4, 0x2000
	s_nop 0
	global_load_lds_dwordx4 v134, s[0:1]
	s_waitcnt vmcnt(6)
	s_barrier
	s_setprio 1
	v_mfma_f32_16x16x32_bf16 v[52:55], v[206:209], v[168:171], v[52:55]
	v_mfma_f32_16x16x32_bf16 v[48:51], v[214:217], v[168:171], v[48:51]
	v_mfma_f32_16x16x32_bf16 v[36:39], v[206:209], v[176:179], v[36:39]
	v_mfma_f32_16x16x32_bf16 v[32:35], v[214:217], v[176:179], v[32:35]
	v_mfma_f32_16x16x32_bf16 v[20:23], v[206:209], v[188:191], v[20:23]
	v_mfma_f32_16x16x32_bf16 v[16:19], v[214:217], v[188:191], v[16:19]
	v_mfma_f32_16x16x32_bf16 v[4:7], v[206:209], v[198:201], v[4:7]
	v_mfma_f32_16x16x32_bf16 v[0:3], v[214:217], v[198:201], v[0:3]
	v_mfma_f32_16x16x32_bf16 v[52:55], v[210:213], v[172:175], v[52:55]
	v_mfma_f32_16x16x32_bf16 v[48:51], v[218:221], v[172:175], v[48:51]
	v_mfma_f32_16x16x32_bf16 v[36:39], v[210:213], v[180:183], v[36:39]
	v_mfma_f32_16x16x32_bf16 v[32:35], v[218:221], v[180:183], v[32:35]
	v_mfma_f32_16x16x32_bf16 v[20:23], v[210:213], v[194:197], v[20:23]
	v_mfma_f32_16x16x32_bf16 v[16:19], v[218:221], v[194:197], v[16:19]
	v_mfma_f32_16x16x32_bf16 v[4:7], v[210:213], v[202:205], v[4:7]
	v_mfma_f32_16x16x32_bf16 v[0:3], v[218:221], v[202:205], v[0:3]
	s_setprio 0
	s_add_i32 s79, s79, 2
	s_add_u32 s42, s42, 0x100
	s_addc_u32 s43, s43, 0
	s_add_u32 s35, s35, 0x100
	s_addc_u32 s41, s41, 0
	s_cmp_gt_u32 s79, 5
	s_barrier
	s_cbranch_scc0 .LBB0_984

;     DI size_t aoff(const Unit& u, size_t tstep) const { return (size_t)u.pm * tstep; }
;     DI size_t boff(const Unit& u, size_t tstep) const { return (size_t)u.pn * tstep; }
;     DI bool next(int i, Unit& u) const { const long L = (long)i * G + c; if (L >= np) return false; u.pm = pmv; u.pn = (int)(L % nN); u.ks = (int)(L / nN); return true; }
;     DI size_t aoff(const Unit& u, size_t) const { return (size_t)u.ks * kbytes; }
;     DI size_t boff(const Unit& u, size_t tstep) const { return (size_t)u.pn * tstep + (size_t)u.ks * kbytes; }
;     DI bool next(int i, Unit& u) const { Unit t; if (!S.next(i / 3, t)) return false; u.pm = t.pm; u.pn = t.pn; u.ks = i % 3; return true; }
;     DI size_t aoff(const Unit& u, size_t tstep) const { return (u.ks < 2 ? offU : offOA) + (size_t)u.pm * tstep; }
; #define PG8_LDA(dst, b, h) do { _Pragma("unroll") for (int m = 0; m < 4; ++m) _Pragma("unroll") for (int k = 0; k < 2; ++k) dst[m][k] = *(const LAS bf16x8*)(lds + PG8_SA(b, h) + aoff + m * 2048 + k * 1024); } while (0)
; template <class Epi, class Sched>
; DI void gemm_phase(LAS unsigned char* lds, const Gemm g, const Sched& S, const Epi& E) {
;     ...
;         const bool has_next = S.next(ui + 1, nxt);
;         const char* nA = has_next ? (const char*)g.A + S.aoff(nxt, tstep) : cA; const char* nB = has_next ? (const char*)g.Bt + S.boff(nxt, tstep) : cB;
;         for (int t = 0; t < nt; t += 2) {
;             if constexpr (Epi::HAS_MID) { if (t == E.mid_t(nt)) { int fr3 = fr, fq3 = fq; asm volatile("" : "+v"(fr3), "+v"(fq3)); E.mid(acc, cur, wr, wc, fr3, fq3); } }
;             const bool last = (t == nt - 2);
;             const char* a1 = cA + (size_t)(t + 1) * kstep;
;             const char* a2 = last ? nA : cA + (size_t)(t + 2) * kstep; const char* b2 = last ? nB : cB + (size_t)(t + 2) * kstep;
;             const char* a3 = a2 + kstep; const char* b3 = b2 + kstep;
;             PG8_LDB(B0, 0, 0); PG8_SCHED; PG8_LDA(At, 0, 0); PG8_STAGE(PG8_SA(1, 1), a1 + hstep, voffA);
;             PG8_WAIT_L(8); PG8_BAR; PG8_WAIT_L(0); PG8_MMA(0, 0, At, B0); PG8_BAR; PG8_SCHED;
;             PG8_LDB(B1, 0, 1); PG8_STAGE(PG8_SB(0, 0), b2, voffB);
;             PG8_BAR; PG8_WAIT_L(0); PG8_MMA(0, 1, At, B1); PG8_BAR;
;             PG8_LDA(At, 0, 1); PG8_STAGE(PG8_SA(0, 0), a2, voffA);
;             PG8_BAR; PG8_WAIT_L(0); PG8_MMA(1, 0, At, B0); PG8_BAR; PG8_SCHED;
.LBB0_1507:
	s_ashr_i32 s37, s36, 31
	s_lshl_b64 s[0:1], s[36:37], 20
	v_cmp_lt_i64_e32 vcc, s[38:39], v[140:141]
	s_add_u32 s38, s13, s0
	s_addc_u32 s39, s50, s1
	s_and_b64 s[0:1], vcc, exec
	s_cselect_b32 s34, s39, s45
	s_cselect_b32 s35, s38, s44
	s_ashr_i32 s31, s30, 31
	s_lshl_b64 s[0:1], s[30:31], 20
	s_add_u32 s40, s55, s0
	s_addc_u32 s41, s56, s1
	s_and_b64 s[0:1], vcc, exec
	s_cselect_b32 s31, s41, s47
	s_cselect_b32 s37, s40, s46
	s_add_u32 s44, s44, 0x80080
	s_addc_u32 s45, s45, 0
	s_add_u32 s43, s46, 0x100
	v_mov_b32_e32 v0, 0
	s_addc_u32 s68, s47, 0
	s_mov_b32 s69, -2
	s_waitcnt lgkmcnt(0)
	ds_read_b128 v[144:147], v150
	ds_read_b128 v[154:157], v150 offset:1024
	ds_read_b128 v[158:161], v150 offset:2048
	ds_read_b128 v[162:165], v150 offset:3072
	s_add_i32 m0, s52, 0xc000
	ds_read_b128 v[166:169], v151
	ds_read_b128 v[170:173], v151 offset:1024
	ds_read_b128 v[174:177], v151 offset:2048
	ds_read_b128 v[178:181], v151 offset:3072
	ds_read_b128 v[188:191], v151 offset:4096
	ds_read_b128 v[206:209], v151 offset:5120
	ds_read_b128 v[210:213], v151 offset:6144
	global_load_lds_dwordx4 v136, s[44:45]
	s_add_i32 m0, s52, 0xe000
	ds_read_b128 v[214:217], v151 offset:7168
	global_load_lds_dwordx4 v138, s[44:45]
	s_add_u32 s0, s44, 0xfff80080
	s_addc_u32 s1, s45, -1
	s_cmp_eq_u32 s69, 28
	s_cselect_b32 s49, s34, s1
	s_cselect_b32 s48, s35, s0
	s_cselect_b32 s47, s31, s68
	s_cselect_b32 s46, s37, s43
	s_waitcnt lgkmcnt(8)
	s_barrier
	s_waitcnt lgkmcnt(0)
	s_setprio 1
	v_mfma_f32_16x16x32_bf16 v[124:127], v[144:147], v[166:169], 0
	v_mfma_f32_16x16x32_bf16 v[120:123], v[158:161], v[166:169], 0
	v_mfma_f32_16x16x32_bf16 v[108:111], v[144:147], v[174:177], 0
	v_mfma_f32_16x16x32_bf16 v[104:107], v[158:161], v[174:177], 0
	v_mfma_f32_16x16x32_bf16 v[92:95], v[144:147], v[188:191], 0
	v_mfma_f32_16x16x32_bf16 v[88:91], v[158:161], v[188:191], 0
	v_mfma_f32_16x16x32_bf16 v[76:79], v[144:147], v[210:213], 0
	v_mfma_f32_16x16x32_bf16 v[72:75], v[158:161], v[210:213], 0
	v_mfma_f32_16x16x32_bf16 v[124:127], v[154:157], v[170:173], v[124:127]
	v_mfma_f32_16x16x32_bf16 v[120:123], v[162:165], v[170:173], v[120:123]
	v_mfma_f32_16x16x32_bf16 v[108:111], v[154:157], v[178:181], v[108:111]
	v_mfma_f32_16x16x32_bf16 v[104:107], v[162:165], v[178:181], v[104:107]
	v_mfma_f32_16x16x32_bf16 v[92:95], v[154:157], v[206:209], v[92:95]
	v_mfma_f32_16x16x32_bf16 v[88:91], v[162:165], v[206:209], v[88:91]
	v_mfma_f32_16x16x32_bf16 v[76:79], v[154:157], v[214:217], v[76:79]
	v_mfma_f32_16x16x32_bf16 v[72:75], v[162:165], v[214:217], v[72:75]
	s_setprio 0
	s_barrier
	s_add_i32 s0, s65, s51
	s_mov_b32 m0, s0
	ds_read_b128 v[218:221], v152
	ds_read_b128 v[222:225], v152 offset:1024
	ds_read_b128 v[226:229], v152 offset:2048
	global_load_lds_dwordx4 v132, s[46:47]
	s_add_i32 m0, s0, 0x2000
	ds_read_b128 v[230:233], v152 offset:3072
	global_load_lds_dwordx4 v134, s[46:47]
	s_barrier
	s_waitcnt lgkmcnt(0)
	s_setprio 1
	v_mfma_f32_16x16x32_bf16 v[116:119], v[218:221], v[166:169], 0
	v_mfma_f32_16x16x32_bf16 v[112:115], v[226:229], v[166:169], 0
	v_mfma_f32_16x16x32_bf16 v[100:103], v[218:221], v[174:177], 0
	v_mfma_f32_16x16x32_bf16 v[96:99], v[226:229], v[174:177], 0
	v_mfma_f32_16x16x32_bf16 v[84:87], v[218:221], v[188:191], 0
	v_mfma_f32_16x16x32_bf16 v[80:83], v[226:229], v[188:191], 0
	v_mfma_f32_16x16x32_bf16 v[68:71], v[218:221], v[210:213], 0
	v_mfma_f32_16x16x32_bf16 v[64:67], v[226:229], v[210:213], 0
	v_mfma_f32_16x16x32_bf16 v[116:119], v[222:225], v[170:173], v[116:119]
	v_mfma_f32_16x16x32_bf16 v[112:115], v[230:233], v[170:173], v[112:115]
	v_mfma_f32_16x16x32_bf16 v[100:103], v[222:225], v[178:181], v[100:103]
	v_mfma_f32_16x16x32_bf16 v[96:99], v[230:233], v[178:181], v[96:99]
	v_mfma_f32_16x16x32_bf16 v[84:87], v[222:225], v[206:209], v[84:87]
	v_mfma_f32_16x16x32_bf16 v[80:83], v[230:233], v[206:209], v[80:83]
	v_mfma_f32_16x16x32_bf16 v[68:71], v[222:225], v[214:217], v[68:71]
	v_mfma_f32_16x16x32_bf16 v[64:67], v[230:233], v[214:217], v[64:67]
	s_setprio 0
	s_mov_b32 m0, s52
	s_barrier
	ds_read_b128 v[166:169], v151 offset:16384
	ds_read_b128 v[170:173], v151 offset:17408
	ds_read_b128 v[174:177], v151 offset:18432
	ds_read_b128 v[178:181], v151 offset:19456
	ds_read_b128 v[188:191], v151 offset:20480
	ds_read_b128 v[206:209], v151 offset:21504
	ds_read_b128 v[210:213], v151 offset:22528
	global_load_lds_dwordx4 v128, s[48:49]
	s_mov_b32 m0, s53
	ds_read_b128 v[214:217], v151 offset:23552
	global_load_lds_dwordx4 v130, s[48:49]
	s_barrier
	s_waitcnt lgkmcnt(0)
	s_setprio 1
	v_mfma_f32_16x16x32_bf16 v[60:63], v[144:147], v[166:169], 0
	v_mfma_f32_16x16x32_bf16 v[56:59], v[158:161], v[166:169], 0
	v_mfma_f32_16x16x32_bf16 v[44:47], v[144:147], v[174:177], 0
	v_mfma_f32_16x16x32_bf16 v[40:43], v[158:161], v[174:177], 0
	v_mfma_f32_16x16x32_bf16 v[28:31], v[144:147], v[188:191], 0
	v_mfma_f32_16x16x32_bf16 v[24:27], v[158:161], v[188:191], 0
	v_mfma_f32_16x16x32_bf16 v[12:15], v[144:147], v[210:213], 0
	v_mfma_f32_16x16x32_bf16 v[8:11], v[158:161], v[210:213], 0
	v_mfma_f32_16x16x32_bf16 v[60:63], v[154:157], v[170:173], v[60:63]
	v_mfma_f32_16x16x32_bf16 v[56:59], v[162:165], v[170:173], v[56:59]
	v_mfma_f32_16x16x32_bf16 v[44:47], v[154:157], v[178:181], v[44:47]
	v_mfma_f32_16x16x32_bf16 v[40:43], v[162:165], v[178:181], v[40:43]
	v_mfma_f32_16x16x32_bf16 v[28:31], v[154:157], v[206:209], v[28:31]
	v_mfma_f32_16x16x32_bf16 v[24:27], v[162:165], v[206:209], v[24:27]
	v_mfma_f32_16x16x32_bf16 v[12:15], v[154:157], v[214:217], v[12:15]
	v_mfma_f32_16x16x32_bf16 v[8:11], v[162:165], v[214:217], v[8:11]
	s_setprio 0
	s_barrier
; #define PG8_STAGE(bufoff, gbase, voff) do { _Pragma("unroll") for (int _i = 0; _i < 2; ++_i) \
;         __builtin_amdgcn_global_load_lds((const unsigned*)((const char*)(gbase) + (voff)[_i]), (LAS unsigned*)(lds + (bufoff) + ldsw + _i * 8192), 16, 0, 0); } while (0)
; #define PG8_LDA(dst, b, h) do { _Pragma("unroll") for (int m = 0; m < 4; ++m) _Pragma("unroll") for (int k = 0; k < 2; ++k) dst[m][k] = *(const LAS bf16x8*)(lds + PG8_SA(b, h) + aoff + m * 2048 + k * 1024); } while (0)
; #define PG8_LDB(dst, b, h) do { _Pragma("unroll") for (int n = 0; n < 2; ++n) _Pragma("unroll") for (int k = 0; k < 2; ++k) dst[n][k] = *(const LAS bf16x8*)(lds + PG8_SB(b, h) + boff + n * 2048 + k * 1024); } while (0)
; #define PG8_MMA(ai, bj, At, Bt) do { __builtin_amdgcn_s_setprio(1); _Pragma("unroll") for (int m = 0; m < 4; ++m) _Pragma("unroll") for (int n = 0; n < 2; ++n) _Pragma("unroll") for (int k = 0; k < 2; ++k) \
;         acc[ai][bj][m][n] = __builtin_amdgcn_mfma_f32_16x16x32_bf16(Bt[n][k], At[m][k], acc[ai][bj][m][n], 0, 0, 0); __builtin_amdgcn_s_setprio(0); } while (0)
; #define PG8_WAIT_V(n) asm volatile("s_waitcnt vmcnt(" #n ")" ::: "memory")
; #define PG8_WAIT_L(n) asm volatile("s_waitcnt lgkmcnt(" #n ")" ::: "memory")
; #define PG8_BAR __builtin_amdgcn_s_barrier()
; #define PG8_SCHED __builtin_amdgcn_sched_barrier(0)
; template <class Epi, class Sched>
; DI void gemm_phase(LAS unsigned char* lds, const Gemm g, const Sched& S, const Epi& E) {
;     ...
;             PG8_STAGE(PG8_SB(0, 1), b2 + hstep, voffB);
;             PG8_WAIT_V(6); PG8_BAR; PG8_MMA(1, 1, At, B1); PG8_BAR;
;             PG8_LDB(B0, 1, 0); PG8_SCHED; PG8_LDA(At, 1, 0); PG8_STAGE(PG8_SA(0, 1), a2 + hstep, voffA);
;             PG8_WAIT_L(8); PG8_BAR; PG8_WAIT_L(0); PG8_MMA(0, 0, At, B0); PG8_BAR; PG8_SCHED;
;             PG8_LDB(B1, 1, 1); PG8_STAGE(PG8_SB(1, 0), b3, voffB);
;             PG8_BAR; PG8_WAIT_L(0); PG8_MMA(0, 1, At, B1); PG8_BAR;
;             PG8_LDA(At, 1, 1); PG8_STAGE(PG8_SA(1, 0), a3, voffA);
;             PG8_BAR; PG8_WAIT_L(0); PG8_MMA(1, 0, At, B0); PG8_BAR; PG8_SCHED;
	s_add_i32 s4, s66, s51
	s_mov_b32 m0, s4
	s_add_u32 s0, s46, 0x80000
	s_addc_u32 s1, s47, 0
	global_load_lds_dwordx4 v132, s[0:1]
	s_add_i32 m0, s4, 0x2000
	s_nop 0
	global_load_lds_dwordx4 v134, s[0:1]
	s_waitcnt vmcnt(6)
	s_barrier
	s_setprio 1
	v_mfma_f32_16x16x32_bf16 v[52:55], v[218:221], v[166:169], 0
	v_mfma_f32_16x16x32_bf16 v[48:51], v[226:229], v[166:169], 0
	v_mfma_f32_16x16x32_bf16 v[36:39], v[218:221], v[174:177], 0
	v_mfma_f32_16x16x32_bf16 v[32:35], v[226:229], v[174:177], 0
	v_mfma_f32_16x16x32_bf16 v[20:23], v[218:221], v[188:191], 0
	v_mfma_f32_16x16x32_bf16 v[16:19], v[226:229], v[188:191], 0
	v_mfma_f32_16x16x32_bf16 v[4:7], v[218:221], v[210:213], 0
	v_mfma_f32_16x16x32_bf16 v[0:3], v[226:229], v[210:213], 0
	v_mfma_f32_16x16x32_bf16 v[52:55], v[222:225], v[170:173], v[52:55]
	v_mfma_f32_16x16x32_bf16 v[48:51], v[230:233], v[170:173], v[48:51]
	v_mfma_f32_16x16x32_bf16 v[36:39], v[222:225], v[178:181], v[36:39]
	v_mfma_f32_16x16x32_bf16 v[32:35], v[230:233], v[178:181], v[32:35]
	v_mfma_f32_16x16x32_bf16 v[20:23], v[222:225], v[206:209], v[20:23]
	v_mfma_f32_16x16x32_bf16 v[16:19], v[230:233], v[206:209], v[16:19]
	v_mfma_f32_16x16x32_bf16 v[4:7], v[222:225], v[214:217], v[4:7]
	v_mfma_f32_16x16x32_bf16 v[0:3], v[230:233], v[214:217], v[0:3]
	s_setprio 0
	s_add_i32 s4, 0, 0x18000
	v_add_u32_e32 v162, s4, v149
	s_barrier
	ds_read_b128 v[144:147], v162
	ds_read_b128 v[154:157], v162 offset:1024
	ds_read_b128 v[158:161], v162 offset:2048
	ds_read_b128 v[162:165], v162 offset:3072
	s_add_u32 s0, s48, 0x80000
	s_addc_u32 s1, s49, 0
	s_mov_b32 m0, s58
	ds_read_b128 v[166:169], v151 offset:32768
	ds_read_b128 v[170:173], v151 offset:33792
	ds_read_b128 v[174:177], v151 offset:34816
	ds_read_b128 v[178:181], v151 offset:35840
	ds_read_b128 v[188:191], v151 offset:36864
	ds_read_b128 v[206:209], v151 offset:37888
	ds_read_b128 v[210:213], v151 offset:38912
	global_load_lds_dwordx4 v128, s[0:1]
	s_mov_b32 m0, s59
	ds_read_b128 v[214:217], v151 offset:39936
	global_load_lds_dwordx4 v130, s[0:1]
	s_waitcnt lgkmcnt(8)
	s_barrier
	s_waitcnt lgkmcnt(0)
	s_setprio 1
	v_mfma_f32_16x16x32_bf16 v[124:127], v[144:147], v[166:169], v[124:127]
	v_mfma_f32_16x16x32_bf16 v[120:123], v[158:161], v[166:169], v[120:123]
	v_mfma_f32_16x16x32_bf16 v[108:111], v[144:147], v[174:177], v[108:111]
	v_mfma_f32_16x16x32_bf16 v[104:107], v[158:161], v[174:177], v[104:107]
	v_mfma_f32_16x16x32_bf16 v[92:95], v[144:147], v[188:191], v[92:95]
	v_mfma_f32_16x16x32_bf16 v[88:91], v[158:161], v[188:191], v[88:91]
	v_mfma_f32_16x16x32_bf16 v[76:79], v[144:147], v[210:213], v[76:79]
	v_mfma_f32_16x16x32_bf16 v[72:75], v[158:161], v[210:213], v[72:75]
	v_mfma_f32_16x16x32_bf16 v[124:127], v[154:157], v[170:173], v[124:127]
	v_mfma_f32_16x16x32_bf16 v[120:123], v[162:165], v[170:173], v[120:123]
	v_mfma_f32_16x16x32_bf16 v[108:111], v[154:157], v[178:181], v[108:111]
	v_mfma_f32_16x16x32_bf16 v[104:107], v[162:165], v[178:181], v[104:107]
	v_mfma_f32_16x16x32_bf16 v[92:95], v[154:157], v[206:209], v[92:95]
	v_mfma_f32_16x16x32_bf16 v[88:91], v[162:165], v[206:209], v[88:91]
	v_mfma_f32_16x16x32_bf16 v[76:79], v[154:157], v[214:217], v[76:79]
	v_mfma_f32_16x16x32_bf16 v[72:75], v[162:165], v[214:217], v[72:75]
	s_setprio 0
	s_barrier
	s_add_i32 s5, 0, 0x1c000
	s_add_i32 s0, s4, s51
	v_add_u32_e32 v201, s5, v149
	s_add_i32 m0, s0, 0xffffff80
	ds_read_b128 v[218:221], v201
	ds_read_b128 v[222:225], v201 offset:1024
	ds_read_b128 v[226:229], v201 offset:2048
	global_load_lds_dwordx4 v132, s[46:47] offset:128
	s_add_i32 m0, s0, 0x1f80
	ds_read_b128 v[230:233], v201 offset:3072
	global_load_lds_dwordx4 v134, s[46:47] offset:128
	s_barrier
	s_waitcnt lgkmcnt(0)
	s_setprio 1
	v_mfma_f32_16x16x32_bf16 v[116:119], v[218:221], v[166:169], v[116:119]
	v_mfma_f32_16x16x32_bf16 v[112:115], v[226:229], v[166:169], v[112:115]
	v_mfma_f32_16x16x32_bf16 v[100:103], v[218:221], v[174:177], v[100:103]
	v_mfma_f32_16x16x32_bf16 v[96:99], v[226:229], v[174:177], v[96:99]
	v_mfma_f32_16x16x32_bf16 v[84:87], v[218:221], v[188:191], v[84:87]
	v_mfma_f32_16x16x32_bf16 v[80:83], v[226:229], v[188:191], v[80:83]
	v_mfma_f32_16x16x32_bf16 v[68:71], v[218:221], v[210:213], v[68:71]
	v_mfma_f32_16x16x32_bf16 v[64:67], v[226:229], v[210:213], v[64:67]
	v_mfma_f32_16x16x32_bf16 v[116:119], v[222:225], v[170:173], v[116:119]
	v_mfma_f32_16x16x32_bf16 v[112:115], v[230:233], v[170:173], v[112:115]
	v_mfma_f32_16x16x32_bf16 v[100:103], v[222:225], v[178:181], v[100:103]
	v_mfma_f32_16x16x32_bf16 v[96:99], v[230:233], v[178:181], v[96:99]
	v_mfma_f32_16x16x32_bf16 v[84:87], v[222:225], v[206:209], v[84:87]
	v_mfma_f32_16x16x32_bf16 v[80:83], v[230:233], v[206:209], v[80:83]
	v_mfma_f32_16x16x32_bf16 v[68:71], v[222:225], v[214:217], v[68:71]
	v_mfma_f32_16x16x32_bf16 v[64:67], v[230:233], v[214:217], v[64:67]
	s_setprio 0
	s_add_i32 m0, s63, 0xffffff80
	s_barrier
	ds_read_b128 v[166:169], v151 offset:49152
	ds_read_b128 v[170:173], v151 offset:50176
	ds_read_b128 v[174:177], v151 offset:51200
	ds_read_b128 v[178:181], v151 offset:52224
	ds_read_b128 v[188:191], v151 offset:53248
	ds_read_b128 v[206:209], v151 offset:54272
	ds_read_b128 v[210:213], v151 offset:55296
	global_load_lds_dwordx4 v128, s[48:49] offset:128
	s_add_i32 m0, s64, 0xffffff80
	ds_read_b128 v[214:217], v151 offset:56320
	global_load_lds_dwordx4 v130, s[48:49] offset:128
	s_barrier
; #define PG8_STAGE(bufoff, gbase, voff) do { _Pragma("unroll") for (int _i = 0; _i < 2; ++_i) \
;         __builtin_amdgcn_global_load_lds((const unsigned*)((const char*)(gbase) + (voff)[_i]), (LAS unsigned*)(lds + (bufoff) + ldsw + _i * 8192), 16, 0, 0); } while (0)
; #define PG8_LDA(dst, b, h) do { _Pragma("unroll") for (int m = 0; m < 4; ++m) _Pragma("unroll") for (int k = 0; k < 2; ++k) dst[m][k] = *(const LAS bf16x8*)(lds + PG8_SA(b, h) + aoff + m * 2048 + k * 1024); } while (0)
; #define PG8_LDB(dst, b, h) do { _Pragma("unroll") for (int n = 0; n < 2; ++n) _Pragma("unroll") for (int k = 0; k < 2; ++k) dst[n][k] = *(const LAS bf16x8*)(lds + PG8_SB(b, h) + boff + n * 2048 + k * 1024); } while (0)
; #define PG8_WAIT_V(n) asm volatile("s_waitcnt vmcnt(" #n ")" ::: "memory")
; #define PG8_WAIT_L(n) asm volatile("s_waitcnt lgkmcnt(" #n ")" ::: "memory")
; #define PG8_BAR __builtin_amdgcn_s_barrier()
; #define PG8_SCHED __builtin_amdgcn_sched_barrier(0)
; template <class Epi, class Sched>
; DI void gemm_phase(LAS unsigned char* lds, const Gemm g, const Sched& S, const Epi& E) {
;     ...
;             PG8_LDB(B0, 0, 0); PG8_SCHED; PG8_LDA(At, 0, 0); PG8_STAGE(PG8_SA(1, 1), a1 + hstep, voffA);
;             PG8_WAIT_L(8); PG8_BAR; PG8_WAIT_L(0); PG8_MMA(0, 0, At, B0); PG8_BAR; PG8_SCHED;
;             PG8_LDB(B1, 0, 1); PG8_STAGE(PG8_SB(0, 0), b2, voffB);
;             PG8_BAR; PG8_WAIT_L(0); PG8_MMA(0, 1, At, B1); PG8_BAR;
;             PG8_LDA(At, 0, 1); PG8_STAGE(PG8_SA(0, 0), a2, voffA);
;             PG8_BAR; PG8_WAIT_L(0); PG8_MMA(1, 0, At, B0); PG8_BAR; PG8_SCHED;
;             PG8_STAGE(PG8_SB(0, 1), b2 + hstep, voffB);
;             PG8_WAIT_V(6); PG8_BAR; PG8_MMA(1, 1, At, B1); PG8_BAR;
;             PG8_LDB(B0, 1, 0); PG8_SCHED; PG8_LDA(At, 1, 0); PG8_STAGE(PG8_SA(0, 1), a2 + hstep, voffA);
;             PG8_WAIT_L(8); PG8_BAR; PG8_WAIT_L(0); PG8_MMA(0, 0, At, B0); PG8_BAR; PG8_SCHED;
;             PG8_LDB(B1, 1, 1); PG8_STAGE(PG8_SB(1, 0), b3, voffB);
;             PG8_BAR; PG8_WAIT_L(0); PG8_MMA(0, 1, At, B1); PG8_BAR;
;             PG8_LDA(At, 1, 1); PG8_STAGE(PG8_SA(1, 0), a3, voffA);
;             PG8_BAR; PG8_WAIT_L(0); PG8_MMA(1, 0, At, B0); PG8_BAR; PG8_SCHED;
;             PG8_STAGE(PG8_SB(1, 1), b3 + hstep, voffB);
;             PG8_WAIT_V(6); PG8_BAR; PG8_MMA(1, 1, At, B1); PG8_BAR;
	s_waitcnt lgkmcnt(0)
	s_setprio 1
	v_mfma_f32_16x16x32_bf16 v[60:63], v[144:147], v[166:169], v[60:63]
	v_mfma_f32_16x16x32_bf16 v[56:59], v[158:161], v[166:169], v[56:59]
	v_mfma_f32_16x16x32_bf16 v[44:47], v[144:147], v[174:177], v[44:47]
	v_mfma_f32_16x16x32_bf16 v[40:43], v[158:161], v[174:177], v[40:43]
	v_mfma_f32_16x16x32_bf16 v[28:31], v[144:147], v[188:191], v[28:31]
	v_mfma_f32_16x16x32_bf16 v[24:27], v[158:161], v[188:191], v[24:27]
	v_mfma_f32_16x16x32_bf16 v[12:15], v[144:147], v[210:213], v[12:15]
	v_mfma_f32_16x16x32_bf16 v[8:11], v[158:161], v[210:213], v[8:11]
	v_mfma_f32_16x16x32_bf16 v[60:63], v[154:157], v[170:173], v[60:63]
	v_mfma_f32_16x16x32_bf16 v[56:59], v[162:165], v[170:173], v[56:59]
	v_mfma_f32_16x16x32_bf16 v[44:47], v[154:157], v[178:181], v[44:47]
	v_mfma_f32_16x16x32_bf16 v[40:43], v[162:165], v[178:181], v[40:43]
	v_mfma_f32_16x16x32_bf16 v[28:31], v[154:157], v[206:209], v[28:31]
	v_mfma_f32_16x16x32_bf16 v[24:27], v[162:165], v[206:209], v[24:27]
	v_mfma_f32_16x16x32_bf16 v[12:15], v[154:157], v[214:217], v[12:15]
	v_mfma_f32_16x16x32_bf16 v[8:11], v[162:165], v[214:217], v[8:11]
	s_setprio 0
	s_barrier
	s_add_i32 s4, s5, s51
	s_mov_b32 m0, s4
	s_add_u32 s0, s46, 0x80080
	s_addc_u32 s1, s47, 0
	global_load_lds_dwordx4 v132, s[0:1]
	s_add_i32 m0, s4, 0x2000
	s_nop 0
	global_load_lds_dwordx4 v134, s[0:1]
	s_waitcnt vmcnt(6)
	s_barrier
	s_setprio 1
	v_mfma_f32_16x16x32_bf16 v[52:55], v[218:221], v[166:169], v[52:55]
	v_mfma_f32_16x16x32_bf16 v[48:51], v[226:229], v[166:169], v[48:51]
	v_mfma_f32_16x16x32_bf16 v[36:39], v[218:221], v[174:177], v[36:39]
	v_mfma_f32_16x16x32_bf16 v[32:35], v[226:229], v[174:177], v[32:35]
	v_mfma_f32_16x16x32_bf16 v[20:23], v[218:221], v[188:191], v[20:23]
	v_mfma_f32_16x16x32_bf16 v[16:19], v[226:229], v[188:191], v[16:19]
	v_mfma_f32_16x16x32_bf16 v[4:7], v[218:221], v[210:213], v[4:7]
	v_mfma_f32_16x16x32_bf16 v[0:3], v[226:229], v[210:213], v[0:3]
	v_mfma_f32_16x16x32_bf16 v[52:55], v[222:225], v[170:173], v[52:55]
	v_mfma_f32_16x16x32_bf16 v[48:51], v[230:233], v[170:173], v[48:51]
	v_mfma_f32_16x16x32_bf16 v[36:39], v[222:225], v[178:181], v[36:39]
	v_mfma_f32_16x16x32_bf16 v[32:35], v[230:233], v[178:181], v[32:35]
	v_mfma_f32_16x16x32_bf16 v[20:23], v[222:225], v[206:209], v[20:23]
	v_mfma_f32_16x16x32_bf16 v[16:19], v[230:233], v[206:209], v[16:19]
	v_mfma_f32_16x16x32_bf16 v[4:7], v[222:225], v[214:217], v[4:7]
	v_mfma_f32_16x16x32_bf16 v[0:3], v[230:233], v[214:217], v[0:3]
	s_setprio 0
	s_add_i32 s69, s69, 2
	s_add_u32 s44, s44, 0x100
	s_addc_u32 s45, s45, 0
	s_add_u32 s43, s43, 0x100
	s_addc_u32 s68, s68, 0
	s_cmp_gt_u32 s69, 29
	s_barrier
	s_cbranch_scc0 .LBB0_1508
	s_branch .Lpeel_done_1508
.LBB0_1508:
	ds_read_b128 v[144:147], v150
	ds_read_b128 v[154:157], v150 offset:1024
	ds_read_b128 v[158:161], v150 offset:2048
	ds_read_b128 v[162:165], v150 offset:3072
	s_add_i32 m0, s52, 0xc000
	ds_read_b128 v[166:169], v151
	ds_read_b128 v[170:173], v151 offset:1024
	ds_read_b128 v[174:177], v151 offset:2048
	ds_read_b128 v[178:181], v151 offset:3072
	ds_read_b128 v[188:191], v151 offset:4096
	ds_read_b128 v[206:209], v151 offset:5120
	ds_read_b128 v[210:213], v151 offset:6144
	global_load_lds_dwordx4 v136, s[44:45]
	s_add_i32 m0, s52, 0xe000
	ds_read_b128 v[214:217], v151 offset:7168
	global_load_lds_dwordx4 v138, s[44:45]
	s_add_u32 s0, s44, 0xfff80080
	s_addc_u32 s1, s45, -1
	s_cmp_eq_u32 s69, 28
	s_cselect_b32 s49, s34, s1
	s_cselect_b32 s48, s35, s0
	s_cselect_b32 s47, s31, s68
	s_cselect_b32 s46, s37, s43
	s_waitcnt lgkmcnt(8)
	s_barrier
	s_waitcnt lgkmcnt(0)
	s_setprio 1
	v_mfma_f32_16x16x32_bf16 v[124:127], v[144:147], v[166:169], v[124:127]
	v_mfma_f32_16x16x32_bf16 v[120:123], v[158:161], v[166:169], v[120:123]
	v_mfma_f32_16x16x32_bf16 v[108:111], v[144:147], v[174:177], v[108:111]
	v_mfma_f32_16x16x32_bf16 v[104:107], v[158:161], v[174:177], v[104:107]
	v_mfma_f32_16x16x32_bf16 v[92:95], v[144:147], v[188:191], v[92:95]
	v_mfma_f32_16x16x32_bf16 v[88:91], v[158:161], v[188:191], v[88:91]
	v_mfma_f32_16x16x32_bf16 v[76:79], v[144:147], v[210:213], v[76:79]
	v_mfma_f32_16x16x32_bf16 v[72:75], v[158:161], v[210:213], v[72:75]
	v_mfma_f32_16x16x32_bf16 v[124:127], v[154:157], v[170:173], v[124:127]
	v_mfma_f32_16x16x32_bf16 v[120:123], v[162:165], v[170:173], v[120:123]
	v_mfma_f32_16x16x32_bf16 v[108:111], v[154:157], v[178:181], v[108:111]
	v_mfma_f32_16x16x32_bf16 v[104:107], v[162:165], v[178:181], v[104:107]
	v_mfma_f32_16x16x32_bf16 v[92:95], v[154:157], v[206:209], v[92:95]
	v_mfma_f32_16x16x32_bf16 v[88:91], v[162:165], v[206:209], v[88:91]
	v_mfma_f32_16x16x32_bf16 v[76:79], v[154:157], v[214:217], v[76:79]
	v_mfma_f32_16x16x32_bf16 v[72:75], v[162:165], v[214:217], v[72:75]
	s_setprio 0
	s_barrier
	s_add_i32 s0, s65, s51
	s_mov_b32 m0, s0
	ds_read_b128 v[218:221], v152
	ds_read_b128 v[222:225], v152 offset:1024
	ds_read_b128 v[226:229], v152 offset:2048
	global_load_lds_dwordx4 v132, s[46:47]
	s_add_i32 m0, s0, 0x2000
	ds_read_b128 v[230:233], v152 offset:3072
	global_load_lds_dwordx4 v134, s[46:47]
	s_barrier
; #define PG8_STAGE(bufoff, gbase, voff) do { _Pragma("unroll") for (int _i = 0; _i < 2; ++_i) \
;         __builtin_amdgcn_global_load_lds((const unsigned*)((const char*)(gbase) + (voff)[_i]), (LAS unsigned*)(lds + (bufoff) + ldsw + _i * 8192), 16, 0, 0); } while (0)
; #define PG8_LDA(dst, b, h) do { _Pragma("unroll") for (int m = 0; m < 4; ++m) _Pragma("unroll") for (int k = 0; k < 2; ++k) dst[m][k] = *(const LAS bf16x8*)(lds + PG8_SA(b, h) + aoff + m * 2048 + k * 1024); } while (0)
; #define PG8_LDB(dst, b, h) do { _Pragma("unroll") for (int n = 0; n < 2; ++n) _Pragma("unroll") for (int k = 0; k < 2; ++k) dst[n][k] = *(const LAS bf16x8*)(lds + PG8_SB(b, h) + boff + n * 2048 + k * 1024); } while (0)
; #define PG8_MMA(ai, bj, At, Bt) do { __builtin_amdgcn_s_setprio(1); _Pragma("unroll") for (int m = 0; m < 4; ++m) _Pragma("unroll") for (int n = 0; n < 2; ++n) _Pragma("unroll") for (int k = 0; k < 2; ++k) \
;         acc[ai][bj][m][n] = __builtin_amdgcn_mfma_f32_16x16x32_bf16(Bt[n][k], At[m][k], acc[ai][bj][m][n], 0, 0, 0); __builtin_amdgcn_s_setprio(0); } while (0)
; #define PG8_WAIT_V(n) asm volatile("s_waitcnt vmcnt(" #n ")" ::: "memory")
; #define PG8_WAIT_L(n) asm volatile("s_waitcnt lgkmcnt(" #n ")" ::: "memory")
; #define PG8_BAR __builtin_amdgcn_s_barrier()
; #define PG8_SCHED __builtin_amdgcn_sched_barrier(0)
; template <class Epi, class Sched>
; DI void gemm_phase(LAS unsigned char* lds, const Gemm g, const Sched& S, const Epi& E) {
;     ...
;             PG8_BAR; PG8_WAIT_L(0); PG8_MMA(0, 1, At, B1); PG8_BAR;
;             PG8_LDA(At, 0, 1); PG8_STAGE(PG8_SA(0, 0), a2, voffA);
;             PG8_BAR; PG8_WAIT_L(0); PG8_MMA(1, 0, At, B0); PG8_BAR; PG8_SCHED;
;             PG8_STAGE(PG8_SB(0, 1), b2 + hstep, voffB);
;             PG8_WAIT_V(6); PG8_BAR; PG8_MMA(1, 1, At, B1); PG8_BAR;
;             PG8_LDB(B0, 1, 0); PG8_SCHED; PG8_LDA(At, 1, 0); PG8_STAGE(PG8_SA(0, 1), a2 + hstep, voffA);
	s_waitcnt lgkmcnt(0)
	s_setprio 1
	v_mfma_f32_16x16x32_bf16 v[116:119], v[218:221], v[166:169], v[116:119]
	v_mfma_f32_16x16x32_bf16 v[112:115], v[226:229], v[166:169], v[112:115]
	v_mfma_f32_16x16x32_bf16 v[100:103], v[218:221], v[174:177], v[100:103]
	v_mfma_f32_16x16x32_bf16 v[96:99], v[226:229], v[174:177], v[96:99]
	v_mfma_f32_16x16x32_bf16 v[84:87], v[218:221], v[188:191], v[84:87]
	v_mfma_f32_16x16x32_bf16 v[80:83], v[226:229], v[188:191], v[80:83]
	v_mfma_f32_16x16x32_bf16 v[68:71], v[218:221], v[210:213], v[68:71]
	v_mfma_f32_16x16x32_bf16 v[64:67], v[226:229], v[210:213], v[64:67]
	v_mfma_f32_16x16x32_bf16 v[116:119], v[222:225], v[170:173], v[116:119]
	v_mfma_f32_16x16x32_bf16 v[112:115], v[230:233], v[170:173], v[112:115]
	v_mfma_f32_16x16x32_bf16 v[100:103], v[222:225], v[178:181], v[100:103]
	v_mfma_f32_16x16x32_bf16 v[96:99], v[230:233], v[178:181], v[96:99]
	v_mfma_f32_16x16x32_bf16 v[84:87], v[222:225], v[206:209], v[84:87]
	v_mfma_f32_16x16x32_bf16 v[80:83], v[230:233], v[206:209], v[80:83]
	v_mfma_f32_16x16x32_bf16 v[68:71], v[222:225], v[214:217], v[68:71]
	v_mfma_f32_16x16x32_bf16 v[64:67], v[230:233], v[214:217], v[64:67]
	s_setprio 0
	s_mov_b32 m0, s52
	s_barrier
	ds_read_b128 v[166:169], v151 offset:16384
	ds_read_b128 v[170:173], v151 offset:17408
	ds_read_b128 v[174:177], v151 offset:18432
	ds_read_b128 v[178:181], v151 offset:19456
	ds_read_b128 v[188:191], v151 offset:20480
	ds_read_b128 v[206:209], v151 offset:21504
	ds_read_b128 v[210:213], v151 offset:22528
	global_load_lds_dwordx4 v128, s[48:49]
	s_mov_b32 m0, s53
	ds_read_b128 v[214:217], v151 offset:23552
	global_load_lds_dwordx4 v130, s[48:49]
	s_barrier
	s_waitcnt lgkmcnt(0)
	s_setprio 1
	v_mfma_f32_16x16x32_bf16 v[60:63], v[144:147], v[166:169], v[60:63]
	v_mfma_f32_16x16x32_bf16 v[56:59], v[158:161], v[166:169], v[56:59]
	v_mfma_f32_16x16x32_bf16 v[44:47], v[144:147], v[174:177], v[44:47]
	v_mfma_f32_16x16x32_bf16 v[40:43], v[158:161], v[174:177], v[40:43]
	v_mfma_f32_16x16x32_bf16 v[28:31], v[144:147], v[188:191], v[28:31]
	v_mfma_f32_16x16x32_bf16 v[24:27], v[158:161], v[188:191], v[24:27]
	v_mfma_f32_16x16x32_bf16 v[12:15], v[144:147], v[210:213], v[12:15]
	v_mfma_f32_16x16x32_bf16 v[8:11], v[158:161], v[210:213], v[8:11]
	v_mfma_f32_16x16x32_bf16 v[60:63], v[154:157], v[170:173], v[60:63]
	v_mfma_f32_16x16x32_bf16 v[56:59], v[162:165], v[170:173], v[56:59]
	v_mfma_f32_16x16x32_bf16 v[44:47], v[154:157], v[178:181], v[44:47]
	v_mfma_f32_16x16x32_bf16 v[40:43], v[162:165], v[178:181], v[40:43]
	v_mfma_f32_16x16x32_bf16 v[28:31], v[154:157], v[206:209], v[28:31]
	v_mfma_f32_16x16x32_bf16 v[24:27], v[162:165], v[206:209], v[24:27]
	v_mfma_f32_16x16x32_bf16 v[12:15], v[154:157], v[214:217], v[12:15]
	v_mfma_f32_16x16x32_bf16 v[8:11], v[162:165], v[214:217], v[8:11]
	s_setprio 0
	s_barrier
	s_add_i32 s4, s66, s51
	s_mov_b32 m0, s4
	s_add_u32 s0, s46, 0x80000
	s_addc_u32 s1, s47, 0
	global_load_lds_dwordx4 v132, s[0:1]
	s_add_i32 m0, s4, 0x2000
	s_nop 0
	global_load_lds_dwordx4 v134, s[0:1]
	s_waitcnt vmcnt(6)
	s_barrier
	s_setprio 1
	v_mfma_f32_16x16x32_bf16 v[52:55], v[218:221], v[166:169], v[52:55]
	v_mfma_f32_16x16x32_bf16 v[48:51], v[226:229], v[166:169], v[48:51]
	v_mfma_f32_16x16x32_bf16 v[36:39], v[218:221], v[174:177], v[36:39]
	v_mfma_f32_16x16x32_bf16 v[32:35], v[226:229], v[174:177], v[32:35]
	v_mfma_f32_16x16x32_bf16 v[20:23], v[218:221], v[188:191], v[20:23]
	v_mfma_f32_16x16x32_bf16 v[16:19], v[226:229], v[188:191], v[16:19]
	v_mfma_f32_16x16x32_bf16 v[4:7], v[218:221], v[210:213], v[4:7]
	v_mfma_f32_16x16x32_bf16 v[0:3], v[226:229], v[210:213], v[0:3]
	v_mfma_f32_16x16x32_bf16 v[52:55], v[222:225], v[170:173], v[52:55]
	v_mfma_f32_16x16x32_bf16 v[48:51], v[230:233], v[170:173], v[48:51]
	v_mfma_f32_16x16x32_bf16 v[36:39], v[222:225], v[178:181], v[36:39]
	v_mfma_f32_16x16x32_bf16 v[32:35], v[230:233], v[178:181], v[32:35]
	v_mfma_f32_16x16x32_bf16 v[20:23], v[222:225], v[206:209], v[20:23]
	v_mfma_f32_16x16x32_bf16 v[16:19], v[230:233], v[206:209], v[16:19]
	v_mfma_f32_16x16x32_bf16 v[4:7], v[222:225], v[214:217], v[4:7]
	v_mfma_f32_16x16x32_bf16 v[0:3], v[230:233], v[214:217], v[0:3]
	s_setprio 0
	s_add_i32 s4, 0, 0x18000
	v_add_u32_e32 v162, s4, v149
	s_barrier
	ds_read_b128 v[144:147], v162
	ds_read_b128 v[154:157], v162 offset:1024
	ds_read_b128 v[158:161], v162 offset:2048
	ds_read_b128 v[162:165], v162 offset:3072
	s_add_u32 s0, s48, 0x80000
	s_addc_u32 s1, s49, 0
	s_mov_b32 m0, s58
	ds_read_b128 v[166:169], v151 offset:32768
	ds_read_b128 v[170:173], v151 offset:33792
	ds_read_b128 v[174:177], v151 offset:34816
	ds_read_b128 v[178:181], v151 offset:35840
	ds_read_b128 v[188:191], v151 offset:36864
	ds_read_b128 v[206:209], v151 offset:37888
	ds_read_b128 v[210:213], v151 offset:38912
	global_load_lds_dwordx4 v128, s[0:1]
	s_mov_b32 m0, s59
	ds_read_b128 v[214:217], v151 offset:39936
	global_load_lds_dwordx4 v130, s[0:1]
	s_waitcnt lgkmcnt(8)
	s_barrier
; #define PG8_STAGE(bufoff, gbase, voff) do { _Pragma("unroll") for (int _i = 0; _i < 2; ++_i) \
;         __builtin_amdgcn_global_load_lds((const unsigned*)((const char*)(gbase) + (voff)[_i]), (LAS unsigned*)(lds + (bufoff) + ldsw + _i * 8192), 16, 0, 0); } while (0)
; #define PG8_LDA(dst, b, h) do { _Pragma("unroll") for (int m = 0; m < 4; ++m) _Pragma("unroll") for (int k = 0; k < 2; ++k) dst[m][k] = *(const LAS bf16x8*)(lds + PG8_SA(b, h) + aoff + m * 2048 + k * 1024); } while (0)
; #define PG8_LDB(dst, b, h) do { _Pragma("unroll") for (int n = 0; n < 2; ++n) _Pragma("unroll") for (int k = 0; k < 2; ++k) dst[n][k] = *(const LAS bf16x8*)(lds + PG8_SB(b, h) + boff + n * 2048 + k * 1024); } while (0)
; #define PG8_MMA(ai, bj, At, Bt) do { __builtin_amdgcn_s_setprio(1); _Pragma("unroll") for (int m = 0; m < 4; ++m) _Pragma("unroll") for (int n = 0; n < 2; ++n) _Pragma("unroll") for (int k = 0; k < 2; ++k) \
;         acc[ai][bj][m][n] = __builtin_amdgcn_mfma_f32_16x16x32_bf16(Bt[n][k], At[m][k], acc[ai][bj][m][n], 0, 0, 0); __builtin_amdgcn_s_setprio(0); } while (0)
; #define PG8_WAIT_V(n) asm volatile("s_waitcnt vmcnt(" #n ")" ::: "memory")
; #define PG8_WAIT_L(n) asm volatile("s_waitcnt lgkmcnt(" #n ")" ::: "memory")
; #define PG8_BAR __builtin_amdgcn_s_barrier()
; #define PG8_SCHED __builtin_amdgcn_sched_barrier(0)
; template <class Epi, class Sched>
; DI void gemm_phase(LAS unsigned char* lds, const Gemm g, const Sched& S, const Epi& E) {
;     ...
;             PG8_WAIT_L(8); PG8_BAR; PG8_WAIT_L(0); PG8_MMA(0, 0, At, B0); PG8_BAR; PG8_SCHED;
;             PG8_LDB(B1, 1, 1); PG8_STAGE(PG8_SB(1, 0), b3, voffB);
;             PG8_BAR; PG8_WAIT_L(0); PG8_MMA(0, 1, At, B1); PG8_BAR;
;             PG8_LDA(At, 1, 1); PG8_STAGE(PG8_SA(1, 0), a3, voffA);
;             PG8_BAR; PG8_WAIT_L(0); PG8_MMA(1, 0, At, B0); PG8_BAR; PG8_SCHED;
;             PG8_STAGE(PG8_SB(1, 1), b3 + hstep, voffB);
;             PG8_WAIT_V(6); PG8_BAR; PG8_MMA(1, 1, At, B1); PG8_BAR;
	s_waitcnt lgkmcnt(0)
	s_setprio 1
	v_mfma_f32_16x16x32_bf16 v[124:127], v[144:147], v[166:169], v[124:127]
	v_mfma_f32_16x16x32_bf16 v[120:123], v[158:161], v[166:169], v[120:123]
	v_mfma_f32_16x16x32_bf16 v[108:111], v[144:147], v[174:177], v[108:111]
	v_mfma_f32_16x16x32_bf16 v[104:107], v[158:161], v[174:177], v[104:107]
	v_mfma_f32_16x16x32_bf16 v[92:95], v[144:147], v[188:191], v[92:95]
	v_mfma_f32_16x16x32_bf16 v[88:91], v[158:161], v[188:191], v[88:91]
	v_mfma_f32_16x16x32_bf16 v[76:79], v[144:147], v[210:213], v[76:79]
	v_mfma_f32_16x16x32_bf16 v[72:75], v[158:161], v[210:213], v[72:75]
	v_mfma_f32_16x16x32_bf16 v[124:127], v[154:157], v[170:173], v[124:127]
	v_mfma_f32_16x16x32_bf16 v[120:123], v[162:165], v[170:173], v[120:123]
	v_mfma_f32_16x16x32_bf16 v[108:111], v[154:157], v[178:181], v[108:111]
	v_mfma_f32_16x16x32_bf16 v[104:107], v[162:165], v[178:181], v[104:107]
	v_mfma_f32_16x16x32_bf16 v[92:95], v[154:157], v[206:209], v[92:95]
	v_mfma_f32_16x16x32_bf16 v[88:91], v[162:165], v[206:209], v[88:91]
	v_mfma_f32_16x16x32_bf16 v[76:79], v[154:157], v[214:217], v[76:79]
	v_mfma_f32_16x16x32_bf16 v[72:75], v[162:165], v[214:217], v[72:75]
	s_setprio 0
	s_barrier
	s_add_i32 s5, 0, 0x1c000
	s_add_i32 s0, s4, s51
	v_add_u32_e32 v201, s5, v149
	s_add_i32 m0, s0, 0xffffff80
	ds_read_b128 v[218:221], v201
	ds_read_b128 v[222:225], v201 offset:1024
	ds_read_b128 v[226:229], v201 offset:2048
	global_load_lds_dwordx4 v132, s[46:47] offset:128
	s_add_i32 m0, s0, 0x1f80
	ds_read_b128 v[230:233], v201 offset:3072
	global_load_lds_dwordx4 v134, s[46:47] offset:128
	s_barrier
	s_waitcnt lgkmcnt(0)
	s_setprio 1
	v_mfma_f32_16x16x32_bf16 v[116:119], v[218:221], v[166:169], v[116:119]
	v_mfma_f32_16x16x32_bf16 v[112:115], v[226:229], v[166:169], v[112:115]
	v_mfma_f32_16x16x32_bf16 v[100:103], v[218:221], v[174:177], v[100:103]
	v_mfma_f32_16x16x32_bf16 v[96:99], v[226:229], v[174:177], v[96:99]
	v_mfma_f32_16x16x32_bf16 v[84:87], v[218:221], v[188:191], v[84:87]
	v_mfma_f32_16x16x32_bf16 v[80:83], v[226:229], v[188:191], v[80:83]
	v_mfma_f32_16x16x32_bf16 v[68:71], v[218:221], v[210:213], v[68:71]
	v_mfma_f32_16x16x32_bf16 v[64:67], v[226:229], v[210:213], v[64:67]
	v_mfma_f32_16x16x32_bf16 v[116:119], v[222:225], v[170:173], v[116:119]
	v_mfma_f32_16x16x32_bf16 v[112:115], v[230:233], v[170:173], v[112:115]
	v_mfma_f32_16x16x32_bf16 v[100:103], v[222:225], v[178:181], v[100:103]
	v_mfma_f32_16x16x32_bf16 v[96:99], v[230:233], v[178:181], v[96:99]
	v_mfma_f32_16x16x32_bf16 v[84:87], v[222:225], v[206:209], v[84:87]
	v_mfma_f32_16x16x32_bf16 v[80:83], v[230:233], v[206:209], v[80:83]
	v_mfma_f32_16x16x32_bf16 v[68:71], v[222:225], v[214:217], v[68:71]
	v_mfma_f32_16x16x32_bf16 v[64:67], v[230:233], v[214:217], v[64:67]
	s_setprio 0
	s_add_i32 m0, s63, 0xffffff80
	s_barrier
	ds_read_b128 v[166:169], v151 offset:49152
	ds_read_b128 v[170:173], v151 offset:50176
	ds_read_b128 v[174:177], v151 offset:51200
	ds_read_b128 v[178:181], v151 offset:52224
	ds_read_b128 v[188:191], v151 offset:53248
	ds_read_b128 v[206:209], v151 offset:54272
	ds_read_b128 v[210:213], v151 offset:55296
	global_load_lds_dwordx4 v128, s[48:49] offset:128
	s_add_i32 m0, s64, 0xffffff80
	ds_read_b128 v[214:217], v151 offset:56320
	global_load_lds_dwordx4 v130, s[48:49] offset:128
	s_barrier
	s_waitcnt lgkmcnt(0)
	s_setprio 1
	v_mfma_f32_16x16x32_bf16 v[60:63], v[144:147], v[166:169], v[60:63]
	v_mfma_f32_16x16x32_bf16 v[56:59], v[158:161], v[166:169], v[56:59]
	v_mfma_f32_16x16x32_bf16 v[44:47], v[144:147], v[174:177], v[44:47]
	v_mfma_f32_16x16x32_bf16 v[40:43], v[158:161], v[174:177], v[40:43]
	v_mfma_f32_16x16x32_bf16 v[28:31], v[144:147], v[188:191], v[28:31]
	v_mfma_f32_16x16x32_bf16 v[24:27], v[158:161], v[188:191], v[24:27]
	v_mfma_f32_16x16x32_bf16 v[12:15], v[144:147], v[210:213], v[12:15]
	v_mfma_f32_16x16x32_bf16 v[8:11], v[158:161], v[210:213], v[8:11]
	v_mfma_f32_16x16x32_bf16 v[60:63], v[154:157], v[170:173], v[60:63]
	v_mfma_f32_16x16x32_bf16 v[56:59], v[162:165], v[170:173], v[56:59]
	v_mfma_f32_16x16x32_bf16 v[44:47], v[154:157], v[178:181], v[44:47]
	v_mfma_f32_16x16x32_bf16 v[40:43], v[162:165], v[178:181], v[40:43]
	v_mfma_f32_16x16x32_bf16 v[28:31], v[154:157], v[206:209], v[28:31]
	v_mfma_f32_16x16x32_bf16 v[24:27], v[162:165], v[206:209], v[24:27]
	v_mfma_f32_16x16x32_bf16 v[12:15], v[154:157], v[214:217], v[12:15]
	v_mfma_f32_16x16x32_bf16 v[8:11], v[162:165], v[214:217], v[8:11]
	s_setprio 0
	s_barrier
	s_add_i32 s4, s5, s51
	s_mov_b32 m0, s4
	s_add_u32 s0, s46, 0x80080
	s_addc_u32 s1, s47, 0
	global_load_lds_dwordx4 v132, s[0:1]
	s_add_i32 m0, s4, 0x2000
	s_nop 0
	global_load_lds_dwordx4 v134, s[0:1]
	s_waitcnt vmcnt(6)
	s_barrier
	s_setprio 1
	v_mfma_f32_16x16x32_bf16 v[52:55], v[218:221], v[166:169], v[52:55]
	v_mfma_f32_16x16x32_bf16 v[48:51], v[226:229], v[166:169], v[48:51]
	v_mfma_f32_16x16x32_bf16 v[36:39], v[218:221], v[174:177], v[36:39]
	v_mfma_f32_16x16x32_bf16 v[32:35], v[226:229], v[174:177], v[32:35]
	v_mfma_f32_16x16x32_bf16 v[20:23], v[218:221], v[188:191], v[20:23]
	v_mfma_f32_16x16x32_bf16 v[16:19], v[226:229], v[188:191], v[16:19]
	v_mfma_f32_16x16x32_bf16 v[4:7], v[218:221], v[210:213], v[4:7]
	v_mfma_f32_16x16x32_bf16 v[0:3], v[226:229], v[210:213], v[0:3]
	v_mfma_f32_16x16x32_bf16 v[52:55], v[222:225], v[170:173], v[52:55]
	v_mfma_f32_16x16x32_bf16 v[48:51], v[230:233], v[170:173], v[48:51]
	v_mfma_f32_16x16x32_bf16 v[36:39], v[222:225], v[178:181], v[36:39]
	v_mfma_f32_16x16x32_bf16 v[32:35], v[230:233], v[178:181], v[32:35]
	v_mfma_f32_16x16x32_bf16 v[20:23], v[222:225], v[206:209], v[20:23]
	v_mfma_f32_16x16x32_bf16 v[16:19], v[230:233], v[206:209], v[16:19]
	v_mfma_f32_16x16x32_bf16 v[4:7], v[222:225], v[214:217], v[4:7]
	v_mfma_f32_16x16x32_bf16 v[0:3], v[230:233], v[214:217], v[0:3]
	s_setprio 0
	s_add_i32 s69, s69, 2
	s_add_u32 s44, s44, 0x100
	s_addc_u32 s45, s45, 0
	s_add_u32 s43, s43, 0x100
	s_addc_u32 s68, s68, 0
	s_cmp_gt_u32 s69, 29
	s_barrier
	s_cbranch_scc0 .LBB0_1508

;     DI size_t aoff(const Unit& u, size_t tstep) const { return (size_t)u.pm * tstep; }
;     DI size_t boff(const Unit& u, size_t tstep) const { return (size_t)u.pn * tstep; }
;     DI bool next(int i, Unit& u) const { const long L = (long)i * G + c; if (L >= np) return false; u.pm = pmv; u.pn = (int)(L % nN); u.ks = (int)(L / nN); return true; }
;     DI size_t aoff(const Unit& u, size_t) const { return (size_t)u.ks * kbytes; }
;     DI size_t boff(const Unit& u, size_t tstep) const { return (size_t)u.pn * tstep + (size_t)u.ks * kbytes; }
;     DI bool next(int i, Unit& u) const { Unit t; if (!S.next(i / 3, t)) return false; u.pm = t.pm; u.pn = t.pn; u.ks = i % 3; return true; }
;     DI size_t aoff(const Unit& u, size_t tstep) const { return (u.ks < 2 ? offU : offOA) + (size_t)u.pm * tstep; }
; #define PG8_LDA(dst, b, h) do { _Pragma("unroll") for (int m = 0; m < 4; ++m) _Pragma("unroll") for (int k = 0; k < 2; ++k) dst[m][k] = *(const LAS bf16x8*)(lds + PG8_SA(b, h) + aoff + m * 2048 + k * 1024); } while (0)
; template <class Epi, class Sched>
; DI void gemm_phase(LAS unsigned char* lds, const Gemm g, const Sched& S, const Epi& E) {
;     ...
;         const bool has_next = S.next(ui + 1, nxt);
;         const char* nA = has_next ? (const char*)g.A + S.aoff(nxt, tstep) : cA; const char* nB = has_next ? (const char*)g.Bt + S.boff(nxt, tstep) : cB;
;         for (int t = 0; t < nt; t += 2) {
;             if constexpr (Epi::HAS_MID) { if (t == E.mid_t(nt)) { int fr3 = fr, fq3 = fq; asm volatile("" : "+v"(fr3), "+v"(fq3)); E.mid(acc, cur, wr, wc, fr3, fq3); } }
;             const bool last = (t == nt - 2);
;             const char* a1 = cA + (size_t)(t + 1) * kstep;
;             const char* a2 = last ? nA : cA + (size_t)(t + 2) * kstep; const char* b2 = last ? nB : cB + (size_t)(t + 2) * kstep;
;             const char* a3 = a2 + kstep; const char* b3 = b2 + kstep;
;             PG8_LDB(B0, 0, 0); PG8_SCHED; PG8_LDA(At, 0, 0); PG8_STAGE(PG8_SA(1, 1), a1 + hstep, voffA);
;             PG8_WAIT_L(8); PG8_BAR; PG8_WAIT_L(0); PG8_MMA(0, 0, At, B0); PG8_BAR; PG8_SCHED;
;             PG8_LDB(B1, 0, 1); PG8_STAGE(PG8_SB(0, 0), b2, voffB);
;             PG8_BAR; PG8_WAIT_L(0); PG8_MMA(0, 1, At, B1); PG8_BAR;
;             PG8_LDA(At, 0, 1); PG8_STAGE(PG8_SA(0, 0), a2, voffA);
;             PG8_BAR; PG8_WAIT_L(0); PG8_MMA(1, 0, At, B0); PG8_BAR; PG8_SCHED;
.LBB0_1667:
	s_ashr_i32 s29, s28, 31
	s_lshl_b64 s[0:1], s[28:29], 20
	s_add_u32 s30, s45, s0
	v_cmp_lt_i64_e32 vcc, s[8:9], v[140:141]
	s_addc_u32 s31, s46, s1
	s_and_b64 s[0:1], vcc, exec
	s_cselect_b32 s29, s31, s43
	s_cselect_b32 s35, s30, s42
	s_ashr_i32 s19, s18, 31
	s_lshl_b64 s[0:1], s[18:19], 20
	s_add_u32 s36, s47, s0
	s_addc_u32 s37, s48, s1
	s_and_b64 s[0:1], vcc, exec
	s_cselect_b32 s19, s37, s41
	s_cselect_b32 s65, s36, s40
	s_add_u32 s8, s42, 0x80080
	s_addc_u32 s9, s43, 0
	s_add_u32 s66, s40, 0x100
	v_mov_b32_e32 v8, 0
	s_addc_u32 s67, s41, 0
	s_mov_b32 s68, -2
	ds_read_b128 v[144:147], v149
	ds_read_b128 v[156:159], v149 offset:1024
	ds_read_b128 v[160:163], v149 offset:2048
	ds_read_b128 v[164:167], v149 offset:3072
	s_add_i32 m0, s39, 0xc000
	ds_read_b128 v[168:171], v150
	ds_read_b128 v[172:175], v150 offset:1024
	ds_read_b128 v[176:179], v150 offset:2048
	ds_read_b128 v[180:183], v150 offset:3072
	ds_read_b128 v[188:191], v150 offset:4096
	ds_read_b128 v[206:209], v150 offset:5120
	ds_read_b128 v[210:213], v150 offset:6144
	global_load_lds_dwordx4 v136, s[8:9]
	s_add_i32 m0, s39, 0xe000
	ds_read_b128 v[214:217], v150 offset:7168
	global_load_lds_dwordx4 v138, s[8:9]
	s_add_u32 s0, s8, 0xfff80080
	s_addc_u32 s1, s9, -1
	s_cmp_eq_u32 s68, 28
	s_cselect_b32 s43, s29, s1
	s_cselect_b32 s42, s35, s0
	s_cselect_b32 s41, s19, s67
	s_cselect_b32 s40, s65, s66
	s_waitcnt lgkmcnt(8)
	s_barrier
	s_waitcnt lgkmcnt(0)
	s_setprio 1
	v_mfma_f32_16x16x32_bf16 v[116:119], v[144:147], v[168:171], 0
	v_mfma_f32_16x16x32_bf16 v[112:115], v[160:163], v[168:171], 0
	v_mfma_f32_16x16x32_bf16 v[100:103], v[144:147], v[176:179], 0
	v_mfma_f32_16x16x32_bf16 v[96:99], v[160:163], v[176:179], 0
	v_mfma_f32_16x16x32_bf16 v[84:87], v[144:147], v[188:191], 0
	v_mfma_f32_16x16x32_bf16 v[80:83], v[160:163], v[188:191], 0
	v_mfma_f32_16x16x32_bf16 v[68:71], v[144:147], v[210:213], 0
	v_mfma_f32_16x16x32_bf16 v[64:67], v[160:163], v[210:213], 0
	v_mfma_f32_16x16x32_bf16 v[116:119], v[156:159], v[172:175], v[116:119]
	v_mfma_f32_16x16x32_bf16 v[112:115], v[164:167], v[172:175], v[112:115]
	v_mfma_f32_16x16x32_bf16 v[100:103], v[156:159], v[180:183], v[100:103]
	v_mfma_f32_16x16x32_bf16 v[96:99], v[164:167], v[180:183], v[96:99]
	v_mfma_f32_16x16x32_bf16 v[84:87], v[156:159], v[206:209], v[84:87]
	v_mfma_f32_16x16x32_bf16 v[80:83], v[164:167], v[206:209], v[80:83]
	v_mfma_f32_16x16x32_bf16 v[68:71], v[156:159], v[214:217], v[68:71]
	v_mfma_f32_16x16x32_bf16 v[64:67], v[164:167], v[214:217], v[64:67]
	s_setprio 0
	s_barrier
	s_add_i32 s0, s61, s50
	s_mov_b32 m0, s0
	ds_read_b128 v[218:221], v151
	ds_read_b128 v[222:225], v151 offset:1024
	ds_read_b128 v[226:229], v151 offset:2048
	global_load_lds_dwordx4 v130, s[40:41]
	s_add_i32 m0, s0, 0x2000
	ds_read_b128 v[230:233], v151 offset:3072
	global_load_lds_dwordx4 v134, s[40:41]
	s_barrier
	s_waitcnt lgkmcnt(0)
	s_setprio 1
	v_mfma_f32_16x16x32_bf16 v[124:127], v[218:221], v[168:171], 0
	v_mfma_f32_16x16x32_bf16 v[120:123], v[226:229], v[168:171], 0
	v_mfma_f32_16x16x32_bf16 v[108:111], v[218:221], v[176:179], 0
	v_mfma_f32_16x16x32_bf16 v[104:107], v[226:229], v[176:179], 0
	v_mfma_f32_16x16x32_bf16 v[92:95], v[218:221], v[188:191], 0
	v_mfma_f32_16x16x32_bf16 v[88:91], v[226:229], v[188:191], 0
	v_mfma_f32_16x16x32_bf16 v[76:79], v[218:221], v[210:213], 0
	v_mfma_f32_16x16x32_bf16 v[72:75], v[226:229], v[210:213], 0
	v_mfma_f32_16x16x32_bf16 v[124:127], v[222:225], v[172:175], v[124:127]
	v_mfma_f32_16x16x32_bf16 v[120:123], v[230:233], v[172:175], v[120:123]
	v_mfma_f32_16x16x32_bf16 v[108:111], v[222:225], v[180:183], v[108:111]
	v_mfma_f32_16x16x32_bf16 v[104:107], v[230:233], v[180:183], v[104:107]
	v_mfma_f32_16x16x32_bf16 v[92:95], v[222:225], v[206:209], v[92:95]
	v_mfma_f32_16x16x32_bf16 v[88:91], v[230:233], v[206:209], v[88:91]
	v_mfma_f32_16x16x32_bf16 v[76:79], v[222:225], v[214:217], v[76:79]
	v_mfma_f32_16x16x32_bf16 v[72:75], v[230:233], v[214:217], v[72:75]
	s_setprio 0
	s_mov_b32 m0, s39
	s_barrier
	ds_read_b128 v[168:171], v150 offset:16384
	ds_read_b128 v[172:175], v150 offset:17408
	ds_read_b128 v[176:179], v150 offset:18432
	ds_read_b128 v[180:183], v150 offset:19456
	ds_read_b128 v[188:191], v150 offset:20480
	ds_read_b128 v[206:209], v150 offset:21504
	ds_read_b128 v[210:213], v150 offset:22528
	global_load_lds_dwordx4 v128, s[42:43]
	s_mov_b32 m0, s51
	ds_read_b128 v[214:217], v150 offset:23552
	global_load_lds_dwordx4 v132, s[42:43]
	s_barrier
	s_waitcnt lgkmcnt(0)
	s_setprio 1
	v_mfma_f32_16x16x32_bf16 v[52:55], v[144:147], v[168:171], 0
	v_mfma_f32_16x16x32_bf16 v[48:51], v[160:163], v[168:171], 0
	v_mfma_f32_16x16x32_bf16 v[36:39], v[144:147], v[176:179], 0
	v_mfma_f32_16x16x32_bf16 v[32:35], v[160:163], v[176:179], 0
	v_mfma_f32_16x16x32_bf16 v[20:23], v[144:147], v[188:191], 0
	v_mfma_f32_16x16x32_bf16 v[16:19], v[160:163], v[188:191], 0
	v_mfma_f32_16x16x32_bf16 v[4:7], v[144:147], v[210:213], 0
	v_mfma_f32_16x16x32_bf16 v[0:3], v[160:163], v[210:213], 0
	v_mfma_f32_16x16x32_bf16 v[52:55], v[156:159], v[172:175], v[52:55]
	v_mfma_f32_16x16x32_bf16 v[48:51], v[164:167], v[172:175], v[48:51]
	v_mfma_f32_16x16x32_bf16 v[36:39], v[156:159], v[180:183], v[36:39]
	v_mfma_f32_16x16x32_bf16 v[32:35], v[164:167], v[180:183], v[32:35]
	v_mfma_f32_16x16x32_bf16 v[20:23], v[156:159], v[206:209], v[20:23]
	v_mfma_f32_16x16x32_bf16 v[16:19], v[164:167], v[206:209], v[16:19]
	v_mfma_f32_16x16x32_bf16 v[4:7], v[156:159], v[214:217], v[4:7]
	v_mfma_f32_16x16x32_bf16 v[0:3], v[164:167], v[214:217], v[0:3]
	s_setprio 0
	s_barrier
; #define PG8_STAGE(bufoff, gbase, voff) do { _Pragma("unroll") for (int _i = 0; _i < 2; ++_i) \
;         __builtin_amdgcn_global_load_lds((const unsigned*)((const char*)(gbase) + (voff)[_i]), (LAS unsigned*)(lds + (bufoff) + ldsw + _i * 8192), 16, 0, 0); } while (0)
; #define PG8_LDA(dst, b, h) do { _Pragma("unroll") for (int m = 0; m < 4; ++m) _Pragma("unroll") for (int k = 0; k < 2; ++k) dst[m][k] = *(const LAS bf16x8*)(lds + PG8_SA(b, h) + aoff + m * 2048 + k * 1024); } while (0)
; #define PG8_LDB(dst, b, h) do { _Pragma("unroll") for (int n = 0; n < 2; ++n) _Pragma("unroll") for (int k = 0; k < 2; ++k) dst[n][k] = *(const LAS bf16x8*)(lds + PG8_SB(b, h) + boff + n * 2048 + k * 1024); } while (0)
; #define PG8_MMA(ai, bj, At, Bt) do { __builtin_amdgcn_s_setprio(1); _Pragma("unroll") for (int m = 0; m < 4; ++m) _Pragma("unroll") for (int n = 0; n < 2; ++n) _Pragma("unroll") for (int k = 0; k < 2; ++k) \
;         acc[ai][bj][m][n] = __builtin_amdgcn_mfma_f32_16x16x32_bf16(Bt[n][k], At[m][k], acc[ai][bj][m][n], 0, 0, 0); __builtin_amdgcn_s_setprio(0); } while (0)
; #define PG8_WAIT_V(n) asm volatile("s_waitcnt vmcnt(" #n ")" ::: "memory")
; #define PG8_WAIT_L(n) asm volatile("s_waitcnt lgkmcnt(" #n ")" ::: "memory")
; #define PG8_BAR __builtin_amdgcn_s_barrier()
; #define PG8_SCHED __builtin_amdgcn_sched_barrier(0)
; template <class Epi, class Sched>
; DI void gemm_phase(LAS unsigned char* lds, const Gemm g, const Sched& S, const Epi& E) {
;     ...
;             PG8_STAGE(PG8_SB(0, 1), b2 + hstep, voffB);
;             PG8_WAIT_V(6); PG8_BAR; PG8_MMA(1, 1, At, B1); PG8_BAR;
;             PG8_LDB(B0, 1, 0); PG8_SCHED; PG8_LDA(At, 1, 0); PG8_STAGE(PG8_SA(0, 1), a2 + hstep, voffA);
;             PG8_WAIT_L(8); PG8_BAR; PG8_WAIT_L(0); PG8_MMA(0, 0, At, B0); PG8_BAR; PG8_SCHED;
;             PG8_LDB(B1, 1, 1); PG8_STAGE(PG8_SB(1, 0), b3, voffB);
;             PG8_BAR; PG8_WAIT_L(0); PG8_MMA(0, 1, At, B1); PG8_BAR;
;             PG8_LDA(At, 1, 1); PG8_STAGE(PG8_SA(1, 0), a3, voffA);
;             PG8_BAR; PG8_WAIT_L(0); PG8_MMA(1, 0, At, B0); PG8_BAR; PG8_SCHED;
	s_add_i32 s4, s62, s50
	s_mov_b32 m0, s4
	s_add_u32 s0, s40, 0x80000
	s_addc_u32 s1, s41, 0
	global_load_lds_dwordx4 v130, s[0:1]
	s_add_i32 m0, s4, 0x2000
	s_nop 0
	global_load_lds_dwordx4 v134, s[0:1]
	s_waitcnt vmcnt(6)
	s_barrier
	s_setprio 1
	v_mfma_f32_16x16x32_bf16 v[60:63], v[218:221], v[168:171], 0
	v_mfma_f32_16x16x32_bf16 v[56:59], v[226:229], v[168:171], 0
	v_mfma_f32_16x16x32_bf16 v[44:47], v[218:221], v[176:179], 0
	v_mfma_f32_16x16x32_bf16 v[40:43], v[226:229], v[176:179], 0
	v_mfma_f32_16x16x32_bf16 v[28:31], v[218:221], v[188:191], 0
	v_mfma_f32_16x16x32_bf16 v[24:27], v[226:229], v[188:191], 0
	v_mfma_f32_16x16x32_bf16 v[12:15], v[218:221], v[210:213], 0
	v_mfma_f32_16x16x32_bf16 v[8:11], v[226:229], v[210:213], 0
	v_mfma_f32_16x16x32_bf16 v[60:63], v[222:225], v[172:175], v[60:63]
	v_mfma_f32_16x16x32_bf16 v[56:59], v[230:233], v[172:175], v[56:59]
	v_mfma_f32_16x16x32_bf16 v[44:47], v[222:225], v[180:183], v[44:47]
	v_mfma_f32_16x16x32_bf16 v[40:43], v[230:233], v[180:183], v[40:43]
	v_mfma_f32_16x16x32_bf16 v[28:31], v[222:225], v[206:209], v[28:31]
	v_mfma_f32_16x16x32_bf16 v[24:27], v[230:233], v[206:209], v[24:27]
	v_mfma_f32_16x16x32_bf16 v[12:15], v[222:225], v[214:217], v[12:15]
	v_mfma_f32_16x16x32_bf16 v[8:11], v[230:233], v[214:217], v[8:11]
	s_setprio 0
	s_add_i32 s4, 0, 0x18000
	v_add_u32_e32 v202, s4, v148
	s_barrier
	ds_read_b128 v[144:147], v202
	ds_read_b128 v[156:159], v202 offset:1024
	ds_read_b128 v[160:163], v202 offset:2048
	ds_read_b128 v[164:167], v202 offset:3072
	s_add_u32 s0, s42, 0x80000
	s_addc_u32 s1, s43, 0
	s_mov_b32 m0, s52
	ds_read_b128 v[168:171], v150 offset:32768
	ds_read_b128 v[172:175], v150 offset:33792
	ds_read_b128 v[176:179], v150 offset:34816
	ds_read_b128 v[180:183], v150 offset:35840
	ds_read_b128 v[188:191], v150 offset:36864
	ds_read_b128 v[206:209], v150 offset:37888
	ds_read_b128 v[210:213], v150 offset:38912
	global_load_lds_dwordx4 v128, s[0:1]
	s_mov_b32 m0, s53
	ds_read_b128 v[214:217], v150 offset:39936
	global_load_lds_dwordx4 v132, s[0:1]
	s_waitcnt lgkmcnt(8)
	s_barrier
	s_waitcnt lgkmcnt(0)
	s_setprio 1
	v_mfma_f32_16x16x32_bf16 v[116:119], v[144:147], v[168:171], v[116:119]
	v_mfma_f32_16x16x32_bf16 v[112:115], v[160:163], v[168:171], v[112:115]
	v_mfma_f32_16x16x32_bf16 v[100:103], v[144:147], v[176:179], v[100:103]
	v_mfma_f32_16x16x32_bf16 v[96:99], v[160:163], v[176:179], v[96:99]
	v_mfma_f32_16x16x32_bf16 v[84:87], v[144:147], v[188:191], v[84:87]
	v_mfma_f32_16x16x32_bf16 v[80:83], v[160:163], v[188:191], v[80:83]
	v_mfma_f32_16x16x32_bf16 v[68:71], v[144:147], v[210:213], v[68:71]
	v_mfma_f32_16x16x32_bf16 v[64:67], v[160:163], v[210:213], v[64:67]
	v_mfma_f32_16x16x32_bf16 v[116:119], v[156:159], v[172:175], v[116:119]
	v_mfma_f32_16x16x32_bf16 v[112:115], v[164:167], v[172:175], v[112:115]
	v_mfma_f32_16x16x32_bf16 v[100:103], v[156:159], v[180:183], v[100:103]
	v_mfma_f32_16x16x32_bf16 v[96:99], v[164:167], v[180:183], v[96:99]
	v_mfma_f32_16x16x32_bf16 v[84:87], v[156:159], v[206:209], v[84:87]
	v_mfma_f32_16x16x32_bf16 v[80:83], v[164:167], v[206:209], v[80:83]
	v_mfma_f32_16x16x32_bf16 v[68:71], v[156:159], v[214:217], v[68:71]
	v_mfma_f32_16x16x32_bf16 v[64:67], v[164:167], v[214:217], v[64:67]
	s_setprio 0
	s_barrier
	s_add_i32 s5, 0, 0x1c000
	s_add_i32 s0, s4, s50
	v_add_u32_e32 v203, s5, v148
	s_add_i32 m0, s0, 0xffffff80
	ds_read_b128 v[218:221], v203
	ds_read_b128 v[222:225], v203 offset:1024
	ds_read_b128 v[226:229], v203 offset:2048
	global_load_lds_dwordx4 v130, s[40:41] offset:128
	s_add_i32 m0, s0, 0x1f80
	ds_read_b128 v[230:233], v203 offset:3072
	global_load_lds_dwordx4 v134, s[40:41] offset:128
	s_barrier
	s_waitcnt lgkmcnt(0)
	s_setprio 1
	v_mfma_f32_16x16x32_bf16 v[124:127], v[218:221], v[168:171], v[124:127]
	v_mfma_f32_16x16x32_bf16 v[120:123], v[226:229], v[168:171], v[120:123]
	v_mfma_f32_16x16x32_bf16 v[108:111], v[218:221], v[176:179], v[108:111]
	v_mfma_f32_16x16x32_bf16 v[104:107], v[226:229], v[176:179], v[104:107]
	v_mfma_f32_16x16x32_bf16 v[92:95], v[218:221], v[188:191], v[92:95]
	v_mfma_f32_16x16x32_bf16 v[88:91], v[226:229], v[188:191], v[88:91]
	v_mfma_f32_16x16x32_bf16 v[76:79], v[218:221], v[210:213], v[76:79]
	v_mfma_f32_16x16x32_bf16 v[72:75], v[226:229], v[210:213], v[72:75]
	v_mfma_f32_16x16x32_bf16 v[124:127], v[222:225], v[172:175], v[124:127]
	v_mfma_f32_16x16x32_bf16 v[120:123], v[230:233], v[172:175], v[120:123]
	v_mfma_f32_16x16x32_bf16 v[108:111], v[222:225], v[180:183], v[108:111]
	v_mfma_f32_16x16x32_bf16 v[104:107], v[230:233], v[180:183], v[104:107]
	v_mfma_f32_16x16x32_bf16 v[92:95], v[222:225], v[206:209], v[92:95]
	v_mfma_f32_16x16x32_bf16 v[88:91], v[230:233], v[206:209], v[88:91]
	v_mfma_f32_16x16x32_bf16 v[76:79], v[222:225], v[214:217], v[76:79]
	v_mfma_f32_16x16x32_bf16 v[72:75], v[230:233], v[214:217], v[72:75]
	s_setprio 0
	s_add_i32 m0, s57, 0xffffff80
	s_barrier
	ds_read_b128 v[168:171], v150 offset:49152
	ds_read_b128 v[172:175], v150 offset:50176
	ds_read_b128 v[176:179], v150 offset:51200
	ds_read_b128 v[180:183], v150 offset:52224
	ds_read_b128 v[188:191], v150 offset:53248
	ds_read_b128 v[206:209], v150 offset:54272
	ds_read_b128 v[210:213], v150 offset:55296
	global_load_lds_dwordx4 v128, s[42:43] offset:128
	s_add_i32 m0, s58, 0xffffff80
	ds_read_b128 v[214:217], v150 offset:56320
	global_load_lds_dwordx4 v132, s[42:43] offset:128
	s_barrier
; #define PG8_STAGE(bufoff, gbase, voff) do { _Pragma("unroll") for (int _i = 0; _i < 2; ++_i) \
;         __builtin_amdgcn_global_load_lds((const unsigned*)((const char*)(gbase) + (voff)[_i]), (LAS unsigned*)(lds + (bufoff) + ldsw + _i * 8192), 16, 0, 0); } while (0)
; #define PG8_LDA(dst, b, h) do { _Pragma("unroll") for (int m = 0; m < 4; ++m) _Pragma("unroll") for (int k = 0; k < 2; ++k) dst[m][k] = *(const LAS bf16x8*)(lds + PG8_SA(b, h) + aoff + m * 2048 + k * 1024); } while (0)
; #define PG8_LDB(dst, b, h) do { _Pragma("unroll") for (int n = 0; n < 2; ++n) _Pragma("unroll") for (int k = 0; k < 2; ++k) dst[n][k] = *(const LAS bf16x8*)(lds + PG8_SB(b, h) + boff + n * 2048 + k * 1024); } while (0)
; #define PG8_WAIT_V(n) asm volatile("s_waitcnt vmcnt(" #n ")" ::: "memory")
; #define PG8_WAIT_L(n) asm volatile("s_waitcnt lgkmcnt(" #n ")" ::: "memory")
; #define PG8_BAR __builtin_amdgcn_s_barrier()
; #define PG8_SCHED __builtin_amdgcn_sched_barrier(0)
; template <class Epi, class Sched>
; DI void gemm_phase(LAS unsigned char* lds, const Gemm g, const Sched& S, const Epi& E) {
;     ...
;             PG8_LDB(B0, 0, 0); PG8_SCHED; PG8_LDA(At, 0, 0); PG8_STAGE(PG8_SA(1, 1), a1 + hstep, voffA);
;             PG8_WAIT_L(8); PG8_BAR; PG8_WAIT_L(0); PG8_MMA(0, 0, At, B0); PG8_BAR; PG8_SCHED;
;             PG8_LDB(B1, 0, 1); PG8_STAGE(PG8_SB(0, 0), b2, voffB);
;             PG8_BAR; PG8_WAIT_L(0); PG8_MMA(0, 1, At, B1); PG8_BAR;
;             PG8_LDA(At, 0, 1); PG8_STAGE(PG8_SA(0, 0), a2, voffA);
;             PG8_BAR; PG8_WAIT_L(0); PG8_MMA(1, 0, At, B0); PG8_BAR; PG8_SCHED;
;             PG8_STAGE(PG8_SB(0, 1), b2 + hstep, voffB);
;             PG8_WAIT_V(6); PG8_BAR; PG8_MMA(1, 1, At, B1); PG8_BAR;
;             PG8_LDB(B0, 1, 0); PG8_SCHED; PG8_LDA(At, 1, 0); PG8_STAGE(PG8_SA(0, 1), a2 + hstep, voffA);
;             PG8_WAIT_L(8); PG8_BAR; PG8_WAIT_L(0); PG8_MMA(0, 0, At, B0); PG8_BAR; PG8_SCHED;
;             PG8_LDB(B1, 1, 1); PG8_STAGE(PG8_SB(1, 0), b3, voffB);
;             PG8_BAR; PG8_WAIT_L(0); PG8_MMA(0, 1, At, B1); PG8_BAR;
;             PG8_LDA(At, 1, 1); PG8_STAGE(PG8_SA(1, 0), a3, voffA);
;             PG8_BAR; PG8_WAIT_L(0); PG8_MMA(1, 0, At, B0); PG8_BAR; PG8_SCHED;
;             PG8_STAGE(PG8_SB(1, 1), b3 + hstep, voffB);
;             PG8_WAIT_V(6); PG8_BAR; PG8_MMA(1, 1, At, B1); PG8_BAR;
	s_waitcnt lgkmcnt(0)
	s_setprio 1
	v_mfma_f32_16x16x32_bf16 v[52:55], v[144:147], v[168:171], v[52:55]
	v_mfma_f32_16x16x32_bf16 v[48:51], v[160:163], v[168:171], v[48:51]
	v_mfma_f32_16x16x32_bf16 v[36:39], v[144:147], v[176:179], v[36:39]
	v_mfma_f32_16x16x32_bf16 v[32:35], v[160:163], v[176:179], v[32:35]
	v_mfma_f32_16x16x32_bf16 v[20:23], v[144:147], v[188:191], v[20:23]
	v_mfma_f32_16x16x32_bf16 v[16:19], v[160:163], v[188:191], v[16:19]
	v_mfma_f32_16x16x32_bf16 v[4:7], v[144:147], v[210:213], v[4:7]
	v_mfma_f32_16x16x32_bf16 v[0:3], v[160:163], v[210:213], v[0:3]
	v_mfma_f32_16x16x32_bf16 v[52:55], v[156:159], v[172:175], v[52:55]
	v_mfma_f32_16x16x32_bf16 v[48:51], v[164:167], v[172:175], v[48:51]
	v_mfma_f32_16x16x32_bf16 v[36:39], v[156:159], v[180:183], v[36:39]
	v_mfma_f32_16x16x32_bf16 v[32:35], v[164:167], v[180:183], v[32:35]
	v_mfma_f32_16x16x32_bf16 v[20:23], v[156:159], v[206:209], v[20:23]
	v_mfma_f32_16x16x32_bf16 v[16:19], v[164:167], v[206:209], v[16:19]
	v_mfma_f32_16x16x32_bf16 v[4:7], v[156:159], v[214:217], v[4:7]
	v_mfma_f32_16x16x32_bf16 v[0:3], v[164:167], v[214:217], v[0:3]
	s_setprio 0
	s_barrier
	s_add_i32 s4, s5, s50
	s_mov_b32 m0, s4
	s_add_u32 s0, s40, 0x80080
	s_addc_u32 s1, s41, 0
	global_load_lds_dwordx4 v130, s[0:1]
	s_add_i32 m0, s4, 0x2000
	s_nop 0
	global_load_lds_dwordx4 v134, s[0:1]
	s_waitcnt vmcnt(6)
	s_barrier
	s_setprio 1
	v_mfma_f32_16x16x32_bf16 v[60:63], v[218:221], v[168:171], v[60:63]
	v_mfma_f32_16x16x32_bf16 v[56:59], v[226:229], v[168:171], v[56:59]
	v_mfma_f32_16x16x32_bf16 v[44:47], v[218:221], v[176:179], v[44:47]
	v_mfma_f32_16x16x32_bf16 v[40:43], v[226:229], v[176:179], v[40:43]
	v_mfma_f32_16x16x32_bf16 v[28:31], v[218:221], v[188:191], v[28:31]
	v_mfma_f32_16x16x32_bf16 v[24:27], v[226:229], v[188:191], v[24:27]
	v_mfma_f32_16x16x32_bf16 v[12:15], v[218:221], v[210:213], v[12:15]
	v_mfma_f32_16x16x32_bf16 v[8:11], v[226:229], v[210:213], v[8:11]
	v_mfma_f32_16x16x32_bf16 v[60:63], v[222:225], v[172:175], v[60:63]
	v_mfma_f32_16x16x32_bf16 v[56:59], v[230:233], v[172:175], v[56:59]
	v_mfma_f32_16x16x32_bf16 v[44:47], v[222:225], v[180:183], v[44:47]
	v_mfma_f32_16x16x32_bf16 v[40:43], v[230:233], v[180:183], v[40:43]
	v_mfma_f32_16x16x32_bf16 v[28:31], v[222:225], v[206:209], v[28:31]
	v_mfma_f32_16x16x32_bf16 v[24:27], v[230:233], v[206:209], v[24:27]
	v_mfma_f32_16x16x32_bf16 v[12:15], v[222:225], v[214:217], v[12:15]
	v_mfma_f32_16x16x32_bf16 v[8:11], v[230:233], v[214:217], v[8:11]
	s_setprio 0
	s_add_i32 s68, s68, 2
	s_add_u32 s8, s8, 0x100
	s_addc_u32 s9, s9, 0
	s_add_u32 s66, s66, 0x100
	s_addc_u32 s67, s67, 0
	s_cmp_gt_u32 s68, 29
	s_barrier
	s_cbranch_scc0 .LBB0_1668
	s_branch .Lpeel_done_1668
.LBB0_1668:
	ds_read_b128 v[144:147], v149
	ds_read_b128 v[156:159], v149 offset:1024
	ds_read_b128 v[160:163], v149 offset:2048
	ds_read_b128 v[164:167], v149 offset:3072
	s_add_i32 m0, s39, 0xc000
	ds_read_b128 v[168:171], v150
	ds_read_b128 v[172:175], v150 offset:1024
	ds_read_b128 v[176:179], v150 offset:2048
	ds_read_b128 v[180:183], v150 offset:3072
	ds_read_b128 v[188:191], v150 offset:4096
	ds_read_b128 v[206:209], v150 offset:5120
	ds_read_b128 v[210:213], v150 offset:6144
	global_load_lds_dwordx4 v136, s[8:9]
	s_add_i32 m0, s39, 0xe000
	ds_read_b128 v[214:217], v150 offset:7168
	global_load_lds_dwordx4 v138, s[8:9]
	s_add_u32 s0, s8, 0xfff80080
	s_addc_u32 s1, s9, -1
	s_cmp_eq_u32 s68, 28
	s_cselect_b32 s43, s29, s1
	s_cselect_b32 s42, s35, s0
	s_cselect_b32 s41, s19, s67
	s_cselect_b32 s40, s65, s66
	s_waitcnt lgkmcnt(8)
	s_barrier
	s_waitcnt lgkmcnt(0)
	s_setprio 1
	v_mfma_f32_16x16x32_bf16 v[116:119], v[144:147], v[168:171], v[116:119]
	v_mfma_f32_16x16x32_bf16 v[112:115], v[160:163], v[168:171], v[112:115]
	v_mfma_f32_16x16x32_bf16 v[100:103], v[144:147], v[176:179], v[100:103]
	v_mfma_f32_16x16x32_bf16 v[96:99], v[160:163], v[176:179], v[96:99]
	v_mfma_f32_16x16x32_bf16 v[84:87], v[144:147], v[188:191], v[84:87]
	v_mfma_f32_16x16x32_bf16 v[80:83], v[160:163], v[188:191], v[80:83]
	v_mfma_f32_16x16x32_bf16 v[68:71], v[144:147], v[210:213], v[68:71]
	v_mfma_f32_16x16x32_bf16 v[64:67], v[160:163], v[210:213], v[64:67]
	v_mfma_f32_16x16x32_bf16 v[116:119], v[156:159], v[172:175], v[116:119]
	v_mfma_f32_16x16x32_bf16 v[112:115], v[164:167], v[172:175], v[112:115]
	v_mfma_f32_16x16x32_bf16 v[100:103], v[156:159], v[180:183], v[100:103]
	v_mfma_f32_16x16x32_bf16 v[96:99], v[164:167], v[180:183], v[96:99]
	v_mfma_f32_16x16x32_bf16 v[84:87], v[156:159], v[206:209], v[84:87]
	v_mfma_f32_16x16x32_bf16 v[80:83], v[164:167], v[206:209], v[80:83]
	v_mfma_f32_16x16x32_bf16 v[68:71], v[156:159], v[214:217], v[68:71]
	v_mfma_f32_16x16x32_bf16 v[64:67], v[164:167], v[214:217], v[64:67]
	s_setprio 0
	s_barrier
	s_add_i32 s0, s61, s50
	s_mov_b32 m0, s0
	ds_read_b128 v[218:221], v151
	ds_read_b128 v[222:225], v151 offset:1024
	ds_read_b128 v[226:229], v151 offset:2048
	global_load_lds_dwordx4 v130, s[40:41]
	s_add_i32 m0, s0, 0x2000
	ds_read_b128 v[230:233], v151 offset:3072
	global_load_lds_dwordx4 v134, s[40:41]
	s_barrier
; #define PG8_STAGE(bufoff, gbase, voff) do { _Pragma("unroll") for (int _i = 0; _i < 2; ++_i) \
;         __builtin_amdgcn_global_load_lds((const unsigned*)((const char*)(gbase) + (voff)[_i]), (LAS unsigned*)(lds + (bufoff) + ldsw + _i * 8192), 16, 0, 0); } while (0)
; #define PG8_LDA(dst, b, h) do { _Pragma("unroll") for (int m = 0; m < 4; ++m) _Pragma("unroll") for (int k = 0; k < 2; ++k) dst[m][k] = *(const LAS bf16x8*)(lds + PG8_SA(b, h) + aoff + m * 2048 + k * 1024); } while (0)
; #define PG8_LDB(dst, b, h) do { _Pragma("unroll") for (int n = 0; n < 2; ++n) _Pragma("unroll") for (int k = 0; k < 2; ++k) dst[n][k] = *(const LAS bf16x8*)(lds + PG8_SB(b, h) + boff + n * 2048 + k * 1024); } while (0)
; #define PG8_MMA(ai, bj, At, Bt) do { __builtin_amdgcn_s_setprio(1); _Pragma("unroll") for (int m = 0; m < 4; ++m) _Pragma("unroll") for (int n = 0; n < 2; ++n) _Pragma("unroll") for (int k = 0; k < 2; ++k) \
;         acc[ai][bj][m][n] = __builtin_amdgcn_mfma_f32_16x16x32_bf16(Bt[n][k], At[m][k], acc[ai][bj][m][n], 0, 0, 0); __builtin_amdgcn_s_setprio(0); } while (0)
; #define PG8_WAIT_V(n) asm volatile("s_waitcnt vmcnt(" #n ")" ::: "memory")
; #define PG8_WAIT_L(n) asm volatile("s_waitcnt lgkmcnt(" #n ")" ::: "memory")
; #define PG8_BAR __builtin_amdgcn_s_barrier()
; #define PG8_SCHED __builtin_amdgcn_sched_barrier(0)
; template <class Epi, class Sched>
; DI void gemm_phase(LAS unsigned char* lds, const Gemm g, const Sched& S, const Epi& E) {
;     ...
;             PG8_BAR; PG8_WAIT_L(0); PG8_MMA(0, 1, At, B1); PG8_BAR;
;             PG8_LDA(At, 0, 1); PG8_STAGE(PG8_SA(0, 0), a2, voffA);
;             PG8_BAR; PG8_WAIT_L(0); PG8_MMA(1, 0, At, B0); PG8_BAR; PG8_SCHED;
;             PG8_STAGE(PG8_SB(0, 1), b2 + hstep, voffB);
;             PG8_WAIT_V(6); PG8_BAR; PG8_MMA(1, 1, At, B1); PG8_BAR;
;             PG8_LDB(B0, 1, 0); PG8_SCHED; PG8_LDA(At, 1, 0); PG8_STAGE(PG8_SA(0, 1), a2 + hstep, voffA);
	s_waitcnt lgkmcnt(0)
	s_setprio 1
	v_mfma_f32_16x16x32_bf16 v[124:127], v[218:221], v[168:171], v[124:127]
	v_mfma_f32_16x16x32_bf16 v[120:123], v[226:229], v[168:171], v[120:123]
	v_mfma_f32_16x16x32_bf16 v[108:111], v[218:221], v[176:179], v[108:111]
	v_mfma_f32_16x16x32_bf16 v[104:107], v[226:229], v[176:179], v[104:107]
	v_mfma_f32_16x16x32_bf16 v[92:95], v[218:221], v[188:191], v[92:95]
	v_mfma_f32_16x16x32_bf16 v[88:91], v[226:229], v[188:191], v[88:91]
	v_mfma_f32_16x16x32_bf16 v[76:79], v[218:221], v[210:213], v[76:79]
	v_mfma_f32_16x16x32_bf16 v[72:75], v[226:229], v[210:213], v[72:75]
	v_mfma_f32_16x16x32_bf16 v[124:127], v[222:225], v[172:175], v[124:127]
	v_mfma_f32_16x16x32_bf16 v[120:123], v[230:233], v[172:175], v[120:123]
	v_mfma_f32_16x16x32_bf16 v[108:111], v[222:225], v[180:183], v[108:111]
	v_mfma_f32_16x16x32_bf16 v[104:107], v[230:233], v[180:183], v[104:107]
	v_mfma_f32_16x16x32_bf16 v[92:95], v[222:225], v[206:209], v[92:95]
	v_mfma_f32_16x16x32_bf16 v[88:91], v[230:233], v[206:209], v[88:91]
	v_mfma_f32_16x16x32_bf16 v[76:79], v[222:225], v[214:217], v[76:79]
	v_mfma_f32_16x16x32_bf16 v[72:75], v[230:233], v[214:217], v[72:75]
	s_setprio 0
	s_mov_b32 m0, s39
	s_barrier
	ds_read_b128 v[168:171], v150 offset:16384
	ds_read_b128 v[172:175], v150 offset:17408
	ds_read_b128 v[176:179], v150 offset:18432
	ds_read_b128 v[180:183], v150 offset:19456
	ds_read_b128 v[188:191], v150 offset:20480
	ds_read_b128 v[206:209], v150 offset:21504
	ds_read_b128 v[210:213], v150 offset:22528
	global_load_lds_dwordx4 v128, s[42:43]
	s_mov_b32 m0, s51
	ds_read_b128 v[214:217], v150 offset:23552
	global_load_lds_dwordx4 v132, s[42:43]
	s_barrier
	s_waitcnt lgkmcnt(0)
	s_setprio 1
	v_mfma_f32_16x16x32_bf16 v[52:55], v[144:147], v[168:171], v[52:55]
	v_mfma_f32_16x16x32_bf16 v[48:51], v[160:163], v[168:171], v[48:51]
	v_mfma_f32_16x16x32_bf16 v[36:39], v[144:147], v[176:179], v[36:39]
	v_mfma_f32_16x16x32_bf16 v[32:35], v[160:163], v[176:179], v[32:35]
	v_mfma_f32_16x16x32_bf16 v[20:23], v[144:147], v[188:191], v[20:23]
	v_mfma_f32_16x16x32_bf16 v[16:19], v[160:163], v[188:191], v[16:19]
	v_mfma_f32_16x16x32_bf16 v[4:7], v[144:147], v[210:213], v[4:7]
	v_mfma_f32_16x16x32_bf16 v[0:3], v[160:163], v[210:213], v[0:3]
	v_mfma_f32_16x16x32_bf16 v[52:55], v[156:159], v[172:175], v[52:55]
	v_mfma_f32_16x16x32_bf16 v[48:51], v[164:167], v[172:175], v[48:51]
	v_mfma_f32_16x16x32_bf16 v[36:39], v[156:159], v[180:183], v[36:39]
	v_mfma_f32_16x16x32_bf16 v[32:35], v[164:167], v[180:183], v[32:35]
	v_mfma_f32_16x16x32_bf16 v[20:23], v[156:159], v[206:209], v[20:23]
	v_mfma_f32_16x16x32_bf16 v[16:19], v[164:167], v[206:209], v[16:19]
	v_mfma_f32_16x16x32_bf16 v[4:7], v[156:159], v[214:217], v[4:7]
	v_mfma_f32_16x16x32_bf16 v[0:3], v[164:167], v[214:217], v[0:3]
	s_setprio 0
	s_barrier
	s_add_i32 s4, s62, s50
	s_mov_b32 m0, s4
	s_add_u32 s0, s40, 0x80000
	s_addc_u32 s1, s41, 0
	global_load_lds_dwordx4 v130, s[0:1]
	s_add_i32 m0, s4, 0x2000
	s_nop 0
	global_load_lds_dwordx4 v134, s[0:1]
	s_waitcnt vmcnt(6)
	s_barrier
	s_setprio 1
	v_mfma_f32_16x16x32_bf16 v[60:63], v[218:221], v[168:171], v[60:63]
	v_mfma_f32_16x16x32_bf16 v[56:59], v[226:229], v[168:171], v[56:59]
	v_mfma_f32_16x16x32_bf16 v[44:47], v[218:221], v[176:179], v[44:47]
	v_mfma_f32_16x16x32_bf16 v[40:43], v[226:229], v[176:179], v[40:43]
	v_mfma_f32_16x16x32_bf16 v[28:31], v[218:221], v[188:191], v[28:31]
	v_mfma_f32_16x16x32_bf16 v[24:27], v[226:229], v[188:191], v[24:27]
	v_mfma_f32_16x16x32_bf16 v[12:15], v[218:221], v[210:213], v[12:15]
	v_mfma_f32_16x16x32_bf16 v[8:11], v[226:229], v[210:213], v[8:11]
	v_mfma_f32_16x16x32_bf16 v[60:63], v[222:225], v[172:175], v[60:63]
	v_mfma_f32_16x16x32_bf16 v[56:59], v[230:233], v[172:175], v[56:59]
	v_mfma_f32_16x16x32_bf16 v[44:47], v[222:225], v[180:183], v[44:47]
	v_mfma_f32_16x16x32_bf16 v[40:43], v[230:233], v[180:183], v[40:43]
	v_mfma_f32_16x16x32_bf16 v[28:31], v[222:225], v[206:209], v[28:31]
	v_mfma_f32_16x16x32_bf16 v[24:27], v[230:233], v[206:209], v[24:27]
	v_mfma_f32_16x16x32_bf16 v[12:15], v[222:225], v[214:217], v[12:15]
	v_mfma_f32_16x16x32_bf16 v[8:11], v[230:233], v[214:217], v[8:11]
	s_setprio 0
	s_add_i32 s4, 0, 0x18000
	s_barrier
	ds_read_b128 v[144:147], v202
	ds_read_b128 v[156:159], v202 offset:1024
	ds_read_b128 v[160:163], v202 offset:2048
	ds_read_b128 v[164:167], v202 offset:3072
	s_add_u32 s0, s42, 0x80000
	s_addc_u32 s1, s43, 0
	s_mov_b32 m0, s52
	ds_read_b128 v[168:171], v150 offset:32768
	ds_read_b128 v[172:175], v150 offset:33792
	ds_read_b128 v[176:179], v150 offset:34816
	ds_read_b128 v[180:183], v150 offset:35840
	ds_read_b128 v[188:191], v150 offset:36864
	ds_read_b128 v[206:209], v150 offset:37888
	ds_read_b128 v[210:213], v150 offset:38912
	global_load_lds_dwordx4 v128, s[0:1]
	s_mov_b32 m0, s53
	ds_read_b128 v[214:217], v150 offset:39936
	global_load_lds_dwordx4 v132, s[0:1]
	s_waitcnt lgkmcnt(8)
	s_barrier
; #define PG8_STAGE(bufoff, gbase, voff) do { _Pragma("unroll") for (int _i = 0; _i < 2; ++_i) \
;         __builtin_amdgcn_global_load_lds((const unsigned*)((const char*)(gbase) + (voff)[_i]), (LAS unsigned*)(lds + (bufoff) + ldsw + _i * 8192), 16, 0, 0); } while (0)
; #define PG8_LDA(dst, b, h) do { _Pragma("unroll") for (int m = 0; m < 4; ++m) _Pragma("unroll") for (int k = 0; k < 2; ++k) dst[m][k] = *(const LAS bf16x8*)(lds + PG8_SA(b, h) + aoff + m * 2048 + k * 1024); } while (0)
; #define PG8_LDB(dst, b, h) do { _Pragma("unroll") for (int n = 0; n < 2; ++n) _Pragma("unroll") for (int k = 0; k < 2; ++k) dst[n][k] = *(const LAS bf16x8*)(lds + PG8_SB(b, h) + boff + n * 2048 + k * 1024); } while (0)
; #define PG8_MMA(ai, bj, At, Bt) do { __builtin_amdgcn_s_setprio(1); _Pragma("unroll") for (int m = 0; m < 4; ++m) _Pragma("unroll") for (int n = 0; n < 2; ++n) _Pragma("unroll") for (int k = 0; k < 2; ++k) \
;         acc[ai][bj][m][n] = __builtin_amdgcn_mfma_f32_16x16x32_bf16(Bt[n][k], At[m][k], acc[ai][bj][m][n], 0, 0, 0); __builtin_amdgcn_s_setprio(0); } while (0)
; #define PG8_WAIT_V(n) asm volatile("s_waitcnt vmcnt(" #n ")" ::: "memory")
; #define PG8_WAIT_L(n) asm volatile("s_waitcnt lgkmcnt(" #n ")" ::: "memory")
; #define PG8_BAR __builtin_amdgcn_s_barrier()
; #define PG8_SCHED __builtin_amdgcn_sched_barrier(0)
; template <class Epi, class Sched>
; DI void gemm_phase(LAS unsigned char* lds, const Gemm g, const Sched& S, const Epi& E) {
;     ...
;             PG8_WAIT_L(8); PG8_BAR; PG8_WAIT_L(0); PG8_MMA(0, 0, At, B0); PG8_BAR; PG8_SCHED;
;             PG8_LDB(B1, 1, 1); PG8_STAGE(PG8_SB(1, 0), b3, voffB);
;             PG8_BAR; PG8_WAIT_L(0); PG8_MMA(0, 1, At, B1); PG8_BAR;
;             PG8_LDA(At, 1, 1); PG8_STAGE(PG8_SA(1, 0), a3, voffA);
;             PG8_BAR; PG8_WAIT_L(0); PG8_MMA(1, 0, At, B0); PG8_BAR; PG8_SCHED;
;             PG8_STAGE(PG8_SB(1, 1), b3 + hstep, voffB);
;             PG8_WAIT_V(6); PG8_BAR; PG8_MMA(1, 1, At, B1); PG8_BAR;
	s_waitcnt lgkmcnt(0)
	s_setprio 1
	v_mfma_f32_16x16x32_bf16 v[116:119], v[144:147], v[168:171], v[116:119]
	v_mfma_f32_16x16x32_bf16 v[112:115], v[160:163], v[168:171], v[112:115]
	v_mfma_f32_16x16x32_bf16 v[100:103], v[144:147], v[176:179], v[100:103]
	v_mfma_f32_16x16x32_bf16 v[96:99], v[160:163], v[176:179], v[96:99]
	v_mfma_f32_16x16x32_bf16 v[84:87], v[144:147], v[188:191], v[84:87]
	v_mfma_f32_16x16x32_bf16 v[80:83], v[160:163], v[188:191], v[80:83]
	v_mfma_f32_16x16x32_bf16 v[68:71], v[144:147], v[210:213], v[68:71]
	v_mfma_f32_16x16x32_bf16 v[64:67], v[160:163], v[210:213], v[64:67]
	v_mfma_f32_16x16x32_bf16 v[116:119], v[156:159], v[172:175], v[116:119]
	v_mfma_f32_16x16x32_bf16 v[112:115], v[164:167], v[172:175], v[112:115]
	v_mfma_f32_16x16x32_bf16 v[100:103], v[156:159], v[180:183], v[100:103]
	v_mfma_f32_16x16x32_bf16 v[96:99], v[164:167], v[180:183], v[96:99]
	v_mfma_f32_16x16x32_bf16 v[84:87], v[156:159], v[206:209], v[84:87]
	v_mfma_f32_16x16x32_bf16 v[80:83], v[164:167], v[206:209], v[80:83]
	v_mfma_f32_16x16x32_bf16 v[68:71], v[156:159], v[214:217], v[68:71]
	v_mfma_f32_16x16x32_bf16 v[64:67], v[164:167], v[214:217], v[64:67]
	s_setprio 0
	s_barrier
	s_add_i32 s5, 0, 0x1c000
	s_add_i32 s0, s4, s50
	s_add_i32 m0, s0, 0xffffff80
	ds_read_b128 v[218:221], v203
	ds_read_b128 v[222:225], v203 offset:1024
	ds_read_b128 v[226:229], v203 offset:2048
	global_load_lds_dwordx4 v130, s[40:41] offset:128
	s_add_i32 m0, s0, 0x1f80
	ds_read_b128 v[230:233], v203 offset:3072
	global_load_lds_dwordx4 v134, s[40:41] offset:128
	s_barrier
	s_waitcnt lgkmcnt(0)
	s_setprio 1
	v_mfma_f32_16x16x32_bf16 v[124:127], v[218:221], v[168:171], v[124:127]
	v_mfma_f32_16x16x32_bf16 v[120:123], v[226:229], v[168:171], v[120:123]
	v_mfma_f32_16x16x32_bf16 v[108:111], v[218:221], v[176:179], v[108:111]
	v_mfma_f32_16x16x32_bf16 v[104:107], v[226:229], v[176:179], v[104:107]
	v_mfma_f32_16x16x32_bf16 v[92:95], v[218:221], v[188:191], v[92:95]
	v_mfma_f32_16x16x32_bf16 v[88:91], v[226:229], v[188:191], v[88:91]
	v_mfma_f32_16x16x32_bf16 v[76:79], v[218:221], v[210:213], v[76:79]
	v_mfma_f32_16x16x32_bf16 v[72:75], v[226:229], v[210:213], v[72:75]
	v_mfma_f32_16x16x32_bf16 v[124:127], v[222:225], v[172:175], v[124:127]
	v_mfma_f32_16x16x32_bf16 v[120:123], v[230:233], v[172:175], v[120:123]
	v_mfma_f32_16x16x32_bf16 v[108:111], v[222:225], v[180:183], v[108:111]
	v_mfma_f32_16x16x32_bf16 v[104:107], v[230:233], v[180:183], v[104:107]
	v_mfma_f32_16x16x32_bf16 v[92:95], v[222:225], v[206:209], v[92:95]
	v_mfma_f32_16x16x32_bf16 v[88:91], v[230:233], v[206:209], v[88:91]
	v_mfma_f32_16x16x32_bf16 v[76:79], v[222:225], v[214:217], v[76:79]
	v_mfma_f32_16x16x32_bf16 v[72:75], v[230:233], v[214:217], v[72:75]
	s_setprio 0
	s_add_i32 m0, s57, 0xffffff80
	s_barrier
	ds_read_b128 v[168:171], v150 offset:49152
	ds_read_b128 v[172:175], v150 offset:50176
	ds_read_b128 v[176:179], v150 offset:51200
	ds_read_b128 v[180:183], v150 offset:52224
	ds_read_b128 v[188:191], v150 offset:53248
	ds_read_b128 v[206:209], v150 offset:54272
	ds_read_b128 v[210:213], v150 offset:55296
	global_load_lds_dwordx4 v128, s[42:43] offset:128
	s_add_i32 m0, s58, 0xffffff80
	ds_read_b128 v[214:217], v150 offset:56320
	global_load_lds_dwordx4 v132, s[42:43] offset:128
	s_barrier
	s_waitcnt lgkmcnt(0)
	s_setprio 1
	v_mfma_f32_16x16x32_bf16 v[52:55], v[144:147], v[168:171], v[52:55]
	v_mfma_f32_16x16x32_bf16 v[48:51], v[160:163], v[168:171], v[48:51]
	v_mfma_f32_16x16x32_bf16 v[36:39], v[144:147], v[176:179], v[36:39]
	v_mfma_f32_16x16x32_bf16 v[32:35], v[160:163], v[176:179], v[32:35]
	v_mfma_f32_16x16x32_bf16 v[20:23], v[144:147], v[188:191], v[20:23]
	v_mfma_f32_16x16x32_bf16 v[16:19], v[160:163], v[188:191], v[16:19]
	v_mfma_f32_16x16x32_bf16 v[4:7], v[144:147], v[210:213], v[4:7]
	v_mfma_f32_16x16x32_bf16 v[0:3], v[160:163], v[210:213], v[0:3]
	v_mfma_f32_16x16x32_bf16 v[52:55], v[156:159], v[172:175], v[52:55]
	v_mfma_f32_16x16x32_bf16 v[48:51], v[164:167], v[172:175], v[48:51]
	v_mfma_f32_16x16x32_bf16 v[36:39], v[156:159], v[180:183], v[36:39]
	v_mfma_f32_16x16x32_bf16 v[32:35], v[164:167], v[180:183], v[32:35]
	v_mfma_f32_16x16x32_bf16 v[20:23], v[156:159], v[206:209], v[20:23]
	v_mfma_f32_16x16x32_bf16 v[16:19], v[164:167], v[206:209], v[16:19]
	v_mfma_f32_16x16x32_bf16 v[4:7], v[156:159], v[214:217], v[4:7]
	v_mfma_f32_16x16x32_bf16 v[0:3], v[164:167], v[214:217], v[0:3]
	s_setprio 0
	s_barrier
	s_add_i32 s4, s5, s50
	s_mov_b32 m0, s4
	s_add_u32 s0, s40, 0x80080
	s_addc_u32 s1, s41, 0
	global_load_lds_dwordx4 v130, s[0:1]
	s_add_i32 m0, s4, 0x2000
	s_nop 0
	global_load_lds_dwordx4 v134, s[0:1]
	s_waitcnt vmcnt(6)
	s_barrier
	s_setprio 1
	v_mfma_f32_16x16x32_bf16 v[60:63], v[218:221], v[168:171], v[60:63]
	v_mfma_f32_16x16x32_bf16 v[56:59], v[226:229], v[168:171], v[56:59]
	v_mfma_f32_16x16x32_bf16 v[44:47], v[218:221], v[176:179], v[44:47]
	v_mfma_f32_16x16x32_bf16 v[40:43], v[226:229], v[176:179], v[40:43]
	v_mfma_f32_16x16x32_bf16 v[28:31], v[218:221], v[188:191], v[28:31]
	v_mfma_f32_16x16x32_bf16 v[24:27], v[226:229], v[188:191], v[24:27]
	v_mfma_f32_16x16x32_bf16 v[12:15], v[218:221], v[210:213], v[12:15]
	v_mfma_f32_16x16x32_bf16 v[8:11], v[226:229], v[210:213], v[8:11]
	v_mfma_f32_16x16x32_bf16 v[60:63], v[222:225], v[172:175], v[60:63]
	v_mfma_f32_16x16x32_bf16 v[56:59], v[230:233], v[172:175], v[56:59]
	v_mfma_f32_16x16x32_bf16 v[44:47], v[222:225], v[180:183], v[44:47]
	v_mfma_f32_16x16x32_bf16 v[40:43], v[230:233], v[180:183], v[40:43]
	v_mfma_f32_16x16x32_bf16 v[28:31], v[222:225], v[206:209], v[28:31]
	v_mfma_f32_16x16x32_bf16 v[24:27], v[230:233], v[206:209], v[24:27]
	v_mfma_f32_16x16x32_bf16 v[12:15], v[222:225], v[214:217], v[12:15]
	v_mfma_f32_16x16x32_bf16 v[8:11], v[230:233], v[214:217], v[8:11]
	s_setprio 0
	s_add_i32 s68, s68, 2
	s_add_u32 s8, s8, 0x100
	s_addc_u32 s9, s9, 0
	s_add_u32 s66, s66, 0x100
	s_addc_u32 s67, s67, 0
	s_cmp_gt_u32 s68, 29
	s_barrier
	s_cbranch_scc0 .LBB0_1668

;     DI size_t aoff(const Unit& u, size_t tstep) const { return (size_t)u.pm * tstep; }
;     DI size_t boff(const Unit& u, size_t tstep) const { return (size_t)u.pn * tstep; }
;     DI bool next(int i, Unit& u) const { const long L = (long)i * G + c; if (L >= np) return false; u.pm = pmv; u.pn = (int)(L % nN); u.ks = (int)(L / nN); return true; }
;     DI size_t aoff(const Unit& u, size_t) const { return (size_t)u.ks * kbytes; }
;     DI size_t boff(const Unit& u, size_t tstep) const { return (size_t)u.pn * tstep + (size_t)u.ks * kbytes; }
;     DI bool next(int i, Unit& u) const { Unit t; if (!S.next(i / 3, t)) return false; u.pm = t.pm; u.pn = t.pn; u.ks = i % 3; return true; }
;     DI size_t aoff(const Unit& u, size_t tstep) const { return (u.ks < 2 ? offU : offOA) + (size_t)u.pm * tstep; }
; #define PG8_WAIT_V(n) asm volatile("s_waitcnt vmcnt(" #n ")" ::: "memory")
; template <class Epi, class Sched>
; DI void gemm_phase(LAS unsigned char* lds, const Gemm g, const Sched& S, const Epi& E) {
;     ...
;         const bool has_next = S.next(ui + 1, nxt);
;         const char* nA = has_next ? (const char*)g.A + S.aoff(nxt, tstep) : cA; const char* nB = has_next ? (const char*)g.Bt + S.boff(nxt, tstep) : cB;
;         for (int t = 0; t < nt; t += 2) {
;             if constexpr (Epi::HAS_MID) { if (t == E.mid_t(nt)) { int fr3 = fr, fq3 = fq; asm volatile("" : "+v"(fr3), "+v"(fq3)); E.mid(acc, cur, wr, wc, fr3, fq3); } }
;             const bool last = (t == nt - 2);
;             const char* a1 = cA + (size_t)(t + 1) * kstep;
;             const char* a2 = last ? nA : cA + (size_t)(t + 2) * kstep; const char* b2 = last ? nB : cB + (size_t)(t + 2) * kstep;
;             const char* a3 = a2 + kstep; const char* b3 = b2 + kstep;
;             PG8_LDB(B0, 0, 0); PG8_SCHED; PG8_LDA(At, 0, 0); PG8_STAGE(PG8_SA(1, 1), a1 + hstep, voffA);
;             PG8_WAIT_L(8); PG8_BAR; PG8_WAIT_L(0); PG8_MMA(0, 0, At, B0); PG8_BAR; PG8_SCHED;
;             PG8_LDB(B1, 0, 1); PG8_STAGE(PG8_SB(0, 0), b2, voffB);
;             PG8_BAR; PG8_WAIT_L(0); PG8_MMA(0, 1, At, B1); PG8_BAR;
;             PG8_LDA(At, 0, 1); PG8_STAGE(PG8_SA(0, 0), a2, voffA);
;             PG8_BAR; PG8_WAIT_L(0); PG8_MMA(1, 0, At, B0); PG8_BAR; PG8_SCHED;
;             PG8_STAGE(PG8_SB(0, 1), b2 + hstep, voffB);
;             PG8_WAIT_V(6); PG8_BAR; PG8_MMA(1, 1, At, B1); PG8_BAR;
.LBB0_1774:
	s_add_u32 s28, s38, s28
	s_addc_u32 s29, s39, s29
	s_and_b64 s[0:1], s[8:9], exec
	s_cselect_b32 s15, s29, s37
	s_cselect_b32 s17, s28, s36
	s_add_u32 s8, s36, 0x160080
	s_addc_u32 s9, s37, 0
	s_add_u32 s64, s30, 0x100
	v_mov_b32_e32 v0, 0
	s_addc_u32 s65, s31, 0
	s_mov_b32 s66, -2
	ds_read_b128 v[146:149], v141
	ds_read_b128 v[154:157], v141 offset:1024
	ds_read_b128 v[158:161], v141 offset:2048
	ds_read_b128 v[162:165], v141 offset:3072
	s_mov_b32 m0, s56
	ds_read_b128 v[166:169], v142
	ds_read_b128 v[170:173], v142 offset:1024
	ds_read_b128 v[174:177], v142 offset:2048
	ds_read_b128 v[178:181], v142 offset:3072
	ds_read_b128 v[188:191], v142 offset:4096
	ds_read_b128 v[206:209], v142 offset:5120
	ds_read_b128 v[210:213], v142 offset:6144
	global_load_lds_dwordx4 v132, s[8:9]
	s_mov_b32 m0, s57
	ds_read_b128 v[214:217], v142 offset:7168
	global_load_lds_dwordx4 v134, s[8:9]
	s_add_u32 s0, s8, 0xffea0080
	s_addc_u32 s1, s9, -1
	s_cmp_eq_u32 s66, 4
	s_cselect_b32 s37, s15, s1
	s_cselect_b32 s36, s17, s0
	s_cselect_b32 s31, s19, s65
	s_cselect_b32 s30, s18, s64
	s_waitcnt lgkmcnt(8)
	s_barrier
	s_waitcnt lgkmcnt(0)
	s_setprio 1
	v_mfma_f32_16x16x32_bf16 v[124:127], v[146:149], v[166:169], 0
	v_mfma_f32_16x16x32_bf16 v[120:123], v[158:161], v[166:169], 0
	v_mfma_f32_16x16x32_bf16 v[116:119], v[146:149], v[174:177], 0
	v_mfma_f32_16x16x32_bf16 v[112:115], v[158:161], v[174:177], 0
	v_mfma_f32_16x16x32_bf16 v[104:107], v[146:149], v[188:191], 0
	v_mfma_f32_16x16x32_bf16 v[96:99], v[158:161], v[188:191], 0
	v_mfma_f32_16x16x32_bf16 v[88:91], v[146:149], v[210:213], 0
	v_mfma_f32_16x16x32_bf16 v[80:83], v[158:161], v[210:213], 0
	v_mfma_f32_16x16x32_bf16 v[124:127], v[154:157], v[170:173], v[124:127]
	v_mfma_f32_16x16x32_bf16 v[120:123], v[162:165], v[170:173], v[120:123]
	v_mfma_f32_16x16x32_bf16 v[116:119], v[154:157], v[178:181], v[116:119]
	v_mfma_f32_16x16x32_bf16 v[112:115], v[162:165], v[178:181], v[112:115]
	v_mfma_f32_16x16x32_bf16 v[104:107], v[154:157], v[206:209], v[104:107]
	v_mfma_f32_16x16x32_bf16 v[96:99], v[162:165], v[206:209], v[96:99]
	v_mfma_f32_16x16x32_bf16 v[88:91], v[154:157], v[214:217], v[88:91]
	v_mfma_f32_16x16x32_bf16 v[80:83], v[162:165], v[214:217], v[80:83]
	s_setprio 0
	s_barrier
	s_mov_b32 m0, s58
	ds_read_b128 v[218:221], v143
	ds_read_b128 v[222:225], v143 offset:1024
	ds_read_b128 v[226:229], v143 offset:2048
	global_load_lds_dwordx4 v130, s[30:31]
	s_mov_b32 m0, s59
	ds_read_b128 v[230:233], v143 offset:3072
	global_load_lds_dwordx4 v128, s[30:31]
	s_barrier
	s_waitcnt lgkmcnt(0)
	s_setprio 1
	v_mfma_f32_16x16x32_bf16 v[108:111], v[218:221], v[166:169], 0
	v_mfma_f32_16x16x32_bf16 v[100:103], v[226:229], v[166:169], 0
	v_mfma_f32_16x16x32_bf16 v[92:95], v[218:221], v[174:177], 0
	v_mfma_f32_16x16x32_bf16 v[84:87], v[226:229], v[174:177], 0
	v_mfma_f32_16x16x32_bf16 v[76:79], v[218:221], v[188:191], 0
	v_mfma_f32_16x16x32_bf16 v[72:75], v[226:229], v[188:191], 0
	v_mfma_f32_16x16x32_bf16 v[68:71], v[218:221], v[210:213], 0
	v_mfma_f32_16x16x32_bf16 v[64:67], v[226:229], v[210:213], 0
	v_mfma_f32_16x16x32_bf16 v[108:111], v[222:225], v[170:173], v[108:111]
	v_mfma_f32_16x16x32_bf16 v[100:103], v[230:233], v[170:173], v[100:103]
	v_mfma_f32_16x16x32_bf16 v[92:95], v[222:225], v[178:181], v[92:95]
	v_mfma_f32_16x16x32_bf16 v[84:87], v[230:233], v[178:181], v[84:87]
	v_mfma_f32_16x16x32_bf16 v[76:79], v[222:225], v[206:209], v[76:79]
	v_mfma_f32_16x16x32_bf16 v[72:75], v[230:233], v[206:209], v[72:75]
	v_mfma_f32_16x16x32_bf16 v[68:71], v[222:225], v[214:217], v[68:71]
	v_mfma_f32_16x16x32_bf16 v[64:67], v[230:233], v[214:217], v[64:67]
	s_setprio 0
	s_mov_b32 m0, s40
	s_barrier
	ds_read_b128 v[166:169], v142 offset:16384
	ds_read_b128 v[170:173], v142 offset:17408
	ds_read_b128 v[174:177], v142 offset:18432
	ds_read_b128 v[178:181], v142 offset:19456
	ds_read_b128 v[188:191], v142 offset:20480
	ds_read_b128 v[206:209], v142 offset:21504
	ds_read_b128 v[210:213], v142 offset:22528
	global_load_lds_dwordx4 v130, s[36:37]
	s_mov_b32 m0, s41
	ds_read_b128 v[214:217], v142 offset:23552
	global_load_lds_dwordx4 v128, s[36:37]
	s_barrier
	s_waitcnt lgkmcnt(0)
	s_setprio 1
	v_mfma_f32_16x16x32_bf16 v[60:63], v[146:149], v[166:169], 0
	v_mfma_f32_16x16x32_bf16 v[56:59], v[158:161], v[166:169], 0
	v_mfma_f32_16x16x32_bf16 v[52:55], v[146:149], v[174:177], 0
	v_mfma_f32_16x16x32_bf16 v[48:51], v[158:161], v[174:177], 0
	v_mfma_f32_16x16x32_bf16 v[40:43], v[146:149], v[188:191], 0
	v_mfma_f32_16x16x32_bf16 v[32:35], v[158:161], v[188:191], 0
	v_mfma_f32_16x16x32_bf16 v[24:27], v[146:149], v[210:213], 0
	v_mfma_f32_16x16x32_bf16 v[16:19], v[158:161], v[210:213], 0
	v_mfma_f32_16x16x32_bf16 v[60:63], v[154:157], v[170:173], v[60:63]
	v_mfma_f32_16x16x32_bf16 v[56:59], v[162:165], v[170:173], v[56:59]
	v_mfma_f32_16x16x32_bf16 v[52:55], v[154:157], v[178:181], v[52:55]
	v_mfma_f32_16x16x32_bf16 v[48:51], v[162:165], v[178:181], v[48:51]
	v_mfma_f32_16x16x32_bf16 v[40:43], v[154:157], v[206:209], v[40:43]
	v_mfma_f32_16x16x32_bf16 v[32:35], v[162:165], v[206:209], v[32:35]
	v_mfma_f32_16x16x32_bf16 v[24:27], v[154:157], v[214:217], v[24:27]
	v_mfma_f32_16x16x32_bf16 v[16:19], v[162:165], v[214:217], v[16:19]
	s_setprio 0
	s_barrier
	s_add_u32 s0, s30, 0x160000
	s_addc_u32 s1, s31, 0
	s_mov_b32 m0, s60
	s_nop 0
	global_load_lds_dwordx4 v130, s[0:1]
	s_mov_b32 m0, s61
	s_nop 0
	global_load_lds_dwordx4 v128, s[0:1]
	s_waitcnt vmcnt(6)
	s_barrier
; #define PG8_STAGE(bufoff, gbase, voff) do { _Pragma("unroll") for (int _i = 0; _i < 2; ++_i) \
;         __builtin_amdgcn_global_load_lds((const unsigned*)((const char*)(gbase) + (voff)[_i]), (LAS unsigned*)(lds + (bufoff) + ldsw + _i * 8192), 16, 0, 0); } while (0)
; #define PG8_LDA(dst, b, h) do { _Pragma("unroll") for (int m = 0; m < 4; ++m) _Pragma("unroll") for (int k = 0; k < 2; ++k) dst[m][k] = *(const LAS bf16x8*)(lds + PG8_SA(b, h) + aoff + m * 2048 + k * 1024); } while (0)
; #define PG8_LDB(dst, b, h) do { _Pragma("unroll") for (int n = 0; n < 2; ++n) _Pragma("unroll") for (int k = 0; k < 2; ++k) dst[n][k] = *(const LAS bf16x8*)(lds + PG8_SB(b, h) + boff + n * 2048 + k * 1024); } while (0)
; #define PG8_MMA(ai, bj, At, Bt) do { __builtin_amdgcn_s_setprio(1); _Pragma("unroll") for (int m = 0; m < 4; ++m) _Pragma("unroll") for (int n = 0; n < 2; ++n) _Pragma("unroll") for (int k = 0; k < 2; ++k) \
;         acc[ai][bj][m][n] = __builtin_amdgcn_mfma_f32_16x16x32_bf16(Bt[n][k], At[m][k], acc[ai][bj][m][n], 0, 0, 0); __builtin_amdgcn_s_setprio(0); } while (0)
; #define PG8_WAIT_V(n) asm volatile("s_waitcnt vmcnt(" #n ")" ::: "memory")
; #define PG8_WAIT_L(n) asm volatile("s_waitcnt lgkmcnt(" #n ")" ::: "memory")
; #define PG8_BAR __builtin_amdgcn_s_barrier()
; #define PG8_SCHED __builtin_amdgcn_sched_barrier(0)
; template <class Epi, class Sched>
; DI void gemm_phase(LAS unsigned char* lds, const Gemm g, const Sched& S, const Epi& E) {
;     ...
;             PG8_WAIT_V(6); PG8_BAR; PG8_MMA(1, 1, At, B1); PG8_BAR;
;             PG8_LDB(B0, 1, 0); PG8_SCHED; PG8_LDA(At, 1, 0); PG8_STAGE(PG8_SA(0, 1), a2 + hstep, voffA);
;             PG8_WAIT_L(8); PG8_BAR; PG8_WAIT_L(0); PG8_MMA(0, 0, At, B0); PG8_BAR; PG8_SCHED;
;             PG8_LDB(B1, 1, 1); PG8_STAGE(PG8_SB(1, 0), b3, voffB);
;             PG8_BAR; PG8_WAIT_L(0); PG8_MMA(0, 1, At, B1); PG8_BAR;
;             PG8_LDA(At, 1, 1); PG8_STAGE(PG8_SA(1, 0), a3, voffA);
;             PG8_BAR; PG8_WAIT_L(0); PG8_MMA(1, 0, At, B0); PG8_BAR; PG8_SCHED;
	s_setprio 1
	v_mfma_f32_16x16x32_bf16 v[44:47], v[218:221], v[166:169], 0
	v_mfma_f32_16x16x32_bf16 v[36:39], v[226:229], v[166:169], 0
	v_mfma_f32_16x16x32_bf16 v[28:31], v[218:221], v[174:177], 0
	v_mfma_f32_16x16x32_bf16 v[20:23], v[226:229], v[174:177], 0
	v_mfma_f32_16x16x32_bf16 v[12:15], v[218:221], v[188:191], 0
	v_mfma_f32_16x16x32_bf16 v[8:11], v[226:229], v[188:191], 0
	v_mfma_f32_16x16x32_bf16 v[4:7], v[218:221], v[210:213], 0
	v_mfma_f32_16x16x32_bf16 v[0:3], v[226:229], v[210:213], 0
	v_mfma_f32_16x16x32_bf16 v[44:47], v[222:225], v[170:173], v[44:47]
	v_mfma_f32_16x16x32_bf16 v[36:39], v[230:233], v[170:173], v[36:39]
	v_mfma_f32_16x16x32_bf16 v[28:31], v[222:225], v[178:181], v[28:31]
	v_mfma_f32_16x16x32_bf16 v[20:23], v[230:233], v[178:181], v[20:23]
	v_mfma_f32_16x16x32_bf16 v[12:15], v[222:225], v[206:209], v[12:15]
	v_mfma_f32_16x16x32_bf16 v[8:11], v[230:233], v[206:209], v[8:11]
	v_mfma_f32_16x16x32_bf16 v[4:7], v[222:225], v[214:217], v[4:7]
	v_mfma_f32_16x16x32_bf16 v[0:3], v[230:233], v[214:217], v[0:3]
	s_setprio 0
	s_barrier
	ds_read_b128 v[146:149], v144
	ds_read_b128 v[154:157], v144 offset:1024
	ds_read_b128 v[158:161], v144 offset:2048
	ds_read_b128 v[162:165], v144 offset:3072
	s_add_u32 s0, s36, 0x160000
	s_addc_u32 s1, s37, 0
	s_mov_b32 m0, s42
	ds_read_b128 v[166:169], v142 offset:32768
	ds_read_b128 v[170:173], v142 offset:33792
	ds_read_b128 v[174:177], v142 offset:34816
	ds_read_b128 v[178:181], v142 offset:35840
	ds_read_b128 v[188:191], v142 offset:36864
	ds_read_b128 v[206:209], v142 offset:37888
	ds_read_b128 v[210:213], v142 offset:38912
	global_load_lds_dwordx4 v130, s[0:1]
	s_mov_b32 m0, s43
	ds_read_b128 v[214:217], v142 offset:39936
	global_load_lds_dwordx4 v128, s[0:1]
	s_waitcnt lgkmcnt(8)
	s_barrier
	s_waitcnt lgkmcnt(0)
	s_setprio 1
	v_mfma_f32_16x16x32_bf16 v[124:127], v[146:149], v[166:169], v[124:127]
	v_mfma_f32_16x16x32_bf16 v[120:123], v[158:161], v[166:169], v[120:123]
	v_mfma_f32_16x16x32_bf16 v[116:119], v[146:149], v[174:177], v[116:119]
	v_mfma_f32_16x16x32_bf16 v[112:115], v[158:161], v[174:177], v[112:115]
	v_mfma_f32_16x16x32_bf16 v[104:107], v[146:149], v[188:191], v[104:107]
	v_mfma_f32_16x16x32_bf16 v[96:99], v[158:161], v[188:191], v[96:99]
	v_mfma_f32_16x16x32_bf16 v[88:91], v[146:149], v[210:213], v[88:91]
	v_mfma_f32_16x16x32_bf16 v[80:83], v[158:161], v[210:213], v[80:83]
	v_mfma_f32_16x16x32_bf16 v[124:127], v[154:157], v[170:173], v[124:127]
	v_mfma_f32_16x16x32_bf16 v[120:123], v[162:165], v[170:173], v[120:123]
	v_mfma_f32_16x16x32_bf16 v[116:119], v[154:157], v[178:181], v[116:119]
	v_mfma_f32_16x16x32_bf16 v[112:115], v[162:165], v[178:181], v[112:115]
	v_mfma_f32_16x16x32_bf16 v[104:107], v[154:157], v[206:209], v[104:107]
	v_mfma_f32_16x16x32_bf16 v[96:99], v[162:165], v[206:209], v[96:99]
	v_mfma_f32_16x16x32_bf16 v[88:91], v[154:157], v[214:217], v[88:91]
	v_mfma_f32_16x16x32_bf16 v[80:83], v[162:165], v[214:217], v[80:83]
	s_setprio 0
	s_barrier
	s_add_i32 s4, 0, 0x1c000
	s_add_i32 s0, s62, s35
	v_add_u32_e32 v145, s4, v140
	s_add_i32 m0, s0, 0xffffff80
	ds_read_b128 v[218:221], v145
	ds_read_b128 v[222:225], v145 offset:1024
	ds_read_b128 v[226:229], v145 offset:2048
	global_load_lds_dwordx4 v130, s[30:31] offset:128
	s_add_i32 m0, s0, 0x1f80
	ds_read_b128 v[230:233], v145 offset:3072
	global_load_lds_dwordx4 v128, s[30:31] offset:128
	s_barrier
	s_waitcnt lgkmcnt(0)
	s_setprio 1
	v_mfma_f32_16x16x32_bf16 v[108:111], v[218:221], v[166:169], v[108:111]
	v_mfma_f32_16x16x32_bf16 v[100:103], v[226:229], v[166:169], v[100:103]
	v_mfma_f32_16x16x32_bf16 v[92:95], v[218:221], v[174:177], v[92:95]
	v_mfma_f32_16x16x32_bf16 v[84:87], v[226:229], v[174:177], v[84:87]
	v_mfma_f32_16x16x32_bf16 v[76:79], v[218:221], v[188:191], v[76:79]
	v_mfma_f32_16x16x32_bf16 v[72:75], v[226:229], v[188:191], v[72:75]
	v_mfma_f32_16x16x32_bf16 v[68:71], v[218:221], v[210:213], v[68:71]
	v_mfma_f32_16x16x32_bf16 v[64:67], v[226:229], v[210:213], v[64:67]
	v_mfma_f32_16x16x32_bf16 v[108:111], v[222:225], v[170:173], v[108:111]
	v_mfma_f32_16x16x32_bf16 v[100:103], v[230:233], v[170:173], v[100:103]
	v_mfma_f32_16x16x32_bf16 v[92:95], v[222:225], v[178:181], v[92:95]
	v_mfma_f32_16x16x32_bf16 v[84:87], v[230:233], v[178:181], v[84:87]
	v_mfma_f32_16x16x32_bf16 v[76:79], v[222:225], v[206:209], v[76:79]
	v_mfma_f32_16x16x32_bf16 v[72:75], v[230:233], v[206:209], v[72:75]
	v_mfma_f32_16x16x32_bf16 v[68:71], v[222:225], v[214:217], v[68:71]
	v_mfma_f32_16x16x32_bf16 v[64:67], v[230:233], v[214:217], v[64:67]
	s_setprio 0
	s_add_i32 m0, s54, 0xffffff80
	s_barrier
	ds_read_b128 v[166:169], v142 offset:49152
	ds_read_b128 v[170:173], v142 offset:50176
	ds_read_b128 v[174:177], v142 offset:51200
	ds_read_b128 v[178:181], v142 offset:52224
	ds_read_b128 v[188:191], v142 offset:53248
	ds_read_b128 v[206:209], v142 offset:54272
	ds_read_b128 v[210:213], v142 offset:55296
	global_load_lds_dwordx4 v130, s[36:37] offset:128
	s_add_i32 m0, s55, 0xffffff80
	ds_read_b128 v[214:217], v142 offset:56320
	global_load_lds_dwordx4 v128, s[36:37] offset:128
	s_barrier
; #define PG8_STAGE(bufoff, gbase, voff) do { _Pragma("unroll") for (int _i = 0; _i < 2; ++_i) \
;         __builtin_amdgcn_global_load_lds((const unsigned*)((const char*)(gbase) + (voff)[_i]), (LAS unsigned*)(lds + (bufoff) + ldsw + _i * 8192), 16, 0, 0); } while (0)
; #define PG8_LDA(dst, b, h) do { _Pragma("unroll") for (int m = 0; m < 4; ++m) _Pragma("unroll") for (int k = 0; k < 2; ++k) dst[m][k] = *(const LAS bf16x8*)(lds + PG8_SA(b, h) + aoff + m * 2048 + k * 1024); } while (0)
; #define PG8_LDB(dst, b, h) do { _Pragma("unroll") for (int n = 0; n < 2; ++n) _Pragma("unroll") for (int k = 0; k < 2; ++k) dst[n][k] = *(const LAS bf16x8*)(lds + PG8_SB(b, h) + boff + n * 2048 + k * 1024); } while (0)
; #define PG8_WAIT_V(n) asm volatile("s_waitcnt vmcnt(" #n ")" ::: "memory")
; #define PG8_WAIT_L(n) asm volatile("s_waitcnt lgkmcnt(" #n ")" ::: "memory")
; #define PG8_BAR __builtin_amdgcn_s_barrier()
; #define PG8_SCHED __builtin_amdgcn_sched_barrier(0)
; template <class Epi, class Sched>
; DI void gemm_phase(LAS unsigned char* lds, const Gemm g, const Sched& S, const Epi& E) {
;     ...
;             PG8_LDB(B0, 0, 0); PG8_SCHED; PG8_LDA(At, 0, 0); PG8_STAGE(PG8_SA(1, 1), a1 + hstep, voffA);
;             PG8_WAIT_L(8); PG8_BAR; PG8_WAIT_L(0); PG8_MMA(0, 0, At, B0); PG8_BAR; PG8_SCHED;
;             PG8_LDB(B1, 0, 1); PG8_STAGE(PG8_SB(0, 0), b2, voffB);
;             PG8_BAR; PG8_WAIT_L(0); PG8_MMA(0, 1, At, B1); PG8_BAR;
;             PG8_LDA(At, 0, 1); PG8_STAGE(PG8_SA(0, 0), a2, voffA);
;             PG8_BAR; PG8_WAIT_L(0); PG8_MMA(1, 0, At, B0); PG8_BAR; PG8_SCHED;
;             PG8_STAGE(PG8_SB(0, 1), b2 + hstep, voffB);
;             PG8_WAIT_V(6); PG8_BAR; PG8_MMA(1, 1, At, B1); PG8_BAR;
;             PG8_LDB(B0, 1, 0); PG8_SCHED; PG8_LDA(At, 1, 0); PG8_STAGE(PG8_SA(0, 1), a2 + hstep, voffA);
;             PG8_WAIT_L(8); PG8_BAR; PG8_WAIT_L(0); PG8_MMA(0, 0, At, B0); PG8_BAR; PG8_SCHED;
;             PG8_LDB(B1, 1, 1); PG8_STAGE(PG8_SB(1, 0), b3, voffB);
;             PG8_BAR; PG8_WAIT_L(0); PG8_MMA(0, 1, At, B1); PG8_BAR;
;             PG8_LDA(At, 1, 1); PG8_STAGE(PG8_SA(1, 0), a3, voffA);
;             PG8_BAR; PG8_WAIT_L(0); PG8_MMA(1, 0, At, B0); PG8_BAR; PG8_SCHED;
;             PG8_STAGE(PG8_SB(1, 1), b3 + hstep, voffB);
;             PG8_WAIT_V(6); PG8_BAR; PG8_MMA(1, 1, At, B1); PG8_BAR;
	s_waitcnt lgkmcnt(0)
	s_setprio 1
	v_mfma_f32_16x16x32_bf16 v[60:63], v[146:149], v[166:169], v[60:63]
	v_mfma_f32_16x16x32_bf16 v[56:59], v[158:161], v[166:169], v[56:59]
	v_mfma_f32_16x16x32_bf16 v[52:55], v[146:149], v[174:177], v[52:55]
	v_mfma_f32_16x16x32_bf16 v[48:51], v[158:161], v[174:177], v[48:51]
	v_mfma_f32_16x16x32_bf16 v[40:43], v[146:149], v[188:191], v[40:43]
	v_mfma_f32_16x16x32_bf16 v[32:35], v[158:161], v[188:191], v[32:35]
	v_mfma_f32_16x16x32_bf16 v[24:27], v[146:149], v[210:213], v[24:27]
	v_mfma_f32_16x16x32_bf16 v[16:19], v[158:161], v[210:213], v[16:19]
	v_mfma_f32_16x16x32_bf16 v[60:63], v[154:157], v[170:173], v[60:63]
	v_mfma_f32_16x16x32_bf16 v[56:59], v[162:165], v[170:173], v[56:59]
	v_mfma_f32_16x16x32_bf16 v[52:55], v[154:157], v[178:181], v[52:55]
	v_mfma_f32_16x16x32_bf16 v[48:51], v[162:165], v[178:181], v[48:51]
	v_mfma_f32_16x16x32_bf16 v[40:43], v[154:157], v[206:209], v[40:43]
	v_mfma_f32_16x16x32_bf16 v[32:35], v[162:165], v[206:209], v[32:35]
	v_mfma_f32_16x16x32_bf16 v[24:27], v[154:157], v[214:217], v[24:27]
	v_mfma_f32_16x16x32_bf16 v[16:19], v[162:165], v[214:217], v[16:19]
	s_setprio 0
	s_barrier
	s_add_i32 s4, s4, s35
	s_mov_b32 m0, s4
	s_add_u32 s0, s30, 0x160080
	s_addc_u32 s1, s31, 0
	global_load_lds_dwordx4 v130, s[0:1]
	s_add_i32 m0, s4, 0x2000
	s_nop 0
	global_load_lds_dwordx4 v128, s[0:1]
	s_waitcnt vmcnt(6)
	s_barrier
	s_setprio 1
	v_mfma_f32_16x16x32_bf16 v[44:47], v[218:221], v[166:169], v[44:47]
	v_mfma_f32_16x16x32_bf16 v[36:39], v[226:229], v[166:169], v[36:39]
	v_mfma_f32_16x16x32_bf16 v[28:31], v[218:221], v[174:177], v[28:31]
	v_mfma_f32_16x16x32_bf16 v[20:23], v[226:229], v[174:177], v[20:23]
	v_mfma_f32_16x16x32_bf16 v[12:15], v[218:221], v[188:191], v[12:15]
	v_mfma_f32_16x16x32_bf16 v[8:11], v[226:229], v[188:191], v[8:11]
	v_mfma_f32_16x16x32_bf16 v[4:7], v[218:221], v[210:213], v[4:7]
	v_mfma_f32_16x16x32_bf16 v[0:3], v[226:229], v[210:213], v[0:3]
	v_mfma_f32_16x16x32_bf16 v[44:47], v[222:225], v[170:173], v[44:47]
	v_mfma_f32_16x16x32_bf16 v[36:39], v[230:233], v[170:173], v[36:39]
	v_mfma_f32_16x16x32_bf16 v[28:31], v[222:225], v[178:181], v[28:31]
	v_mfma_f32_16x16x32_bf16 v[20:23], v[230:233], v[178:181], v[20:23]
	v_mfma_f32_16x16x32_bf16 v[12:15], v[222:225], v[206:209], v[12:15]
	v_mfma_f32_16x16x32_bf16 v[8:11], v[230:233], v[206:209], v[8:11]
	v_mfma_f32_16x16x32_bf16 v[4:7], v[222:225], v[214:217], v[4:7]
	v_mfma_f32_16x16x32_bf16 v[0:3], v[230:233], v[214:217], v[0:3]
	s_setprio 0
	s_add_i32 s66, s66, 2
	s_add_u32 s8, s8, 0x100
	s_addc_u32 s9, s9, 0
	s_add_u32 s64, s64, 0x100
	s_addc_u32 s65, s65, 0
	s_cmp_gt_u32 s66, 5
	s_barrier
	s_cbranch_scc0 .LBB0_1775
	s_branch .Lpeel_done_1775
.LBB0_1775:
	ds_read_b128 v[146:149], v141
	ds_read_b128 v[154:157], v141 offset:1024
	ds_read_b128 v[158:161], v141 offset:2048
	ds_read_b128 v[162:165], v141 offset:3072
	s_mov_b32 m0, s56
	ds_read_b128 v[166:169], v142
	ds_read_b128 v[170:173], v142 offset:1024
	ds_read_b128 v[174:177], v142 offset:2048
	ds_read_b128 v[178:181], v142 offset:3072
	ds_read_b128 v[188:191], v142 offset:4096
	ds_read_b128 v[206:209], v142 offset:5120
	ds_read_b128 v[210:213], v142 offset:6144
	global_load_lds_dwordx4 v132, s[8:9]
	s_mov_b32 m0, s57
	ds_read_b128 v[214:217], v142 offset:7168
	global_load_lds_dwordx4 v134, s[8:9]
	s_add_u32 s0, s8, 0xffea0080
	s_addc_u32 s1, s9, -1
	s_cmp_eq_u32 s66, 4
	s_cselect_b32 s37, s15, s1
	s_cselect_b32 s36, s17, s0
	s_cselect_b32 s31, s19, s65
	s_cselect_b32 s30, s18, s64
	s_waitcnt lgkmcnt(8)
	s_barrier
	s_waitcnt lgkmcnt(0)
	s_setprio 1
	v_mfma_f32_16x16x32_bf16 v[124:127], v[146:149], v[166:169], v[124:127]
	v_mfma_f32_16x16x32_bf16 v[120:123], v[158:161], v[166:169], v[120:123]
	v_mfma_f32_16x16x32_bf16 v[116:119], v[146:149], v[174:177], v[116:119]
	v_mfma_f32_16x16x32_bf16 v[112:115], v[158:161], v[174:177], v[112:115]
	v_mfma_f32_16x16x32_bf16 v[104:107], v[146:149], v[188:191], v[104:107]
	v_mfma_f32_16x16x32_bf16 v[96:99], v[158:161], v[188:191], v[96:99]
	v_mfma_f32_16x16x32_bf16 v[88:91], v[146:149], v[210:213], v[88:91]
	v_mfma_f32_16x16x32_bf16 v[80:83], v[158:161], v[210:213], v[80:83]
	v_mfma_f32_16x16x32_bf16 v[124:127], v[154:157], v[170:173], v[124:127]
	v_mfma_f32_16x16x32_bf16 v[120:123], v[162:165], v[170:173], v[120:123]
	v_mfma_f32_16x16x32_bf16 v[116:119], v[154:157], v[178:181], v[116:119]
	v_mfma_f32_16x16x32_bf16 v[112:115], v[162:165], v[178:181], v[112:115]
	v_mfma_f32_16x16x32_bf16 v[104:107], v[154:157], v[206:209], v[104:107]
	v_mfma_f32_16x16x32_bf16 v[96:99], v[162:165], v[206:209], v[96:99]
	v_mfma_f32_16x16x32_bf16 v[88:91], v[154:157], v[214:217], v[88:91]
	v_mfma_f32_16x16x32_bf16 v[80:83], v[162:165], v[214:217], v[80:83]
	s_setprio 0
	s_barrier
	s_mov_b32 m0, s58
	ds_read_b128 v[218:221], v143
	ds_read_b128 v[222:225], v143 offset:1024
	ds_read_b128 v[226:229], v143 offset:2048
	global_load_lds_dwordx4 v130, s[30:31]
	s_mov_b32 m0, s59
	ds_read_b128 v[230:233], v143 offset:3072
	global_load_lds_dwordx4 v128, s[30:31]
	s_barrier
; #define PG8_STAGE(bufoff, gbase, voff) do { _Pragma("unroll") for (int _i = 0; _i < 2; ++_i) \
;         __builtin_amdgcn_global_load_lds((const unsigned*)((const char*)(gbase) + (voff)[_i]), (LAS unsigned*)(lds + (bufoff) + ldsw + _i * 8192), 16, 0, 0); } while (0)
; #define PG8_LDA(dst, b, h) do { _Pragma("unroll") for (int m = 0; m < 4; ++m) _Pragma("unroll") for (int k = 0; k < 2; ++k) dst[m][k] = *(const LAS bf16x8*)(lds + PG8_SA(b, h) + aoff + m * 2048 + k * 1024); } while (0)
; #define PG8_LDB(dst, b, h) do { _Pragma("unroll") for (int n = 0; n < 2; ++n) _Pragma("unroll") for (int k = 0; k < 2; ++k) dst[n][k] = *(const LAS bf16x8*)(lds + PG8_SB(b, h) + boff + n * 2048 + k * 1024); } while (0)
; #define PG8_MMA(ai, bj, At, Bt) do { __builtin_amdgcn_s_setprio(1); _Pragma("unroll") for (int m = 0; m < 4; ++m) _Pragma("unroll") for (int n = 0; n < 2; ++n) _Pragma("unroll") for (int k = 0; k < 2; ++k) \
;         acc[ai][bj][m][n] = __builtin_amdgcn_mfma_f32_16x16x32_bf16(Bt[n][k], At[m][k], acc[ai][bj][m][n], 0, 0, 0); __builtin_amdgcn_s_setprio(0); } while (0)
; #define PG8_WAIT_V(n) asm volatile("s_waitcnt vmcnt(" #n ")" ::: "memory")
; #define PG8_WAIT_L(n) asm volatile("s_waitcnt lgkmcnt(" #n ")" ::: "memory")
; #define PG8_BAR __builtin_amdgcn_s_barrier()
; #define PG8_SCHED __builtin_amdgcn_sched_barrier(0)
; template <class Epi, class Sched>
; DI void gemm_phase(LAS unsigned char* lds, const Gemm g, const Sched& S, const Epi& E) {
;     ...
;             PG8_BAR; PG8_WAIT_L(0); PG8_MMA(0, 1, At, B1); PG8_BAR;
;             PG8_LDA(At, 0, 1); PG8_STAGE(PG8_SA(0, 0), a2, voffA);
;             PG8_BAR; PG8_WAIT_L(0); PG8_MMA(1, 0, At, B0); PG8_BAR; PG8_SCHED;
;             PG8_STAGE(PG8_SB(0, 1), b2 + hstep, voffB);
;             PG8_WAIT_V(6); PG8_BAR; PG8_MMA(1, 1, At, B1); PG8_BAR;
;             PG8_LDB(B0, 1, 0); PG8_SCHED; PG8_LDA(At, 1, 0); PG8_STAGE(PG8_SA(0, 1), a2 + hstep, voffA);
	s_waitcnt lgkmcnt(0)
	s_setprio 1
	v_mfma_f32_16x16x32_bf16 v[108:111], v[218:221], v[166:169], v[108:111]
	v_mfma_f32_16x16x32_bf16 v[100:103], v[226:229], v[166:169], v[100:103]
	v_mfma_f32_16x16x32_bf16 v[92:95], v[218:221], v[174:177], v[92:95]
	v_mfma_f32_16x16x32_bf16 v[84:87], v[226:229], v[174:177], v[84:87]
	v_mfma_f32_16x16x32_bf16 v[76:79], v[218:221], v[188:191], v[76:79]
	v_mfma_f32_16x16x32_bf16 v[72:75], v[226:229], v[188:191], v[72:75]
	v_mfma_f32_16x16x32_bf16 v[68:71], v[218:221], v[210:213], v[68:71]
	v_mfma_f32_16x16x32_bf16 v[64:67], v[226:229], v[210:213], v[64:67]
	v_mfma_f32_16x16x32_bf16 v[108:111], v[222:225], v[170:173], v[108:111]
	v_mfma_f32_16x16x32_bf16 v[100:103], v[230:233], v[170:173], v[100:103]
	v_mfma_f32_16x16x32_bf16 v[92:95], v[222:225], v[178:181], v[92:95]
	v_mfma_f32_16x16x32_bf16 v[84:87], v[230:233], v[178:181], v[84:87]
	v_mfma_f32_16x16x32_bf16 v[76:79], v[222:225], v[206:209], v[76:79]
	v_mfma_f32_16x16x32_bf16 v[72:75], v[230:233], v[206:209], v[72:75]
	v_mfma_f32_16x16x32_bf16 v[68:71], v[222:225], v[214:217], v[68:71]
	v_mfma_f32_16x16x32_bf16 v[64:67], v[230:233], v[214:217], v[64:67]
	s_setprio 0
	s_mov_b32 m0, s40
	s_barrier
	ds_read_b128 v[166:169], v142 offset:16384
	ds_read_b128 v[170:173], v142 offset:17408
	ds_read_b128 v[174:177], v142 offset:18432
	ds_read_b128 v[178:181], v142 offset:19456
	ds_read_b128 v[188:191], v142 offset:20480
	ds_read_b128 v[206:209], v142 offset:21504
	ds_read_b128 v[210:213], v142 offset:22528
	global_load_lds_dwordx4 v130, s[36:37]
	s_mov_b32 m0, s41
	ds_read_b128 v[214:217], v142 offset:23552
	global_load_lds_dwordx4 v128, s[36:37]
	s_barrier
	s_waitcnt lgkmcnt(0)
	s_setprio 1
	v_mfma_f32_16x16x32_bf16 v[60:63], v[146:149], v[166:169], v[60:63]
	v_mfma_f32_16x16x32_bf16 v[56:59], v[158:161], v[166:169], v[56:59]
	v_mfma_f32_16x16x32_bf16 v[52:55], v[146:149], v[174:177], v[52:55]
	v_mfma_f32_16x16x32_bf16 v[48:51], v[158:161], v[174:177], v[48:51]
	v_mfma_f32_16x16x32_bf16 v[40:43], v[146:149], v[188:191], v[40:43]
	v_mfma_f32_16x16x32_bf16 v[32:35], v[158:161], v[188:191], v[32:35]
	v_mfma_f32_16x16x32_bf16 v[24:27], v[146:149], v[210:213], v[24:27]
	v_mfma_f32_16x16x32_bf16 v[16:19], v[158:161], v[210:213], v[16:19]
	v_mfma_f32_16x16x32_bf16 v[60:63], v[154:157], v[170:173], v[60:63]
	v_mfma_f32_16x16x32_bf16 v[56:59], v[162:165], v[170:173], v[56:59]
	v_mfma_f32_16x16x32_bf16 v[52:55], v[154:157], v[178:181], v[52:55]
	v_mfma_f32_16x16x32_bf16 v[48:51], v[162:165], v[178:181], v[48:51]
	v_mfma_f32_16x16x32_bf16 v[40:43], v[154:157], v[206:209], v[40:43]
	v_mfma_f32_16x16x32_bf16 v[32:35], v[162:165], v[206:209], v[32:35]
	v_mfma_f32_16x16x32_bf16 v[24:27], v[154:157], v[214:217], v[24:27]
	v_mfma_f32_16x16x32_bf16 v[16:19], v[162:165], v[214:217], v[16:19]
	s_setprio 0
	s_barrier
	s_add_u32 s0, s30, 0x160000
	s_addc_u32 s1, s31, 0
	s_mov_b32 m0, s60
	s_nop 0
	global_load_lds_dwordx4 v130, s[0:1]
	s_mov_b32 m0, s61
	s_nop 0
	global_load_lds_dwordx4 v128, s[0:1]
	s_waitcnt vmcnt(6)
	s_barrier
	s_setprio 1
	v_mfma_f32_16x16x32_bf16 v[44:47], v[218:221], v[166:169], v[44:47]
	v_mfma_f32_16x16x32_bf16 v[36:39], v[226:229], v[166:169], v[36:39]
	v_mfma_f32_16x16x32_bf16 v[28:31], v[218:221], v[174:177], v[28:31]
	v_mfma_f32_16x16x32_bf16 v[20:23], v[226:229], v[174:177], v[20:23]
	v_mfma_f32_16x16x32_bf16 v[12:15], v[218:221], v[188:191], v[12:15]
	v_mfma_f32_16x16x32_bf16 v[8:11], v[226:229], v[188:191], v[8:11]
	v_mfma_f32_16x16x32_bf16 v[4:7], v[218:221], v[210:213], v[4:7]
	v_mfma_f32_16x16x32_bf16 v[0:3], v[226:229], v[210:213], v[0:3]
	v_mfma_f32_16x16x32_bf16 v[44:47], v[222:225], v[170:173], v[44:47]
	v_mfma_f32_16x16x32_bf16 v[36:39], v[230:233], v[170:173], v[36:39]
	v_mfma_f32_16x16x32_bf16 v[28:31], v[222:225], v[178:181], v[28:31]
	v_mfma_f32_16x16x32_bf16 v[20:23], v[230:233], v[178:181], v[20:23]
	v_mfma_f32_16x16x32_bf16 v[12:15], v[222:225], v[206:209], v[12:15]
	v_mfma_f32_16x16x32_bf16 v[8:11], v[230:233], v[206:209], v[8:11]
	v_mfma_f32_16x16x32_bf16 v[4:7], v[222:225], v[214:217], v[4:7]
	v_mfma_f32_16x16x32_bf16 v[0:3], v[230:233], v[214:217], v[0:3]
	s_setprio 0
	s_barrier
	ds_read_b128 v[146:149], v144
	ds_read_b128 v[154:157], v144 offset:1024
	ds_read_b128 v[158:161], v144 offset:2048
	ds_read_b128 v[162:165], v144 offset:3072
	s_add_u32 s0, s36, 0x160000
	s_addc_u32 s1, s37, 0
	s_mov_b32 m0, s42
	ds_read_b128 v[166:169], v142 offset:32768
	ds_read_b128 v[170:173], v142 offset:33792
	ds_read_b128 v[174:177], v142 offset:34816
	ds_read_b128 v[178:181], v142 offset:35840
	ds_read_b128 v[188:191], v142 offset:36864
	ds_read_b128 v[206:209], v142 offset:37888
	ds_read_b128 v[210:213], v142 offset:38912
	global_load_lds_dwordx4 v130, s[0:1]
	s_mov_b32 m0, s43
	ds_read_b128 v[214:217], v142 offset:39936
	global_load_lds_dwordx4 v128, s[0:1]
	s_waitcnt lgkmcnt(8)
	s_barrier
; #define PG8_STAGE(bufoff, gbase, voff) do { _Pragma("unroll") for (int _i = 0; _i < 2; ++_i) \
;         __builtin_amdgcn_global_load_lds((const unsigned*)((const char*)(gbase) + (voff)[_i]), (LAS unsigned*)(lds + (bufoff) + ldsw + _i * 8192), 16, 0, 0); } while (0)
; #define PG8_LDA(dst, b, h) do { _Pragma("unroll") for (int m = 0; m < 4; ++m) _Pragma("unroll") for (int k = 0; k < 2; ++k) dst[m][k] = *(const LAS bf16x8*)(lds + PG8_SA(b, h) + aoff + m * 2048 + k * 1024); } while (0)
; #define PG8_LDB(dst, b, h) do { _Pragma("unroll") for (int n = 0; n < 2; ++n) _Pragma("unroll") for (int k = 0; k < 2; ++k) dst[n][k] = *(const LAS bf16x8*)(lds + PG8_SB(b, h) + boff + n * 2048 + k * 1024); } while (0)
; #define PG8_MMA(ai, bj, At, Bt) do { __builtin_amdgcn_s_setprio(1); _Pragma("unroll") for (int m = 0; m < 4; ++m) _Pragma("unroll") for (int n = 0; n < 2; ++n) _Pragma("unroll") for (int k = 0; k < 2; ++k) \
;         acc[ai][bj][m][n] = __builtin_amdgcn_mfma_f32_16x16x32_bf16(Bt[n][k], At[m][k], acc[ai][bj][m][n], 0, 0, 0); __builtin_amdgcn_s_setprio(0); } while (0)
; #define PG8_WAIT_V(n) asm volatile("s_waitcnt vmcnt(" #n ")" ::: "memory")
; #define PG8_WAIT_L(n) asm volatile("s_waitcnt lgkmcnt(" #n ")" ::: "memory")
; #define PG8_BAR __builtin_amdgcn_s_barrier()
; #define PG8_SCHED __builtin_amdgcn_sched_barrier(0)
; template <class Epi, class Sched>
; DI void gemm_phase(LAS unsigned char* lds, const Gemm g, const Sched& S, const Epi& E) {
;     ...
;             PG8_WAIT_L(8); PG8_BAR; PG8_WAIT_L(0); PG8_MMA(0, 0, At, B0); PG8_BAR; PG8_SCHED;
;             PG8_LDB(B1, 1, 1); PG8_STAGE(PG8_SB(1, 0), b3, voffB);
;             PG8_BAR; PG8_WAIT_L(0); PG8_MMA(0, 1, At, B1); PG8_BAR;
;             PG8_LDA(At, 1, 1); PG8_STAGE(PG8_SA(1, 0), a3, voffA);
;             PG8_BAR; PG8_WAIT_L(0); PG8_MMA(1, 0, At, B0); PG8_BAR; PG8_SCHED;
;             PG8_STAGE(PG8_SB(1, 1), b3 + hstep, voffB);
;             PG8_WAIT_V(6); PG8_BAR; PG8_MMA(1, 1, At, B1); PG8_BAR;
	s_waitcnt lgkmcnt(0)
	s_setprio 1
	v_mfma_f32_16x16x32_bf16 v[124:127], v[146:149], v[166:169], v[124:127]
	v_mfma_f32_16x16x32_bf16 v[120:123], v[158:161], v[166:169], v[120:123]
	v_mfma_f32_16x16x32_bf16 v[116:119], v[146:149], v[174:177], v[116:119]
	v_mfma_f32_16x16x32_bf16 v[112:115], v[158:161], v[174:177], v[112:115]
	v_mfma_f32_16x16x32_bf16 v[104:107], v[146:149], v[188:191], v[104:107]
	v_mfma_f32_16x16x32_bf16 v[96:99], v[158:161], v[188:191], v[96:99]
	v_mfma_f32_16x16x32_bf16 v[88:91], v[146:149], v[210:213], v[88:91]
	v_mfma_f32_16x16x32_bf16 v[80:83], v[158:161], v[210:213], v[80:83]
	v_mfma_f32_16x16x32_bf16 v[124:127], v[154:157], v[170:173], v[124:127]
	v_mfma_f32_16x16x32_bf16 v[120:123], v[162:165], v[170:173], v[120:123]
	v_mfma_f32_16x16x32_bf16 v[116:119], v[154:157], v[178:181], v[116:119]
	v_mfma_f32_16x16x32_bf16 v[112:115], v[162:165], v[178:181], v[112:115]
	v_mfma_f32_16x16x32_bf16 v[104:107], v[154:157], v[206:209], v[104:107]
	v_mfma_f32_16x16x32_bf16 v[96:99], v[162:165], v[206:209], v[96:99]
	v_mfma_f32_16x16x32_bf16 v[88:91], v[154:157], v[214:217], v[88:91]
	v_mfma_f32_16x16x32_bf16 v[80:83], v[162:165], v[214:217], v[80:83]
	s_setprio 0
	s_barrier
	s_add_i32 s4, 0, 0x1c000
	s_add_i32 s0, s62, s35
	v_add_u32_e32 v145, s4, v140
	s_add_i32 m0, s0, 0xffffff80
	ds_read_b128 v[218:221], v145
	ds_read_b128 v[222:225], v145 offset:1024
	ds_read_b128 v[226:229], v145 offset:2048
	global_load_lds_dwordx4 v130, s[30:31] offset:128
	s_add_i32 m0, s0, 0x1f80
	ds_read_b128 v[230:233], v145 offset:3072
	global_load_lds_dwordx4 v128, s[30:31] offset:128
	s_barrier
	s_waitcnt lgkmcnt(0)
	s_setprio 1
	v_mfma_f32_16x16x32_bf16 v[108:111], v[218:221], v[166:169], v[108:111]
	v_mfma_f32_16x16x32_bf16 v[100:103], v[226:229], v[166:169], v[100:103]
	v_mfma_f32_16x16x32_bf16 v[92:95], v[218:221], v[174:177], v[92:95]
	v_mfma_f32_16x16x32_bf16 v[84:87], v[226:229], v[174:177], v[84:87]
	v_mfma_f32_16x16x32_bf16 v[76:79], v[218:221], v[188:191], v[76:79]
	v_mfma_f32_16x16x32_bf16 v[72:75], v[226:229], v[188:191], v[72:75]
	v_mfma_f32_16x16x32_bf16 v[68:71], v[218:221], v[210:213], v[68:71]
	v_mfma_f32_16x16x32_bf16 v[64:67], v[226:229], v[210:213], v[64:67]
	v_mfma_f32_16x16x32_bf16 v[108:111], v[222:225], v[170:173], v[108:111]
	v_mfma_f32_16x16x32_bf16 v[100:103], v[230:233], v[170:173], v[100:103]
	v_mfma_f32_16x16x32_bf16 v[92:95], v[222:225], v[178:181], v[92:95]
	v_mfma_f32_16x16x32_bf16 v[84:87], v[230:233], v[178:181], v[84:87]
	v_mfma_f32_16x16x32_bf16 v[76:79], v[222:225], v[206:209], v[76:79]
	v_mfma_f32_16x16x32_bf16 v[72:75], v[230:233], v[206:209], v[72:75]
	v_mfma_f32_16x16x32_bf16 v[68:71], v[222:225], v[214:217], v[68:71]
	v_mfma_f32_16x16x32_bf16 v[64:67], v[230:233], v[214:217], v[64:67]
	s_setprio 0
	s_add_i32 m0, s54, 0xffffff80
	s_barrier
	ds_read_b128 v[166:169], v142 offset:49152
	ds_read_b128 v[170:173], v142 offset:50176
	ds_read_b128 v[174:177], v142 offset:51200
	ds_read_b128 v[178:181], v142 offset:52224
	ds_read_b128 v[188:191], v142 offset:53248
	ds_read_b128 v[206:209], v142 offset:54272
	ds_read_b128 v[210:213], v142 offset:55296
	global_load_lds_dwordx4 v130, s[36:37] offset:128
	s_add_i32 m0, s55, 0xffffff80
	ds_read_b128 v[214:217], v142 offset:56320
	global_load_lds_dwordx4 v128, s[36:37] offset:128
	s_barrier
	s_waitcnt lgkmcnt(0)
	s_setprio 1
	v_mfma_f32_16x16x32_bf16 v[60:63], v[146:149], v[166:169], v[60:63]
	v_mfma_f32_16x16x32_bf16 v[56:59], v[158:161], v[166:169], v[56:59]
	v_mfma_f32_16x16x32_bf16 v[52:55], v[146:149], v[174:177], v[52:55]
	v_mfma_f32_16x16x32_bf16 v[48:51], v[158:161], v[174:177], v[48:51]
	v_mfma_f32_16x16x32_bf16 v[40:43], v[146:149], v[188:191], v[40:43]
	v_mfma_f32_16x16x32_bf16 v[32:35], v[158:161], v[188:191], v[32:35]
	v_mfma_f32_16x16x32_bf16 v[24:27], v[146:149], v[210:213], v[24:27]
	v_mfma_f32_16x16x32_bf16 v[16:19], v[158:161], v[210:213], v[16:19]
	v_mfma_f32_16x16x32_bf16 v[60:63], v[154:157], v[170:173], v[60:63]
	v_mfma_f32_16x16x32_bf16 v[56:59], v[162:165], v[170:173], v[56:59]
	v_mfma_f32_16x16x32_bf16 v[52:55], v[154:157], v[178:181], v[52:55]
	v_mfma_f32_16x16x32_bf16 v[48:51], v[162:165], v[178:181], v[48:51]
	v_mfma_f32_16x16x32_bf16 v[40:43], v[154:157], v[206:209], v[40:43]
	v_mfma_f32_16x16x32_bf16 v[32:35], v[162:165], v[206:209], v[32:35]
	v_mfma_f32_16x16x32_bf16 v[24:27], v[154:157], v[214:217], v[24:27]
	v_mfma_f32_16x16x32_bf16 v[16:19], v[162:165], v[214:217], v[16:19]
	s_setprio 0
	s_barrier
	s_add_i32 s4, s4, s35
	s_mov_b32 m0, s4
	s_add_u32 s0, s30, 0x160080
	s_addc_u32 s1, s31, 0
	global_load_lds_dwordx4 v130, s[0:1]
	s_add_i32 m0, s4, 0x2000
	s_nop 0
	global_load_lds_dwordx4 v128, s[0:1]
	s_waitcnt vmcnt(6)
	s_barrier
	s_setprio 1
	v_mfma_f32_16x16x32_bf16 v[44:47], v[218:221], v[166:169], v[44:47]
	v_mfma_f32_16x16x32_bf16 v[36:39], v[226:229], v[166:169], v[36:39]
	v_mfma_f32_16x16x32_bf16 v[28:31], v[218:221], v[174:177], v[28:31]
	v_mfma_f32_16x16x32_bf16 v[20:23], v[226:229], v[174:177], v[20:23]
	v_mfma_f32_16x16x32_bf16 v[12:15], v[218:221], v[188:191], v[12:15]
	v_mfma_f32_16x16x32_bf16 v[8:11], v[226:229], v[188:191], v[8:11]
	v_mfma_f32_16x16x32_bf16 v[4:7], v[218:221], v[210:213], v[4:7]
	v_mfma_f32_16x16x32_bf16 v[0:3], v[226:229], v[210:213], v[0:3]
	v_mfma_f32_16x16x32_bf16 v[44:47], v[222:225], v[170:173], v[44:47]
	v_mfma_f32_16x16x32_bf16 v[36:39], v[230:233], v[170:173], v[36:39]
	v_mfma_f32_16x16x32_bf16 v[28:31], v[222:225], v[178:181], v[28:31]
	v_mfma_f32_16x16x32_bf16 v[20:23], v[230:233], v[178:181], v[20:23]
	v_mfma_f32_16x16x32_bf16 v[12:15], v[222:225], v[206:209], v[12:15]
	v_mfma_f32_16x16x32_bf16 v[8:11], v[230:233], v[206:209], v[8:11]
	v_mfma_f32_16x16x32_bf16 v[4:7], v[222:225], v[214:217], v[4:7]
	v_mfma_f32_16x16x32_bf16 v[0:3], v[230:233], v[214:217], v[0:3]
	s_setprio 0
	s_add_i32 s66, s66, 2
	s_add_u32 s8, s8, 0x100
	s_addc_u32 s9, s9, 0
	s_add_u32 s64, s64, 0x100
	s_addc_u32 s65, s65, 0
	s_cmp_gt_u32 s66, 5
	s_barrier
	s_cbranch_scc0 .LBB0_1775
